# loop-edge edit: K-loop back edge rotated (counter/exit test moved in front of the loop-closing barrier, barrier becomes loop head) in all six GEMM loops
# baseline (speedup 1.0000x reference)
; #define PG8_STAGE(bufoff, gbase, voff) do { _Pragma("unroll") for (int _i = 0; _i < 2; ++_i) \
;         __builtin_amdgcn_global_load_lds((const unsigned*)((const char*)(gbase) + (voff)[_i]), (PG8_LAS unsigned*)(lds + (bufoff) + ldsw + _i * 8192), 16, 0, 0); } while (0)
; #define PG8_LDA(dst, b, h) do { _Pragma("unroll") for (int m = 0; m < 4; ++m) _Pragma("unroll") for (int k = 0; k < 2; ++k) dst[m][k] = *(const PG8_LAS bf16x8*)(lds + PG8_SA(b, h) + aoff + m * 2048 + k * 1024); } while (0)
; #define PG8_SCHED __builtin_amdgcn_sched_barrier(0)
; __device__ __forceinline__ unsigned pk2(float lo, float hi) { return pg8::cvt_pk_bf16(lo, hi); }
; template <class Epi, class Sched, bool ALIGN_EPI = false, bool SP2 = false>
; __device__ __forceinline__ void gemm_phase(PG8_LAS unsigned char* lds, const Gemm g, const Sched& S, const Epi& E) {
;     ...
;         const bool has_next = S.next(ui + 1, nxt);
;         const char* nA = has_next ? (const char*)g.A + (size_t)nxt.pm * tstep : cA; const char* nB = has_next ? (const char*)g.Bt + (size_t)nxt.pn * tstep : cB;
;         for (int t = 0; t < nt; t += 2) {
;             const bool last = (t == nt - 2);
;             const char* a1 = cA + (size_t)(t + 1) * kstep;
;             const char* a2 = last ? nA : cA + (size_t)(t + 2) * kstep; const char* b2 = last ? nB : cB + (size_t)(t + 2) * kstep;
;             const char* a3 = a2 + kstep; const char* b3 = b2 + kstep;
;             if (last && has_next) S.a_ready(nxt);
;             if constexpr (SP2) {
;             PG8_LDB(B0, 0, 0); PG8_LDB(B1, 0, 1); PG8_SCHED; PG8_LDA(At, 0, 0); PG8_STAGE(PG8_SA(1, 1), a1 + hstep, voffA);
;     __device__ __forceinline__ void operator()(const f32x4 (&acc)[2][2][4][2], const pg8::Unit& u, int wr, int wc, int fr, int fq) const {
;     ...
;                 const int row = row0 + ai * 128 + m * 16;
;                 const float rs = sumsq ? rsqrtf(sumsq[row] * (1.f / 1024.f) + EPS) : 1.f;
;                 float o[8];
; #pragma unroll
;                 for (int n = 0; n < 2; ++n)
; #pragma unroll
;                     for (int e = 0; e < 4; ++e) { const float g = acc[ai][0][m][n][e] * rs, up = acc[ai][1][m][n][e] * rs; o[4 * n + e] = silu_f(g) * up; }
;                 u32x4 w; w.x = pk2(o[0], o[1]); w.y = pk2(o[2], o[3]); w.z = pk2(o[4], o[5]); w.w = pk2(o[6], o[7]);
;                 *(u32x4*)(H + (size_t)row * DFF + col) = w;
.LBB0_191:
	s_ashr_i32 s15, s14, 31
	s_lshl_b64 s[16:17], s[14:15], 19
	v_readlane_b32 s18, v235, 31
	v_readlane_b32 s19, v235, 32
	s_add_u32 s16, s18, s16
	s_addc_u32 s17, s19, s17
	s_and_b64 s[18:19], s[0:1], exec
	s_cselect_b32 s15, s17, s23
	s_cselect_b32 s50, s16, s22
	s_ashr_i32 s9, s8, 31
	s_lshl_b64 s[18:19], s[8:9], 19
	s_add_u32 s18, s33, s18
	s_addc_u32 s19, s34, s19
	s_and_b64 s[30:31], s[0:1], exec
	s_cselect_b32 s9, s19, s25
	s_cselect_b32 s51, s18, s24
	s_add_u32 s22, s22, 0x40080
	s_addc_u32 s23, s23, 0
	s_add_u32 s52, s24, 0x100
	s_addc_u32 s53, s25, 0
	s_mov_b32 s54, -2
	s_cmp_eq_u32 s98, 0
	s_cbranch_scc1 .Lp1_plain
	ds_read_b128 v[150:153], v147
	ds_read_b128 v[154:157], v147 offset:1024
	ds_read_b128 v[158:161], v147 offset:2048
	ds_read_b128 v[162:165], v147 offset:3072
	ds_read_b128 v[166:169], v148
	ds_read_b128 v[170:173], v148 offset:1024
	ds_read_b128 v[174:177], v148 offset:2048
	ds_read_b128 v[178:181], v148 offset:3072
	s_add_u32 s24, s22, 0xfffc0080
	s_addc_u32 s25, s23, -1
	s_cmp_eq_u32 s54, 12
	s_cselect_b32 s31, s15, s25
	s_cselect_b32 s30, s50, s24
	s_cselect_b32 s25, s9, s53
	s_cselect_b32 s24, s51, s52
	v_lshl_add_u64 v[186:187], s[22:23], 0, v[136:137]
	s_add_i32 m0, s21, 0xc000
	ds_read_b128 v[182:185], v149
	ds_read_b128 v[192:195], v149 offset:1024
	ds_read_b128 v[196:199], v149 offset:2048
	ds_read_b128 v[200:203], v149 offset:3072
	ds_read_b128 v[204:207], v149 offset:4096
	ds_read_b128 v[208:211], v149 offset:5120
	ds_read_b128 v[212:215], v149 offset:6144
	ds_read_b128 v[216:219], v149 offset:7168
	global_load_lds_dwordx4 v[186:187], off
	v_lshl_add_u64 v[186:187], s[22:23], 0, v[138:139]
	s_add_i32 m0, s21, 0xe000
	s_nop 0
	global_load_lds_dwordx4 v[186:187], off
	s_nop 1
	v_add_f32_e32 v64, 1.0, v70
	v_rcp_f32_e32 v64, v64
	v_add_f32_e32 v65, 1.0, v71
	v_rcp_f32_e32 v65, v65
	v_add_u32_e32 v66, 0x80, v228
	v_mul_f32_e32 v60, v60, v64
	v_mul_f32_e32 v52, v60, v52
	v_mul_f32_e32 v60, v61, v65
	v_mul_f32_e32 v61, 0xbfb8aa3b, v62
	v_exp_f32_e32 v61, v61
	v_mul_f32_e32 v64, 0xbfb8aa3b, v63
	v_exp_f32_e32 v64, v64
	v_mul_f32_e32 v53, v60, v53
	v_add_f32_e32 v60, 1.0, v61
	v_rcp_f32_e32 v60, v60
	v_add_f32_e32 v61, 1.0, v64
	v_mul_f32_e32 v64, 0xbfb8aa3b, v56
	v_rcp_f32_e32 v61, v61
	v_exp_f32_e32 v64, v64
	v_mul_f32_e32 v60, v62, v60
	v_mul_f32_e32 v54, v60, v54
	v_mul_f32_e32 v60, v63, v61
	v_add_f32_e32 v61, 1.0, v64
	v_rcp_f32_e32 v61, v61
	v_mul_f32_e32 v62, 0xbfb8aa3b, v57
	v_exp_f32_e32 v62, v62
	v_mul_f32_e32 v55, v60, v55
	v_mul_f32_e32 v56, v56, v61
	v_mul_f32_e32 v56, v56, v48
	v_add_f32_e32 v48, 1.0, v62
	v_mul_f32_e32 v60, 0xbfb8aa3b, v58
	v_rcp_f32_e32 v48, v48
	v_exp_f32_e32 v60, v60
	v_mul_f32_e32 v61, 0xbfb8aa3b, v59
	v_exp_f32_e32 v61, v61
	v_mul_f32_e32 v48, v57, v48
	v_add_f32_e32 v57, 1.0, v60
	v_rcp_f32_e32 v57, v57
	v_add_f32_e32 v60, 1.0, v61
	v_rcp_f32_e32 v60, v60
	v_mul_f32_e32 v61, v48, v49
	v_mul_f32_e32 v48, v58, v57
	v_mul_f32_e32 v57, v48, v50
	v_mul_f32_e32 v48, v59, v60
	v_mul_f32_e32 v51, v48, v51
	v_cvt_pk_bf16_f32 v48, v52, v53
	v_cvt_pk_bf16_f32 v49, v54, v55
	v_mul_f32_e32 v54, 0xbfb8aa3b, v44
	v_exp_f32_e32 v54, v54
	v_mul_f32_e32 v55, 0xbfb8aa3b, v45
	v_exp_f32_e32 v55, v55
	v_mad_i64_i32 v[52:53], s[100:101], v66, s48, v[112:113]
	v_lshl_add_u64 v[52:53], v[52:53], 0, v[114:115]
	v_cvt_pk_bf16_f32 v50, v56, v61
	v_cvt_pk_bf16_f32 v51, v57, v51
	global_store_dwordx4 v[52:53], v[48:51], off
	s_nop 1
	v_add_f32_e32 v48, 1.0, v54
	v_rcp_f32_e32 v48, v48
	v_add_f32_e32 v49, 1.0, v55
	v_rcp_f32_e32 v49, v49
	v_add_u32_e32 v50, 0x90, v228
	v_mul_f32_e32 v44, v44, v48
	v_mul_f32_e32 v36, v44, v36
	v_mul_f32_e32 v44, v45, v49
	v_mul_f32_e32 v45, 0xbfb8aa3b, v46
	v_exp_f32_e32 v45, v45
	v_mul_f32_e32 v48, 0xbfb8aa3b, v47
	v_exp_f32_e32 v48, v48
	v_mul_f32_e32 v37, v44, v37
	v_add_f32_e32 v44, 1.0, v45
	v_rcp_f32_e32 v44, v44
	v_add_f32_e32 v45, 1.0, v48
	v_mul_f32_e32 v48, 0xbfb8aa3b, v40
	v_rcp_f32_e32 v45, v45
	v_exp_f32_e32 v48, v48
	v_mul_f32_e32 v44, v46, v44
	v_mul_f32_e32 v38, v44, v38
	v_mul_f32_e32 v44, v47, v45
	v_add_f32_e32 v45, 1.0, v48
	v_rcp_f32_e32 v45, v45
	v_mul_f32_e32 v46, 0xbfb8aa3b, v41
	v_exp_f32_e32 v46, v46
	v_mul_f32_e32 v39, v44, v39
	v_mul_f32_e32 v40, v40, v45
	v_mul_f32_e32 v40, v40, v32
	v_add_f32_e32 v32, 1.0, v46
	v_mul_f32_e32 v44, 0xbfb8aa3b, v42
	v_rcp_f32_e32 v32, v32
	v_exp_f32_e32 v44, v44
	v_mul_f32_e32 v45, 0xbfb8aa3b, v43
	v_exp_f32_e32 v45, v45
	v_mul_f32_e32 v32, v41, v32
	v_add_f32_e32 v41, 1.0, v44
	v_rcp_f32_e32 v41, v41
	v_add_f32_e32 v44, 1.0, v45
	v_rcp_f32_e32 v44, v44
	v_mul_f32_e32 v45, v32, v33
	v_mul_f32_e32 v32, v42, v41
	v_mul_f32_e32 v41, v32, v34
	v_mul_f32_e32 v32, v43, v44
	v_mul_f32_e32 v35, v32, v35
	v_cvt_pk_bf16_f32 v32, v36, v37
	v_cvt_pk_bf16_f32 v33, v38, v39
	v_mul_f32_e32 v38, 0xbfb8aa3b, v28
	v_exp_f32_e32 v38, v38
	v_mul_f32_e32 v39, 0xbfb8aa3b, v29
	v_exp_f32_e32 v39, v39
	v_mad_i64_i32 v[36:37], s[100:101], v50, s48, v[112:113]
	v_lshl_add_u64 v[36:37], v[36:37], 0, v[114:115]
	v_cvt_pk_bf16_f32 v34, v40, v45
	v_cvt_pk_bf16_f32 v35, v41, v35
	global_store_dwordx4 v[36:37], v[32:35], off
	s_nop 1
	v_add_f32_e32 v32, 1.0, v38
	v_rcp_f32_e32 v32, v32
	v_add_f32_e32 v33, 1.0, v39
	v_rcp_f32_e32 v33, v33
	v_add_u32_e32 v34, 0xa0, v228
	v_mul_f32_e32 v28, v28, v32
	v_mul_f32_e32 v20, v28, v20
	v_mul_f32_e32 v28, v29, v33
	v_mul_f32_e32 v29, 0xbfb8aa3b, v30
	v_exp_f32_e32 v29, v29
	v_mul_f32_e32 v32, 0xbfb8aa3b, v31
	v_exp_f32_e32 v32, v32
	v_mul_f32_e32 v21, v28, v21
	v_add_f32_e32 v28, 1.0, v29
	v_rcp_f32_e32 v28, v28
	v_add_f32_e32 v29, 1.0, v32
	v_mul_f32_e32 v32, 0xbfb8aa3b, v24
	v_rcp_f32_e32 v29, v29
; #define PG8_STAGE(bufoff, gbase, voff) do { _Pragma("unroll") for (int _i = 0; _i < 2; ++_i) \
;         __builtin_amdgcn_global_load_lds((const unsigned*)((const char*)(gbase) + (voff)[_i]), (PG8_LAS unsigned*)(lds + (bufoff) + ldsw + _i * 8192), 16, 0, 0); } while (0)
; #define PG8_LDA(dst, b, h) do { _Pragma("unroll") for (int m = 0; m < 4; ++m) _Pragma("unroll") for (int k = 0; k < 2; ++k) dst[m][k] = *(const PG8_LAS bf16x8*)(lds + PG8_SA(b, h) + aoff + m * 2048 + k * 1024); } while (0)
; #define PG8_LDB(dst, b, h) do { _Pragma("unroll") for (int n = 0; n < 2; ++n) _Pragma("unroll") for (int k = 0; k < 2; ++k) dst[n][k] = *(const PG8_LAS bf16x8*)(lds + PG8_SB(b, h) + boff + n * 2048 + k * 1024); } while (0)
; #define PG8_WAIT_V(n) asm volatile("s_waitcnt vmcnt(" #n ")" ::: "memory")
; #define PG8_WAIT_L(n) asm volatile("s_waitcnt lgkmcnt(" #n ")" ::: "memory")
; #define PG8_BAR __builtin_amdgcn_s_barrier()
; #define PG8_SCHED __builtin_amdgcn_sched_barrier(0)
; __device__ __forceinline__ float silu_f(float x) { return x * sigmoid_f(x); }
; template <class Epi, class Sched, bool ALIGN_EPI = false, bool SP2 = false>
; __device__ __forceinline__ void gemm_phase(PG8_LAS unsigned char* lds, const Gemm g, const Sched& S, const Epi& E) {
;     ...
;             PG8_LDB(B0, 0, 0); PG8_LDB(B1, 0, 1); PG8_SCHED; PG8_LDA(At, 0, 0); PG8_STAGE(PG8_SA(1, 1), a1 + hstep, voffA);
;             PG8_WAIT_V(8); PG8_WAIT_L(0); PG8_BAR; PG8_MMA(0, 0, At, B0); PG8_MMA(0, 1, At, B1); PG8_BAR; PG8_SCHED;
;             PG8_LDA(At, 0, 1); PG8_STAGE(PG8_SB(0, 0), b2, voffB); PG8_STAGE(PG8_SB(0, 1), b2 + hstep, voffB); PG8_STAGE(PG8_SA(0, 0), a2, voffA);
;     __device__ __forceinline__ void operator()(const f32x4 (&acc)[2][2][4][2], const pg8::Unit& u, int wr, int wc, int fr, int fq) const {
;     ...
;                 const int row = row0 + ai * 128 + m * 16;
;                 const float rs = sumsq ? rsqrtf(sumsq[row] * (1.f / 1024.f) + EPS) : 1.f;
;                 float o[8];
; #pragma unroll
;                 for (int n = 0; n < 2; ++n)
; #pragma unroll
;                     for (int e = 0; e < 4; ++e) { const float g = acc[ai][0][m][n][e] * rs, up = acc[ai][1][m][n][e] * rs; o[4 * n + e] = silu_f(g) * up; }
;                 u32x4 w; w.x = pk2(o[0], o[1]); w.y = pk2(o[2], o[3]); w.z = pk2(o[4], o[5]); w.w = pk2(o[6], o[7]);
;                 *(u32x4*)(H + (size_t)row * DFF + col) = w;
	v_exp_f32_e32 v32, v32
	v_mul_f32_e32 v28, v30, v28
	v_mul_f32_e32 v22, v28, v22
	v_mul_f32_e32 v28, v31, v29
	v_add_f32_e32 v29, 1.0, v32
	v_rcp_f32_e32 v29, v29
	v_mul_f32_e32 v30, 0xbfb8aa3b, v25
	v_exp_f32_e32 v30, v30
	v_mul_f32_e32 v23, v28, v23
	v_mul_f32_e32 v24, v24, v29
	v_mul_f32_e32 v24, v24, v16
	v_add_f32_e32 v16, 1.0, v30
	v_mul_f32_e32 v28, 0xbfb8aa3b, v26
	v_rcp_f32_e32 v16, v16
	v_exp_f32_e32 v28, v28
	v_mul_f32_e32 v29, 0xbfb8aa3b, v27
	v_exp_f32_e32 v29, v29
	v_mul_f32_e32 v16, v25, v16
	v_add_f32_e32 v25, 1.0, v28
	v_rcp_f32_e32 v25, v25
	v_add_f32_e32 v28, 1.0, v29
	v_rcp_f32_e32 v28, v28
	v_mul_f32_e32 v29, v16, v17
	v_mul_f32_e32 v16, v26, v25
	v_mul_f32_e32 v25, v16, v18
	v_mul_f32_e32 v16, v27, v28
	v_mul_f32_e32 v19, v16, v19
	v_cvt_pk_bf16_f32 v16, v20, v21
	v_cvt_pk_bf16_f32 v17, v22, v23
	v_mul_f32_e32 v22, 0xbfb8aa3b, v12
	v_exp_f32_e32 v22, v22
	v_mul_f32_e32 v23, 0xbfb8aa3b, v13
	v_exp_f32_e32 v23, v23
	v_mad_i64_i32 v[20:21], s[100:101], v34, s48, v[112:113]
	v_lshl_add_u64 v[20:21], v[20:21], 0, v[114:115]
	v_cvt_pk_bf16_f32 v18, v24, v29
	v_cvt_pk_bf16_f32 v19, v25, v19
	global_store_dwordx4 v[20:21], v[16:19], off
	s_nop 1
	v_add_f32_e32 v16, 1.0, v22
	v_rcp_f32_e32 v16, v16
	v_add_f32_e32 v17, 1.0, v23
	v_rcp_f32_e32 v17, v17
	v_add_u32_e32 v18, 0xb0, v228
	v_mul_f32_e32 v12, v12, v16
	v_mul_f32_e32 v4, v12, v4
	v_mul_f32_e32 v12, v13, v17
	v_mul_f32_e32 v13, 0xbfb8aa3b, v14
	v_exp_f32_e32 v13, v13
	v_mul_f32_e32 v16, 0xbfb8aa3b, v15
	v_exp_f32_e32 v16, v16
	v_mul_f32_e32 v5, v12, v5
	v_add_f32_e32 v12, 1.0, v13
	v_rcp_f32_e32 v12, v12
	v_add_f32_e32 v13, 1.0, v16
	v_mul_f32_e32 v16, 0xbfb8aa3b, v8
	v_rcp_f32_e32 v13, v13
	v_exp_f32_e32 v16, v16
	v_mul_f32_e32 v12, v14, v12
	v_mul_f32_e32 v6, v12, v6
	v_mul_f32_e32 v12, v15, v13
	v_add_f32_e32 v13, 1.0, v16
	v_rcp_f32_e32 v13, v13
	v_mul_f32_e32 v14, 0xbfb8aa3b, v9
	v_exp_f32_e32 v14, v14
	v_mul_f32_e32 v7, v12, v7
	v_mul_f32_e32 v8, v8, v13
	v_mul_f32_e32 v8, v8, v0
	v_add_f32_e32 v0, 1.0, v14
	v_mul_f32_e32 v12, 0xbfb8aa3b, v10
	v_rcp_f32_e32 v0, v0
	v_exp_f32_e32 v12, v12
	v_mul_f32_e32 v13, 0xbfb8aa3b, v11
	v_exp_f32_e32 v13, v13
	v_mul_f32_e32 v0, v9, v0
	v_add_f32_e32 v9, 1.0, v12
	v_rcp_f32_e32 v9, v9
	v_add_f32_e32 v12, 1.0, v13
	v_rcp_f32_e32 v12, v12
	v_mul_f32_e32 v13, v0, v1
	v_mul_f32_e32 v0, v10, v9
	v_mul_f32_e32 v9, v0, v2
	v_mul_f32_e32 v0, v11, v12
	v_mul_f32_e32 v3, v0, v3
	v_cvt_pk_bf16_f32 v0, v4, v5
	v_mad_i64_i32 v[4:5], s[100:101], v18, s48, v[112:113]
	v_lshl_add_u64 v[4:5], v[4:5], 0, v[114:115]
	v_cvt_pk_bf16_f32 v1, v6, v7
	v_cvt_pk_bf16_f32 v2, v8, v13
	v_cvt_pk_bf16_f32 v3, v9, v3
	global_store_dwordx4 v[4:5], v[0:3], off
	s_waitcnt vmcnt(16)
	s_waitcnt lgkmcnt(0)
	s_barrier
	s_setprio 1
	v_mfma_f32_16x16x32_bf16 v[124:127], v[150:153], v[182:185], 0
	v_mfma_f32_16x16x32_bf16 v[120:123], v[158:161], v[182:185], 0
	v_mfma_f32_16x16x32_bf16 v[108:111], v[150:153], v[196:199], 0
	v_mfma_f32_16x16x32_bf16 v[104:107], v[158:161], v[196:199], 0
	v_mfma_f32_16x16x32_bf16 v[92:95], v[150:153], v[204:207], 0
	v_mfma_f32_16x16x32_bf16 v[88:91], v[158:161], v[204:207], 0
	v_mfma_f32_16x16x32_bf16 v[76:79], v[150:153], v[212:215], 0
	v_mfma_f32_16x16x32_bf16 v[72:75], v[158:161], v[212:215], 0
	v_mfma_f32_16x16x32_bf16 v[124:127], v[154:157], v[192:195], v[124:127]
	v_mfma_f32_16x16x32_bf16 v[120:123], v[162:165], v[192:195], v[120:123]
	v_mfma_f32_16x16x32_bf16 v[108:111], v[154:157], v[200:203], v[108:111]
	v_mfma_f32_16x16x32_bf16 v[104:107], v[162:165], v[200:203], v[104:107]
	v_mfma_f32_16x16x32_bf16 v[92:95], v[154:157], v[208:211], v[92:95]
	v_mfma_f32_16x16x32_bf16 v[88:91], v[162:165], v[208:211], v[88:91]
	v_mfma_f32_16x16x32_bf16 v[76:79], v[154:157], v[216:219], v[76:79]
	v_mfma_f32_16x16x32_bf16 v[72:75], v[162:165], v[216:219], v[72:75]
	v_mfma_f32_16x16x32_bf16 v[116:119], v[166:169], v[182:185], 0
	v_mfma_f32_16x16x32_bf16 v[112:115], v[174:177], v[182:185], 0
	v_mfma_f32_16x16x32_bf16 v[100:103], v[166:169], v[196:199], 0
	v_mfma_f32_16x16x32_bf16 v[96:99], v[174:177], v[196:199], 0
	v_mfma_f32_16x16x32_bf16 v[84:87], v[166:169], v[204:207], 0
	v_mfma_f32_16x16x32_bf16 v[80:83], v[174:177], v[204:207], 0
	v_mfma_f32_16x16x32_bf16 v[68:71], v[166:169], v[212:215], 0
	v_mfma_f32_16x16x32_bf16 v[64:67], v[174:177], v[212:215], 0
	v_mfma_f32_16x16x32_bf16 v[116:119], v[170:173], v[192:195], v[116:119]
	v_mfma_f32_16x16x32_bf16 v[112:115], v[178:181], v[192:195], v[112:115]
	v_mfma_f32_16x16x32_bf16 v[100:103], v[170:173], v[200:203], v[100:103]
	v_mfma_f32_16x16x32_bf16 v[96:99], v[178:181], v[200:203], v[96:99]
	v_mfma_f32_16x16x32_bf16 v[84:87], v[170:173], v[208:211], v[84:87]
	v_mfma_f32_16x16x32_bf16 v[80:83], v[178:181], v[208:211], v[80:83]
	v_mfma_f32_16x16x32_bf16 v[68:71], v[170:173], v[216:219], v[68:71]
	v_mfma_f32_16x16x32_bf16 v[64:67], v[178:181], v[216:219], v[64:67]
	s_setprio 0
	s_barrier
	s_add_i32 s55, s46, s35
	v_lshl_add_u64 v[186:187], s[24:25], 0, v[132:133]
	s_mov_b32 m0, s55
	ds_read_b128 v[182:185], v149 offset:16384
	ds_read_b128 v[192:195], v149 offset:17408
	ds_read_b128 v[196:199], v149 offset:18432
	ds_read_b128 v[200:203], v149 offset:19456
	ds_read_b128 v[204:207], v149 offset:20480
	ds_read_b128 v[208:211], v149 offset:21504
	ds_read_b128 v[212:215], v149 offset:22528
	ds_read_b128 v[216:219], v149 offset:23552
	global_load_lds_dwordx4 v[186:187], off
	s_add_i32 m0, s55, 0x2000
	s_add_u32 s56, s24, 0x40000
	v_lshl_add_u64 v[220:221], s[24:25], 0, v[128:129]
	s_addc_u32 s57, s25, 0
	s_add_i32 s55, s47, s35
	global_load_lds_dwordx4 v[220:221], off
	v_lshl_add_u64 v[222:223], s[56:57], 0, v[132:133]
	s_mov_b32 m0, s55
	v_lshl_add_u64 v[224:225], s[30:31], 0, v[130:131]
	global_load_lds_dwordx4 v[222:223], off
	v_lshl_add_u64 v[222:223], s[56:57], 0, v[128:129]
	s_add_i32 m0, s55, 0x2000
	s_nop 0
	global_load_lds_dwordx4 v[222:223], off
	v_lshl_add_u64 v[222:223], s[30:31], 0, v[134:135]
	s_mov_b32 m0, s21
	s_nop 0
	global_load_lds_dwordx4 v[222:223], off
	s_mov_b32 m0, s38
	s_nop 0
	global_load_lds_dwordx4 v[224:225], off
	s_waitcnt vmcnt(16)
	s_waitcnt lgkmcnt(0)
	s_barrier
; #define PG8_STAGE(bufoff, gbase, voff) do { _Pragma("unroll") for (int _i = 0; _i < 2; ++_i) \
;         __builtin_amdgcn_global_load_lds((const unsigned*)((const char*)(gbase) + (voff)[_i]), (PG8_LAS unsigned*)(lds + (bufoff) + ldsw + _i * 8192), 16, 0, 0); } while (0)
; #define PG8_LDA(dst, b, h) do { _Pragma("unroll") for (int m = 0; m < 4; ++m) _Pragma("unroll") for (int k = 0; k < 2; ++k) dst[m][k] = *(const PG8_LAS bf16x8*)(lds + PG8_SA(b, h) + aoff + m * 2048 + k * 1024); } while (0)
; #define PG8_LDB(dst, b, h) do { _Pragma("unroll") for (int n = 0; n < 2; ++n) _Pragma("unroll") for (int k = 0; k < 2; ++k) dst[n][k] = *(const PG8_LAS bf16x8*)(lds + PG8_SB(b, h) + boff + n * 2048 + k * 1024); } while (0)
; #define PG8_MMA(ai, bj, At, Bt) do { __builtin_amdgcn_s_setprio(1); _Pragma("unroll") for (int m = 0; m < 4; ++m) _Pragma("unroll") for (int n = 0; n < 2; ++n) _Pragma("unroll") for (int k = 0; k < 2; ++k) \
;         acc[ai][bj][m][n] = __builtin_amdgcn_mfma_f32_16x16x32_bf16(Bt[n][k], At[m][k], acc[ai][bj][m][n], 0, 0, 0); __builtin_amdgcn_s_setprio(0); } while (0)
; #define PG8_WAIT_V(n) asm volatile("s_waitcnt vmcnt(" #n ")" ::: "memory")
; #define PG8_WAIT_L(n) asm volatile("s_waitcnt lgkmcnt(" #n ")" ::: "memory")
; #define PG8_BAR __builtin_amdgcn_s_barrier()
; #define PG8_SCHED __builtin_amdgcn_sched_barrier(0)
; template <class Epi, class Sched, bool ALIGN_EPI = false, bool SP2 = false>
; __device__ __forceinline__ void gemm_phase(PG8_LAS unsigned char* lds, const Gemm g, const Sched& S, const Epi& E) {
;     ...
;             PG8_WAIT_V(8); PG8_WAIT_L(0); PG8_BAR; PG8_MMA(1, 0, At, B0); PG8_MMA(1, 1, At, B1); PG8_BAR; PG8_SCHED;
;             PG8_LDB(B0, 1, 0); PG8_LDB(B1, 1, 1); PG8_SCHED; PG8_LDA(At, 1, 0); PG8_STAGE(PG8_SA(0, 1), a2 + hstep, voffA);
;             PG8_WAIT_V(8); PG8_WAIT_L(0); PG8_BAR; PG8_MMA(0, 0, At, B0); PG8_MMA(0, 1, At, B1); PG8_BAR; PG8_SCHED;
	s_setprio 1
	v_mfma_f32_16x16x32_bf16 v[60:63], v[150:153], v[182:185], 0
	v_mfma_f32_16x16x32_bf16 v[56:59], v[158:161], v[182:185], 0
	v_mfma_f32_16x16x32_bf16 v[44:47], v[150:153], v[196:199], 0
	v_mfma_f32_16x16x32_bf16 v[40:43], v[158:161], v[196:199], 0
	v_mfma_f32_16x16x32_bf16 v[28:31], v[150:153], v[204:207], 0
	v_mfma_f32_16x16x32_bf16 v[24:27], v[158:161], v[204:207], 0
	v_mfma_f32_16x16x32_bf16 v[12:15], v[150:153], v[212:215], 0
	v_mfma_f32_16x16x32_bf16 v[8:11], v[158:161], v[212:215], 0
	v_mfma_f32_16x16x32_bf16 v[60:63], v[154:157], v[192:195], v[60:63]
	v_mfma_f32_16x16x32_bf16 v[56:59], v[162:165], v[192:195], v[56:59]
	v_mfma_f32_16x16x32_bf16 v[44:47], v[154:157], v[200:203], v[44:47]
	v_mfma_f32_16x16x32_bf16 v[40:43], v[162:165], v[200:203], v[40:43]
	v_mfma_f32_16x16x32_bf16 v[28:31], v[154:157], v[208:211], v[28:31]
	v_mfma_f32_16x16x32_bf16 v[24:27], v[162:165], v[208:211], v[24:27]
	v_mfma_f32_16x16x32_bf16 v[12:15], v[154:157], v[216:219], v[12:15]
	v_mfma_f32_16x16x32_bf16 v[8:11], v[162:165], v[216:219], v[8:11]
	v_mfma_f32_16x16x32_bf16 v[52:55], v[166:169], v[182:185], 0
	v_mfma_f32_16x16x32_bf16 v[48:51], v[174:177], v[182:185], 0
	v_mfma_f32_16x16x32_bf16 v[36:39], v[166:169], v[196:199], 0
	v_mfma_f32_16x16x32_bf16 v[32:35], v[174:177], v[196:199], 0
	v_mfma_f32_16x16x32_bf16 v[20:23], v[166:169], v[204:207], 0
	v_mfma_f32_16x16x32_bf16 v[16:19], v[174:177], v[204:207], 0
	v_mfma_f32_16x16x32_bf16 v[4:7], v[166:169], v[212:215], 0
	v_mfma_f32_16x16x32_bf16 v[0:3], v[174:177], v[212:215], 0
	v_mfma_f32_16x16x32_bf16 v[52:55], v[170:173], v[192:195], v[52:55]
	v_mfma_f32_16x16x32_bf16 v[48:51], v[178:181], v[192:195], v[48:51]
	v_mfma_f32_16x16x32_bf16 v[36:39], v[170:173], v[200:203], v[36:39]
	v_mfma_f32_16x16x32_bf16 v[32:35], v[178:181], v[200:203], v[32:35]
	v_mfma_f32_16x16x32_bf16 v[20:23], v[170:173], v[208:211], v[20:23]
	v_mfma_f32_16x16x32_bf16 v[16:19], v[178:181], v[208:211], v[16:19]
	v_mfma_f32_16x16x32_bf16 v[4:7], v[170:173], v[216:219], v[4:7]
	v_mfma_f32_16x16x32_bf16 v[0:3], v[178:181], v[216:219], v[0:3]
	s_setprio 0
	s_barrier
	s_add_i32 s55, 0, 0x18000
	s_add_i32 s56, 0, 0x1c000
	v_add_u32_e32 v162, s55, v145
	v_add_u32_e32 v178, s56, v145
	ds_read_b128 v[150:153], v162
	ds_read_b128 v[154:157], v162 offset:1024
	ds_read_b128 v[158:161], v162 offset:2048
	ds_read_b128 v[162:165], v162 offset:3072
	ds_read_b128 v[166:169], v178
	ds_read_b128 v[170:173], v178 offset:1024
	ds_read_b128 v[174:177], v178 offset:2048
	ds_read_b128 v[178:181], v178 offset:3072
	s_add_u32 s30, s30, 0x40000
	s_addc_u32 s31, s31, 0
	s_mov_b32 m0, s39
	v_lshl_add_u64 v[226:227], s[30:31], 0, v[134:135]
	ds_read_b128 v[182:185], v149 offset:32768
	ds_read_b128 v[192:195], v149 offset:33792
	ds_read_b128 v[196:199], v149 offset:34816
	ds_read_b128 v[200:203], v149 offset:35840
	ds_read_b128 v[204:207], v149 offset:36864
	ds_read_b128 v[208:211], v149 offset:37888
	ds_read_b128 v[212:215], v149 offset:38912
	ds_read_b128 v[216:219], v149 offset:39936
	global_load_lds_dwordx4 v[226:227], off
	v_lshl_add_u64 v[226:227], s[30:31], 0, v[130:131]
	s_mov_b32 m0, s40
	s_nop 0
	global_load_lds_dwordx4 v[226:227], off
	s_waitcnt vmcnt(8)
	s_waitcnt lgkmcnt(0)
	s_barrier
	s_setprio 1
	v_mfma_f32_16x16x32_bf16 v[124:127], v[150:153], v[182:185], v[124:127]
	v_mfma_f32_16x16x32_bf16 v[120:123], v[158:161], v[182:185], v[120:123]
	v_mfma_f32_16x16x32_bf16 v[108:111], v[150:153], v[196:199], v[108:111]
	v_mfma_f32_16x16x32_bf16 v[104:107], v[158:161], v[196:199], v[104:107]
	v_mfma_f32_16x16x32_bf16 v[92:95], v[150:153], v[204:207], v[92:95]
	v_mfma_f32_16x16x32_bf16 v[88:91], v[158:161], v[204:207], v[88:91]
	v_mfma_f32_16x16x32_bf16 v[76:79], v[150:153], v[212:215], v[76:79]
	v_mfma_f32_16x16x32_bf16 v[72:75], v[158:161], v[212:215], v[72:75]
	v_mfma_f32_16x16x32_bf16 v[124:127], v[154:157], v[192:195], v[124:127]
	v_mfma_f32_16x16x32_bf16 v[120:123], v[162:165], v[192:195], v[120:123]
	v_mfma_f32_16x16x32_bf16 v[108:111], v[154:157], v[200:203], v[108:111]
	v_mfma_f32_16x16x32_bf16 v[104:107], v[162:165], v[200:203], v[104:107]
	v_mfma_f32_16x16x32_bf16 v[92:95], v[154:157], v[208:211], v[92:95]
	v_mfma_f32_16x16x32_bf16 v[88:91], v[162:165], v[208:211], v[88:91]
	v_mfma_f32_16x16x32_bf16 v[76:79], v[154:157], v[216:219], v[76:79]
	v_mfma_f32_16x16x32_bf16 v[72:75], v[162:165], v[216:219], v[72:75]
	v_mfma_f32_16x16x32_bf16 v[116:119], v[166:169], v[182:185], v[116:119]
	v_mfma_f32_16x16x32_bf16 v[112:115], v[174:177], v[182:185], v[112:115]
	v_mfma_f32_16x16x32_bf16 v[100:103], v[166:169], v[196:199], v[100:103]
	v_mfma_f32_16x16x32_bf16 v[96:99], v[174:177], v[196:199], v[96:99]
	v_mfma_f32_16x16x32_bf16 v[84:87], v[166:169], v[204:207], v[84:87]
	v_mfma_f32_16x16x32_bf16 v[80:83], v[174:177], v[204:207], v[80:83]
	v_mfma_f32_16x16x32_bf16 v[68:71], v[166:169], v[212:215], v[68:71]
	v_mfma_f32_16x16x32_bf16 v[64:67], v[174:177], v[212:215], v[64:67]
	v_mfma_f32_16x16x32_bf16 v[116:119], v[170:173], v[192:195], v[116:119]
	v_mfma_f32_16x16x32_bf16 v[112:115], v[178:181], v[192:195], v[112:115]
	v_mfma_f32_16x16x32_bf16 v[100:103], v[170:173], v[200:203], v[100:103]
	v_mfma_f32_16x16x32_bf16 v[96:99], v[178:181], v[200:203], v[96:99]
	v_mfma_f32_16x16x32_bf16 v[84:87], v[170:173], v[208:211], v[84:87]
	v_mfma_f32_16x16x32_bf16 v[80:83], v[178:181], v[208:211], v[80:83]
	v_mfma_f32_16x16x32_bf16 v[68:71], v[170:173], v[216:219], v[68:71]
	v_mfma_f32_16x16x32_bf16 v[64:67], v[178:181], v[216:219], v[64:67]
	s_setprio 0
	s_barrier
; #define PG8_STAGE(bufoff, gbase, voff) do { _Pragma("unroll") for (int _i = 0; _i < 2; ++_i) \
;         __builtin_amdgcn_global_load_lds((const unsigned*)((const char*)(gbase) + (voff)[_i]), (PG8_LAS unsigned*)(lds + (bufoff) + ldsw + _i * 8192), 16, 0, 0); } while (0)
; #define PG8_LDA(dst, b, h) do { _Pragma("unroll") for (int m = 0; m < 4; ++m) _Pragma("unroll") for (int k = 0; k < 2; ++k) dst[m][k] = *(const PG8_LAS bf16x8*)(lds + PG8_SA(b, h) + aoff + m * 2048 + k * 1024); } while (0)
; #define PG8_LDB(dst, b, h) do { _Pragma("unroll") for (int n = 0; n < 2; ++n) _Pragma("unroll") for (int k = 0; k < 2; ++k) dst[n][k] = *(const PG8_LAS bf16x8*)(lds + PG8_SB(b, h) + boff + n * 2048 + k * 1024); } while (0)
; template <class Epi, class Sched, bool ALIGN_EPI = false, bool SP2 = false>
; __device__ __forceinline__ void gemm_phase(PG8_LAS unsigned char* lds, const Gemm g, const Sched& S, const Epi& E) {
;     ...
;         for (int t = 0; t < nt; t += 2) {
;             const bool last = (t == nt - 2);
;             const char* a1 = cA + (size_t)(t + 1) * kstep;
;             const char* a2 = last ? nA : cA + (size_t)(t + 2) * kstep; const char* b2 = last ? nB : cB + (size_t)(t + 2) * kstep;
;             const char* a3 = a2 + kstep; const char* b3 = b2 + kstep;
;             if (last && has_next) S.a_ready(nxt);
;             if constexpr (SP2) {
;             PG8_LDB(B0, 0, 0); PG8_LDB(B1, 0, 1); PG8_SCHED; PG8_LDA(At, 0, 0); PG8_STAGE(PG8_SA(1, 1), a1 + hstep, voffA);
;             PG8_WAIT_V(8); PG8_WAIT_L(0); PG8_BAR; PG8_MMA(0, 0, At, B0); PG8_MMA(0, 1, At, B1); PG8_BAR; PG8_SCHED;
;             PG8_LDA(At, 0, 1); PG8_STAGE(PG8_SB(0, 0), b2, voffB); PG8_STAGE(PG8_SB(0, 1), b2 + hstep, voffB); PG8_STAGE(PG8_SA(0, 0), a2, voffA);
;             PG8_WAIT_V(8); PG8_WAIT_L(0); PG8_BAR; PG8_MMA(1, 0, At, B0); PG8_MMA(1, 1, At, B1); PG8_BAR; PG8_SCHED;
;             PG8_LDB(B0, 1, 0); PG8_LDB(B1, 1, 1); PG8_SCHED; PG8_LDA(At, 1, 0); PG8_STAGE(PG8_SA(0, 1), a2 + hstep, voffA);
;             PG8_WAIT_V(8); PG8_WAIT_L(0); PG8_BAR; PG8_MMA(0, 0, At, B0); PG8_MMA(0, 1, At, B1); PG8_BAR; PG8_SCHED;
;             PG8_LDA(At, 1, 1); PG8_STAGE(PG8_SB(1, 0), b3, voffB); PG8_STAGE(PG8_SB(1, 1), b3 + hstep, voffB); PG8_STAGE(PG8_SA(1, 0), a3, voffA);
;             PG8_WAIT_V(8); PG8_WAIT_L(0); PG8_BAR; PG8_MMA(1, 0, At, B0); PG8_MMA(1, 1, At, B1); PG8_BAR; PG8_SCHED;
	s_add_i32 s30, s55, s35
	v_lshl_add_u64 v[186:187], v[186:187], 0, s[4:5]
	s_mov_b32 m0, s30
	ds_read_b128 v[182:185], v149 offset:49152
	ds_read_b128 v[192:195], v149 offset:50176
	ds_read_b128 v[196:199], v149 offset:51200
	ds_read_b128 v[200:203], v149 offset:52224
	ds_read_b128 v[204:207], v149 offset:53248
	ds_read_b128 v[208:211], v149 offset:54272
	ds_read_b128 v[212:215], v149 offset:55296
	ds_read_b128 v[216:219], v149 offset:56320
	global_load_lds_dwordx4 v[186:187], off
	s_add_i32 m0, s30, 0x2000
	s_add_u32 s24, s24, 0x40080
	v_lshl_add_u64 v[186:187], v[220:221], 0, s[4:5]
	s_addc_u32 s25, s25, 0
	s_add_i32 s30, s56, s35
	global_load_lds_dwordx4 v[186:187], off
	v_lshl_add_u64 v[186:187], s[24:25], 0, v[132:133]
	s_mov_b32 m0, s30
	s_nop 0
	global_load_lds_dwordx4 v[186:187], off
	v_lshl_add_u64 v[186:187], s[24:25], 0, v[128:129]
	s_add_i32 m0, s30, 0x2000
	s_nop 0
	global_load_lds_dwordx4 v[186:187], off
	v_lshl_add_u64 v[186:187], v[222:223], 0, s[4:5]
	s_mov_b32 m0, s42
	s_nop 0
	global_load_lds_dwordx4 v[186:187], off
	v_lshl_add_u64 v[186:187], v[224:225], 0, s[4:5]
	s_mov_b32 m0, s43
	s_nop 0
	global_load_lds_dwordx4 v[186:187], off
	s_waitcnt vmcnt(8)
	s_waitcnt lgkmcnt(0)
	s_barrier
	s_setprio 1
	v_mfma_f32_16x16x32_bf16 v[60:63], v[150:153], v[182:185], v[60:63]
	v_mfma_f32_16x16x32_bf16 v[56:59], v[158:161], v[182:185], v[56:59]
	v_mfma_f32_16x16x32_bf16 v[44:47], v[150:153], v[196:199], v[44:47]
	v_mfma_f32_16x16x32_bf16 v[40:43], v[158:161], v[196:199], v[40:43]
	v_mfma_f32_16x16x32_bf16 v[28:31], v[150:153], v[204:207], v[28:31]
	v_mfma_f32_16x16x32_bf16 v[24:27], v[158:161], v[204:207], v[24:27]
	v_mfma_f32_16x16x32_bf16 v[12:15], v[150:153], v[212:215], v[12:15]
	v_mfma_f32_16x16x32_bf16 v[8:11], v[158:161], v[212:215], v[8:11]
	v_mfma_f32_16x16x32_bf16 v[60:63], v[154:157], v[192:195], v[60:63]
	v_mfma_f32_16x16x32_bf16 v[56:59], v[162:165], v[192:195], v[56:59]
	v_mfma_f32_16x16x32_bf16 v[44:47], v[154:157], v[200:203], v[44:47]
	v_mfma_f32_16x16x32_bf16 v[40:43], v[162:165], v[200:203], v[40:43]
	v_mfma_f32_16x16x32_bf16 v[28:31], v[154:157], v[208:211], v[28:31]
	v_mfma_f32_16x16x32_bf16 v[24:27], v[162:165], v[208:211], v[24:27]
	v_mfma_f32_16x16x32_bf16 v[12:15], v[154:157], v[216:219], v[12:15]
	v_mfma_f32_16x16x32_bf16 v[8:11], v[162:165], v[216:219], v[8:11]
	v_mfma_f32_16x16x32_bf16 v[52:55], v[166:169], v[182:185], v[52:55]
	v_mfma_f32_16x16x32_bf16 v[48:51], v[174:177], v[182:185], v[48:51]
	v_mfma_f32_16x16x32_bf16 v[36:39], v[166:169], v[196:199], v[36:39]
	v_mfma_f32_16x16x32_bf16 v[32:35], v[174:177], v[196:199], v[32:35]
	v_mfma_f32_16x16x32_bf16 v[20:23], v[166:169], v[204:207], v[20:23]
	v_mfma_f32_16x16x32_bf16 v[16:19], v[174:177], v[204:207], v[16:19]
	v_mfma_f32_16x16x32_bf16 v[4:7], v[166:169], v[212:215], v[4:7]
	v_mfma_f32_16x16x32_bf16 v[0:3], v[174:177], v[212:215], v[0:3]
	v_mfma_f32_16x16x32_bf16 v[52:55], v[170:173], v[192:195], v[52:55]
	v_mfma_f32_16x16x32_bf16 v[48:51], v[178:181], v[192:195], v[48:51]
	v_mfma_f32_16x16x32_bf16 v[36:39], v[170:173], v[200:203], v[36:39]
	v_mfma_f32_16x16x32_bf16 v[32:35], v[178:181], v[200:203], v[32:35]
	v_mfma_f32_16x16x32_bf16 v[20:23], v[170:173], v[208:211], v[20:23]
	v_mfma_f32_16x16x32_bf16 v[16:19], v[178:181], v[208:211], v[16:19]
	v_mfma_f32_16x16x32_bf16 v[4:7], v[170:173], v[216:219], v[4:7]
	v_mfma_f32_16x16x32_bf16 v[0:3], v[178:181], v[216:219], v[0:3]
	s_setprio 0
	s_nop 0
	s_add_i32 s54, s54, 2
	s_add_u32 s22, s22, 0x100
	s_addc_u32 s23, s23, 0
	s_add_u32 s52, s52, 0x100
	s_addc_u32 s53, s53, 0
	s_branch .Lrot_192
.Lp1_plain:
	ds_read_b128 v[150:153], v147
	ds_read_b128 v[154:157], v147 offset:1024
	ds_read_b128 v[158:161], v147 offset:2048
	ds_read_b128 v[162:165], v147 offset:3072
	ds_read_b128 v[166:169], v148
	ds_read_b128 v[170:173], v148 offset:1024
	ds_read_b128 v[174:177], v148 offset:2048
	ds_read_b128 v[178:181], v148 offset:3072
	s_add_u32 s24, s22, 0xfffc0080
	s_addc_u32 s25, s23, -1
	s_cmp_eq_u32 s54, 12
	s_cselect_b32 s31, s15, s25
	s_cselect_b32 s30, s50, s24
	s_cselect_b32 s25, s9, s53
	s_cselect_b32 s24, s51, s52
	v_lshl_add_u64 v[186:187], s[22:23], 0, v[136:137]
	s_add_i32 m0, s21, 0xc000
	ds_read_b128 v[182:185], v149
	ds_read_b128 v[192:195], v149 offset:1024
	ds_read_b128 v[196:199], v149 offset:2048
	ds_read_b128 v[200:203], v149 offset:3072
	ds_read_b128 v[204:207], v149 offset:4096
	ds_read_b128 v[208:211], v149 offset:5120
	ds_read_b128 v[212:215], v149 offset:6144
	ds_read_b128 v[216:219], v149 offset:7168
	global_load_lds_dwordx4 v[186:187], off
	v_lshl_add_u64 v[186:187], s[22:23], 0, v[138:139]
	s_add_i32 m0, s21, 0xe000
	s_nop 0
	global_load_lds_dwordx4 v[186:187], off
	s_waitcnt vmcnt(16)
	s_waitcnt lgkmcnt(0)
	s_barrier
; #define PG8_STAGE(bufoff, gbase, voff) do { _Pragma("unroll") for (int _i = 0; _i < 2; ++_i) \
;         __builtin_amdgcn_global_load_lds((const unsigned*)((const char*)(gbase) + (voff)[_i]), (PG8_LAS unsigned*)(lds + (bufoff) + ldsw + _i * 8192), 16, 0, 0); } while (0)
; #define PG8_LDA(dst, b, h) do { _Pragma("unroll") for (int m = 0; m < 4; ++m) _Pragma("unroll") for (int k = 0; k < 2; ++k) dst[m][k] = *(const PG8_LAS bf16x8*)(lds + PG8_SA(b, h) + aoff + m * 2048 + k * 1024); } while (0)
; #define PG8_MMA(ai, bj, At, Bt) do { __builtin_amdgcn_s_setprio(1); _Pragma("unroll") for (int m = 0; m < 4; ++m) _Pragma("unroll") for (int n = 0; n < 2; ++n) _Pragma("unroll") for (int k = 0; k < 2; ++k) \
;         acc[ai][bj][m][n] = __builtin_amdgcn_mfma_f32_16x16x32_bf16(Bt[n][k], At[m][k], acc[ai][bj][m][n], 0, 0, 0); __builtin_amdgcn_s_setprio(0); } while (0)
; #define PG8_WAIT_V(n) asm volatile("s_waitcnt vmcnt(" #n ")" ::: "memory")
; #define PG8_WAIT_L(n) asm volatile("s_waitcnt lgkmcnt(" #n ")" ::: "memory")
; #define PG8_BAR __builtin_amdgcn_s_barrier()
; #define PG8_SCHED __builtin_amdgcn_sched_barrier(0)
; template <class Epi, class Sched, bool ALIGN_EPI = false, bool SP2 = false>
; __device__ __forceinline__ void gemm_phase(PG8_LAS unsigned char* lds, const Gemm g, const Sched& S, const Epi& E) {
;     ...
;             PG8_WAIT_V(8); PG8_WAIT_L(0); PG8_BAR; PG8_MMA(0, 0, At, B0); PG8_MMA(0, 1, At, B1); PG8_BAR; PG8_SCHED;
;             PG8_LDA(At, 0, 1); PG8_STAGE(PG8_SB(0, 0), b2, voffB); PG8_STAGE(PG8_SB(0, 1), b2 + hstep, voffB); PG8_STAGE(PG8_SA(0, 0), a2, voffA);
;             PG8_WAIT_V(8); PG8_WAIT_L(0); PG8_BAR; PG8_MMA(1, 0, At, B0); PG8_MMA(1, 1, At, B1); PG8_BAR; PG8_SCHED;
	s_setprio 1
	v_mfma_f32_16x16x32_bf16 v[124:127], v[150:153], v[182:185], 0
	v_mfma_f32_16x16x32_bf16 v[120:123], v[158:161], v[182:185], 0
	v_mfma_f32_16x16x32_bf16 v[108:111], v[150:153], v[196:199], 0
	v_mfma_f32_16x16x32_bf16 v[104:107], v[158:161], v[196:199], 0
	v_mfma_f32_16x16x32_bf16 v[92:95], v[150:153], v[204:207], 0
	v_mfma_f32_16x16x32_bf16 v[88:91], v[158:161], v[204:207], 0
	v_mfma_f32_16x16x32_bf16 v[76:79], v[150:153], v[212:215], 0
	v_mfma_f32_16x16x32_bf16 v[72:75], v[158:161], v[212:215], 0
	v_mfma_f32_16x16x32_bf16 v[124:127], v[154:157], v[192:195], v[124:127]
	v_mfma_f32_16x16x32_bf16 v[120:123], v[162:165], v[192:195], v[120:123]
	v_mfma_f32_16x16x32_bf16 v[108:111], v[154:157], v[200:203], v[108:111]
	v_mfma_f32_16x16x32_bf16 v[104:107], v[162:165], v[200:203], v[104:107]
	v_mfma_f32_16x16x32_bf16 v[92:95], v[154:157], v[208:211], v[92:95]
	v_mfma_f32_16x16x32_bf16 v[88:91], v[162:165], v[208:211], v[88:91]
	v_mfma_f32_16x16x32_bf16 v[76:79], v[154:157], v[216:219], v[76:79]
	v_mfma_f32_16x16x32_bf16 v[72:75], v[162:165], v[216:219], v[72:75]
	v_mfma_f32_16x16x32_bf16 v[116:119], v[166:169], v[182:185], 0
	v_mfma_f32_16x16x32_bf16 v[112:115], v[174:177], v[182:185], 0
	v_mfma_f32_16x16x32_bf16 v[100:103], v[166:169], v[196:199], 0
	v_mfma_f32_16x16x32_bf16 v[96:99], v[174:177], v[196:199], 0
	v_mfma_f32_16x16x32_bf16 v[84:87], v[166:169], v[204:207], 0
	v_mfma_f32_16x16x32_bf16 v[80:83], v[174:177], v[204:207], 0
	v_mfma_f32_16x16x32_bf16 v[68:71], v[166:169], v[212:215], 0
	v_mfma_f32_16x16x32_bf16 v[64:67], v[174:177], v[212:215], 0
	v_mfma_f32_16x16x32_bf16 v[116:119], v[170:173], v[192:195], v[116:119]
	v_mfma_f32_16x16x32_bf16 v[112:115], v[178:181], v[192:195], v[112:115]
	v_mfma_f32_16x16x32_bf16 v[100:103], v[170:173], v[200:203], v[100:103]
	v_mfma_f32_16x16x32_bf16 v[96:99], v[178:181], v[200:203], v[96:99]
	v_mfma_f32_16x16x32_bf16 v[84:87], v[170:173], v[208:211], v[84:87]
	v_mfma_f32_16x16x32_bf16 v[80:83], v[178:181], v[208:211], v[80:83]
	v_mfma_f32_16x16x32_bf16 v[68:71], v[170:173], v[216:219], v[68:71]
	v_mfma_f32_16x16x32_bf16 v[64:67], v[178:181], v[216:219], v[64:67]
	s_setprio 0
	s_barrier
	s_add_i32 s55, s46, s35
	v_lshl_add_u64 v[186:187], s[24:25], 0, v[132:133]
	s_mov_b32 m0, s55
	ds_read_b128 v[182:185], v149 offset:16384
	ds_read_b128 v[192:195], v149 offset:17408
	ds_read_b128 v[196:199], v149 offset:18432
	ds_read_b128 v[200:203], v149 offset:19456
	ds_read_b128 v[204:207], v149 offset:20480
	ds_read_b128 v[208:211], v149 offset:21504
	ds_read_b128 v[212:215], v149 offset:22528
	ds_read_b128 v[216:219], v149 offset:23552
	global_load_lds_dwordx4 v[186:187], off
	s_add_i32 m0, s55, 0x2000
	s_add_u32 s56, s24, 0x40000
	v_lshl_add_u64 v[220:221], s[24:25], 0, v[128:129]
	s_addc_u32 s57, s25, 0
	s_add_i32 s55, s47, s35
	global_load_lds_dwordx4 v[220:221], off
	v_lshl_add_u64 v[222:223], s[56:57], 0, v[132:133]
	s_mov_b32 m0, s55
	v_lshl_add_u64 v[224:225], s[30:31], 0, v[130:131]
	global_load_lds_dwordx4 v[222:223], off
	v_lshl_add_u64 v[222:223], s[56:57], 0, v[128:129]
	s_add_i32 m0, s55, 0x2000
	s_nop 0
	global_load_lds_dwordx4 v[222:223], off
	v_lshl_add_u64 v[222:223], s[30:31], 0, v[134:135]
	s_mov_b32 m0, s21
	s_nop 0
	global_load_lds_dwordx4 v[222:223], off
	s_mov_b32 m0, s38
	s_nop 0
	global_load_lds_dwordx4 v[224:225], off
	s_waitcnt vmcnt(16)
	s_waitcnt lgkmcnt(0)
	s_barrier
	s_setprio 1
	v_mfma_f32_16x16x32_bf16 v[60:63], v[150:153], v[182:185], 0
	v_mfma_f32_16x16x32_bf16 v[56:59], v[158:161], v[182:185], 0
	v_mfma_f32_16x16x32_bf16 v[44:47], v[150:153], v[196:199], 0
	v_mfma_f32_16x16x32_bf16 v[40:43], v[158:161], v[196:199], 0
	v_mfma_f32_16x16x32_bf16 v[28:31], v[150:153], v[204:207], 0
	v_mfma_f32_16x16x32_bf16 v[24:27], v[158:161], v[204:207], 0
	v_mfma_f32_16x16x32_bf16 v[12:15], v[150:153], v[212:215], 0
	v_mfma_f32_16x16x32_bf16 v[8:11], v[158:161], v[212:215], 0
	v_mfma_f32_16x16x32_bf16 v[60:63], v[154:157], v[192:195], v[60:63]
	v_mfma_f32_16x16x32_bf16 v[56:59], v[162:165], v[192:195], v[56:59]
	v_mfma_f32_16x16x32_bf16 v[44:47], v[154:157], v[200:203], v[44:47]
	v_mfma_f32_16x16x32_bf16 v[40:43], v[162:165], v[200:203], v[40:43]
	v_mfma_f32_16x16x32_bf16 v[28:31], v[154:157], v[208:211], v[28:31]
	v_mfma_f32_16x16x32_bf16 v[24:27], v[162:165], v[208:211], v[24:27]
	v_mfma_f32_16x16x32_bf16 v[12:15], v[154:157], v[216:219], v[12:15]
	v_mfma_f32_16x16x32_bf16 v[8:11], v[162:165], v[216:219], v[8:11]
	v_mfma_f32_16x16x32_bf16 v[52:55], v[166:169], v[182:185], 0
	v_mfma_f32_16x16x32_bf16 v[48:51], v[174:177], v[182:185], 0
	v_mfma_f32_16x16x32_bf16 v[36:39], v[166:169], v[196:199], 0
	v_mfma_f32_16x16x32_bf16 v[32:35], v[174:177], v[196:199], 0
	v_mfma_f32_16x16x32_bf16 v[20:23], v[166:169], v[204:207], 0
	v_mfma_f32_16x16x32_bf16 v[16:19], v[174:177], v[204:207], 0
	v_mfma_f32_16x16x32_bf16 v[4:7], v[166:169], v[212:215], 0
	v_mfma_f32_16x16x32_bf16 v[0:3], v[174:177], v[212:215], 0
	v_mfma_f32_16x16x32_bf16 v[52:55], v[170:173], v[192:195], v[52:55]
	v_mfma_f32_16x16x32_bf16 v[48:51], v[178:181], v[192:195], v[48:51]
	v_mfma_f32_16x16x32_bf16 v[36:39], v[170:173], v[200:203], v[36:39]
	v_mfma_f32_16x16x32_bf16 v[32:35], v[178:181], v[200:203], v[32:35]
	v_mfma_f32_16x16x32_bf16 v[20:23], v[170:173], v[208:211], v[20:23]
	v_mfma_f32_16x16x32_bf16 v[16:19], v[178:181], v[208:211], v[16:19]
	v_mfma_f32_16x16x32_bf16 v[4:7], v[170:173], v[216:219], v[4:7]
	v_mfma_f32_16x16x32_bf16 v[0:3], v[178:181], v[216:219], v[0:3]
	s_setprio 0
	s_barrier
; #define PG8_STAGE(bufoff, gbase, voff) do { _Pragma("unroll") for (int _i = 0; _i < 2; ++_i) \
;         __builtin_amdgcn_global_load_lds((const unsigned*)((const char*)(gbase) + (voff)[_i]), (PG8_LAS unsigned*)(lds + (bufoff) + ldsw + _i * 8192), 16, 0, 0); } while (0)
; #define PG8_LDA(dst, b, h) do { _Pragma("unroll") for (int m = 0; m < 4; ++m) _Pragma("unroll") for (int k = 0; k < 2; ++k) dst[m][k] = *(const PG8_LAS bf16x8*)(lds + PG8_SA(b, h) + aoff + m * 2048 + k * 1024); } while (0)
; #define PG8_LDB(dst, b, h) do { _Pragma("unroll") for (int n = 0; n < 2; ++n) _Pragma("unroll") for (int k = 0; k < 2; ++k) dst[n][k] = *(const PG8_LAS bf16x8*)(lds + PG8_SB(b, h) + boff + n * 2048 + k * 1024); } while (0)
; #define PG8_MMA(ai, bj, At, Bt) do { __builtin_amdgcn_s_setprio(1); _Pragma("unroll") for (int m = 0; m < 4; ++m) _Pragma("unroll") for (int n = 0; n < 2; ++n) _Pragma("unroll") for (int k = 0; k < 2; ++k) \
;         acc[ai][bj][m][n] = __builtin_amdgcn_mfma_f32_16x16x32_bf16(Bt[n][k], At[m][k], acc[ai][bj][m][n], 0, 0, 0); __builtin_amdgcn_s_setprio(0); } while (0)
; #define PG8_WAIT_V(n) asm volatile("s_waitcnt vmcnt(" #n ")" ::: "memory")
; #define PG8_WAIT_L(n) asm volatile("s_waitcnt lgkmcnt(" #n ")" ::: "memory")
; #define PG8_BAR __builtin_amdgcn_s_barrier()
; #define PG8_SCHED __builtin_amdgcn_sched_barrier(0)
; template <class Epi, class Sched, bool ALIGN_EPI = false, bool SP2 = false>
; __device__ __forceinline__ void gemm_phase(PG8_LAS unsigned char* lds, const Gemm g, const Sched& S, const Epi& E) {
;     ...
;             PG8_LDB(B0, 1, 0); PG8_LDB(B1, 1, 1); PG8_SCHED; PG8_LDA(At, 1, 0); PG8_STAGE(PG8_SA(0, 1), a2 + hstep, voffA);
;             PG8_WAIT_V(8); PG8_WAIT_L(0); PG8_BAR; PG8_MMA(0, 0, At, B0); PG8_MMA(0, 1, At, B1); PG8_BAR; PG8_SCHED;
;             PG8_LDA(At, 1, 1); PG8_STAGE(PG8_SB(1, 0), b3, voffB); PG8_STAGE(PG8_SB(1, 1), b3 + hstep, voffB); PG8_STAGE(PG8_SA(1, 0), a3, voffA);
;             PG8_WAIT_V(8); PG8_WAIT_L(0); PG8_BAR; PG8_MMA(1, 0, At, B0); PG8_MMA(1, 1, At, B1); PG8_BAR; PG8_SCHED;
	s_add_i32 s55, 0, 0x18000
	s_add_i32 s56, 0, 0x1c000
	v_add_u32_e32 v162, s55, v145
	v_add_u32_e32 v178, s56, v145
	ds_read_b128 v[150:153], v162
	ds_read_b128 v[154:157], v162 offset:1024
	ds_read_b128 v[158:161], v162 offset:2048
	ds_read_b128 v[162:165], v162 offset:3072
	ds_read_b128 v[166:169], v178
	ds_read_b128 v[170:173], v178 offset:1024
	ds_read_b128 v[174:177], v178 offset:2048
	ds_read_b128 v[178:181], v178 offset:3072
	s_add_u32 s30, s30, 0x40000
	s_addc_u32 s31, s31, 0
	s_mov_b32 m0, s39
	v_lshl_add_u64 v[226:227], s[30:31], 0, v[134:135]
	ds_read_b128 v[182:185], v149 offset:32768
	ds_read_b128 v[192:195], v149 offset:33792
	ds_read_b128 v[196:199], v149 offset:34816
	ds_read_b128 v[200:203], v149 offset:35840
	ds_read_b128 v[204:207], v149 offset:36864
	ds_read_b128 v[208:211], v149 offset:37888
	ds_read_b128 v[212:215], v149 offset:38912
	ds_read_b128 v[216:219], v149 offset:39936
	global_load_lds_dwordx4 v[226:227], off
	v_lshl_add_u64 v[226:227], s[30:31], 0, v[130:131]
	s_mov_b32 m0, s40
	s_nop 0
	global_load_lds_dwordx4 v[226:227], off
	s_waitcnt vmcnt(8)
	s_waitcnt lgkmcnt(0)
	s_barrier
	s_setprio 1
	v_mfma_f32_16x16x32_bf16 v[124:127], v[150:153], v[182:185], v[124:127]
	v_mfma_f32_16x16x32_bf16 v[120:123], v[158:161], v[182:185], v[120:123]
	v_mfma_f32_16x16x32_bf16 v[108:111], v[150:153], v[196:199], v[108:111]
	v_mfma_f32_16x16x32_bf16 v[104:107], v[158:161], v[196:199], v[104:107]
	v_mfma_f32_16x16x32_bf16 v[92:95], v[150:153], v[204:207], v[92:95]
	v_mfma_f32_16x16x32_bf16 v[88:91], v[158:161], v[204:207], v[88:91]
	v_mfma_f32_16x16x32_bf16 v[76:79], v[150:153], v[212:215], v[76:79]
	v_mfma_f32_16x16x32_bf16 v[72:75], v[158:161], v[212:215], v[72:75]
	v_mfma_f32_16x16x32_bf16 v[124:127], v[154:157], v[192:195], v[124:127]
	v_mfma_f32_16x16x32_bf16 v[120:123], v[162:165], v[192:195], v[120:123]
	v_mfma_f32_16x16x32_bf16 v[108:111], v[154:157], v[200:203], v[108:111]
	v_mfma_f32_16x16x32_bf16 v[104:107], v[162:165], v[200:203], v[104:107]
	v_mfma_f32_16x16x32_bf16 v[92:95], v[154:157], v[208:211], v[92:95]
	v_mfma_f32_16x16x32_bf16 v[88:91], v[162:165], v[208:211], v[88:91]
	v_mfma_f32_16x16x32_bf16 v[76:79], v[154:157], v[216:219], v[76:79]
	v_mfma_f32_16x16x32_bf16 v[72:75], v[162:165], v[216:219], v[72:75]
	v_mfma_f32_16x16x32_bf16 v[116:119], v[166:169], v[182:185], v[116:119]
	v_mfma_f32_16x16x32_bf16 v[112:115], v[174:177], v[182:185], v[112:115]
	v_mfma_f32_16x16x32_bf16 v[100:103], v[166:169], v[196:199], v[100:103]
	v_mfma_f32_16x16x32_bf16 v[96:99], v[174:177], v[196:199], v[96:99]
	v_mfma_f32_16x16x32_bf16 v[84:87], v[166:169], v[204:207], v[84:87]
	v_mfma_f32_16x16x32_bf16 v[80:83], v[174:177], v[204:207], v[80:83]
	v_mfma_f32_16x16x32_bf16 v[68:71], v[166:169], v[212:215], v[68:71]
	v_mfma_f32_16x16x32_bf16 v[64:67], v[174:177], v[212:215], v[64:67]
	v_mfma_f32_16x16x32_bf16 v[116:119], v[170:173], v[192:195], v[116:119]
	v_mfma_f32_16x16x32_bf16 v[112:115], v[178:181], v[192:195], v[112:115]
	v_mfma_f32_16x16x32_bf16 v[100:103], v[170:173], v[200:203], v[100:103]
	v_mfma_f32_16x16x32_bf16 v[96:99], v[178:181], v[200:203], v[96:99]
	v_mfma_f32_16x16x32_bf16 v[84:87], v[170:173], v[208:211], v[84:87]
	v_mfma_f32_16x16x32_bf16 v[80:83], v[178:181], v[208:211], v[80:83]
	v_mfma_f32_16x16x32_bf16 v[68:71], v[170:173], v[216:219], v[68:71]
	v_mfma_f32_16x16x32_bf16 v[64:67], v[178:181], v[216:219], v[64:67]
	s_setprio 0
	s_barrier
	s_add_i32 s30, s55, s35
	v_lshl_add_u64 v[186:187], v[186:187], 0, s[4:5]
	s_mov_b32 m0, s30
	ds_read_b128 v[182:185], v149 offset:49152
	ds_read_b128 v[192:195], v149 offset:50176
	ds_read_b128 v[196:199], v149 offset:51200
	ds_read_b128 v[200:203], v149 offset:52224
	ds_read_b128 v[204:207], v149 offset:53248
	ds_read_b128 v[208:211], v149 offset:54272
	ds_read_b128 v[212:215], v149 offset:55296
	ds_read_b128 v[216:219], v149 offset:56320
	global_load_lds_dwordx4 v[186:187], off
	s_add_i32 m0, s30, 0x2000
	s_add_u32 s24, s24, 0x40080
	v_lshl_add_u64 v[186:187], v[220:221], 0, s[4:5]
	s_addc_u32 s25, s25, 0
	s_add_i32 s30, s56, s35
	global_load_lds_dwordx4 v[186:187], off
	v_lshl_add_u64 v[186:187], s[24:25], 0, v[132:133]
	s_mov_b32 m0, s30
	s_nop 0
	global_load_lds_dwordx4 v[186:187], off
	v_lshl_add_u64 v[186:187], s[24:25], 0, v[128:129]
	s_add_i32 m0, s30, 0x2000
	s_nop 0
	global_load_lds_dwordx4 v[186:187], off
	v_lshl_add_u64 v[186:187], v[222:223], 0, s[4:5]
	s_mov_b32 m0, s42
	s_nop 0
	global_load_lds_dwordx4 v[186:187], off
	v_lshl_add_u64 v[186:187], v[224:225], 0, s[4:5]
	s_mov_b32 m0, s43
	s_nop 0
	global_load_lds_dwordx4 v[186:187], off
	s_waitcnt vmcnt(8)
	s_waitcnt lgkmcnt(0)
	s_barrier
	s_setprio 1
	v_mfma_f32_16x16x32_bf16 v[60:63], v[150:153], v[182:185], v[60:63]
	v_mfma_f32_16x16x32_bf16 v[56:59], v[158:161], v[182:185], v[56:59]
	v_mfma_f32_16x16x32_bf16 v[44:47], v[150:153], v[196:199], v[44:47]
	v_mfma_f32_16x16x32_bf16 v[40:43], v[158:161], v[196:199], v[40:43]
	v_mfma_f32_16x16x32_bf16 v[28:31], v[150:153], v[204:207], v[28:31]
	v_mfma_f32_16x16x32_bf16 v[24:27], v[158:161], v[204:207], v[24:27]
	v_mfma_f32_16x16x32_bf16 v[12:15], v[150:153], v[212:215], v[12:15]
	v_mfma_f32_16x16x32_bf16 v[8:11], v[158:161], v[212:215], v[8:11]
	v_mfma_f32_16x16x32_bf16 v[60:63], v[154:157], v[192:195], v[60:63]
	v_mfma_f32_16x16x32_bf16 v[56:59], v[162:165], v[192:195], v[56:59]
	v_mfma_f32_16x16x32_bf16 v[44:47], v[154:157], v[200:203], v[44:47]
	v_mfma_f32_16x16x32_bf16 v[40:43], v[162:165], v[200:203], v[40:43]
	v_mfma_f32_16x16x32_bf16 v[28:31], v[154:157], v[208:211], v[28:31]
	v_mfma_f32_16x16x32_bf16 v[24:27], v[162:165], v[208:211], v[24:27]
	v_mfma_f32_16x16x32_bf16 v[12:15], v[154:157], v[216:219], v[12:15]
	v_mfma_f32_16x16x32_bf16 v[8:11], v[162:165], v[216:219], v[8:11]
	v_mfma_f32_16x16x32_bf16 v[52:55], v[166:169], v[182:185], v[52:55]
	v_mfma_f32_16x16x32_bf16 v[48:51], v[174:177], v[182:185], v[48:51]
	v_mfma_f32_16x16x32_bf16 v[36:39], v[166:169], v[196:199], v[36:39]
	v_mfma_f32_16x16x32_bf16 v[32:35], v[174:177], v[196:199], v[32:35]
	v_mfma_f32_16x16x32_bf16 v[20:23], v[166:169], v[204:207], v[20:23]
	v_mfma_f32_16x16x32_bf16 v[16:19], v[174:177], v[204:207], v[16:19]
	v_mfma_f32_16x16x32_bf16 v[4:7], v[166:169], v[212:215], v[4:7]
	v_mfma_f32_16x16x32_bf16 v[0:3], v[174:177], v[212:215], v[0:3]
	v_mfma_f32_16x16x32_bf16 v[52:55], v[170:173], v[192:195], v[52:55]
	v_mfma_f32_16x16x32_bf16 v[48:51], v[178:181], v[192:195], v[48:51]
	v_mfma_f32_16x16x32_bf16 v[36:39], v[170:173], v[200:203], v[36:39]
	v_mfma_f32_16x16x32_bf16 v[32:35], v[178:181], v[200:203], v[32:35]
	v_mfma_f32_16x16x32_bf16 v[20:23], v[170:173], v[208:211], v[20:23]
	v_mfma_f32_16x16x32_bf16 v[16:19], v[178:181], v[208:211], v[16:19]
	v_mfma_f32_16x16x32_bf16 v[4:7], v[170:173], v[216:219], v[4:7]
	v_mfma_f32_16x16x32_bf16 v[0:3], v[178:181], v[216:219], v[0:3]
	s_setprio 0
	s_nop 0
	s_add_i32 s54, s54, 2
	s_add_u32 s22, s22, 0x100
	s_addc_u32 s23, s23, 0
	s_add_u32 s52, s52, 0x100
	s_addc_u32 s53, s53, 0

; #define PG8_STAGE(bufoff, gbase, voff) do { _Pragma("unroll") for (int _i = 0; _i < 2; ++_i) \
;         __builtin_amdgcn_global_load_lds((const unsigned*)((const char*)(gbase) + (voff)[_i]), (PG8_LAS unsigned*)(lds + (bufoff) + ldsw + _i * 8192), 16, 0, 0); } while (0)
; #define PG8_LDA(dst, b, h) do { _Pragma("unroll") for (int m = 0; m < 4; ++m) _Pragma("unroll") for (int k = 0; k < 2; ++k) dst[m][k] = *(const PG8_LAS bf16x8*)(lds + PG8_SA(b, h) + aoff + m * 2048 + k * 1024); } while (0)
; #define PG8_LDB(dst, b, h) do { _Pragma("unroll") for (int n = 0; n < 2; ++n) _Pragma("unroll") for (int k = 0; k < 2; ++k) dst[n][k] = *(const PG8_LAS bf16x8*)(lds + PG8_SB(b, h) + boff + n * 2048 + k * 1024); } while (0)
; #define PG8_MMA(ai, bj, At, Bt) do { __builtin_amdgcn_s_setprio(1); _Pragma("unroll") for (int m = 0; m < 4; ++m) _Pragma("unroll") for (int n = 0; n < 2; ++n) _Pragma("unroll") for (int k = 0; k < 2; ++k) \
;         acc[ai][bj][m][n] = __builtin_amdgcn_mfma_f32_16x16x32_bf16(Bt[n][k], At[m][k], acc[ai][bj][m][n], 0, 0, 0); __builtin_amdgcn_s_setprio(0); } while (0)
; #define PG8_WAIT_V(n) asm volatile("s_waitcnt vmcnt(" #n ")" ::: "memory")
; #define PG8_WAIT_L(n) asm volatile("s_waitcnt lgkmcnt(" #n ")" ::: "memory")
; #define PG8_BAR __builtin_amdgcn_s_barrier()
; #define PG8_SCHED __builtin_amdgcn_sched_barrier(0)
; template <class Epi, class Sched, bool ALIGN_EPI = false, bool SP2 = false>
; __device__ __forceinline__ void gemm_phase(PG8_LAS unsigned char* lds, const Gemm g, const Sched& S, const Epi& E) {
;     ...
;         for (int t = 0; t < nt; t += 2) {
;             const bool last = (t == nt - 2);
;             const char* a1 = cA + (size_t)(t + 1) * kstep;
;             const char* a2 = last ? nA : cA + (size_t)(t + 2) * kstep; const char* b2 = last ? nB : cB + (size_t)(t + 2) * kstep;
;             const char* a3 = a2 + kstep; const char* b3 = b2 + kstep;
;             if (last && has_next) S.a_ready(nxt);
;             if constexpr (SP2) {
;             PG8_LDB(B0, 0, 0); PG8_LDB(B1, 0, 1); PG8_SCHED; PG8_LDA(At, 0, 0); PG8_STAGE(PG8_SA(1, 1), a1 + hstep, voffA);
;             PG8_WAIT_V(8); PG8_WAIT_L(0); PG8_BAR; PG8_MMA(0, 0, At, B0); PG8_MMA(0, 1, At, B1); PG8_BAR; PG8_SCHED;
;             PG8_LDA(At, 0, 1); PG8_STAGE(PG8_SB(0, 0), b2, voffB); PG8_STAGE(PG8_SB(0, 1), b2 + hstep, voffB); PG8_STAGE(PG8_SA(0, 0), a2, voffA);
.LBB0_192:
	ds_read_b128 v[150:153], v147
	ds_read_b128 v[154:157], v147 offset:1024
	ds_read_b128 v[158:161], v147 offset:2048
	ds_read_b128 v[162:165], v147 offset:3072
	ds_read_b128 v[166:169], v148
	ds_read_b128 v[170:173], v148 offset:1024
	ds_read_b128 v[174:177], v148 offset:2048
	ds_read_b128 v[178:181], v148 offset:3072
	s_add_u32 s24, s22, 0xfffc0080
	s_addc_u32 s25, s23, -1
	s_cmp_eq_u32 s54, 12
	s_cselect_b32 s31, s15, s25
	s_cselect_b32 s30, s50, s24
	s_cselect_b32 s25, s9, s53
	s_cselect_b32 s24, s51, s52
	v_lshl_add_u64 v[186:187], s[22:23], 0, v[136:137]
	s_add_i32 m0, s21, 0xc000
	ds_read_b128 v[182:185], v149
	ds_read_b128 v[192:195], v149 offset:1024
	ds_read_b128 v[196:199], v149 offset:2048
	ds_read_b128 v[200:203], v149 offset:3072
	ds_read_b128 v[204:207], v149 offset:4096
	ds_read_b128 v[208:211], v149 offset:5120
	ds_read_b128 v[212:215], v149 offset:6144
	ds_read_b128 v[216:219], v149 offset:7168
	global_load_lds_dwordx4 v[186:187], off
	v_lshl_add_u64 v[186:187], s[22:23], 0, v[138:139]
	s_add_i32 m0, s21, 0xe000
	s_nop 0
	global_load_lds_dwordx4 v[186:187], off
	s_waitcnt vmcnt(8)
	s_waitcnt lgkmcnt(0)
	s_barrier
	s_setprio 1
	v_mfma_f32_16x16x32_bf16 v[124:127], v[150:153], v[182:185], v[124:127]
	v_mfma_f32_16x16x32_bf16 v[120:123], v[158:161], v[182:185], v[120:123]
	v_mfma_f32_16x16x32_bf16 v[108:111], v[150:153], v[196:199], v[108:111]
	v_mfma_f32_16x16x32_bf16 v[104:107], v[158:161], v[196:199], v[104:107]
	v_mfma_f32_16x16x32_bf16 v[92:95], v[150:153], v[204:207], v[92:95]
	v_mfma_f32_16x16x32_bf16 v[88:91], v[158:161], v[204:207], v[88:91]
	v_mfma_f32_16x16x32_bf16 v[76:79], v[150:153], v[212:215], v[76:79]
	v_mfma_f32_16x16x32_bf16 v[72:75], v[158:161], v[212:215], v[72:75]
	v_mfma_f32_16x16x32_bf16 v[124:127], v[154:157], v[192:195], v[124:127]
	v_mfma_f32_16x16x32_bf16 v[120:123], v[162:165], v[192:195], v[120:123]
	v_mfma_f32_16x16x32_bf16 v[108:111], v[154:157], v[200:203], v[108:111]
	v_mfma_f32_16x16x32_bf16 v[104:107], v[162:165], v[200:203], v[104:107]
	v_mfma_f32_16x16x32_bf16 v[92:95], v[154:157], v[208:211], v[92:95]
	v_mfma_f32_16x16x32_bf16 v[88:91], v[162:165], v[208:211], v[88:91]
	v_mfma_f32_16x16x32_bf16 v[76:79], v[154:157], v[216:219], v[76:79]
	v_mfma_f32_16x16x32_bf16 v[72:75], v[162:165], v[216:219], v[72:75]
	v_mfma_f32_16x16x32_bf16 v[116:119], v[166:169], v[182:185], v[116:119]
	v_mfma_f32_16x16x32_bf16 v[112:115], v[174:177], v[182:185], v[112:115]
	v_mfma_f32_16x16x32_bf16 v[100:103], v[166:169], v[196:199], v[100:103]
	v_mfma_f32_16x16x32_bf16 v[96:99], v[174:177], v[196:199], v[96:99]
	v_mfma_f32_16x16x32_bf16 v[84:87], v[166:169], v[204:207], v[84:87]
	v_mfma_f32_16x16x32_bf16 v[80:83], v[174:177], v[204:207], v[80:83]
	v_mfma_f32_16x16x32_bf16 v[68:71], v[166:169], v[212:215], v[68:71]
	v_mfma_f32_16x16x32_bf16 v[64:67], v[174:177], v[212:215], v[64:67]
	v_mfma_f32_16x16x32_bf16 v[116:119], v[170:173], v[192:195], v[116:119]
	v_mfma_f32_16x16x32_bf16 v[112:115], v[178:181], v[192:195], v[112:115]
	v_mfma_f32_16x16x32_bf16 v[100:103], v[170:173], v[200:203], v[100:103]
	v_mfma_f32_16x16x32_bf16 v[96:99], v[178:181], v[200:203], v[96:99]
	v_mfma_f32_16x16x32_bf16 v[84:87], v[170:173], v[208:211], v[84:87]
	v_mfma_f32_16x16x32_bf16 v[80:83], v[178:181], v[208:211], v[80:83]
	v_mfma_f32_16x16x32_bf16 v[68:71], v[170:173], v[216:219], v[68:71]
	v_mfma_f32_16x16x32_bf16 v[64:67], v[178:181], v[216:219], v[64:67]
	s_setprio 0
	s_barrier
	s_add_i32 s55, s46, s35
	v_lshl_add_u64 v[186:187], s[24:25], 0, v[132:133]
	s_mov_b32 m0, s55
	ds_read_b128 v[182:185], v149 offset:16384
	ds_read_b128 v[192:195], v149 offset:17408
	ds_read_b128 v[196:199], v149 offset:18432
	ds_read_b128 v[200:203], v149 offset:19456
	ds_read_b128 v[204:207], v149 offset:20480
	ds_read_b128 v[208:211], v149 offset:21504
	ds_read_b128 v[212:215], v149 offset:22528
	ds_read_b128 v[216:219], v149 offset:23552
	global_load_lds_dwordx4 v[186:187], off
	s_add_i32 m0, s55, 0x2000
	s_add_u32 s56, s24, 0x40000
	v_lshl_add_u64 v[220:221], s[24:25], 0, v[128:129]
	s_addc_u32 s57, s25, 0
	s_add_i32 s55, s47, s35
	global_load_lds_dwordx4 v[220:221], off
	v_lshl_add_u64 v[222:223], s[56:57], 0, v[132:133]
	s_mov_b32 m0, s55
	v_lshl_add_u64 v[224:225], s[30:31], 0, v[130:131]
	global_load_lds_dwordx4 v[222:223], off
	v_lshl_add_u64 v[222:223], s[56:57], 0, v[128:129]
	s_add_i32 m0, s55, 0x2000
	s_nop 0
	global_load_lds_dwordx4 v[222:223], off
	v_lshl_add_u64 v[222:223], s[30:31], 0, v[134:135]
	s_mov_b32 m0, s21
	s_nop 0
	global_load_lds_dwordx4 v[222:223], off
	s_mov_b32 m0, s38
	s_nop 0
	global_load_lds_dwordx4 v[224:225], off
	s_waitcnt vmcnt(8)
	s_waitcnt lgkmcnt(0)
	s_barrier
; #define PG8_STAGE(bufoff, gbase, voff) do { _Pragma("unroll") for (int _i = 0; _i < 2; ++_i) \
;         __builtin_amdgcn_global_load_lds((const unsigned*)((const char*)(gbase) + (voff)[_i]), (PG8_LAS unsigned*)(lds + (bufoff) + ldsw + _i * 8192), 16, 0, 0); } while (0)
; #define PG8_LDA(dst, b, h) do { _Pragma("unroll") for (int m = 0; m < 4; ++m) _Pragma("unroll") for (int k = 0; k < 2; ++k) dst[m][k] = *(const PG8_LAS bf16x8*)(lds + PG8_SA(b, h) + aoff + m * 2048 + k * 1024); } while (0)
; #define PG8_LDB(dst, b, h) do { _Pragma("unroll") for (int n = 0; n < 2; ++n) _Pragma("unroll") for (int k = 0; k < 2; ++k) dst[n][k] = *(const PG8_LAS bf16x8*)(lds + PG8_SB(b, h) + boff + n * 2048 + k * 1024); } while (0)
; #define PG8_MMA(ai, bj, At, Bt) do { __builtin_amdgcn_s_setprio(1); _Pragma("unroll") for (int m = 0; m < 4; ++m) _Pragma("unroll") for (int n = 0; n < 2; ++n) _Pragma("unroll") for (int k = 0; k < 2; ++k) \
;         acc[ai][bj][m][n] = __builtin_amdgcn_mfma_f32_16x16x32_bf16(Bt[n][k], At[m][k], acc[ai][bj][m][n], 0, 0, 0); __builtin_amdgcn_s_setprio(0); } while (0)
; #define PG8_WAIT_V(n) asm volatile("s_waitcnt vmcnt(" #n ")" ::: "memory")
; #define PG8_WAIT_L(n) asm volatile("s_waitcnt lgkmcnt(" #n ")" ::: "memory")
; #define PG8_BAR __builtin_amdgcn_s_barrier()
; #define PG8_SCHED __builtin_amdgcn_sched_barrier(0)
; template <class Epi, class Sched, bool ALIGN_EPI = false, bool SP2 = false>
; __device__ __forceinline__ void gemm_phase(PG8_LAS unsigned char* lds, const Gemm g, const Sched& S, const Epi& E) {
;     ...
;             PG8_WAIT_V(8); PG8_WAIT_L(0); PG8_BAR; PG8_MMA(1, 0, At, B0); PG8_MMA(1, 1, At, B1); PG8_BAR; PG8_SCHED;
;             PG8_LDB(B0, 1, 0); PG8_LDB(B1, 1, 1); PG8_SCHED; PG8_LDA(At, 1, 0); PG8_STAGE(PG8_SA(0, 1), a2 + hstep, voffA);
;             PG8_WAIT_V(8); PG8_WAIT_L(0); PG8_BAR; PG8_MMA(0, 0, At, B0); PG8_MMA(0, 1, At, B1); PG8_BAR; PG8_SCHED;
	s_setprio 1
	v_mfma_f32_16x16x32_bf16 v[60:63], v[150:153], v[182:185], v[60:63]
	v_mfma_f32_16x16x32_bf16 v[56:59], v[158:161], v[182:185], v[56:59]
	v_mfma_f32_16x16x32_bf16 v[44:47], v[150:153], v[196:199], v[44:47]
	v_mfma_f32_16x16x32_bf16 v[40:43], v[158:161], v[196:199], v[40:43]
	v_mfma_f32_16x16x32_bf16 v[28:31], v[150:153], v[204:207], v[28:31]
	v_mfma_f32_16x16x32_bf16 v[24:27], v[158:161], v[204:207], v[24:27]
	v_mfma_f32_16x16x32_bf16 v[12:15], v[150:153], v[212:215], v[12:15]
	v_mfma_f32_16x16x32_bf16 v[8:11], v[158:161], v[212:215], v[8:11]
	v_mfma_f32_16x16x32_bf16 v[60:63], v[154:157], v[192:195], v[60:63]
	v_mfma_f32_16x16x32_bf16 v[56:59], v[162:165], v[192:195], v[56:59]
	v_mfma_f32_16x16x32_bf16 v[44:47], v[154:157], v[200:203], v[44:47]
	v_mfma_f32_16x16x32_bf16 v[40:43], v[162:165], v[200:203], v[40:43]
	v_mfma_f32_16x16x32_bf16 v[28:31], v[154:157], v[208:211], v[28:31]
	v_mfma_f32_16x16x32_bf16 v[24:27], v[162:165], v[208:211], v[24:27]
	v_mfma_f32_16x16x32_bf16 v[12:15], v[154:157], v[216:219], v[12:15]
	v_mfma_f32_16x16x32_bf16 v[8:11], v[162:165], v[216:219], v[8:11]
	v_mfma_f32_16x16x32_bf16 v[52:55], v[166:169], v[182:185], v[52:55]
	v_mfma_f32_16x16x32_bf16 v[48:51], v[174:177], v[182:185], v[48:51]
	v_mfma_f32_16x16x32_bf16 v[36:39], v[166:169], v[196:199], v[36:39]
	v_mfma_f32_16x16x32_bf16 v[32:35], v[174:177], v[196:199], v[32:35]
	v_mfma_f32_16x16x32_bf16 v[20:23], v[166:169], v[204:207], v[20:23]
	v_mfma_f32_16x16x32_bf16 v[16:19], v[174:177], v[204:207], v[16:19]
	v_mfma_f32_16x16x32_bf16 v[4:7], v[166:169], v[212:215], v[4:7]
	v_mfma_f32_16x16x32_bf16 v[0:3], v[174:177], v[212:215], v[0:3]
	v_mfma_f32_16x16x32_bf16 v[52:55], v[170:173], v[192:195], v[52:55]
	v_mfma_f32_16x16x32_bf16 v[48:51], v[178:181], v[192:195], v[48:51]
	v_mfma_f32_16x16x32_bf16 v[36:39], v[170:173], v[200:203], v[36:39]
	v_mfma_f32_16x16x32_bf16 v[32:35], v[178:181], v[200:203], v[32:35]
	v_mfma_f32_16x16x32_bf16 v[20:23], v[170:173], v[208:211], v[20:23]
	v_mfma_f32_16x16x32_bf16 v[16:19], v[178:181], v[208:211], v[16:19]
	v_mfma_f32_16x16x32_bf16 v[4:7], v[170:173], v[216:219], v[4:7]
	v_mfma_f32_16x16x32_bf16 v[0:3], v[178:181], v[216:219], v[0:3]
	s_setprio 0
	s_barrier
	s_add_i32 s55, 0, 0x18000
	s_add_i32 s56, 0, 0x1c000
	v_add_u32_e32 v162, s55, v145
	v_add_u32_e32 v178, s56, v145
	ds_read_b128 v[150:153], v162
	ds_read_b128 v[154:157], v162 offset:1024
	ds_read_b128 v[158:161], v162 offset:2048
	ds_read_b128 v[162:165], v162 offset:3072
	ds_read_b128 v[166:169], v178
	ds_read_b128 v[170:173], v178 offset:1024
	ds_read_b128 v[174:177], v178 offset:2048
	ds_read_b128 v[178:181], v178 offset:3072
	s_add_u32 s30, s30, 0x40000
	s_addc_u32 s31, s31, 0
	s_mov_b32 m0, s39
	v_lshl_add_u64 v[226:227], s[30:31], 0, v[134:135]
	ds_read_b128 v[182:185], v149 offset:32768
	ds_read_b128 v[192:195], v149 offset:33792
	ds_read_b128 v[196:199], v149 offset:34816
	ds_read_b128 v[200:203], v149 offset:35840
	ds_read_b128 v[204:207], v149 offset:36864
	ds_read_b128 v[208:211], v149 offset:37888
	ds_read_b128 v[212:215], v149 offset:38912
	ds_read_b128 v[216:219], v149 offset:39936
	global_load_lds_dwordx4 v[226:227], off
	v_lshl_add_u64 v[226:227], s[30:31], 0, v[130:131]
	s_mov_b32 m0, s40
	s_nop 0
	global_load_lds_dwordx4 v[226:227], off
	s_waitcnt vmcnt(8)
	s_waitcnt lgkmcnt(0)
	s_barrier
	s_setprio 1
	v_mfma_f32_16x16x32_bf16 v[124:127], v[150:153], v[182:185], v[124:127]
	v_mfma_f32_16x16x32_bf16 v[120:123], v[158:161], v[182:185], v[120:123]
	v_mfma_f32_16x16x32_bf16 v[108:111], v[150:153], v[196:199], v[108:111]
	v_mfma_f32_16x16x32_bf16 v[104:107], v[158:161], v[196:199], v[104:107]
	v_mfma_f32_16x16x32_bf16 v[92:95], v[150:153], v[204:207], v[92:95]
	v_mfma_f32_16x16x32_bf16 v[88:91], v[158:161], v[204:207], v[88:91]
	v_mfma_f32_16x16x32_bf16 v[76:79], v[150:153], v[212:215], v[76:79]
	v_mfma_f32_16x16x32_bf16 v[72:75], v[158:161], v[212:215], v[72:75]
	v_mfma_f32_16x16x32_bf16 v[124:127], v[154:157], v[192:195], v[124:127]
	v_mfma_f32_16x16x32_bf16 v[120:123], v[162:165], v[192:195], v[120:123]
	v_mfma_f32_16x16x32_bf16 v[108:111], v[154:157], v[200:203], v[108:111]
	v_mfma_f32_16x16x32_bf16 v[104:107], v[162:165], v[200:203], v[104:107]
	v_mfma_f32_16x16x32_bf16 v[92:95], v[154:157], v[208:211], v[92:95]
	v_mfma_f32_16x16x32_bf16 v[88:91], v[162:165], v[208:211], v[88:91]
	v_mfma_f32_16x16x32_bf16 v[76:79], v[154:157], v[216:219], v[76:79]
	v_mfma_f32_16x16x32_bf16 v[72:75], v[162:165], v[216:219], v[72:75]
	v_mfma_f32_16x16x32_bf16 v[116:119], v[166:169], v[182:185], v[116:119]
	v_mfma_f32_16x16x32_bf16 v[112:115], v[174:177], v[182:185], v[112:115]
	v_mfma_f32_16x16x32_bf16 v[100:103], v[166:169], v[196:199], v[100:103]
	v_mfma_f32_16x16x32_bf16 v[96:99], v[174:177], v[196:199], v[96:99]
	v_mfma_f32_16x16x32_bf16 v[84:87], v[166:169], v[204:207], v[84:87]
	v_mfma_f32_16x16x32_bf16 v[80:83], v[174:177], v[204:207], v[80:83]
	v_mfma_f32_16x16x32_bf16 v[68:71], v[166:169], v[212:215], v[68:71]
	v_mfma_f32_16x16x32_bf16 v[64:67], v[174:177], v[212:215], v[64:67]
	v_mfma_f32_16x16x32_bf16 v[116:119], v[170:173], v[192:195], v[116:119]
	v_mfma_f32_16x16x32_bf16 v[112:115], v[178:181], v[192:195], v[112:115]
	v_mfma_f32_16x16x32_bf16 v[100:103], v[170:173], v[200:203], v[100:103]
	v_mfma_f32_16x16x32_bf16 v[96:99], v[178:181], v[200:203], v[96:99]
	v_mfma_f32_16x16x32_bf16 v[84:87], v[170:173], v[208:211], v[84:87]
	v_mfma_f32_16x16x32_bf16 v[80:83], v[178:181], v[208:211], v[80:83]
	v_mfma_f32_16x16x32_bf16 v[68:71], v[170:173], v[216:219], v[68:71]
	v_mfma_f32_16x16x32_bf16 v[64:67], v[178:181], v[216:219], v[64:67]
	s_setprio 0
	s_barrier
; #define PG8_STAGE(bufoff, gbase, voff) do { _Pragma("unroll") for (int _i = 0; _i < 2; ++_i) \
;         __builtin_amdgcn_global_load_lds((const unsigned*)((const char*)(gbase) + (voff)[_i]), (PG8_LAS unsigned*)(lds + (bufoff) + ldsw + _i * 8192), 16, 0, 0); } while (0)
; #define PG8_LDA(dst, b, h) do { _Pragma("unroll") for (int m = 0; m < 4; ++m) _Pragma("unroll") for (int k = 0; k < 2; ++k) dst[m][k] = *(const PG8_LAS bf16x8*)(lds + PG8_SA(b, h) + aoff + m * 2048 + k * 1024); } while (0)
; #define PG8_MMA(ai, bj, At, Bt) do { __builtin_amdgcn_s_setprio(1); _Pragma("unroll") for (int m = 0; m < 4; ++m) _Pragma("unroll") for (int n = 0; n < 2; ++n) _Pragma("unroll") for (int k = 0; k < 2; ++k) \
;         acc[ai][bj][m][n] = __builtin_amdgcn_mfma_f32_16x16x32_bf16(Bt[n][k], At[m][k], acc[ai][bj][m][n], 0, 0, 0); __builtin_amdgcn_s_setprio(0); } while (0)
; #define PG8_WAIT_V(n) asm volatile("s_waitcnt vmcnt(" #n ")" ::: "memory")
; #define PG8_WAIT_L(n) asm volatile("s_waitcnt lgkmcnt(" #n ")" ::: "memory")
; #define PG8_BAR __builtin_amdgcn_s_barrier()
; #define PG8_SCHED __builtin_amdgcn_sched_barrier(0)
; template <class Epi, class Sched, bool ALIGN_EPI = false, bool SP2 = false>
; __device__ __forceinline__ void gemm_phase(PG8_LAS unsigned char* lds, const Gemm g, const Sched& S, const Epi& E) {
;     ...
;             PG8_LDA(At, 1, 1); PG8_STAGE(PG8_SB(1, 0), b3, voffB); PG8_STAGE(PG8_SB(1, 1), b3 + hstep, voffB); PG8_STAGE(PG8_SA(1, 0), a3, voffA);
;             PG8_WAIT_V(8); PG8_WAIT_L(0); PG8_BAR; PG8_MMA(1, 0, At, B0); PG8_MMA(1, 1, At, B1); PG8_BAR; PG8_SCHED;
;     ...
;         if constexpr (ALIGN_EPI) { if (wr == 0) PG8_BAR; }
;         if constexpr (!Epi::AFTER_DRAIN) { E(acc, cur, wr, wc, fr, fq); S.done(cur); }
	s_add_i32 s30, s55, s35
	v_lshl_add_u64 v[186:187], v[186:187], 0, s[4:5]
	s_mov_b32 m0, s30
	ds_read_b128 v[182:185], v149 offset:49152
	ds_read_b128 v[192:195], v149 offset:50176
	ds_read_b128 v[196:199], v149 offset:51200
	ds_read_b128 v[200:203], v149 offset:52224
	ds_read_b128 v[204:207], v149 offset:53248
	ds_read_b128 v[208:211], v149 offset:54272
	ds_read_b128 v[212:215], v149 offset:55296
	ds_read_b128 v[216:219], v149 offset:56320
	global_load_lds_dwordx4 v[186:187], off
	s_add_i32 m0, s30, 0x2000
	s_add_u32 s24, s24, 0x40080
	v_lshl_add_u64 v[186:187], v[220:221], 0, s[4:5]
	s_addc_u32 s25, s25, 0
	s_add_i32 s30, s56, s35
	global_load_lds_dwordx4 v[186:187], off
	v_lshl_add_u64 v[186:187], s[24:25], 0, v[132:133]
	s_mov_b32 m0, s30
	s_nop 0
	global_load_lds_dwordx4 v[186:187], off
	v_lshl_add_u64 v[186:187], s[24:25], 0, v[128:129]
	s_add_i32 m0, s30, 0x2000
	s_nop 0
	global_load_lds_dwordx4 v[186:187], off
	v_lshl_add_u64 v[186:187], v[222:223], 0, s[4:5]
	s_mov_b32 m0, s42
	s_nop 0
	global_load_lds_dwordx4 v[186:187], off
	v_lshl_add_u64 v[186:187], v[224:225], 0, s[4:5]
	s_mov_b32 m0, s43
	s_nop 0
	global_load_lds_dwordx4 v[186:187], off
	s_waitcnt vmcnt(8)
	s_waitcnt lgkmcnt(0)
	s_barrier
	s_setprio 1
	v_mfma_f32_16x16x32_bf16 v[60:63], v[150:153], v[182:185], v[60:63]
	v_mfma_f32_16x16x32_bf16 v[56:59], v[158:161], v[182:185], v[56:59]
	v_mfma_f32_16x16x32_bf16 v[44:47], v[150:153], v[196:199], v[44:47]
	v_mfma_f32_16x16x32_bf16 v[40:43], v[158:161], v[196:199], v[40:43]
	v_mfma_f32_16x16x32_bf16 v[28:31], v[150:153], v[204:207], v[28:31]
	v_mfma_f32_16x16x32_bf16 v[24:27], v[158:161], v[204:207], v[24:27]
	v_mfma_f32_16x16x32_bf16 v[12:15], v[150:153], v[212:215], v[12:15]
	v_mfma_f32_16x16x32_bf16 v[8:11], v[158:161], v[212:215], v[8:11]
	v_mfma_f32_16x16x32_bf16 v[60:63], v[154:157], v[192:195], v[60:63]
	v_mfma_f32_16x16x32_bf16 v[56:59], v[162:165], v[192:195], v[56:59]
	v_mfma_f32_16x16x32_bf16 v[44:47], v[154:157], v[200:203], v[44:47]
	v_mfma_f32_16x16x32_bf16 v[40:43], v[162:165], v[200:203], v[40:43]
	v_mfma_f32_16x16x32_bf16 v[28:31], v[154:157], v[208:211], v[28:31]
	v_mfma_f32_16x16x32_bf16 v[24:27], v[162:165], v[208:211], v[24:27]
	v_mfma_f32_16x16x32_bf16 v[12:15], v[154:157], v[216:219], v[12:15]
	v_mfma_f32_16x16x32_bf16 v[8:11], v[162:165], v[216:219], v[8:11]
	v_mfma_f32_16x16x32_bf16 v[52:55], v[166:169], v[182:185], v[52:55]
	v_mfma_f32_16x16x32_bf16 v[48:51], v[174:177], v[182:185], v[48:51]
	v_mfma_f32_16x16x32_bf16 v[36:39], v[166:169], v[196:199], v[36:39]
	v_mfma_f32_16x16x32_bf16 v[32:35], v[174:177], v[196:199], v[32:35]
	v_mfma_f32_16x16x32_bf16 v[20:23], v[166:169], v[204:207], v[20:23]
	v_mfma_f32_16x16x32_bf16 v[16:19], v[174:177], v[204:207], v[16:19]
	v_mfma_f32_16x16x32_bf16 v[4:7], v[166:169], v[212:215], v[4:7]
	v_mfma_f32_16x16x32_bf16 v[0:3], v[174:177], v[212:215], v[0:3]
	v_mfma_f32_16x16x32_bf16 v[52:55], v[170:173], v[192:195], v[52:55]
	v_mfma_f32_16x16x32_bf16 v[48:51], v[178:181], v[192:195], v[48:51]
	v_mfma_f32_16x16x32_bf16 v[36:39], v[170:173], v[200:203], v[36:39]
	v_mfma_f32_16x16x32_bf16 v[32:35], v[178:181], v[200:203], v[32:35]
	v_mfma_f32_16x16x32_bf16 v[20:23], v[170:173], v[208:211], v[20:23]
	v_mfma_f32_16x16x32_bf16 v[16:19], v[178:181], v[208:211], v[16:19]
	v_mfma_f32_16x16x32_bf16 v[4:7], v[170:173], v[216:219], v[4:7]
	v_mfma_f32_16x16x32_bf16 v[0:3], v[178:181], v[216:219], v[0:3]
	s_setprio 0
	s_nop 0
	s_add_i32 s54, s54, 2
	s_add_u32 s22, s22, 0x100
	s_addc_u32 s23, s23, 0
	s_add_u32 s52, s52, 0x100
	s_addc_u32 s53, s53, 0
	s_cmp_gt_u32 s54, 13
	s_cbranch_scc0 .Lrot_192
	s_barrier
	s_and_b64 vcc, exec, s[6:7]
	s_cbranch_vccz .LBB0_195
	s_barrier

; #define PG8_STAGE(bufoff, gbase, voff) do { _Pragma("unroll") for (int _i = 0; _i < 2; ++_i) \
;         __builtin_amdgcn_global_load_lds((const unsigned*)((const char*)(gbase) + (voff)[_i]), (PG8_LAS unsigned*)(lds + (bufoff) + ldsw + _i * 8192), 16, 0, 0); } while (0)
; #define PG8_LDA(dst, b, h) do { _Pragma("unroll") for (int m = 0; m < 4; ++m) _Pragma("unroll") for (int k = 0; k < 2; ++k) dst[m][k] = *(const PG8_LAS bf16x8*)(lds + PG8_SA(b, h) + aoff + m * 2048 + k * 1024); } while (0)
; #define PG8_LDB(dst, b, h) do { _Pragma("unroll") for (int n = 0; n < 2; ++n) _Pragma("unroll") for (int k = 0; k < 2; ++k) dst[n][k] = *(const PG8_LAS bf16x8*)(lds + PG8_SB(b, h) + boff + n * 2048 + k * 1024); } while (0)
; #define PG8_MMA(ai, bj, At, Bt) do { __builtin_amdgcn_s_setprio(1); _Pragma("unroll") for (int m = 0; m < 4; ++m) _Pragma("unroll") for (int n = 0; n < 2; ++n) _Pragma("unroll") for (int k = 0; k < 2; ++k) \
;         acc[ai][bj][m][n] = __builtin_amdgcn_mfma_f32_16x16x32_bf16(Bt[n][k], At[m][k], acc[ai][bj][m][n], 0, 0, 0); __builtin_amdgcn_s_setprio(0); } while (0)
; #define PG8_BAR __builtin_amdgcn_s_barrier()
; template <class Epi, class Sched, bool ALIGN_EPI = false, bool SP2 = false>
; __device__ __forceinline__ void gemm_phase(PG8_LAS unsigned char* lds, const Gemm g, const Sched& S, const Epi& E) {
;     ...
;         const bool has_next = S.next(ui + 1, nxt);
;         const char* nA = has_next ? (const char*)g.A + (size_t)nxt.pm * tstep : cA; const char* nB = has_next ? (const char*)g.Bt + (size_t)nxt.pn * tstep : cB;
;         for (int t = 0; t < nt; t += 2) {
;             const bool last = (t == nt - 2);
;             const char* a1 = cA + (size_t)(t + 1) * kstep;
;             const char* a2 = last ? nA : cA + (size_t)(t + 2) * kstep; const char* b2 = last ? nB : cB + (size_t)(t + 2) * kstep;
;             const char* a3 = a2 + kstep; const char* b3 = b2 + kstep;
;             if (last && has_next) S.a_ready(nxt);
;             if constexpr (SP2) {
;             PG8_LDB(B0, 0, 0); PG8_LDB(B1, 0, 1); PG8_SCHED; PG8_LDA(At, 0, 0); PG8_STAGE(PG8_SA(1, 1), a1 + hstep, voffA);
;             PG8_WAIT_V(8); PG8_WAIT_L(0); PG8_BAR; PG8_MMA(0, 0, At, B0); PG8_MMA(0, 1, At, B1); PG8_BAR; PG8_SCHED;
;             PG8_LDA(At, 0, 1); PG8_STAGE(PG8_SB(0, 0), b2, voffB); PG8_STAGE(PG8_SB(0, 1), b2 + hstep, voffB); PG8_STAGE(PG8_SA(0, 0), a2, voffA);
.LBB0_273:
	s_add_u32 s58, s34, 0x100
	s_addc_u32 s59, s35, 0
	s_mov_b32 s60, -2
	s_waitcnt lgkmcnt(0)
	ds_read_b128 v[128:131], v161
	ds_read_b128 v[132:135], v161 offset:1024
	ds_read_b128 v[152:155], v161 offset:2048
	ds_read_b128 v[166:169], v161 offset:3072
	ds_read_b128 v[170:173], v162
	ds_read_b128 v[174:177], v162 offset:1024
	ds_read_b128 v[178:181], v162 offset:2048
	ds_read_b128 v[182:185], v162 offset:3072
	s_add_u32 s34, s8, 0x100
	s_addc_u32 s35, s9, 0
	s_cmp_eq_u32 s60, 40
	s_cselect_b32 s39, s1, s35
	s_cselect_b32 s38, s0, s34
	s_cselect_b32 s37, s31, s59
	s_cselect_b32 s36, s30, s58
	v_lshl_add_u64 v[156:157], s[8:9], 0, v[144:145]
	s_add_i32 m0, s42, 0xc000
	ds_read_b128 v[192:195], v163
	ds_read_b128 v[196:199], v163 offset:1024
	ds_read_b128 v[200:203], v163 offset:2048
	ds_read_b128 v[204:207], v163 offset:3072
	ds_read_b128 v[208:211], v163 offset:4096
	ds_read_b128 v[212:215], v163 offset:5120
	ds_read_b128 v[216:219], v163 offset:6144
	ds_read_b128 v[220:223], v163 offset:7168
	global_load_lds_dwordx4 v[156:157], off
	v_lshl_add_u64 v[156:157], s[8:9], 0, v[146:147]
	s_add_i32 m0, s42, 0xe000
	s_nop 0
	global_load_lds_dwordx4 v[156:157], off
	s_waitcnt vmcnt(8)
	s_waitcnt lgkmcnt(0)
	s_barrier
	s_setprio 1
	v_mfma_f32_16x16x32_bf16 v[124:127], v[128:131], v[192:195], 0
	v_mfma_f32_16x16x32_bf16 v[120:123], v[152:155], v[192:195], 0
	v_mfma_f32_16x16x32_bf16 v[108:111], v[128:131], v[200:203], 0
	v_mfma_f32_16x16x32_bf16 v[104:107], v[152:155], v[200:203], 0
	v_mfma_f32_16x16x32_bf16 v[92:95], v[128:131], v[208:211], 0
	v_mfma_f32_16x16x32_bf16 v[88:91], v[152:155], v[208:211], 0
	v_mfma_f32_16x16x32_bf16 v[76:79], v[128:131], v[216:219], 0
	v_mfma_f32_16x16x32_bf16 v[72:75], v[152:155], v[216:219], 0
	v_mfma_f32_16x16x32_bf16 v[124:127], v[132:135], v[196:199], v[124:127]
	v_mfma_f32_16x16x32_bf16 v[120:123], v[166:169], v[196:199], v[120:123]
	v_mfma_f32_16x16x32_bf16 v[108:111], v[132:135], v[204:207], v[108:111]
	v_mfma_f32_16x16x32_bf16 v[104:107], v[166:169], v[204:207], v[104:107]
	v_mfma_f32_16x16x32_bf16 v[92:95], v[132:135], v[212:215], v[92:95]
	v_mfma_f32_16x16x32_bf16 v[88:91], v[166:169], v[212:215], v[88:91]
	v_mfma_f32_16x16x32_bf16 v[76:79], v[132:135], v[220:223], v[76:79]
	v_mfma_f32_16x16x32_bf16 v[72:75], v[166:169], v[220:223], v[72:75]
	v_mfma_f32_16x16x32_bf16 v[116:119], v[170:173], v[192:195], 0
	v_mfma_f32_16x16x32_bf16 v[112:115], v[178:181], v[192:195], 0
	v_mfma_f32_16x16x32_bf16 v[100:103], v[170:173], v[200:203], 0
	v_mfma_f32_16x16x32_bf16 v[96:99], v[178:181], v[200:203], 0
	v_mfma_f32_16x16x32_bf16 v[84:87], v[170:173], v[208:211], 0
	v_mfma_f32_16x16x32_bf16 v[80:83], v[178:181], v[208:211], 0
	v_mfma_f32_16x16x32_bf16 v[68:71], v[170:173], v[216:219], 0
	v_mfma_f32_16x16x32_bf16 v[64:67], v[178:181], v[216:219], 0
	v_mfma_f32_16x16x32_bf16 v[116:119], v[174:177], v[196:199], v[116:119]
	v_mfma_f32_16x16x32_bf16 v[112:115], v[182:185], v[196:199], v[112:115]
	v_mfma_f32_16x16x32_bf16 v[100:103], v[174:177], v[204:207], v[100:103]
	v_mfma_f32_16x16x32_bf16 v[96:99], v[182:185], v[204:207], v[96:99]
	v_mfma_f32_16x16x32_bf16 v[84:87], v[174:177], v[212:215], v[84:87]
	v_mfma_f32_16x16x32_bf16 v[80:83], v[182:185], v[212:215], v[80:83]
	v_mfma_f32_16x16x32_bf16 v[68:71], v[174:177], v[220:223], v[68:71]
	v_mfma_f32_16x16x32_bf16 v[64:67], v[182:185], v[220:223], v[64:67]
	s_setprio 0
	s_barrier
	s_add_i32 s8, s52, s41
	v_lshl_add_u64 v[156:157], s[36:37], 0, v[138:139]
	s_mov_b32 m0, s8
	ds_read_b128 v[192:195], v163 offset:16384
	ds_read_b128 v[196:199], v163 offset:17408
	ds_read_b128 v[200:203], v163 offset:18432
	ds_read_b128 v[204:207], v163 offset:19456
	ds_read_b128 v[208:211], v163 offset:20480
	ds_read_b128 v[212:215], v163 offset:21504
	ds_read_b128 v[216:219], v163 offset:22528
	ds_read_b128 v[220:223], v163 offset:23552
	global_load_lds_dwordx4 v[156:157], off
	s_add_i32 m0, s8, 0x2000
	s_add_u32 s8, s36, 0xb0000
	v_lshl_add_u64 v[186:187], s[36:37], 0, v[142:143]
	s_addc_u32 s9, s37, 0
	s_add_i32 s61, s53, s41
	global_load_lds_dwordx4 v[186:187], off
	v_lshl_add_u64 v[224:225], s[8:9], 0, v[138:139]
	s_mov_b32 m0, s61
	v_lshl_add_u64 v[226:227], s[38:39], 0, v[140:141]
	global_load_lds_dwordx4 v[224:225], off
	v_lshl_add_u64 v[224:225], s[8:9], 0, v[142:143]
	s_add_i32 m0, s61, 0x2000
	s_nop 0
	global_load_lds_dwordx4 v[224:225], off
	v_lshl_add_u64 v[224:225], s[38:39], 0, v[136:137]
	s_mov_b32 m0, s42
	s_nop 0
	global_load_lds_dwordx4 v[224:225], off
	s_mov_b32 m0, s43
	s_nop 0
	global_load_lds_dwordx4 v[226:227], off
	s_waitcnt vmcnt(8)
	s_waitcnt lgkmcnt(0)
	s_barrier
; #define PG8_STAGE(bufoff, gbase, voff) do { _Pragma("unroll") for (int _i = 0; _i < 2; ++_i) \
;         __builtin_amdgcn_global_load_lds((const unsigned*)((const char*)(gbase) + (voff)[_i]), (PG8_LAS unsigned*)(lds + (bufoff) + ldsw + _i * 8192), 16, 0, 0); } while (0)
; #define PG8_LDA(dst, b, h) do { _Pragma("unroll") for (int m = 0; m < 4; ++m) _Pragma("unroll") for (int k = 0; k < 2; ++k) dst[m][k] = *(const PG8_LAS bf16x8*)(lds + PG8_SA(b, h) + aoff + m * 2048 + k * 1024); } while (0)
; #define PG8_LDB(dst, b, h) do { _Pragma("unroll") for (int n = 0; n < 2; ++n) _Pragma("unroll") for (int k = 0; k < 2; ++k) dst[n][k] = *(const PG8_LAS bf16x8*)(lds + PG8_SB(b, h) + boff + n * 2048 + k * 1024); } while (0)
; #define PG8_MMA(ai, bj, At, Bt) do { __builtin_amdgcn_s_setprio(1); _Pragma("unroll") for (int m = 0; m < 4; ++m) _Pragma("unroll") for (int n = 0; n < 2; ++n) _Pragma("unroll") for (int k = 0; k < 2; ++k) \
;         acc[ai][bj][m][n] = __builtin_amdgcn_mfma_f32_16x16x32_bf16(Bt[n][k], At[m][k], acc[ai][bj][m][n], 0, 0, 0); __builtin_amdgcn_s_setprio(0); } while (0)
; #define PG8_WAIT_V(n) asm volatile("s_waitcnt vmcnt(" #n ")" ::: "memory")
; #define PG8_WAIT_L(n) asm volatile("s_waitcnt lgkmcnt(" #n ")" ::: "memory")
; #define PG8_BAR __builtin_amdgcn_s_barrier()
; #define PG8_SCHED __builtin_amdgcn_sched_barrier(0)
; template <class Epi, class Sched, bool ALIGN_EPI = false, bool SP2 = false>
; __device__ __forceinline__ void gemm_phase(PG8_LAS unsigned char* lds, const Gemm g, const Sched& S, const Epi& E) {
;     ...
;             PG8_WAIT_V(8); PG8_WAIT_L(0); PG8_BAR; PG8_MMA(1, 0, At, B0); PG8_MMA(1, 1, At, B1); PG8_BAR; PG8_SCHED;
;             PG8_LDB(B0, 1, 0); PG8_LDB(B1, 1, 1); PG8_SCHED; PG8_LDA(At, 1, 0); PG8_STAGE(PG8_SA(0, 1), a2 + hstep, voffA);
;             PG8_WAIT_V(8); PG8_WAIT_L(0); PG8_BAR; PG8_MMA(0, 0, At, B0); PG8_MMA(0, 1, At, B1); PG8_BAR; PG8_SCHED;
	s_setprio 1
	v_mfma_f32_16x16x32_bf16 v[60:63], v[128:131], v[192:195], 0
	v_mfma_f32_16x16x32_bf16 v[56:59], v[152:155], v[192:195], 0
	v_mfma_f32_16x16x32_bf16 v[44:47], v[128:131], v[200:203], 0
	v_mfma_f32_16x16x32_bf16 v[40:43], v[152:155], v[200:203], 0
	v_mfma_f32_16x16x32_bf16 v[28:31], v[128:131], v[208:211], 0
	v_mfma_f32_16x16x32_bf16 v[24:27], v[152:155], v[208:211], 0
	v_mfma_f32_16x16x32_bf16 v[12:15], v[128:131], v[216:219], 0
	v_mfma_f32_16x16x32_bf16 v[8:11], v[152:155], v[216:219], 0
	v_mfma_f32_16x16x32_bf16 v[60:63], v[132:135], v[196:199], v[60:63]
	v_mfma_f32_16x16x32_bf16 v[56:59], v[166:169], v[196:199], v[56:59]
	v_mfma_f32_16x16x32_bf16 v[44:47], v[132:135], v[204:207], v[44:47]
	v_mfma_f32_16x16x32_bf16 v[40:43], v[166:169], v[204:207], v[40:43]
	v_mfma_f32_16x16x32_bf16 v[28:31], v[132:135], v[212:215], v[28:31]
	v_mfma_f32_16x16x32_bf16 v[24:27], v[166:169], v[212:215], v[24:27]
	v_mfma_f32_16x16x32_bf16 v[12:15], v[132:135], v[220:223], v[12:15]
	v_mfma_f32_16x16x32_bf16 v[8:11], v[166:169], v[220:223], v[8:11]
	v_mfma_f32_16x16x32_bf16 v[52:55], v[170:173], v[192:195], 0
	v_mfma_f32_16x16x32_bf16 v[48:51], v[178:181], v[192:195], 0
	v_mfma_f32_16x16x32_bf16 v[36:39], v[170:173], v[200:203], 0
	v_mfma_f32_16x16x32_bf16 v[32:35], v[178:181], v[200:203], 0
	v_mfma_f32_16x16x32_bf16 v[20:23], v[170:173], v[208:211], 0
	v_mfma_f32_16x16x32_bf16 v[16:19], v[178:181], v[208:211], 0
	v_mfma_f32_16x16x32_bf16 v[4:7], v[170:173], v[216:219], 0
	v_mfma_f32_16x16x32_bf16 v[0:3], v[178:181], v[216:219], 0
	v_mfma_f32_16x16x32_bf16 v[52:55], v[174:177], v[196:199], v[52:55]
	v_mfma_f32_16x16x32_bf16 v[48:51], v[182:185], v[196:199], v[48:51]
	v_mfma_f32_16x16x32_bf16 v[36:39], v[174:177], v[204:207], v[36:39]
	v_mfma_f32_16x16x32_bf16 v[32:35], v[182:185], v[204:207], v[32:35]
	v_mfma_f32_16x16x32_bf16 v[20:23], v[174:177], v[212:215], v[20:23]
	v_mfma_f32_16x16x32_bf16 v[16:19], v[182:185], v[212:215], v[16:19]
	v_mfma_f32_16x16x32_bf16 v[4:7], v[174:177], v[220:223], v[4:7]
	v_mfma_f32_16x16x32_bf16 v[0:3], v[182:185], v[220:223], v[0:3]
	s_setprio 0
	s_barrier
	s_add_i32 s61, 0, 0x18000
	v_add_u32_e32 v165, s61, v159
	s_add_i32 s62, 0, 0x1c000
	ds_read_b128 v[128:131], v165
	ds_read_b128 v[132:135], v165 offset:1024
	ds_read_b128 v[152:155], v165 offset:2048
	ds_read_b128 v[166:169], v165 offset:3072
	v_add_u32_e32 v165, s62, v159
	ds_read_b128 v[170:173], v165
	ds_read_b128 v[174:177], v165 offset:1024
	ds_read_b128 v[178:181], v165 offset:2048
	ds_read_b128 v[182:185], v165 offset:3072
	s_add_u32 s8, s38, 0xb0000
	s_addc_u32 s9, s39, 0
	s_mov_b32 m0, s44
	v_lshl_add_u64 v[228:229], s[8:9], 0, v[136:137]
	ds_read_b128 v[192:195], v163 offset:32768
	ds_read_b128 v[196:199], v163 offset:33792
	ds_read_b128 v[200:203], v163 offset:34816
	ds_read_b128 v[204:207], v163 offset:35840
	ds_read_b128 v[208:211], v163 offset:36864
	ds_read_b128 v[212:215], v163 offset:37888
	ds_read_b128 v[216:219], v163 offset:38912
	ds_read_b128 v[220:223], v163 offset:39936
	global_load_lds_dwordx4 v[228:229], off
	v_lshl_add_u64 v[228:229], s[8:9], 0, v[140:141]
	s_mov_b32 m0, s45
	s_nop 0
	global_load_lds_dwordx4 v[228:229], off
	s_waitcnt vmcnt(8)
	s_waitcnt lgkmcnt(0)
	s_barrier
	s_setprio 1
	v_mfma_f32_16x16x32_bf16 v[124:127], v[128:131], v[192:195], v[124:127]
	v_mfma_f32_16x16x32_bf16 v[120:123], v[152:155], v[192:195], v[120:123]
	v_mfma_f32_16x16x32_bf16 v[108:111], v[128:131], v[200:203], v[108:111]
	v_mfma_f32_16x16x32_bf16 v[104:107], v[152:155], v[200:203], v[104:107]
	v_mfma_f32_16x16x32_bf16 v[92:95], v[128:131], v[208:211], v[92:95]
	v_mfma_f32_16x16x32_bf16 v[88:91], v[152:155], v[208:211], v[88:91]
	v_mfma_f32_16x16x32_bf16 v[76:79], v[128:131], v[216:219], v[76:79]
	v_mfma_f32_16x16x32_bf16 v[72:75], v[152:155], v[216:219], v[72:75]
	v_mfma_f32_16x16x32_bf16 v[124:127], v[132:135], v[196:199], v[124:127]
	v_mfma_f32_16x16x32_bf16 v[120:123], v[166:169], v[196:199], v[120:123]
	v_mfma_f32_16x16x32_bf16 v[108:111], v[132:135], v[204:207], v[108:111]
	v_mfma_f32_16x16x32_bf16 v[104:107], v[166:169], v[204:207], v[104:107]
	v_mfma_f32_16x16x32_bf16 v[92:95], v[132:135], v[212:215], v[92:95]
	v_mfma_f32_16x16x32_bf16 v[88:91], v[166:169], v[212:215], v[88:91]
	v_mfma_f32_16x16x32_bf16 v[76:79], v[132:135], v[220:223], v[76:79]
	v_mfma_f32_16x16x32_bf16 v[72:75], v[166:169], v[220:223], v[72:75]
	v_mfma_f32_16x16x32_bf16 v[116:119], v[170:173], v[192:195], v[116:119]
	v_mfma_f32_16x16x32_bf16 v[112:115], v[178:181], v[192:195], v[112:115]
	v_mfma_f32_16x16x32_bf16 v[100:103], v[170:173], v[200:203], v[100:103]
	v_mfma_f32_16x16x32_bf16 v[96:99], v[178:181], v[200:203], v[96:99]
	v_mfma_f32_16x16x32_bf16 v[84:87], v[170:173], v[208:211], v[84:87]
	v_mfma_f32_16x16x32_bf16 v[80:83], v[178:181], v[208:211], v[80:83]
	v_mfma_f32_16x16x32_bf16 v[68:71], v[170:173], v[216:219], v[68:71]
	v_mfma_f32_16x16x32_bf16 v[64:67], v[178:181], v[216:219], v[64:67]
	v_mfma_f32_16x16x32_bf16 v[116:119], v[174:177], v[196:199], v[116:119]
	v_mfma_f32_16x16x32_bf16 v[112:115], v[182:185], v[196:199], v[112:115]
	v_mfma_f32_16x16x32_bf16 v[100:103], v[174:177], v[204:207], v[100:103]
	v_mfma_f32_16x16x32_bf16 v[96:99], v[182:185], v[204:207], v[96:99]
	v_mfma_f32_16x16x32_bf16 v[84:87], v[174:177], v[212:215], v[84:87]
	v_mfma_f32_16x16x32_bf16 v[80:83], v[182:185], v[212:215], v[80:83]
	v_mfma_f32_16x16x32_bf16 v[68:71], v[174:177], v[220:223], v[68:71]
	v_mfma_f32_16x16x32_bf16 v[64:67], v[182:185], v[220:223], v[64:67]
	s_setprio 0
	s_barrier
; #define PG8_STAGE(bufoff, gbase, voff) do { _Pragma("unroll") for (int _i = 0; _i < 2; ++_i) \
;         __builtin_amdgcn_global_load_lds((const unsigned*)((const char*)(gbase) + (voff)[_i]), (PG8_LAS unsigned*)(lds + (bufoff) + ldsw + _i * 8192), 16, 0, 0); } while (0)
; #define PG8_LDA(dst, b, h) do { _Pragma("unroll") for (int m = 0; m < 4; ++m) _Pragma("unroll") for (int k = 0; k < 2; ++k) dst[m][k] = *(const PG8_LAS bf16x8*)(lds + PG8_SA(b, h) + aoff + m * 2048 + k * 1024); } while (0)
; #define PG8_MMA(ai, bj, At, Bt) do { __builtin_amdgcn_s_setprio(1); _Pragma("unroll") for (int m = 0; m < 4; ++m) _Pragma("unroll") for (int n = 0; n < 2; ++n) _Pragma("unroll") for (int k = 0; k < 2; ++k) \
;         acc[ai][bj][m][n] = __builtin_amdgcn_mfma_f32_16x16x32_bf16(Bt[n][k], At[m][k], acc[ai][bj][m][n], 0, 0, 0); __builtin_amdgcn_s_setprio(0); } while (0)
; #define PG8_WAIT_V(n) asm volatile("s_waitcnt vmcnt(" #n ")" ::: "memory")
; #define PG8_WAIT_L(n) asm volatile("s_waitcnt lgkmcnt(" #n ")" ::: "memory")
; #define PG8_BAR __builtin_amdgcn_s_barrier()
; #define PG8_SCHED __builtin_amdgcn_sched_barrier(0)
; template <class Epi, class Sched, bool ALIGN_EPI = false, bool SP2 = false>
; __device__ __forceinline__ void gemm_phase(PG8_LAS unsigned char* lds, const Gemm g, const Sched& S, const Epi& E) {
;     ...
;         for (int t = 0; t < nt; t += 2) {
;             const bool last = (t == nt - 2);
;             const char* a1 = cA + (size_t)(t + 1) * kstep;
;             const char* a2 = last ? nA : cA + (size_t)(t + 2) * kstep; const char* b2 = last ? nB : cB + (size_t)(t + 2) * kstep;
;     ...
;             PG8_LDA(At, 1, 1); PG8_STAGE(PG8_SB(1, 0), b3, voffB); PG8_STAGE(PG8_SB(1, 1), b3 + hstep, voffB); PG8_STAGE(PG8_SA(1, 0), a3, voffA);
;             PG8_WAIT_V(8); PG8_WAIT_L(0); PG8_BAR; PG8_MMA(1, 0, At, B0); PG8_MMA(1, 1, At, B1); PG8_BAR; PG8_SCHED;
	s_add_i32 s8, s61, s41
	v_lshl_add_u64 v[156:157], v[156:157], 0, s[14:15]
	s_mov_b32 m0, s8
	ds_read_b128 v[192:195], v163 offset:49152
	ds_read_b128 v[196:199], v163 offset:50176
	ds_read_b128 v[200:203], v163 offset:51200
	ds_read_b128 v[204:207], v163 offset:52224
	ds_read_b128 v[208:211], v163 offset:53248
	ds_read_b128 v[212:215], v163 offset:54272
	ds_read_b128 v[216:219], v163 offset:55296
	ds_read_b128 v[220:223], v163 offset:56320
	global_load_lds_dwordx4 v[156:157], off
	s_add_i32 m0, s8, 0x2000
	s_add_u32 s8, s36, 0xb0080
	v_lshl_add_u64 v[156:157], v[186:187], 0, s[14:15]
	s_addc_u32 s9, s37, 0
	s_add_i32 s36, s62, s41
	global_load_lds_dwordx4 v[156:157], off
	v_lshl_add_u64 v[156:157], s[8:9], 0, v[138:139]
	s_mov_b32 m0, s36
	s_nop 0
	global_load_lds_dwordx4 v[156:157], off
	v_lshl_add_u64 v[156:157], s[8:9], 0, v[142:143]
	s_add_i32 m0, s36, 0x2000
	s_nop 0
	global_load_lds_dwordx4 v[156:157], off
	v_lshl_add_u64 v[156:157], v[224:225], 0, s[14:15]
	s_mov_b32 m0, s47
	s_nop 0
	global_load_lds_dwordx4 v[156:157], off
	v_lshl_add_u64 v[156:157], v[226:227], 0, s[14:15]
	s_mov_b32 m0, s48
	s_nop 0
	global_load_lds_dwordx4 v[156:157], off
	s_waitcnt vmcnt(8)
	s_waitcnt lgkmcnt(0)
	s_barrier
	s_setprio 1
	v_mfma_f32_16x16x32_bf16 v[60:63], v[128:131], v[192:195], v[60:63]
	v_mfma_f32_16x16x32_bf16 v[56:59], v[152:155], v[192:195], v[56:59]
	v_mfma_f32_16x16x32_bf16 v[44:47], v[128:131], v[200:203], v[44:47]
	v_mfma_f32_16x16x32_bf16 v[40:43], v[152:155], v[200:203], v[40:43]
	v_mfma_f32_16x16x32_bf16 v[28:31], v[128:131], v[208:211], v[28:31]
	v_mfma_f32_16x16x32_bf16 v[24:27], v[152:155], v[208:211], v[24:27]
	v_mfma_f32_16x16x32_bf16 v[12:15], v[128:131], v[216:219], v[12:15]
	v_mfma_f32_16x16x32_bf16 v[8:11], v[152:155], v[216:219], v[8:11]
	v_mfma_f32_16x16x32_bf16 v[60:63], v[132:135], v[196:199], v[60:63]
	v_mfma_f32_16x16x32_bf16 v[56:59], v[166:169], v[196:199], v[56:59]
	v_mfma_f32_16x16x32_bf16 v[44:47], v[132:135], v[204:207], v[44:47]
	v_mfma_f32_16x16x32_bf16 v[40:43], v[166:169], v[204:207], v[40:43]
	v_mfma_f32_16x16x32_bf16 v[28:31], v[132:135], v[212:215], v[28:31]
	v_mfma_f32_16x16x32_bf16 v[24:27], v[166:169], v[212:215], v[24:27]
	v_mfma_f32_16x16x32_bf16 v[12:15], v[132:135], v[220:223], v[12:15]
	v_mfma_f32_16x16x32_bf16 v[8:11], v[166:169], v[220:223], v[8:11]
	v_mfma_f32_16x16x32_bf16 v[52:55], v[170:173], v[192:195], v[52:55]
	v_mfma_f32_16x16x32_bf16 v[48:51], v[178:181], v[192:195], v[48:51]
	v_mfma_f32_16x16x32_bf16 v[36:39], v[170:173], v[200:203], v[36:39]
	v_mfma_f32_16x16x32_bf16 v[32:35], v[178:181], v[200:203], v[32:35]
	v_mfma_f32_16x16x32_bf16 v[20:23], v[170:173], v[208:211], v[20:23]
	v_mfma_f32_16x16x32_bf16 v[16:19], v[178:181], v[208:211], v[16:19]
	v_mfma_f32_16x16x32_bf16 v[4:7], v[170:173], v[216:219], v[4:7]
	v_mfma_f32_16x16x32_bf16 v[0:3], v[178:181], v[216:219], v[0:3]
	v_mfma_f32_16x16x32_bf16 v[52:55], v[174:177], v[196:199], v[52:55]
	v_mfma_f32_16x16x32_bf16 v[48:51], v[182:185], v[196:199], v[48:51]
	v_mfma_f32_16x16x32_bf16 v[36:39], v[174:177], v[204:207], v[36:39]
	v_mfma_f32_16x16x32_bf16 v[32:35], v[182:185], v[204:207], v[32:35]
	v_mfma_f32_16x16x32_bf16 v[20:23], v[174:177], v[212:215], v[20:23]
	v_mfma_f32_16x16x32_bf16 v[16:19], v[182:185], v[212:215], v[16:19]
	v_mfma_f32_16x16x32_bf16 v[4:7], v[174:177], v[220:223], v[4:7]
	v_mfma_f32_16x16x32_bf16 v[0:3], v[182:185], v[220:223], v[0:3]
	s_setprio 0
	s_nop 0
	s_add_i32 s60, s60, 2
	s_add_u32 s58, s58, 0x100
	s_addc_u32 s59, s59, 0
	s_mov_b64 s[8:9], s[34:35]

; #define PG8_STAGE(bufoff, gbase, voff) do { _Pragma("unroll") for (int _i = 0; _i < 2; ++_i) \
;         __builtin_amdgcn_global_load_lds((const unsigned*)((const char*)(gbase) + (voff)[_i]), (PG8_LAS unsigned*)(lds + (bufoff) + ldsw + _i * 8192), 16, 0, 0); } while (0)
; #define PG8_LDA(dst, b, h) do { _Pragma("unroll") for (int m = 0; m < 4; ++m) _Pragma("unroll") for (int k = 0; k < 2; ++k) dst[m][k] = *(const PG8_LAS bf16x8*)(lds + PG8_SA(b, h) + aoff + m * 2048 + k * 1024); } while (0)
; #define PG8_LDB(dst, b, h) do { _Pragma("unroll") for (int n = 0; n < 2; ++n) _Pragma("unroll") for (int k = 0; k < 2; ++k) dst[n][k] = *(const PG8_LAS bf16x8*)(lds + PG8_SB(b, h) + boff + n * 2048 + k * 1024); } while (0)
; #define PG8_MMA(ai, bj, At, Bt) do { __builtin_amdgcn_s_setprio(1); _Pragma("unroll") for (int m = 0; m < 4; ++m) _Pragma("unroll") for (int n = 0; n < 2; ++n) _Pragma("unroll") for (int k = 0; k < 2; ++k) \
;         acc[ai][bj][m][n] = __builtin_amdgcn_mfma_f32_16x16x32_bf16(Bt[n][k], At[m][k], acc[ai][bj][m][n], 0, 0, 0); __builtin_amdgcn_s_setprio(0); } while (0)
; #define PG8_WAIT_V(n) asm volatile("s_waitcnt vmcnt(" #n ")" ::: "memory")
; #define PG8_WAIT_L(n) asm volatile("s_waitcnt lgkmcnt(" #n ")" ::: "memory")
; #define PG8_BAR __builtin_amdgcn_s_barrier()
; #define PG8_SCHED __builtin_amdgcn_sched_barrier(0)
; template <class Epi, class Sched, bool ALIGN_EPI = false, bool SP2 = false>
; __device__ __forceinline__ void gemm_phase(PG8_LAS unsigned char* lds, const Gemm g, const Sched& S, const Epi& E) {
;     ...
;         for (int t = 0; t < nt; t += 2) {
;             const bool last = (t == nt - 2);
;             const char* a1 = cA + (size_t)(t + 1) * kstep;
;             const char* a2 = last ? nA : cA + (size_t)(t + 2) * kstep; const char* b2 = last ? nB : cB + (size_t)(t + 2) * kstep;
;             const char* a3 = a2 + kstep; const char* b3 = b2 + kstep;
;             if (last && has_next) S.a_ready(nxt);
;             if constexpr (SP2) {
;             PG8_LDB(B0, 0, 0); PG8_LDB(B1, 0, 1); PG8_SCHED; PG8_LDA(At, 0, 0); PG8_STAGE(PG8_SA(1, 1), a1 + hstep, voffA);
;             PG8_WAIT_V(8); PG8_WAIT_L(0); PG8_BAR; PG8_MMA(0, 0, At, B0); PG8_MMA(0, 1, At, B1); PG8_BAR; PG8_SCHED;
;             PG8_LDA(At, 0, 1); PG8_STAGE(PG8_SB(0, 0), b2, voffB); PG8_STAGE(PG8_SB(0, 1), b2 + hstep, voffB); PG8_STAGE(PG8_SA(0, 0), a2, voffA);
.LBB0_274:
	ds_read_b128 v[128:131], v161
	ds_read_b128 v[132:135], v161 offset:1024
	ds_read_b128 v[152:155], v161 offset:2048
	ds_read_b128 v[166:169], v161 offset:3072
	ds_read_b128 v[170:173], v162
	ds_read_b128 v[174:177], v162 offset:1024
	ds_read_b128 v[178:181], v162 offset:2048
	ds_read_b128 v[182:185], v162 offset:3072
	s_add_u32 s34, s8, 0x100
	s_addc_u32 s35, s9, 0
	s_cmp_eq_u32 s60, 40
	s_cselect_b32 s39, s1, s35
	s_cselect_b32 s38, s0, s34
	s_cselect_b32 s37, s31, s59
	s_cselect_b32 s36, s30, s58
	v_lshl_add_u64 v[156:157], s[8:9], 0, v[144:145]
	s_add_i32 m0, s42, 0xc000
	ds_read_b128 v[192:195], v163
	ds_read_b128 v[196:199], v163 offset:1024
	ds_read_b128 v[200:203], v163 offset:2048
	ds_read_b128 v[204:207], v163 offset:3072
	ds_read_b128 v[208:211], v163 offset:4096
	ds_read_b128 v[212:215], v163 offset:5120
	ds_read_b128 v[216:219], v163 offset:6144
	ds_read_b128 v[220:223], v163 offset:7168
	global_load_lds_dwordx4 v[156:157], off
	v_lshl_add_u64 v[156:157], s[8:9], 0, v[146:147]
	s_add_i32 m0, s42, 0xe000
	s_nop 0
	global_load_lds_dwordx4 v[156:157], off
	s_waitcnt vmcnt(8)
	s_waitcnt lgkmcnt(0)
	s_barrier
	s_setprio 1
	v_mfma_f32_16x16x32_bf16 v[124:127], v[128:131], v[192:195], v[124:127]
	v_mfma_f32_16x16x32_bf16 v[120:123], v[152:155], v[192:195], v[120:123]
	v_mfma_f32_16x16x32_bf16 v[108:111], v[128:131], v[200:203], v[108:111]
	v_mfma_f32_16x16x32_bf16 v[104:107], v[152:155], v[200:203], v[104:107]
	v_mfma_f32_16x16x32_bf16 v[92:95], v[128:131], v[208:211], v[92:95]
	v_mfma_f32_16x16x32_bf16 v[88:91], v[152:155], v[208:211], v[88:91]
	v_mfma_f32_16x16x32_bf16 v[76:79], v[128:131], v[216:219], v[76:79]
	v_mfma_f32_16x16x32_bf16 v[72:75], v[152:155], v[216:219], v[72:75]
	v_mfma_f32_16x16x32_bf16 v[124:127], v[132:135], v[196:199], v[124:127]
	v_mfma_f32_16x16x32_bf16 v[120:123], v[166:169], v[196:199], v[120:123]
	v_mfma_f32_16x16x32_bf16 v[108:111], v[132:135], v[204:207], v[108:111]
	v_mfma_f32_16x16x32_bf16 v[104:107], v[166:169], v[204:207], v[104:107]
	v_mfma_f32_16x16x32_bf16 v[92:95], v[132:135], v[212:215], v[92:95]
	v_mfma_f32_16x16x32_bf16 v[88:91], v[166:169], v[212:215], v[88:91]
	v_mfma_f32_16x16x32_bf16 v[76:79], v[132:135], v[220:223], v[76:79]
	v_mfma_f32_16x16x32_bf16 v[72:75], v[166:169], v[220:223], v[72:75]
	v_mfma_f32_16x16x32_bf16 v[116:119], v[170:173], v[192:195], v[116:119]
	v_mfma_f32_16x16x32_bf16 v[112:115], v[178:181], v[192:195], v[112:115]
	v_mfma_f32_16x16x32_bf16 v[100:103], v[170:173], v[200:203], v[100:103]
	v_mfma_f32_16x16x32_bf16 v[96:99], v[178:181], v[200:203], v[96:99]
	v_mfma_f32_16x16x32_bf16 v[84:87], v[170:173], v[208:211], v[84:87]
	v_mfma_f32_16x16x32_bf16 v[80:83], v[178:181], v[208:211], v[80:83]
	v_mfma_f32_16x16x32_bf16 v[68:71], v[170:173], v[216:219], v[68:71]
	v_mfma_f32_16x16x32_bf16 v[64:67], v[178:181], v[216:219], v[64:67]
	v_mfma_f32_16x16x32_bf16 v[116:119], v[174:177], v[196:199], v[116:119]
	v_mfma_f32_16x16x32_bf16 v[112:115], v[182:185], v[196:199], v[112:115]
	v_mfma_f32_16x16x32_bf16 v[100:103], v[174:177], v[204:207], v[100:103]
	v_mfma_f32_16x16x32_bf16 v[96:99], v[182:185], v[204:207], v[96:99]
	v_mfma_f32_16x16x32_bf16 v[84:87], v[174:177], v[212:215], v[84:87]
	v_mfma_f32_16x16x32_bf16 v[80:83], v[182:185], v[212:215], v[80:83]
	v_mfma_f32_16x16x32_bf16 v[68:71], v[174:177], v[220:223], v[68:71]
	v_mfma_f32_16x16x32_bf16 v[64:67], v[182:185], v[220:223], v[64:67]
	s_setprio 0
	s_barrier
	s_add_i32 s8, s52, s41
	v_lshl_add_u64 v[156:157], s[36:37], 0, v[138:139]
	s_mov_b32 m0, s8
	ds_read_b128 v[192:195], v163 offset:16384
	ds_read_b128 v[196:199], v163 offset:17408
	ds_read_b128 v[200:203], v163 offset:18432
	ds_read_b128 v[204:207], v163 offset:19456
	ds_read_b128 v[208:211], v163 offset:20480
	ds_read_b128 v[212:215], v163 offset:21504
	ds_read_b128 v[216:219], v163 offset:22528
	ds_read_b128 v[220:223], v163 offset:23552
	global_load_lds_dwordx4 v[156:157], off
	s_add_i32 m0, s8, 0x2000
	s_add_u32 s8, s36, 0xb0000
	v_lshl_add_u64 v[186:187], s[36:37], 0, v[142:143]
	s_addc_u32 s9, s37, 0
	s_add_i32 s61, s53, s41
	global_load_lds_dwordx4 v[186:187], off
	v_lshl_add_u64 v[224:225], s[8:9], 0, v[138:139]
	s_mov_b32 m0, s61
	v_lshl_add_u64 v[226:227], s[38:39], 0, v[140:141]
	global_load_lds_dwordx4 v[224:225], off
	v_lshl_add_u64 v[224:225], s[8:9], 0, v[142:143]
	s_add_i32 m0, s61, 0x2000
	s_nop 0
	global_load_lds_dwordx4 v[224:225], off
	v_lshl_add_u64 v[224:225], s[38:39], 0, v[136:137]
	s_mov_b32 m0, s42
	s_nop 0
	global_load_lds_dwordx4 v[224:225], off
	s_mov_b32 m0, s43
	s_nop 0
	global_load_lds_dwordx4 v[226:227], off
	s_waitcnt vmcnt(8)
	s_waitcnt lgkmcnt(0)
	s_barrier
; #define PG8_STAGE(bufoff, gbase, voff) do { _Pragma("unroll") for (int _i = 0; _i < 2; ++_i) \
;         __builtin_amdgcn_global_load_lds((const unsigned*)((const char*)(gbase) + (voff)[_i]), (PG8_LAS unsigned*)(lds + (bufoff) + ldsw + _i * 8192), 16, 0, 0); } while (0)
; #define PG8_LDA(dst, b, h) do { _Pragma("unroll") for (int m = 0; m < 4; ++m) _Pragma("unroll") for (int k = 0; k < 2; ++k) dst[m][k] = *(const PG8_LAS bf16x8*)(lds + PG8_SA(b, h) + aoff + m * 2048 + k * 1024); } while (0)
; #define PG8_LDB(dst, b, h) do { _Pragma("unroll") for (int n = 0; n < 2; ++n) _Pragma("unroll") for (int k = 0; k < 2; ++k) dst[n][k] = *(const PG8_LAS bf16x8*)(lds + PG8_SB(b, h) + boff + n * 2048 + k * 1024); } while (0)
; #define PG8_MMA(ai, bj, At, Bt) do { __builtin_amdgcn_s_setprio(1); _Pragma("unroll") for (int m = 0; m < 4; ++m) _Pragma("unroll") for (int n = 0; n < 2; ++n) _Pragma("unroll") for (int k = 0; k < 2; ++k) \
;         acc[ai][bj][m][n] = __builtin_amdgcn_mfma_f32_16x16x32_bf16(Bt[n][k], At[m][k], acc[ai][bj][m][n], 0, 0, 0); __builtin_amdgcn_s_setprio(0); } while (0)
; #define PG8_WAIT_V(n) asm volatile("s_waitcnt vmcnt(" #n ")" ::: "memory")
; #define PG8_WAIT_L(n) asm volatile("s_waitcnt lgkmcnt(" #n ")" ::: "memory")
; #define PG8_BAR __builtin_amdgcn_s_barrier()
; #define PG8_SCHED __builtin_amdgcn_sched_barrier(0)
; template <class Epi, class Sched, bool ALIGN_EPI = false, bool SP2 = false>
; __device__ __forceinline__ void gemm_phase(PG8_LAS unsigned char* lds, const Gemm g, const Sched& S, const Epi& E) {
;     ...
;             PG8_WAIT_V(8); PG8_WAIT_L(0); PG8_BAR; PG8_MMA(1, 0, At, B0); PG8_MMA(1, 1, At, B1); PG8_BAR; PG8_SCHED;
;             PG8_LDB(B0, 1, 0); PG8_LDB(B1, 1, 1); PG8_SCHED; PG8_LDA(At, 1, 0); PG8_STAGE(PG8_SA(0, 1), a2 + hstep, voffA);
;             PG8_WAIT_V(8); PG8_WAIT_L(0); PG8_BAR; PG8_MMA(0, 0, At, B0); PG8_MMA(0, 1, At, B1); PG8_BAR; PG8_SCHED;
	s_setprio 1
	v_mfma_f32_16x16x32_bf16 v[60:63], v[128:131], v[192:195], v[60:63]
	v_mfma_f32_16x16x32_bf16 v[56:59], v[152:155], v[192:195], v[56:59]
	v_mfma_f32_16x16x32_bf16 v[44:47], v[128:131], v[200:203], v[44:47]
	v_mfma_f32_16x16x32_bf16 v[40:43], v[152:155], v[200:203], v[40:43]
	v_mfma_f32_16x16x32_bf16 v[28:31], v[128:131], v[208:211], v[28:31]
	v_mfma_f32_16x16x32_bf16 v[24:27], v[152:155], v[208:211], v[24:27]
	v_mfma_f32_16x16x32_bf16 v[12:15], v[128:131], v[216:219], v[12:15]
	v_mfma_f32_16x16x32_bf16 v[8:11], v[152:155], v[216:219], v[8:11]
	v_mfma_f32_16x16x32_bf16 v[60:63], v[132:135], v[196:199], v[60:63]
	v_mfma_f32_16x16x32_bf16 v[56:59], v[166:169], v[196:199], v[56:59]
	v_mfma_f32_16x16x32_bf16 v[44:47], v[132:135], v[204:207], v[44:47]
	v_mfma_f32_16x16x32_bf16 v[40:43], v[166:169], v[204:207], v[40:43]
	v_mfma_f32_16x16x32_bf16 v[28:31], v[132:135], v[212:215], v[28:31]
	v_mfma_f32_16x16x32_bf16 v[24:27], v[166:169], v[212:215], v[24:27]
	v_mfma_f32_16x16x32_bf16 v[12:15], v[132:135], v[220:223], v[12:15]
	v_mfma_f32_16x16x32_bf16 v[8:11], v[166:169], v[220:223], v[8:11]
	v_mfma_f32_16x16x32_bf16 v[52:55], v[170:173], v[192:195], v[52:55]
	v_mfma_f32_16x16x32_bf16 v[48:51], v[178:181], v[192:195], v[48:51]
	v_mfma_f32_16x16x32_bf16 v[36:39], v[170:173], v[200:203], v[36:39]
	v_mfma_f32_16x16x32_bf16 v[32:35], v[178:181], v[200:203], v[32:35]
	v_mfma_f32_16x16x32_bf16 v[20:23], v[170:173], v[208:211], v[20:23]
	v_mfma_f32_16x16x32_bf16 v[16:19], v[178:181], v[208:211], v[16:19]
	v_mfma_f32_16x16x32_bf16 v[4:7], v[170:173], v[216:219], v[4:7]
	v_mfma_f32_16x16x32_bf16 v[0:3], v[178:181], v[216:219], v[0:3]
	v_mfma_f32_16x16x32_bf16 v[52:55], v[174:177], v[196:199], v[52:55]
	v_mfma_f32_16x16x32_bf16 v[48:51], v[182:185], v[196:199], v[48:51]
	v_mfma_f32_16x16x32_bf16 v[36:39], v[174:177], v[204:207], v[36:39]
	v_mfma_f32_16x16x32_bf16 v[32:35], v[182:185], v[204:207], v[32:35]
	v_mfma_f32_16x16x32_bf16 v[20:23], v[174:177], v[212:215], v[20:23]
	v_mfma_f32_16x16x32_bf16 v[16:19], v[182:185], v[212:215], v[16:19]
	v_mfma_f32_16x16x32_bf16 v[4:7], v[174:177], v[220:223], v[4:7]
	v_mfma_f32_16x16x32_bf16 v[0:3], v[182:185], v[220:223], v[0:3]
	s_setprio 0
	s_barrier
	s_add_i32 s61, 0, 0x18000
	v_add_u32_e32 v165, s61, v159
	s_add_i32 s62, 0, 0x1c000
	ds_read_b128 v[128:131], v165
	ds_read_b128 v[132:135], v165 offset:1024
	ds_read_b128 v[152:155], v165 offset:2048
	ds_read_b128 v[166:169], v165 offset:3072
	v_add_u32_e32 v165, s62, v159
	ds_read_b128 v[170:173], v165
	ds_read_b128 v[174:177], v165 offset:1024
	ds_read_b128 v[178:181], v165 offset:2048
	ds_read_b128 v[182:185], v165 offset:3072
	s_add_u32 s8, s38, 0xb0000
	s_addc_u32 s9, s39, 0
	s_mov_b32 m0, s44
	v_lshl_add_u64 v[228:229], s[8:9], 0, v[136:137]
	ds_read_b128 v[192:195], v163 offset:32768
	ds_read_b128 v[196:199], v163 offset:33792
	ds_read_b128 v[200:203], v163 offset:34816
	ds_read_b128 v[204:207], v163 offset:35840
	ds_read_b128 v[208:211], v163 offset:36864
	ds_read_b128 v[212:215], v163 offset:37888
	ds_read_b128 v[216:219], v163 offset:38912
	ds_read_b128 v[220:223], v163 offset:39936
	global_load_lds_dwordx4 v[228:229], off
	v_lshl_add_u64 v[228:229], s[8:9], 0, v[140:141]
	s_mov_b32 m0, s45
	s_nop 0
	global_load_lds_dwordx4 v[228:229], off
	s_waitcnt vmcnt(8)
	s_waitcnt lgkmcnt(0)
	s_barrier
	s_setprio 1
	v_mfma_f32_16x16x32_bf16 v[124:127], v[128:131], v[192:195], v[124:127]
	v_mfma_f32_16x16x32_bf16 v[120:123], v[152:155], v[192:195], v[120:123]
	v_mfma_f32_16x16x32_bf16 v[108:111], v[128:131], v[200:203], v[108:111]
	v_mfma_f32_16x16x32_bf16 v[104:107], v[152:155], v[200:203], v[104:107]
	v_mfma_f32_16x16x32_bf16 v[92:95], v[128:131], v[208:211], v[92:95]
	v_mfma_f32_16x16x32_bf16 v[88:91], v[152:155], v[208:211], v[88:91]
	v_mfma_f32_16x16x32_bf16 v[76:79], v[128:131], v[216:219], v[76:79]
	v_mfma_f32_16x16x32_bf16 v[72:75], v[152:155], v[216:219], v[72:75]
	v_mfma_f32_16x16x32_bf16 v[124:127], v[132:135], v[196:199], v[124:127]
	v_mfma_f32_16x16x32_bf16 v[120:123], v[166:169], v[196:199], v[120:123]
	v_mfma_f32_16x16x32_bf16 v[108:111], v[132:135], v[204:207], v[108:111]
	v_mfma_f32_16x16x32_bf16 v[104:107], v[166:169], v[204:207], v[104:107]
	v_mfma_f32_16x16x32_bf16 v[92:95], v[132:135], v[212:215], v[92:95]
	v_mfma_f32_16x16x32_bf16 v[88:91], v[166:169], v[212:215], v[88:91]
	v_mfma_f32_16x16x32_bf16 v[76:79], v[132:135], v[220:223], v[76:79]
	v_mfma_f32_16x16x32_bf16 v[72:75], v[166:169], v[220:223], v[72:75]
	v_mfma_f32_16x16x32_bf16 v[116:119], v[170:173], v[192:195], v[116:119]
	v_mfma_f32_16x16x32_bf16 v[112:115], v[178:181], v[192:195], v[112:115]
	v_mfma_f32_16x16x32_bf16 v[100:103], v[170:173], v[200:203], v[100:103]
	v_mfma_f32_16x16x32_bf16 v[96:99], v[178:181], v[200:203], v[96:99]
	v_mfma_f32_16x16x32_bf16 v[84:87], v[170:173], v[208:211], v[84:87]
	v_mfma_f32_16x16x32_bf16 v[80:83], v[178:181], v[208:211], v[80:83]
	v_mfma_f32_16x16x32_bf16 v[68:71], v[170:173], v[216:219], v[68:71]
	v_mfma_f32_16x16x32_bf16 v[64:67], v[178:181], v[216:219], v[64:67]
	v_mfma_f32_16x16x32_bf16 v[116:119], v[174:177], v[196:199], v[116:119]
	v_mfma_f32_16x16x32_bf16 v[112:115], v[182:185], v[196:199], v[112:115]
	v_mfma_f32_16x16x32_bf16 v[100:103], v[174:177], v[204:207], v[100:103]
	v_mfma_f32_16x16x32_bf16 v[96:99], v[182:185], v[204:207], v[96:99]
	v_mfma_f32_16x16x32_bf16 v[84:87], v[174:177], v[212:215], v[84:87]
	v_mfma_f32_16x16x32_bf16 v[80:83], v[182:185], v[212:215], v[80:83]
	v_mfma_f32_16x16x32_bf16 v[68:71], v[174:177], v[220:223], v[68:71]
	v_mfma_f32_16x16x32_bf16 v[64:67], v[182:185], v[220:223], v[64:67]
	s_setprio 0
	s_barrier
; #define PG8_STAGE(bufoff, gbase, voff) do { _Pragma("unroll") for (int _i = 0; _i < 2; ++_i) \
;         __builtin_amdgcn_global_load_lds((const unsigned*)((const char*)(gbase) + (voff)[_i]), (PG8_LAS unsigned*)(lds + (bufoff) + ldsw + _i * 8192), 16, 0, 0); } while (0)
; #define PG8_LDA(dst, b, h) do { _Pragma("unroll") for (int m = 0; m < 4; ++m) _Pragma("unroll") for (int k = 0; k < 2; ++k) dst[m][k] = *(const PG8_LAS bf16x8*)(lds + PG8_SA(b, h) + aoff + m * 2048 + k * 1024); } while (0)
; #define PG8_MMA(ai, bj, At, Bt) do { __builtin_amdgcn_s_setprio(1); _Pragma("unroll") for (int m = 0; m < 4; ++m) _Pragma("unroll") for (int n = 0; n < 2; ++n) _Pragma("unroll") for (int k = 0; k < 2; ++k) \
;         acc[ai][bj][m][n] = __builtin_amdgcn_mfma_f32_16x16x32_bf16(Bt[n][k], At[m][k], acc[ai][bj][m][n], 0, 0, 0); __builtin_amdgcn_s_setprio(0); } while (0)
; #define PG8_WAIT_V(n) asm volatile("s_waitcnt vmcnt(" #n ")" ::: "memory")
; #define PG8_WAIT_L(n) asm volatile("s_waitcnt lgkmcnt(" #n ")" ::: "memory")
; #define PG8_BAR __builtin_amdgcn_s_barrier()
; #define PG8_SCHED __builtin_amdgcn_sched_barrier(0)
; template <class Epi, class Sched, bool ALIGN_EPI = false, bool SP2 = false>
; __device__ __forceinline__ void gemm_phase(PG8_LAS unsigned char* lds, const Gemm g, const Sched& S, const Epi& E) {
;     ...
;             PG8_LDA(At, 1, 1); PG8_STAGE(PG8_SB(1, 0), b3, voffB); PG8_STAGE(PG8_SB(1, 1), b3 + hstep, voffB); PG8_STAGE(PG8_SA(1, 0), a3, voffA);
;             PG8_WAIT_V(8); PG8_WAIT_L(0); PG8_BAR; PG8_MMA(1, 0, At, B0); PG8_MMA(1, 1, At, B1); PG8_BAR; PG8_SCHED;
;     ...
;         if constexpr (ALIGN_EPI) { if (wr == 0) PG8_BAR; }
;         if constexpr (!Epi::AFTER_DRAIN) { E(acc, cur, wr, wc, fr, fq); S.done(cur); }
	s_add_i32 s8, s61, s41
	v_lshl_add_u64 v[156:157], v[156:157], 0, s[14:15]
	s_mov_b32 m0, s8
	ds_read_b128 v[192:195], v163 offset:49152
	ds_read_b128 v[196:199], v163 offset:50176
	ds_read_b128 v[200:203], v163 offset:51200
	ds_read_b128 v[204:207], v163 offset:52224
	ds_read_b128 v[208:211], v163 offset:53248
	ds_read_b128 v[212:215], v163 offset:54272
	ds_read_b128 v[216:219], v163 offset:55296
	ds_read_b128 v[220:223], v163 offset:56320
	global_load_lds_dwordx4 v[156:157], off
	s_add_i32 m0, s8, 0x2000
	s_add_u32 s8, s36, 0xb0080
	v_lshl_add_u64 v[156:157], v[186:187], 0, s[14:15]
	s_addc_u32 s9, s37, 0
	s_add_i32 s36, s62, s41
	global_load_lds_dwordx4 v[156:157], off
	v_lshl_add_u64 v[156:157], s[8:9], 0, v[138:139]
	s_mov_b32 m0, s36
	s_nop 0
	global_load_lds_dwordx4 v[156:157], off
	v_lshl_add_u64 v[156:157], s[8:9], 0, v[142:143]
	s_add_i32 m0, s36, 0x2000
	s_nop 0
	global_load_lds_dwordx4 v[156:157], off
	v_lshl_add_u64 v[156:157], v[224:225], 0, s[14:15]
	s_mov_b32 m0, s47
	s_nop 0
	global_load_lds_dwordx4 v[156:157], off
	v_lshl_add_u64 v[156:157], v[226:227], 0, s[14:15]
	s_mov_b32 m0, s48
	s_nop 0
	global_load_lds_dwordx4 v[156:157], off
	s_waitcnt vmcnt(8)
	s_waitcnt lgkmcnt(0)
	s_barrier
	s_setprio 1
	v_mfma_f32_16x16x32_bf16 v[60:63], v[128:131], v[192:195], v[60:63]
	v_mfma_f32_16x16x32_bf16 v[56:59], v[152:155], v[192:195], v[56:59]
	v_mfma_f32_16x16x32_bf16 v[44:47], v[128:131], v[200:203], v[44:47]
	v_mfma_f32_16x16x32_bf16 v[40:43], v[152:155], v[200:203], v[40:43]
	v_mfma_f32_16x16x32_bf16 v[28:31], v[128:131], v[208:211], v[28:31]
	v_mfma_f32_16x16x32_bf16 v[24:27], v[152:155], v[208:211], v[24:27]
	v_mfma_f32_16x16x32_bf16 v[12:15], v[128:131], v[216:219], v[12:15]
	v_mfma_f32_16x16x32_bf16 v[8:11], v[152:155], v[216:219], v[8:11]
	v_mfma_f32_16x16x32_bf16 v[60:63], v[132:135], v[196:199], v[60:63]
	v_mfma_f32_16x16x32_bf16 v[56:59], v[166:169], v[196:199], v[56:59]
	v_mfma_f32_16x16x32_bf16 v[44:47], v[132:135], v[204:207], v[44:47]
	v_mfma_f32_16x16x32_bf16 v[40:43], v[166:169], v[204:207], v[40:43]
	v_mfma_f32_16x16x32_bf16 v[28:31], v[132:135], v[212:215], v[28:31]
	v_mfma_f32_16x16x32_bf16 v[24:27], v[166:169], v[212:215], v[24:27]
	v_mfma_f32_16x16x32_bf16 v[12:15], v[132:135], v[220:223], v[12:15]
	v_mfma_f32_16x16x32_bf16 v[8:11], v[166:169], v[220:223], v[8:11]
	v_mfma_f32_16x16x32_bf16 v[52:55], v[170:173], v[192:195], v[52:55]
	v_mfma_f32_16x16x32_bf16 v[48:51], v[178:181], v[192:195], v[48:51]
	v_mfma_f32_16x16x32_bf16 v[36:39], v[170:173], v[200:203], v[36:39]
	v_mfma_f32_16x16x32_bf16 v[32:35], v[178:181], v[200:203], v[32:35]
	v_mfma_f32_16x16x32_bf16 v[20:23], v[170:173], v[208:211], v[20:23]
	v_mfma_f32_16x16x32_bf16 v[16:19], v[178:181], v[208:211], v[16:19]
	v_mfma_f32_16x16x32_bf16 v[4:7], v[170:173], v[216:219], v[4:7]
	v_mfma_f32_16x16x32_bf16 v[0:3], v[178:181], v[216:219], v[0:3]
	v_mfma_f32_16x16x32_bf16 v[52:55], v[174:177], v[196:199], v[52:55]
	v_mfma_f32_16x16x32_bf16 v[48:51], v[182:185], v[196:199], v[48:51]
	v_mfma_f32_16x16x32_bf16 v[36:39], v[174:177], v[204:207], v[36:39]
	v_mfma_f32_16x16x32_bf16 v[32:35], v[182:185], v[204:207], v[32:35]
	v_mfma_f32_16x16x32_bf16 v[20:23], v[174:177], v[212:215], v[20:23]
	v_mfma_f32_16x16x32_bf16 v[16:19], v[182:185], v[212:215], v[16:19]
	v_mfma_f32_16x16x32_bf16 v[4:7], v[174:177], v[220:223], v[4:7]
	v_mfma_f32_16x16x32_bf16 v[0:3], v[182:185], v[220:223], v[0:3]
	s_setprio 0
	s_nop 0
	s_add_i32 s60, s60, 2
	s_add_u32 s58, s58, 0x100
	s_addc_u32 s59, s59, 0
	s_cmp_gt_u32 s60, 41
	s_mov_b64 s[8:9], s[34:35]
	s_cbranch_scc0 .Lrot_274
	s_barrier
	s_and_b64 vcc, exec, s[16:17]
	s_cbranch_vccz .LBB0_277
	s_barrier

; #define PG8_STAGE(bufoff, gbase, voff) do { _Pragma("unroll") for (int _i = 0; _i < 2; ++_i) \
;         __builtin_amdgcn_global_load_lds((const unsigned*)((const char*)(gbase) + (voff)[_i]), (PG8_LAS unsigned*)(lds + (bufoff) + ldsw + _i * 8192), 16, 0, 0); } while (0)
; #define PG8_LDA(dst, b, h) do { _Pragma("unroll") for (int m = 0; m < 4; ++m) _Pragma("unroll") for (int k = 0; k < 2; ++k) dst[m][k] = *(const PG8_LAS bf16x8*)(lds + PG8_SA(b, h) + aoff + m * 2048 + k * 1024); } while (0)
; #define PG8_LDB(dst, b, h) do { _Pragma("unroll") for (int n = 0; n < 2; ++n) _Pragma("unroll") for (int k = 0; k < 2; ++k) dst[n][k] = *(const PG8_LAS bf16x8*)(lds + PG8_SB(b, h) + boff + n * 2048 + k * 1024); } while (0)
; #define PG8_MMA(ai, bj, At, Bt) do { __builtin_amdgcn_s_setprio(1); _Pragma("unroll") for (int m = 0; m < 4; ++m) _Pragma("unroll") for (int n = 0; n < 2; ++n) _Pragma("unroll") for (int k = 0; k < 2; ++k) \
;         acc[ai][bj][m][n] = __builtin_amdgcn_mfma_f32_16x16x32_bf16(Bt[n][k], At[m][k], acc[ai][bj][m][n], 0, 0, 0); __builtin_amdgcn_s_setprio(0); } while (0)
; #define PG8_BAR __builtin_amdgcn_s_barrier()
; template <class Epi, class Sched, bool ALIGN_EPI = false, bool SP2 = false>
; __device__ __forceinline__ void gemm_phase(PG8_LAS unsigned char* lds, const Gemm g, const Sched& S, const Epi& E) {
;     ...
;         const bool has_next = S.next(ui + 1, nxt);
;         const char* nA = has_next ? (const char*)g.A + (size_t)nxt.pm * tstep : cA; const char* nB = has_next ? (const char*)g.Bt + (size_t)nxt.pn * tstep : cB;
;         for (int t = 0; t < nt; t += 2) {
;             const bool last = (t == nt - 2);
;             const char* a1 = cA + (size_t)(t + 1) * kstep;
;             const char* a2 = last ? nA : cA + (size_t)(t + 2) * kstep; const char* b2 = last ? nB : cB + (size_t)(t + 2) * kstep;
;             const char* a3 = a2 + kstep; const char* b3 = b2 + kstep;
;             if (last && has_next) S.a_ready(nxt);
;             if constexpr (SP2) {
;             PG8_LDB(B0, 0, 0); PG8_LDB(B1, 0, 1); PG8_SCHED; PG8_LDA(At, 0, 0); PG8_STAGE(PG8_SA(1, 1), a1 + hstep, voffA);
;             PG8_WAIT_V(8); PG8_WAIT_L(0); PG8_BAR; PG8_MMA(0, 0, At, B0); PG8_MMA(0, 1, At, B1); PG8_BAR; PG8_SCHED;
;             PG8_LDA(At, 0, 1); PG8_STAGE(PG8_SB(0, 0), b2, voffB); PG8_STAGE(PG8_SB(0, 1), b2 + hstep, voffB); PG8_STAGE(PG8_SA(0, 0), a2, voffA);
.LBB0_373:
	s_ashr_i32 s31, s30, 31
	s_lshl_b64 s[34:35], s[30:31], 19
	v_readlane_b32 s36, v235, 31
	v_readlane_b32 s37, v235, 32
	s_add_u32 s34, s36, s34
	s_addc_u32 s35, s37, s35
	s_and_b64 s[36:37], s[6:7], exec
	s_cselect_b32 s1, s35, s3
	s_cselect_b32 s25, s34, s2
	s_ashr_i32 s29, s28, 31
	s_lshl_b64 s[36:37], s[28:29], 19
	s_add_u32 s36, s10, s36
	s_addc_u32 s37, s11, s37
	s_and_b64 s[40:41], s[6:7], exec
	s_cselect_b32 s29, s37, s39
	s_cselect_b32 s31, s36, s38
	s_add_u32 s2, s2, 0x40080
	s_addc_u32 s3, s3, 0
	s_add_u32 s58, s38, 0x100
	s_addc_u32 s59, s39, 0
	s_mov_b32 s60, -2
	ds_read_b128 v[128:131], v171
	ds_read_b128 v[132:135], v171 offset:1024
	ds_read_b128 v[136:139], v171 offset:2048
	ds_read_b128 v[140:143], v171 offset:3072
	ds_read_b128 v[164:167], v172
	ds_read_b128 v[178:181], v172 offset:1024
	ds_read_b128 v[182:185], v172 offset:2048
	ds_read_b128 v[192:195], v172 offset:3072
	s_add_u32 s38, s2, 0xfffc0080
	s_addc_u32 s39, s3, -1
	s_cmp_eq_u32 s60, 12
	s_cselect_b32 s41, s1, s39
	s_cselect_b32 s40, s25, s38
	s_cselect_b32 s39, s29, s59
	s_cselect_b32 s38, s31, s58
	v_lshl_add_u64 v[168:169], s[2:3], 0, v[156:157]
	s_add_i32 m0, s44, 0xc000
	ds_read_b128 v[196:199], v173
	ds_read_b128 v[200:203], v173 offset:1024
	ds_read_b128 v[204:207], v173 offset:2048
	ds_read_b128 v[208:211], v173 offset:3072
	ds_read_b128 v[212:215], v173 offset:4096
	ds_read_b128 v[216:219], v173 offset:5120
	ds_read_b128 v[220:223], v173 offset:6144
	ds_read_b128 v[224:227], v173 offset:7168
	global_load_lds_dwordx4 v[168:169], off
	v_lshl_add_u64 v[168:169], s[2:3], 0, v[158:159]
	s_add_i32 m0, s44, 0xe000
	s_nop 0
	global_load_lds_dwordx4 v[168:169], off
	s_waitcnt vmcnt(8)
	s_waitcnt lgkmcnt(0)
	s_barrier
	s_setprio 1
	v_mfma_f32_16x16x32_bf16 v[124:127], v[128:131], v[196:199], 0
	v_mfma_f32_16x16x32_bf16 v[120:123], v[136:139], v[196:199], 0
	v_mfma_f32_16x16x32_bf16 v[108:111], v[128:131], v[204:207], 0
	v_mfma_f32_16x16x32_bf16 v[104:107], v[136:139], v[204:207], 0
	v_mfma_f32_16x16x32_bf16 v[92:95], v[128:131], v[212:215], 0
	v_mfma_f32_16x16x32_bf16 v[88:91], v[136:139], v[212:215], 0
	v_mfma_f32_16x16x32_bf16 v[76:79], v[128:131], v[220:223], 0
	v_mfma_f32_16x16x32_bf16 v[72:75], v[136:139], v[220:223], 0
	v_mfma_f32_16x16x32_bf16 v[124:127], v[132:135], v[200:203], v[124:127]
	v_mfma_f32_16x16x32_bf16 v[120:123], v[140:143], v[200:203], v[120:123]
	v_mfma_f32_16x16x32_bf16 v[108:111], v[132:135], v[208:211], v[108:111]
	v_mfma_f32_16x16x32_bf16 v[104:107], v[140:143], v[208:211], v[104:107]
	v_mfma_f32_16x16x32_bf16 v[92:95], v[132:135], v[216:219], v[92:95]
	v_mfma_f32_16x16x32_bf16 v[88:91], v[140:143], v[216:219], v[88:91]
	v_mfma_f32_16x16x32_bf16 v[76:79], v[132:135], v[224:227], v[76:79]
	v_mfma_f32_16x16x32_bf16 v[72:75], v[140:143], v[224:227], v[72:75]
	v_mfma_f32_16x16x32_bf16 v[116:119], v[164:167], v[196:199], 0
	v_mfma_f32_16x16x32_bf16 v[112:115], v[182:185], v[196:199], 0
	v_mfma_f32_16x16x32_bf16 v[100:103], v[164:167], v[204:207], 0
	v_mfma_f32_16x16x32_bf16 v[96:99], v[182:185], v[204:207], 0
	v_mfma_f32_16x16x32_bf16 v[84:87], v[164:167], v[212:215], 0
	v_mfma_f32_16x16x32_bf16 v[80:83], v[182:185], v[212:215], 0
	v_mfma_f32_16x16x32_bf16 v[68:71], v[164:167], v[220:223], 0
	v_mfma_f32_16x16x32_bf16 v[64:67], v[182:185], v[220:223], 0
	v_mfma_f32_16x16x32_bf16 v[116:119], v[178:181], v[200:203], v[116:119]
	v_mfma_f32_16x16x32_bf16 v[112:115], v[192:195], v[200:203], v[112:115]
	v_mfma_f32_16x16x32_bf16 v[100:103], v[178:181], v[208:211], v[100:103]
	v_mfma_f32_16x16x32_bf16 v[96:99], v[192:195], v[208:211], v[96:99]
	v_mfma_f32_16x16x32_bf16 v[84:87], v[178:181], v[216:219], v[84:87]
	v_mfma_f32_16x16x32_bf16 v[80:83], v[192:195], v[216:219], v[80:83]
	v_mfma_f32_16x16x32_bf16 v[68:71], v[178:181], v[224:227], v[68:71]
	v_mfma_f32_16x16x32_bf16 v[64:67], v[192:195], v[224:227], v[64:67]
	s_setprio 0
	s_barrier
	s_add_i32 s61, s52, s33
	v_lshl_add_u64 v[168:169], s[38:39], 0, v[148:149]
	s_mov_b32 m0, s61
	ds_read_b128 v[196:199], v173 offset:16384
	ds_read_b128 v[200:203], v173 offset:17408
	ds_read_b128 v[204:207], v173 offset:18432
	ds_read_b128 v[208:211], v173 offset:19456
	ds_read_b128 v[212:215], v173 offset:20480
	ds_read_b128 v[216:219], v173 offset:21504
	ds_read_b128 v[220:223], v173 offset:22528
	ds_read_b128 v[224:227], v173 offset:23552
	global_load_lds_dwordx4 v[168:169], off
	s_add_i32 m0, s61, 0x2000
	s_add_u32 s62, s38, 0x40000
	v_lshl_add_u64 v[186:187], s[38:39], 0, v[144:145]
	s_addc_u32 s63, s39, 0
	s_add_i32 s61, s53, s33
	global_load_lds_dwordx4 v[186:187], off
	v_lshl_add_u64 v[228:229], s[62:63], 0, v[148:149]
	s_mov_b32 m0, s61
	v_lshl_add_u64 v[230:231], s[40:41], 0, v[146:147]
	global_load_lds_dwordx4 v[228:229], off
	v_lshl_add_u64 v[228:229], s[62:63], 0, v[144:145]
	s_add_i32 m0, s61, 0x2000
	s_nop 0
	global_load_lds_dwordx4 v[228:229], off
	v_lshl_add_u64 v[228:229], s[40:41], 0, v[150:151]
	s_mov_b32 m0, s44
	s_nop 0
	global_load_lds_dwordx4 v[228:229], off
	s_mov_b32 m0, s45
	s_nop 0
	global_load_lds_dwordx4 v[230:231], off
	s_waitcnt vmcnt(8)
	s_waitcnt lgkmcnt(0)
	s_barrier
; #define PG8_STAGE(bufoff, gbase, voff) do { _Pragma("unroll") for (int _i = 0; _i < 2; ++_i) \
;         __builtin_amdgcn_global_load_lds((const unsigned*)((const char*)(gbase) + (voff)[_i]), (PG8_LAS unsigned*)(lds + (bufoff) + ldsw + _i * 8192), 16, 0, 0); } while (0)
; #define PG8_LDA(dst, b, h) do { _Pragma("unroll") for (int m = 0; m < 4; ++m) _Pragma("unroll") for (int k = 0; k < 2; ++k) dst[m][k] = *(const PG8_LAS bf16x8*)(lds + PG8_SA(b, h) + aoff + m * 2048 + k * 1024); } while (0)
; #define PG8_LDB(dst, b, h) do { _Pragma("unroll") for (int n = 0; n < 2; ++n) _Pragma("unroll") for (int k = 0; k < 2; ++k) dst[n][k] = *(const PG8_LAS bf16x8*)(lds + PG8_SB(b, h) + boff + n * 2048 + k * 1024); } while (0)
; #define PG8_MMA(ai, bj, At, Bt) do { __builtin_amdgcn_s_setprio(1); _Pragma("unroll") for (int m = 0; m < 4; ++m) _Pragma("unroll") for (int n = 0; n < 2; ++n) _Pragma("unroll") for (int k = 0; k < 2; ++k) \
;         acc[ai][bj][m][n] = __builtin_amdgcn_mfma_f32_16x16x32_bf16(Bt[n][k], At[m][k], acc[ai][bj][m][n], 0, 0, 0); __builtin_amdgcn_s_setprio(0); } while (0)
; #define PG8_WAIT_V(n) asm volatile("s_waitcnt vmcnt(" #n ")" ::: "memory")
; #define PG8_WAIT_L(n) asm volatile("s_waitcnt lgkmcnt(" #n ")" ::: "memory")
; #define PG8_BAR __builtin_amdgcn_s_barrier()
; #define PG8_SCHED __builtin_amdgcn_sched_barrier(0)
; template <class Epi, class Sched, bool ALIGN_EPI = false, bool SP2 = false>
; __device__ __forceinline__ void gemm_phase(PG8_LAS unsigned char* lds, const Gemm g, const Sched& S, const Epi& E) {
;     ...
;             PG8_WAIT_V(8); PG8_WAIT_L(0); PG8_BAR; PG8_MMA(1, 0, At, B0); PG8_MMA(1, 1, At, B1); PG8_BAR; PG8_SCHED;
;             PG8_LDB(B0, 1, 0); PG8_LDB(B1, 1, 1); PG8_SCHED; PG8_LDA(At, 1, 0); PG8_STAGE(PG8_SA(0, 1), a2 + hstep, voffA);
;             PG8_WAIT_V(8); PG8_WAIT_L(0); PG8_BAR; PG8_MMA(0, 0, At, B0); PG8_MMA(0, 1, At, B1); PG8_BAR; PG8_SCHED;
	s_setprio 1
	v_mfma_f32_16x16x32_bf16 v[60:63], v[128:131], v[196:199], 0
	v_mfma_f32_16x16x32_bf16 v[56:59], v[136:139], v[196:199], 0
	v_mfma_f32_16x16x32_bf16 v[44:47], v[128:131], v[204:207], 0
	v_mfma_f32_16x16x32_bf16 v[40:43], v[136:139], v[204:207], 0
	v_mfma_f32_16x16x32_bf16 v[28:31], v[128:131], v[212:215], 0
	v_mfma_f32_16x16x32_bf16 v[24:27], v[136:139], v[212:215], 0
	v_mfma_f32_16x16x32_bf16 v[12:15], v[128:131], v[220:223], 0
	v_mfma_f32_16x16x32_bf16 v[8:11], v[136:139], v[220:223], 0
	v_mfma_f32_16x16x32_bf16 v[60:63], v[132:135], v[200:203], v[60:63]
	v_mfma_f32_16x16x32_bf16 v[56:59], v[140:143], v[200:203], v[56:59]
	v_mfma_f32_16x16x32_bf16 v[44:47], v[132:135], v[208:211], v[44:47]
	v_mfma_f32_16x16x32_bf16 v[40:43], v[140:143], v[208:211], v[40:43]
	v_mfma_f32_16x16x32_bf16 v[28:31], v[132:135], v[216:219], v[28:31]
	v_mfma_f32_16x16x32_bf16 v[24:27], v[140:143], v[216:219], v[24:27]
	v_mfma_f32_16x16x32_bf16 v[12:15], v[132:135], v[224:227], v[12:15]
	v_mfma_f32_16x16x32_bf16 v[8:11], v[140:143], v[224:227], v[8:11]
	v_mfma_f32_16x16x32_bf16 v[52:55], v[164:167], v[196:199], 0
	v_mfma_f32_16x16x32_bf16 v[48:51], v[182:185], v[196:199], 0
	v_mfma_f32_16x16x32_bf16 v[36:39], v[164:167], v[204:207], 0
	v_mfma_f32_16x16x32_bf16 v[32:35], v[182:185], v[204:207], 0
	v_mfma_f32_16x16x32_bf16 v[20:23], v[164:167], v[212:215], 0
	v_mfma_f32_16x16x32_bf16 v[16:19], v[182:185], v[212:215], 0
	v_mfma_f32_16x16x32_bf16 v[4:7], v[164:167], v[220:223], 0
	v_mfma_f32_16x16x32_bf16 v[0:3], v[182:185], v[220:223], 0
	v_mfma_f32_16x16x32_bf16 v[52:55], v[178:181], v[200:203], v[52:55]
	v_mfma_f32_16x16x32_bf16 v[48:51], v[192:195], v[200:203], v[48:51]
	v_mfma_f32_16x16x32_bf16 v[36:39], v[178:181], v[208:211], v[36:39]
	v_mfma_f32_16x16x32_bf16 v[32:35], v[192:195], v[208:211], v[32:35]
	v_mfma_f32_16x16x32_bf16 v[20:23], v[178:181], v[216:219], v[20:23]
	v_mfma_f32_16x16x32_bf16 v[16:19], v[192:195], v[216:219], v[16:19]
	v_mfma_f32_16x16x32_bf16 v[4:7], v[178:181], v[224:227], v[4:7]
	v_mfma_f32_16x16x32_bf16 v[0:3], v[192:195], v[224:227], v[0:3]
	s_setprio 0
	s_barrier
	s_add_i32 s61, 0, 0x18000
	s_add_i32 s62, 0, 0x1c000
	v_add_u32_e32 v140, s61, v170
	v_add_u32_e32 v152, s62, v170
	ds_read_b128 v[128:131], v140
	ds_read_b128 v[132:135], v140 offset:1024
	ds_read_b128 v[136:139], v140 offset:2048
	ds_read_b128 v[140:143], v140 offset:3072
	ds_read_b128 v[164:167], v152
	ds_read_b128 v[178:181], v152 offset:1024
	ds_read_b128 v[182:185], v152 offset:2048
	ds_read_b128 v[192:195], v152 offset:3072
	s_add_u32 s40, s40, 0x40000
	s_addc_u32 s41, s41, 0
	s_mov_b32 m0, s46
	v_lshl_add_u64 v[232:233], s[40:41], 0, v[150:151]
	ds_read_b128 v[196:199], v173 offset:32768
	ds_read_b128 v[200:203], v173 offset:33792
	ds_read_b128 v[204:207], v173 offset:34816
	ds_read_b128 v[208:211], v173 offset:35840
	ds_read_b128 v[212:215], v173 offset:36864
	ds_read_b128 v[216:219], v173 offset:37888
	ds_read_b128 v[220:223], v173 offset:38912
	ds_read_b128 v[224:227], v173 offset:39936
	global_load_lds_dwordx4 v[232:233], off
	v_lshl_add_u64 v[232:233], s[40:41], 0, v[146:147]
	s_mov_b32 m0, s47
	s_nop 0
	global_load_lds_dwordx4 v[232:233], off
	s_waitcnt vmcnt(8)
	s_waitcnt lgkmcnt(0)
	s_barrier
	s_setprio 1
	v_mfma_f32_16x16x32_bf16 v[124:127], v[128:131], v[196:199], v[124:127]
	v_mfma_f32_16x16x32_bf16 v[120:123], v[136:139], v[196:199], v[120:123]
	v_mfma_f32_16x16x32_bf16 v[108:111], v[128:131], v[204:207], v[108:111]
	v_mfma_f32_16x16x32_bf16 v[104:107], v[136:139], v[204:207], v[104:107]
	v_mfma_f32_16x16x32_bf16 v[92:95], v[128:131], v[212:215], v[92:95]
	v_mfma_f32_16x16x32_bf16 v[88:91], v[136:139], v[212:215], v[88:91]
	v_mfma_f32_16x16x32_bf16 v[76:79], v[128:131], v[220:223], v[76:79]
	v_mfma_f32_16x16x32_bf16 v[72:75], v[136:139], v[220:223], v[72:75]
	v_mfma_f32_16x16x32_bf16 v[124:127], v[132:135], v[200:203], v[124:127]
	v_mfma_f32_16x16x32_bf16 v[120:123], v[140:143], v[200:203], v[120:123]
	v_mfma_f32_16x16x32_bf16 v[108:111], v[132:135], v[208:211], v[108:111]
	v_mfma_f32_16x16x32_bf16 v[104:107], v[140:143], v[208:211], v[104:107]
	v_mfma_f32_16x16x32_bf16 v[92:95], v[132:135], v[216:219], v[92:95]
	v_mfma_f32_16x16x32_bf16 v[88:91], v[140:143], v[216:219], v[88:91]
	v_mfma_f32_16x16x32_bf16 v[76:79], v[132:135], v[224:227], v[76:79]
	v_mfma_f32_16x16x32_bf16 v[72:75], v[140:143], v[224:227], v[72:75]
	v_mfma_f32_16x16x32_bf16 v[116:119], v[164:167], v[196:199], v[116:119]
	v_mfma_f32_16x16x32_bf16 v[112:115], v[182:185], v[196:199], v[112:115]
	v_mfma_f32_16x16x32_bf16 v[100:103], v[164:167], v[204:207], v[100:103]
	v_mfma_f32_16x16x32_bf16 v[96:99], v[182:185], v[204:207], v[96:99]
	v_mfma_f32_16x16x32_bf16 v[84:87], v[164:167], v[212:215], v[84:87]
	v_mfma_f32_16x16x32_bf16 v[80:83], v[182:185], v[212:215], v[80:83]
	v_mfma_f32_16x16x32_bf16 v[68:71], v[164:167], v[220:223], v[68:71]
	v_mfma_f32_16x16x32_bf16 v[64:67], v[182:185], v[220:223], v[64:67]
	v_mfma_f32_16x16x32_bf16 v[116:119], v[178:181], v[200:203], v[116:119]
	v_mfma_f32_16x16x32_bf16 v[112:115], v[192:195], v[200:203], v[112:115]
	v_mfma_f32_16x16x32_bf16 v[100:103], v[178:181], v[208:211], v[100:103]
	v_mfma_f32_16x16x32_bf16 v[96:99], v[192:195], v[208:211], v[96:99]
	v_mfma_f32_16x16x32_bf16 v[84:87], v[178:181], v[216:219], v[84:87]
	v_mfma_f32_16x16x32_bf16 v[80:83], v[192:195], v[216:219], v[80:83]
	v_mfma_f32_16x16x32_bf16 v[68:71], v[178:181], v[224:227], v[68:71]
	v_mfma_f32_16x16x32_bf16 v[64:67], v[192:195], v[224:227], v[64:67]
	s_setprio 0
	s_barrier
; #define PG8_STAGE(bufoff, gbase, voff) do { _Pragma("unroll") for (int _i = 0; _i < 2; ++_i) \
;         __builtin_amdgcn_global_load_lds((const unsigned*)((const char*)(gbase) + (voff)[_i]), (PG8_LAS unsigned*)(lds + (bufoff) + ldsw + _i * 8192), 16, 0, 0); } while (0)
; #define PG8_LDA(dst, b, h) do { _Pragma("unroll") for (int m = 0; m < 4; ++m) _Pragma("unroll") for (int k = 0; k < 2; ++k) dst[m][k] = *(const PG8_LAS bf16x8*)(lds + PG8_SA(b, h) + aoff + m * 2048 + k * 1024); } while (0)
; #define PG8_MMA(ai, bj, At, Bt) do { __builtin_amdgcn_s_setprio(1); _Pragma("unroll") for (int m = 0; m < 4; ++m) _Pragma("unroll") for (int n = 0; n < 2; ++n) _Pragma("unroll") for (int k = 0; k < 2; ++k) \
;         acc[ai][bj][m][n] = __builtin_amdgcn_mfma_f32_16x16x32_bf16(Bt[n][k], At[m][k], acc[ai][bj][m][n], 0, 0, 0); __builtin_amdgcn_s_setprio(0); } while (0)
; #define PG8_WAIT_V(n) asm volatile("s_waitcnt vmcnt(" #n ")" ::: "memory")
; #define PG8_WAIT_L(n) asm volatile("s_waitcnt lgkmcnt(" #n ")" ::: "memory")
; #define PG8_BAR __builtin_amdgcn_s_barrier()
; #define PG8_SCHED __builtin_amdgcn_sched_barrier(0)
; template <class Epi, class Sched, bool ALIGN_EPI = false, bool SP2 = false>
; __device__ __forceinline__ void gemm_phase(PG8_LAS unsigned char* lds, const Gemm g, const Sched& S, const Epi& E) {
;     ...
;             PG8_LDA(At, 1, 1); PG8_STAGE(PG8_SB(1, 0), b3, voffB); PG8_STAGE(PG8_SB(1, 1), b3 + hstep, voffB); PG8_STAGE(PG8_SA(1, 0), a3, voffA);
;             PG8_WAIT_V(8); PG8_WAIT_L(0); PG8_BAR; PG8_MMA(1, 0, At, B0); PG8_MMA(1, 1, At, B1); PG8_BAR; PG8_SCHED;
	s_add_i32 s40, s61, s33
	v_lshl_add_u64 v[168:169], v[168:169], 0, s[16:17]
	s_mov_b32 m0, s40
	ds_read_b128 v[196:199], v173 offset:49152
	ds_read_b128 v[200:203], v173 offset:50176
	ds_read_b128 v[204:207], v173 offset:51200
	ds_read_b128 v[208:211], v173 offset:52224
	ds_read_b128 v[212:215], v173 offset:53248
	ds_read_b128 v[216:219], v173 offset:54272
	ds_read_b128 v[220:223], v173 offset:55296
	ds_read_b128 v[224:227], v173 offset:56320
	global_load_lds_dwordx4 v[168:169], off
	s_add_i32 m0, s40, 0x2000
	s_add_u32 s38, s38, 0x40080
	v_lshl_add_u64 v[168:169], v[186:187], 0, s[16:17]
	s_addc_u32 s39, s39, 0
	s_add_i32 s40, s62, s33
	global_load_lds_dwordx4 v[168:169], off
	v_lshl_add_u64 v[168:169], s[38:39], 0, v[148:149]
	s_mov_b32 m0, s40
	s_nop 0
	global_load_lds_dwordx4 v[168:169], off
	v_lshl_add_u64 v[168:169], s[38:39], 0, v[144:145]
	s_add_i32 m0, s40, 0x2000
	s_nop 0
	global_load_lds_dwordx4 v[168:169], off
	v_lshl_add_u64 v[168:169], v[228:229], 0, s[16:17]
	s_mov_b32 m0, s48
	s_nop 0
	global_load_lds_dwordx4 v[168:169], off
	v_lshl_add_u64 v[168:169], v[230:231], 0, s[16:17]
	s_mov_b32 m0, s49
	s_nop 0
	global_load_lds_dwordx4 v[168:169], off
	s_waitcnt vmcnt(8)
	s_waitcnt lgkmcnt(0)
	s_barrier
	s_setprio 1
	v_mfma_f32_16x16x32_bf16 v[60:63], v[128:131], v[196:199], v[60:63]
	v_mfma_f32_16x16x32_bf16 v[56:59], v[136:139], v[196:199], v[56:59]
	v_mfma_f32_16x16x32_bf16 v[44:47], v[128:131], v[204:207], v[44:47]
	v_mfma_f32_16x16x32_bf16 v[40:43], v[136:139], v[204:207], v[40:43]
	v_mfma_f32_16x16x32_bf16 v[28:31], v[128:131], v[212:215], v[28:31]
	v_mfma_f32_16x16x32_bf16 v[24:27], v[136:139], v[212:215], v[24:27]
	v_mfma_f32_16x16x32_bf16 v[12:15], v[128:131], v[220:223], v[12:15]
	v_mfma_f32_16x16x32_bf16 v[8:11], v[136:139], v[220:223], v[8:11]
	v_mfma_f32_16x16x32_bf16 v[60:63], v[132:135], v[200:203], v[60:63]
	v_mfma_f32_16x16x32_bf16 v[56:59], v[140:143], v[200:203], v[56:59]
	v_mfma_f32_16x16x32_bf16 v[44:47], v[132:135], v[208:211], v[44:47]
	v_mfma_f32_16x16x32_bf16 v[40:43], v[140:143], v[208:211], v[40:43]
	v_mfma_f32_16x16x32_bf16 v[28:31], v[132:135], v[216:219], v[28:31]
	v_mfma_f32_16x16x32_bf16 v[24:27], v[140:143], v[216:219], v[24:27]
	v_mfma_f32_16x16x32_bf16 v[12:15], v[132:135], v[224:227], v[12:15]
	v_mfma_f32_16x16x32_bf16 v[8:11], v[140:143], v[224:227], v[8:11]
	v_mfma_f32_16x16x32_bf16 v[52:55], v[164:167], v[196:199], v[52:55]
	v_mfma_f32_16x16x32_bf16 v[48:51], v[182:185], v[196:199], v[48:51]
	v_mfma_f32_16x16x32_bf16 v[36:39], v[164:167], v[204:207], v[36:39]
	v_mfma_f32_16x16x32_bf16 v[32:35], v[182:185], v[204:207], v[32:35]
	v_mfma_f32_16x16x32_bf16 v[20:23], v[164:167], v[212:215], v[20:23]
	v_mfma_f32_16x16x32_bf16 v[16:19], v[182:185], v[212:215], v[16:19]
	v_mfma_f32_16x16x32_bf16 v[4:7], v[164:167], v[220:223], v[4:7]
	v_mfma_f32_16x16x32_bf16 v[0:3], v[182:185], v[220:223], v[0:3]
	v_mfma_f32_16x16x32_bf16 v[52:55], v[178:181], v[200:203], v[52:55]
	v_mfma_f32_16x16x32_bf16 v[48:51], v[192:195], v[200:203], v[48:51]
	v_mfma_f32_16x16x32_bf16 v[36:39], v[178:181], v[208:211], v[36:39]
	v_mfma_f32_16x16x32_bf16 v[32:35], v[192:195], v[208:211], v[32:35]
	v_mfma_f32_16x16x32_bf16 v[20:23], v[178:181], v[216:219], v[20:23]
	v_mfma_f32_16x16x32_bf16 v[16:19], v[192:195], v[216:219], v[16:19]
	v_mfma_f32_16x16x32_bf16 v[4:7], v[178:181], v[224:227], v[4:7]
	v_mfma_f32_16x16x32_bf16 v[0:3], v[192:195], v[224:227], v[0:3]
	s_setprio 0
	s_nop 0
	s_add_i32 s60, s60, 2
	s_add_u32 s2, s2, 0x100
	s_addc_u32 s3, s3, 0
	s_add_u32 s58, s58, 0x100
	s_addc_u32 s59, s59, 0

; #define PG8_STAGE(bufoff, gbase, voff) do { _Pragma("unroll") for (int _i = 0; _i < 2; ++_i) \
;         __builtin_amdgcn_global_load_lds((const unsigned*)((const char*)(gbase) + (voff)[_i]), (PG8_LAS unsigned*)(lds + (bufoff) + ldsw + _i * 8192), 16, 0, 0); } while (0)
; #define PG8_LDA(dst, b, h) do { _Pragma("unroll") for (int m = 0; m < 4; ++m) _Pragma("unroll") for (int k = 0; k < 2; ++k) dst[m][k] = *(const PG8_LAS bf16x8*)(lds + PG8_SA(b, h) + aoff + m * 2048 + k * 1024); } while (0)
; #define PG8_LDB(dst, b, h) do { _Pragma("unroll") for (int n = 0; n < 2; ++n) _Pragma("unroll") for (int k = 0; k < 2; ++k) dst[n][k] = *(const PG8_LAS bf16x8*)(lds + PG8_SB(b, h) + boff + n * 2048 + k * 1024); } while (0)
; #define PG8_MMA(ai, bj, At, Bt) do { __builtin_amdgcn_s_setprio(1); _Pragma("unroll") for (int m = 0; m < 4; ++m) _Pragma("unroll") for (int n = 0; n < 2; ++n) _Pragma("unroll") for (int k = 0; k < 2; ++k) \
;         acc[ai][bj][m][n] = __builtin_amdgcn_mfma_f32_16x16x32_bf16(Bt[n][k], At[m][k], acc[ai][bj][m][n], 0, 0, 0); __builtin_amdgcn_s_setprio(0); } while (0)
; #define PG8_WAIT_V(n) asm volatile("s_waitcnt vmcnt(" #n ")" ::: "memory")
; #define PG8_WAIT_L(n) asm volatile("s_waitcnt lgkmcnt(" #n ")" ::: "memory")
; #define PG8_BAR __builtin_amdgcn_s_barrier()
; #define PG8_SCHED __builtin_amdgcn_sched_barrier(0)
; template <class Epi, class Sched, bool ALIGN_EPI = false, bool SP2 = false>
; __device__ __forceinline__ void gemm_phase(PG8_LAS unsigned char* lds, const Gemm g, const Sched& S, const Epi& E) {
;     ...
;         for (int t = 0; t < nt; t += 2) {
;             const bool last = (t == nt - 2);
;             const char* a1 = cA + (size_t)(t + 1) * kstep;
;             const char* a2 = last ? nA : cA + (size_t)(t + 2) * kstep; const char* b2 = last ? nB : cB + (size_t)(t + 2) * kstep;
;             const char* a3 = a2 + kstep; const char* b3 = b2 + kstep;
;             if (last && has_next) S.a_ready(nxt);
;             if constexpr (SP2) {
;             PG8_LDB(B0, 0, 0); PG8_LDB(B1, 0, 1); PG8_SCHED; PG8_LDA(At, 0, 0); PG8_STAGE(PG8_SA(1, 1), a1 + hstep, voffA);
;             PG8_WAIT_V(8); PG8_WAIT_L(0); PG8_BAR; PG8_MMA(0, 0, At, B0); PG8_MMA(0, 1, At, B1); PG8_BAR; PG8_SCHED;
;             PG8_LDA(At, 0, 1); PG8_STAGE(PG8_SB(0, 0), b2, voffB); PG8_STAGE(PG8_SB(0, 1), b2 + hstep, voffB); PG8_STAGE(PG8_SA(0, 0), a2, voffA);
.LBB0_374:
	ds_read_b128 v[128:131], v171
	ds_read_b128 v[132:135], v171 offset:1024
	ds_read_b128 v[136:139], v171 offset:2048
	ds_read_b128 v[140:143], v171 offset:3072
	ds_read_b128 v[164:167], v172
	ds_read_b128 v[178:181], v172 offset:1024
	ds_read_b128 v[182:185], v172 offset:2048
	ds_read_b128 v[192:195], v172 offset:3072
	s_add_u32 s38, s2, 0xfffc0080
	s_addc_u32 s39, s3, -1
	s_cmp_eq_u32 s60, 12
	s_cselect_b32 s41, s1, s39
	s_cselect_b32 s40, s25, s38
	s_cselect_b32 s39, s29, s59
	s_cselect_b32 s38, s31, s58
	v_lshl_add_u64 v[168:169], s[2:3], 0, v[156:157]
	s_add_i32 m0, s44, 0xc000
	ds_read_b128 v[196:199], v173
	ds_read_b128 v[200:203], v173 offset:1024
	ds_read_b128 v[204:207], v173 offset:2048
	ds_read_b128 v[208:211], v173 offset:3072
	ds_read_b128 v[212:215], v173 offset:4096
	ds_read_b128 v[216:219], v173 offset:5120
	ds_read_b128 v[220:223], v173 offset:6144
	ds_read_b128 v[224:227], v173 offset:7168
	global_load_lds_dwordx4 v[168:169], off
	v_lshl_add_u64 v[168:169], s[2:3], 0, v[158:159]
	s_add_i32 m0, s44, 0xe000
	s_nop 0
	global_load_lds_dwordx4 v[168:169], off
	s_waitcnt vmcnt(8)
	s_waitcnt lgkmcnt(0)
	s_barrier
	s_setprio 1
	v_mfma_f32_16x16x32_bf16 v[124:127], v[128:131], v[196:199], v[124:127]
	v_mfma_f32_16x16x32_bf16 v[120:123], v[136:139], v[196:199], v[120:123]
	v_mfma_f32_16x16x32_bf16 v[108:111], v[128:131], v[204:207], v[108:111]
	v_mfma_f32_16x16x32_bf16 v[104:107], v[136:139], v[204:207], v[104:107]
	v_mfma_f32_16x16x32_bf16 v[92:95], v[128:131], v[212:215], v[92:95]
	v_mfma_f32_16x16x32_bf16 v[88:91], v[136:139], v[212:215], v[88:91]
	v_mfma_f32_16x16x32_bf16 v[76:79], v[128:131], v[220:223], v[76:79]
	v_mfma_f32_16x16x32_bf16 v[72:75], v[136:139], v[220:223], v[72:75]
	v_mfma_f32_16x16x32_bf16 v[124:127], v[132:135], v[200:203], v[124:127]
	v_mfma_f32_16x16x32_bf16 v[120:123], v[140:143], v[200:203], v[120:123]
	v_mfma_f32_16x16x32_bf16 v[108:111], v[132:135], v[208:211], v[108:111]
	v_mfma_f32_16x16x32_bf16 v[104:107], v[140:143], v[208:211], v[104:107]
	v_mfma_f32_16x16x32_bf16 v[92:95], v[132:135], v[216:219], v[92:95]
	v_mfma_f32_16x16x32_bf16 v[88:91], v[140:143], v[216:219], v[88:91]
	v_mfma_f32_16x16x32_bf16 v[76:79], v[132:135], v[224:227], v[76:79]
	v_mfma_f32_16x16x32_bf16 v[72:75], v[140:143], v[224:227], v[72:75]
	v_mfma_f32_16x16x32_bf16 v[116:119], v[164:167], v[196:199], v[116:119]
	v_mfma_f32_16x16x32_bf16 v[112:115], v[182:185], v[196:199], v[112:115]
	v_mfma_f32_16x16x32_bf16 v[100:103], v[164:167], v[204:207], v[100:103]
	v_mfma_f32_16x16x32_bf16 v[96:99], v[182:185], v[204:207], v[96:99]
	v_mfma_f32_16x16x32_bf16 v[84:87], v[164:167], v[212:215], v[84:87]
	v_mfma_f32_16x16x32_bf16 v[80:83], v[182:185], v[212:215], v[80:83]
	v_mfma_f32_16x16x32_bf16 v[68:71], v[164:167], v[220:223], v[68:71]
	v_mfma_f32_16x16x32_bf16 v[64:67], v[182:185], v[220:223], v[64:67]
	v_mfma_f32_16x16x32_bf16 v[116:119], v[178:181], v[200:203], v[116:119]
	v_mfma_f32_16x16x32_bf16 v[112:115], v[192:195], v[200:203], v[112:115]
	v_mfma_f32_16x16x32_bf16 v[100:103], v[178:181], v[208:211], v[100:103]
	v_mfma_f32_16x16x32_bf16 v[96:99], v[192:195], v[208:211], v[96:99]
	v_mfma_f32_16x16x32_bf16 v[84:87], v[178:181], v[216:219], v[84:87]
	v_mfma_f32_16x16x32_bf16 v[80:83], v[192:195], v[216:219], v[80:83]
	v_mfma_f32_16x16x32_bf16 v[68:71], v[178:181], v[224:227], v[68:71]
	v_mfma_f32_16x16x32_bf16 v[64:67], v[192:195], v[224:227], v[64:67]
	s_setprio 0
	s_barrier
	s_add_i32 s61, s52, s33
	v_lshl_add_u64 v[168:169], s[38:39], 0, v[148:149]
	s_mov_b32 m0, s61
	ds_read_b128 v[196:199], v173 offset:16384
	ds_read_b128 v[200:203], v173 offset:17408
	ds_read_b128 v[204:207], v173 offset:18432
	ds_read_b128 v[208:211], v173 offset:19456
	ds_read_b128 v[212:215], v173 offset:20480
	ds_read_b128 v[216:219], v173 offset:21504
	ds_read_b128 v[220:223], v173 offset:22528
	ds_read_b128 v[224:227], v173 offset:23552
	global_load_lds_dwordx4 v[168:169], off
	s_add_i32 m0, s61, 0x2000
	s_add_u32 s62, s38, 0x40000
	v_lshl_add_u64 v[186:187], s[38:39], 0, v[144:145]
	s_addc_u32 s63, s39, 0
	s_add_i32 s61, s53, s33
	global_load_lds_dwordx4 v[186:187], off
	v_lshl_add_u64 v[228:229], s[62:63], 0, v[148:149]
	s_mov_b32 m0, s61
	v_lshl_add_u64 v[230:231], s[40:41], 0, v[146:147]
	global_load_lds_dwordx4 v[228:229], off
	v_lshl_add_u64 v[228:229], s[62:63], 0, v[144:145]
	s_add_i32 m0, s61, 0x2000
	s_nop 0
	global_load_lds_dwordx4 v[228:229], off
	v_lshl_add_u64 v[228:229], s[40:41], 0, v[150:151]
	s_mov_b32 m0, s44
	s_nop 0
	global_load_lds_dwordx4 v[228:229], off
	s_mov_b32 m0, s45
	s_nop 0
	global_load_lds_dwordx4 v[230:231], off
	s_waitcnt vmcnt(8)
	s_waitcnt lgkmcnt(0)
	s_barrier
; #define PG8_STAGE(bufoff, gbase, voff) do { _Pragma("unroll") for (int _i = 0; _i < 2; ++_i) \
;         __builtin_amdgcn_global_load_lds((const unsigned*)((const char*)(gbase) + (voff)[_i]), (PG8_LAS unsigned*)(lds + (bufoff) + ldsw + _i * 8192), 16, 0, 0); } while (0)
; #define PG8_LDA(dst, b, h) do { _Pragma("unroll") for (int m = 0; m < 4; ++m) _Pragma("unroll") for (int k = 0; k < 2; ++k) dst[m][k] = *(const PG8_LAS bf16x8*)(lds + PG8_SA(b, h) + aoff + m * 2048 + k * 1024); } while (0)
; #define PG8_LDB(dst, b, h) do { _Pragma("unroll") for (int n = 0; n < 2; ++n) _Pragma("unroll") for (int k = 0; k < 2; ++k) dst[n][k] = *(const PG8_LAS bf16x8*)(lds + PG8_SB(b, h) + boff + n * 2048 + k * 1024); } while (0)
; #define PG8_MMA(ai, bj, At, Bt) do { __builtin_amdgcn_s_setprio(1); _Pragma("unroll") for (int m = 0; m < 4; ++m) _Pragma("unroll") for (int n = 0; n < 2; ++n) _Pragma("unroll") for (int k = 0; k < 2; ++k) \
;         acc[ai][bj][m][n] = __builtin_amdgcn_mfma_f32_16x16x32_bf16(Bt[n][k], At[m][k], acc[ai][bj][m][n], 0, 0, 0); __builtin_amdgcn_s_setprio(0); } while (0)
; #define PG8_WAIT_V(n) asm volatile("s_waitcnt vmcnt(" #n ")" ::: "memory")
; #define PG8_WAIT_L(n) asm volatile("s_waitcnt lgkmcnt(" #n ")" ::: "memory")
; #define PG8_BAR __builtin_amdgcn_s_barrier()
; #define PG8_SCHED __builtin_amdgcn_sched_barrier(0)
; template <class Epi, class Sched, bool ALIGN_EPI = false, bool SP2 = false>
; __device__ __forceinline__ void gemm_phase(PG8_LAS unsigned char* lds, const Gemm g, const Sched& S, const Epi& E) {
;     ...
;             PG8_WAIT_V(8); PG8_WAIT_L(0); PG8_BAR; PG8_MMA(1, 0, At, B0); PG8_MMA(1, 1, At, B1); PG8_BAR; PG8_SCHED;
;             PG8_LDB(B0, 1, 0); PG8_LDB(B1, 1, 1); PG8_SCHED; PG8_LDA(At, 1, 0); PG8_STAGE(PG8_SA(0, 1), a2 + hstep, voffA);
;             PG8_WAIT_V(8); PG8_WAIT_L(0); PG8_BAR; PG8_MMA(0, 0, At, B0); PG8_MMA(0, 1, At, B1); PG8_BAR; PG8_SCHED;
	s_setprio 1
	v_mfma_f32_16x16x32_bf16 v[60:63], v[128:131], v[196:199], v[60:63]
	v_mfma_f32_16x16x32_bf16 v[56:59], v[136:139], v[196:199], v[56:59]
	v_mfma_f32_16x16x32_bf16 v[44:47], v[128:131], v[204:207], v[44:47]
	v_mfma_f32_16x16x32_bf16 v[40:43], v[136:139], v[204:207], v[40:43]
	v_mfma_f32_16x16x32_bf16 v[28:31], v[128:131], v[212:215], v[28:31]
	v_mfma_f32_16x16x32_bf16 v[24:27], v[136:139], v[212:215], v[24:27]
	v_mfma_f32_16x16x32_bf16 v[12:15], v[128:131], v[220:223], v[12:15]
	v_mfma_f32_16x16x32_bf16 v[8:11], v[136:139], v[220:223], v[8:11]
	v_mfma_f32_16x16x32_bf16 v[60:63], v[132:135], v[200:203], v[60:63]
	v_mfma_f32_16x16x32_bf16 v[56:59], v[140:143], v[200:203], v[56:59]
	v_mfma_f32_16x16x32_bf16 v[44:47], v[132:135], v[208:211], v[44:47]
	v_mfma_f32_16x16x32_bf16 v[40:43], v[140:143], v[208:211], v[40:43]
	v_mfma_f32_16x16x32_bf16 v[28:31], v[132:135], v[216:219], v[28:31]
	v_mfma_f32_16x16x32_bf16 v[24:27], v[140:143], v[216:219], v[24:27]
	v_mfma_f32_16x16x32_bf16 v[12:15], v[132:135], v[224:227], v[12:15]
	v_mfma_f32_16x16x32_bf16 v[8:11], v[140:143], v[224:227], v[8:11]
	v_mfma_f32_16x16x32_bf16 v[52:55], v[164:167], v[196:199], v[52:55]
	v_mfma_f32_16x16x32_bf16 v[48:51], v[182:185], v[196:199], v[48:51]
	v_mfma_f32_16x16x32_bf16 v[36:39], v[164:167], v[204:207], v[36:39]
	v_mfma_f32_16x16x32_bf16 v[32:35], v[182:185], v[204:207], v[32:35]
	v_mfma_f32_16x16x32_bf16 v[20:23], v[164:167], v[212:215], v[20:23]
	v_mfma_f32_16x16x32_bf16 v[16:19], v[182:185], v[212:215], v[16:19]
	v_mfma_f32_16x16x32_bf16 v[4:7], v[164:167], v[220:223], v[4:7]
	v_mfma_f32_16x16x32_bf16 v[0:3], v[182:185], v[220:223], v[0:3]
	v_mfma_f32_16x16x32_bf16 v[52:55], v[178:181], v[200:203], v[52:55]
	v_mfma_f32_16x16x32_bf16 v[48:51], v[192:195], v[200:203], v[48:51]
	v_mfma_f32_16x16x32_bf16 v[36:39], v[178:181], v[208:211], v[36:39]
	v_mfma_f32_16x16x32_bf16 v[32:35], v[192:195], v[208:211], v[32:35]
	v_mfma_f32_16x16x32_bf16 v[20:23], v[178:181], v[216:219], v[20:23]
	v_mfma_f32_16x16x32_bf16 v[16:19], v[192:195], v[216:219], v[16:19]
	v_mfma_f32_16x16x32_bf16 v[4:7], v[178:181], v[224:227], v[4:7]
	v_mfma_f32_16x16x32_bf16 v[0:3], v[192:195], v[224:227], v[0:3]
	s_setprio 0
	s_barrier
	s_add_i32 s61, 0, 0x18000
	s_add_i32 s62, 0, 0x1c000
	v_add_u32_e32 v140, s61, v170
	v_add_u32_e32 v152, s62, v170
	ds_read_b128 v[128:131], v140
	ds_read_b128 v[132:135], v140 offset:1024
	ds_read_b128 v[136:139], v140 offset:2048
	ds_read_b128 v[140:143], v140 offset:3072
	ds_read_b128 v[164:167], v152
	ds_read_b128 v[178:181], v152 offset:1024
	ds_read_b128 v[182:185], v152 offset:2048
	ds_read_b128 v[192:195], v152 offset:3072
	s_add_u32 s40, s40, 0x40000
	s_addc_u32 s41, s41, 0
	s_mov_b32 m0, s46
	v_lshl_add_u64 v[232:233], s[40:41], 0, v[150:151]
	ds_read_b128 v[196:199], v173 offset:32768
	ds_read_b128 v[200:203], v173 offset:33792
	ds_read_b128 v[204:207], v173 offset:34816
	ds_read_b128 v[208:211], v173 offset:35840
	ds_read_b128 v[212:215], v173 offset:36864
	ds_read_b128 v[216:219], v173 offset:37888
	ds_read_b128 v[220:223], v173 offset:38912
	ds_read_b128 v[224:227], v173 offset:39936
	global_load_lds_dwordx4 v[232:233], off
	v_lshl_add_u64 v[232:233], s[40:41], 0, v[146:147]
	s_mov_b32 m0, s47
	s_nop 0
	global_load_lds_dwordx4 v[232:233], off
	s_waitcnt vmcnt(8)
	s_waitcnt lgkmcnt(0)
	s_barrier
	s_setprio 1
	v_mfma_f32_16x16x32_bf16 v[124:127], v[128:131], v[196:199], v[124:127]
	v_mfma_f32_16x16x32_bf16 v[120:123], v[136:139], v[196:199], v[120:123]
	v_mfma_f32_16x16x32_bf16 v[108:111], v[128:131], v[204:207], v[108:111]
	v_mfma_f32_16x16x32_bf16 v[104:107], v[136:139], v[204:207], v[104:107]
	v_mfma_f32_16x16x32_bf16 v[92:95], v[128:131], v[212:215], v[92:95]
	v_mfma_f32_16x16x32_bf16 v[88:91], v[136:139], v[212:215], v[88:91]
	v_mfma_f32_16x16x32_bf16 v[76:79], v[128:131], v[220:223], v[76:79]
	v_mfma_f32_16x16x32_bf16 v[72:75], v[136:139], v[220:223], v[72:75]
	v_mfma_f32_16x16x32_bf16 v[124:127], v[132:135], v[200:203], v[124:127]
	v_mfma_f32_16x16x32_bf16 v[120:123], v[140:143], v[200:203], v[120:123]
	v_mfma_f32_16x16x32_bf16 v[108:111], v[132:135], v[208:211], v[108:111]
	v_mfma_f32_16x16x32_bf16 v[104:107], v[140:143], v[208:211], v[104:107]
	v_mfma_f32_16x16x32_bf16 v[92:95], v[132:135], v[216:219], v[92:95]
	v_mfma_f32_16x16x32_bf16 v[88:91], v[140:143], v[216:219], v[88:91]
	v_mfma_f32_16x16x32_bf16 v[76:79], v[132:135], v[224:227], v[76:79]
	v_mfma_f32_16x16x32_bf16 v[72:75], v[140:143], v[224:227], v[72:75]
	v_mfma_f32_16x16x32_bf16 v[116:119], v[164:167], v[196:199], v[116:119]
	v_mfma_f32_16x16x32_bf16 v[112:115], v[182:185], v[196:199], v[112:115]
	v_mfma_f32_16x16x32_bf16 v[100:103], v[164:167], v[204:207], v[100:103]
	v_mfma_f32_16x16x32_bf16 v[96:99], v[182:185], v[204:207], v[96:99]
	v_mfma_f32_16x16x32_bf16 v[84:87], v[164:167], v[212:215], v[84:87]
	v_mfma_f32_16x16x32_bf16 v[80:83], v[182:185], v[212:215], v[80:83]
	v_mfma_f32_16x16x32_bf16 v[68:71], v[164:167], v[220:223], v[68:71]
	v_mfma_f32_16x16x32_bf16 v[64:67], v[182:185], v[220:223], v[64:67]
	v_mfma_f32_16x16x32_bf16 v[116:119], v[178:181], v[200:203], v[116:119]
	v_mfma_f32_16x16x32_bf16 v[112:115], v[192:195], v[200:203], v[112:115]
	v_mfma_f32_16x16x32_bf16 v[100:103], v[178:181], v[208:211], v[100:103]
	v_mfma_f32_16x16x32_bf16 v[96:99], v[192:195], v[208:211], v[96:99]
	v_mfma_f32_16x16x32_bf16 v[84:87], v[178:181], v[216:219], v[84:87]
	v_mfma_f32_16x16x32_bf16 v[80:83], v[192:195], v[216:219], v[80:83]
	v_mfma_f32_16x16x32_bf16 v[68:71], v[178:181], v[224:227], v[68:71]
	v_mfma_f32_16x16x32_bf16 v[64:67], v[192:195], v[224:227], v[64:67]
	s_setprio 0
	s_barrier
; #define PG8_STAGE(bufoff, gbase, voff) do { _Pragma("unroll") for (int _i = 0; _i < 2; ++_i) \
;         __builtin_amdgcn_global_load_lds((const unsigned*)((const char*)(gbase) + (voff)[_i]), (PG8_LAS unsigned*)(lds + (bufoff) + ldsw + _i * 8192), 16, 0, 0); } while (0)
; #define PG8_LDA(dst, b, h) do { _Pragma("unroll") for (int m = 0; m < 4; ++m) _Pragma("unroll") for (int k = 0; k < 2; ++k) dst[m][k] = *(const PG8_LAS bf16x8*)(lds + PG8_SA(b, h) + aoff + m * 2048 + k * 1024); } while (0)
; #define PG8_MMA(ai, bj, At, Bt) do { __builtin_amdgcn_s_setprio(1); _Pragma("unroll") for (int m = 0; m < 4; ++m) _Pragma("unroll") for (int n = 0; n < 2; ++n) _Pragma("unroll") for (int k = 0; k < 2; ++k) \
;         acc[ai][bj][m][n] = __builtin_amdgcn_mfma_f32_16x16x32_bf16(Bt[n][k], At[m][k], acc[ai][bj][m][n], 0, 0, 0); __builtin_amdgcn_s_setprio(0); } while (0)
; #define PG8_WAIT_V(n) asm volatile("s_waitcnt vmcnt(" #n ")" ::: "memory")
; #define PG8_WAIT_L(n) asm volatile("s_waitcnt lgkmcnt(" #n ")" ::: "memory")
; #define PG8_BAR __builtin_amdgcn_s_barrier()
; #define PG8_SCHED __builtin_amdgcn_sched_barrier(0)
; template <class Epi, class Sched, bool ALIGN_EPI = false, bool SP2 = false>
; __device__ __forceinline__ void gemm_phase(PG8_LAS unsigned char* lds, const Gemm g, const Sched& S, const Epi& E) {
;     ...
;             PG8_LDA(At, 1, 1); PG8_STAGE(PG8_SB(1, 0), b3, voffB); PG8_STAGE(PG8_SB(1, 1), b3 + hstep, voffB); PG8_STAGE(PG8_SA(1, 0), a3, voffA);
;             PG8_WAIT_V(8); PG8_WAIT_L(0); PG8_BAR; PG8_MMA(1, 0, At, B0); PG8_MMA(1, 1, At, B1); PG8_BAR; PG8_SCHED;
;     ...
;         if constexpr (ALIGN_EPI) { if (wr == 0) PG8_BAR; }
;         if constexpr (!Epi::AFTER_DRAIN) { E(acc, cur, wr, wc, fr, fq); S.done(cur); }
	s_add_i32 s40, s61, s33
	v_lshl_add_u64 v[168:169], v[168:169], 0, s[16:17]
	s_mov_b32 m0, s40
	ds_read_b128 v[196:199], v173 offset:49152
	ds_read_b128 v[200:203], v173 offset:50176
	ds_read_b128 v[204:207], v173 offset:51200
	ds_read_b128 v[208:211], v173 offset:52224
	ds_read_b128 v[212:215], v173 offset:53248
	ds_read_b128 v[216:219], v173 offset:54272
	ds_read_b128 v[220:223], v173 offset:55296
	ds_read_b128 v[224:227], v173 offset:56320
	global_load_lds_dwordx4 v[168:169], off
	s_add_i32 m0, s40, 0x2000
	s_add_u32 s38, s38, 0x40080
	v_lshl_add_u64 v[168:169], v[186:187], 0, s[16:17]
	s_addc_u32 s39, s39, 0
	s_add_i32 s40, s62, s33
	global_load_lds_dwordx4 v[168:169], off
	v_lshl_add_u64 v[168:169], s[38:39], 0, v[148:149]
	s_mov_b32 m0, s40
	s_nop 0
	global_load_lds_dwordx4 v[168:169], off
	v_lshl_add_u64 v[168:169], s[38:39], 0, v[144:145]
	s_add_i32 m0, s40, 0x2000
	s_nop 0
	global_load_lds_dwordx4 v[168:169], off
	v_lshl_add_u64 v[168:169], v[228:229], 0, s[16:17]
	s_mov_b32 m0, s48
	s_nop 0
	global_load_lds_dwordx4 v[168:169], off
	v_lshl_add_u64 v[168:169], v[230:231], 0, s[16:17]
	s_mov_b32 m0, s49
	s_nop 0
	global_load_lds_dwordx4 v[168:169], off
	s_waitcnt vmcnt(8)
	s_waitcnt lgkmcnt(0)
	s_barrier
	s_setprio 1
	v_mfma_f32_16x16x32_bf16 v[60:63], v[128:131], v[196:199], v[60:63]
	v_mfma_f32_16x16x32_bf16 v[56:59], v[136:139], v[196:199], v[56:59]
	v_mfma_f32_16x16x32_bf16 v[44:47], v[128:131], v[204:207], v[44:47]
	v_mfma_f32_16x16x32_bf16 v[40:43], v[136:139], v[204:207], v[40:43]
	v_mfma_f32_16x16x32_bf16 v[28:31], v[128:131], v[212:215], v[28:31]
	v_mfma_f32_16x16x32_bf16 v[24:27], v[136:139], v[212:215], v[24:27]
	v_mfma_f32_16x16x32_bf16 v[12:15], v[128:131], v[220:223], v[12:15]
	v_mfma_f32_16x16x32_bf16 v[8:11], v[136:139], v[220:223], v[8:11]
	v_mfma_f32_16x16x32_bf16 v[60:63], v[132:135], v[200:203], v[60:63]
	v_mfma_f32_16x16x32_bf16 v[56:59], v[140:143], v[200:203], v[56:59]
	v_mfma_f32_16x16x32_bf16 v[44:47], v[132:135], v[208:211], v[44:47]
	v_mfma_f32_16x16x32_bf16 v[40:43], v[140:143], v[208:211], v[40:43]
	v_mfma_f32_16x16x32_bf16 v[28:31], v[132:135], v[216:219], v[28:31]
	v_mfma_f32_16x16x32_bf16 v[24:27], v[140:143], v[216:219], v[24:27]
	v_mfma_f32_16x16x32_bf16 v[12:15], v[132:135], v[224:227], v[12:15]
	v_mfma_f32_16x16x32_bf16 v[8:11], v[140:143], v[224:227], v[8:11]
	v_mfma_f32_16x16x32_bf16 v[52:55], v[164:167], v[196:199], v[52:55]
	v_mfma_f32_16x16x32_bf16 v[48:51], v[182:185], v[196:199], v[48:51]
	v_mfma_f32_16x16x32_bf16 v[36:39], v[164:167], v[204:207], v[36:39]
	v_mfma_f32_16x16x32_bf16 v[32:35], v[182:185], v[204:207], v[32:35]
	v_mfma_f32_16x16x32_bf16 v[20:23], v[164:167], v[212:215], v[20:23]
	v_mfma_f32_16x16x32_bf16 v[16:19], v[182:185], v[212:215], v[16:19]
	v_mfma_f32_16x16x32_bf16 v[4:7], v[164:167], v[220:223], v[4:7]
	v_mfma_f32_16x16x32_bf16 v[0:3], v[182:185], v[220:223], v[0:3]
	v_mfma_f32_16x16x32_bf16 v[52:55], v[178:181], v[200:203], v[52:55]
	v_mfma_f32_16x16x32_bf16 v[48:51], v[192:195], v[200:203], v[48:51]
	v_mfma_f32_16x16x32_bf16 v[36:39], v[178:181], v[208:211], v[36:39]
	v_mfma_f32_16x16x32_bf16 v[32:35], v[192:195], v[208:211], v[32:35]
	v_mfma_f32_16x16x32_bf16 v[20:23], v[178:181], v[216:219], v[20:23]
	v_mfma_f32_16x16x32_bf16 v[16:19], v[192:195], v[216:219], v[16:19]
	v_mfma_f32_16x16x32_bf16 v[4:7], v[178:181], v[224:227], v[4:7]
	v_mfma_f32_16x16x32_bf16 v[0:3], v[192:195], v[224:227], v[0:3]
	s_setprio 0
	s_nop 0
	s_add_i32 s60, s60, 2
	s_add_u32 s2, s2, 0x100
	s_addc_u32 s3, s3, 0
	s_add_u32 s58, s58, 0x100
	s_addc_u32 s59, s59, 0
	s_cmp_gt_u32 s60, 13
	s_cbranch_scc0 .Lrot_374
	s_barrier
	s_and_b64 vcc, exec, s[18:19]
	s_cbranch_vccnz .LBB0_379
	v_lshl_add_u32 v164, s0, 8, v155
	s_cmp_gt_i32 s57, 3
	s_mov_b64 s[0:1], -1
	s_cbranch_scc1 .LBB0_380

; #define PG8_STAGE(bufoff, gbase, voff) do { _Pragma("unroll") for (int _i = 0; _i < 2; ++_i) \
;         __builtin_amdgcn_global_load_lds((const unsigned*)((const char*)(gbase) + (voff)[_i]), (PG8_LAS unsigned*)(lds + (bufoff) + ldsw + _i * 8192), 16, 0, 0); } while (0)
; #define PG8_LDA(dst, b, h) do { _Pragma("unroll") for (int m = 0; m < 4; ++m) _Pragma("unroll") for (int k = 0; k < 2; ++k) dst[m][k] = *(const PG8_LAS bf16x8*)(lds + PG8_SA(b, h) + aoff + m * 2048 + k * 1024); } while (0)
; #define PG8_LDB(dst, b, h) do { _Pragma("unroll") for (int n = 0; n < 2; ++n) _Pragma("unroll") for (int k = 0; k < 2; ++k) dst[n][k] = *(const PG8_LAS bf16x8*)(lds + PG8_SB(b, h) + boff + n * 2048 + k * 1024); } while (0)
; #define PG8_MMA(ai, bj, At, Bt) do { __builtin_amdgcn_s_setprio(1); _Pragma("unroll") for (int m = 0; m < 4; ++m) _Pragma("unroll") for (int n = 0; n < 2; ++n) _Pragma("unroll") for (int k = 0; k < 2; ++k) \
;         acc[ai][bj][m][n] = __builtin_amdgcn_mfma_f32_16x16x32_bf16(Bt[n][k], At[m][k], acc[ai][bj][m][n], 0, 0, 0); __builtin_amdgcn_s_setprio(0); } while (0)
; #define PG8_BAR __builtin_amdgcn_s_barrier()
; template <class Epi, class Sched, bool ALIGN_EPI = false, bool SP2 = false>
; __device__ __forceinline__ void gemm_phase(PG8_LAS unsigned char* lds, const Gemm g, const Sched& S, const Epi& E) {
;     ...
;         const bool has_next = S.next(ui + 1, nxt);
;         const char* nA = has_next ? (const char*)g.A + (size_t)nxt.pm * tstep : cA; const char* nB = has_next ? (const char*)g.Bt + (size_t)nxt.pn * tstep : cB;
;         for (int t = 0; t < nt; t += 2) {
;             const bool last = (t == nt - 2);
;             const char* a1 = cA + (size_t)(t + 1) * kstep;
;             const char* a2 = last ? nA : cA + (size_t)(t + 2) * kstep; const char* b2 = last ? nB : cB + (size_t)(t + 2) * kstep;
;             const char* a3 = a2 + kstep; const char* b3 = b2 + kstep;
;             if (last && has_next) S.a_ready(nxt);
;             if constexpr (SP2) {
;             PG8_LDB(B0, 0, 0); PG8_LDB(B1, 0, 1); PG8_SCHED; PG8_LDA(At, 0, 0); PG8_STAGE(PG8_SA(1, 1), a1 + hstep, voffA);
;             PG8_WAIT_V(8); PG8_WAIT_L(0); PG8_BAR; PG8_MMA(0, 0, At, B0); PG8_MMA(0, 1, At, B1); PG8_BAR; PG8_SCHED;
;             PG8_LDA(At, 0, 1); PG8_STAGE(PG8_SB(0, 0), b2, voffB); PG8_STAGE(PG8_SB(0, 1), b2 + hstep, voffB); PG8_STAGE(PG8_SA(0, 0), a2, voffA);
.LBB0_697:
	s_ashr_i32 s17, s16, 31
	s_lshl_b64 s[18:19], s[16:17], 19
	v_readlane_b32 s48, v235, 2
	v_readlane_b32 s49, v235, 3
	s_add_u32 s18, s48, s18
	s_addc_u32 s19, s49, s19
	s_and_b64 s[20:21], s[6:7], exec
	s_cselect_b32 s17, s19, s27
	s_cselect_b32 s23, s18, s26
	s_ashr_i32 s15, s14, 31
	s_lshl_b64 s[20:21], s[14:15], 19
	s_add_u32 s20, s33, s20
	s_addc_u32 s21, s34, s21
	s_and_b64 s[30:31], s[6:7], exec
	s_cselect_b32 s15, s21, s29
	s_cselect_b32 s47, s20, s28
	s_add_u32 s26, s26, 0x40080
	s_addc_u32 s27, s27, 0
	v_readlane_b32 s50, v235, 4
	s_add_u32 s48, s28, 0x100
	s_addc_u32 s49, s29, 0
	s_mov_b32 s50, -2
	s_waitcnt lgkmcnt(0)
	v_readlane_b32 s51, v235, 5
	ds_read_b128 v[144:147], v151
	ds_read_b128 v[156:159], v151 offset:1024
	ds_read_b128 v[160:163], v151 offset:2048
	ds_read_b128 v[164:167], v151 offset:3072
	ds_read_b128 v[168:171], v152
	ds_read_b128 v[172:175], v152 offset:1024
	ds_read_b128 v[176:179], v152 offset:2048
	ds_read_b128 v[180:183], v152 offset:3072
	s_add_u32 s28, s26, 0xfffc0080
	s_addc_u32 s29, s27, -1
	s_cmp_eq_u32 s50, 12
	s_cselect_b32 s31, s17, s29
	s_cselect_b32 s30, s23, s28
	s_cselect_b32 s29, s15, s49
	s_cselect_b32 s28, s47, s48
	v_lshl_add_u64 v[218:219], s[26:27], 0, v[136:137]
	s_add_i32 m0, s25, 0xc000
	ds_read_b128 v[184:187], v153
	ds_read_b128 v[190:193], v153 offset:1024
	ds_read_b128 v[194:197], v153 offset:2048
	ds_read_b128 v[198:201], v153 offset:3072
	ds_read_b128 v[202:205], v153 offset:4096
	ds_read_b128 v[206:209], v153 offset:5120
	ds_read_b128 v[210:213], v153 offset:6144
	ds_read_b128 v[214:217], v153 offset:7168
	global_load_lds_dwordx4 v[218:219], off
	v_lshl_add_u64 v[218:219], s[26:27], 0, v[138:139]
	s_add_i32 m0, s25, 0xe000
	s_nop 0
	global_load_lds_dwordx4 v[218:219], off
	s_waitcnt vmcnt(8)
	s_waitcnt lgkmcnt(0)
	s_barrier
	s_setprio 1
	v_mfma_f32_16x16x32_bf16 v[124:127], v[144:147], v[184:187], 0
	v_mfma_f32_16x16x32_bf16 v[120:123], v[160:163], v[184:187], 0
	v_mfma_f32_16x16x32_bf16 v[108:111], v[144:147], v[194:197], 0
	v_mfma_f32_16x16x32_bf16 v[104:107], v[160:163], v[194:197], 0
	v_mfma_f32_16x16x32_bf16 v[92:95], v[144:147], v[202:205], 0
	v_mfma_f32_16x16x32_bf16 v[88:91], v[160:163], v[202:205], 0
	v_mfma_f32_16x16x32_bf16 v[76:79], v[144:147], v[210:213], 0
	v_mfma_f32_16x16x32_bf16 v[72:75], v[160:163], v[210:213], 0
	v_mfma_f32_16x16x32_bf16 v[124:127], v[156:159], v[190:193], v[124:127]
	v_mfma_f32_16x16x32_bf16 v[120:123], v[164:167], v[190:193], v[120:123]
	v_mfma_f32_16x16x32_bf16 v[108:111], v[156:159], v[198:201], v[108:111]
	v_mfma_f32_16x16x32_bf16 v[104:107], v[164:167], v[198:201], v[104:107]
	v_mfma_f32_16x16x32_bf16 v[92:95], v[156:159], v[206:209], v[92:95]
	v_mfma_f32_16x16x32_bf16 v[88:91], v[164:167], v[206:209], v[88:91]
	v_mfma_f32_16x16x32_bf16 v[76:79], v[156:159], v[214:217], v[76:79]
	v_mfma_f32_16x16x32_bf16 v[72:75], v[164:167], v[214:217], v[72:75]
	v_mfma_f32_16x16x32_bf16 v[116:119], v[168:171], v[184:187], 0
	v_mfma_f32_16x16x32_bf16 v[112:115], v[176:179], v[184:187], 0
	v_mfma_f32_16x16x32_bf16 v[100:103], v[168:171], v[194:197], 0
	v_mfma_f32_16x16x32_bf16 v[96:99], v[176:179], v[194:197], 0
	v_mfma_f32_16x16x32_bf16 v[84:87], v[168:171], v[202:205], 0
	v_mfma_f32_16x16x32_bf16 v[80:83], v[176:179], v[202:205], 0
	v_mfma_f32_16x16x32_bf16 v[68:71], v[168:171], v[210:213], 0
	v_mfma_f32_16x16x32_bf16 v[64:67], v[176:179], v[210:213], 0
	v_mfma_f32_16x16x32_bf16 v[116:119], v[172:175], v[190:193], v[116:119]
	v_mfma_f32_16x16x32_bf16 v[112:115], v[180:183], v[190:193], v[112:115]
	v_mfma_f32_16x16x32_bf16 v[100:103], v[172:175], v[198:201], v[100:103]
	v_mfma_f32_16x16x32_bf16 v[96:99], v[180:183], v[198:201], v[96:99]
	v_mfma_f32_16x16x32_bf16 v[84:87], v[172:175], v[206:209], v[84:87]
	v_mfma_f32_16x16x32_bf16 v[80:83], v[180:183], v[206:209], v[80:83]
	v_mfma_f32_16x16x32_bf16 v[68:71], v[172:175], v[214:217], v[68:71]
	v_mfma_f32_16x16x32_bf16 v[64:67], v[180:183], v[214:217], v[64:67]
	s_setprio 0
	s_barrier
	s_add_i32 s51, s45, s35
	v_lshl_add_u64 v[218:219], s[28:29], 0, v[130:131]
	s_mov_b32 m0, s51
	ds_read_b128 v[184:187], v153 offset:16384
	ds_read_b128 v[190:193], v153 offset:17408
	ds_read_b128 v[194:197], v153 offset:18432
	ds_read_b128 v[198:201], v153 offset:19456
	ds_read_b128 v[202:205], v153 offset:20480
	ds_read_b128 v[206:209], v153 offset:21504
	ds_read_b128 v[210:213], v153 offset:22528
	ds_read_b128 v[214:217], v153 offset:23552
	global_load_lds_dwordx4 v[218:219], off
	s_add_i32 m0, s51, 0x2000
	s_add_u32 s52, s28, 0x40000
	v_lshl_add_u64 v[220:221], s[28:29], 0, v[134:135]
	s_addc_u32 s53, s29, 0
	s_add_i32 s51, s46, s35
	global_load_lds_dwordx4 v[220:221], off
	v_lshl_add_u64 v[222:223], s[52:53], 0, v[130:131]
	s_mov_b32 m0, s51
	v_lshl_add_u64 v[224:225], s[30:31], 0, v[132:133]
	global_load_lds_dwordx4 v[222:223], off
	v_lshl_add_u64 v[222:223], s[52:53], 0, v[134:135]
	s_add_i32 m0, s51, 0x2000
	s_nop 0
	global_load_lds_dwordx4 v[222:223], off
	v_lshl_add_u64 v[222:223], s[30:31], 0, v[128:129]
	s_mov_b32 m0, s25
	s_nop 0
	global_load_lds_dwordx4 v[222:223], off
	s_mov_b32 m0, s36
	s_nop 0
	global_load_lds_dwordx4 v[224:225], off
	s_waitcnt vmcnt(8)
	s_waitcnt lgkmcnt(0)
	s_barrier
; #define PG8_STAGE(bufoff, gbase, voff) do { _Pragma("unroll") for (int _i = 0; _i < 2; ++_i) \
;         __builtin_amdgcn_global_load_lds((const unsigned*)((const char*)(gbase) + (voff)[_i]), (PG8_LAS unsigned*)(lds + (bufoff) + ldsw + _i * 8192), 16, 0, 0); } while (0)
; #define PG8_LDA(dst, b, h) do { _Pragma("unroll") for (int m = 0; m < 4; ++m) _Pragma("unroll") for (int k = 0; k < 2; ++k) dst[m][k] = *(const PG8_LAS bf16x8*)(lds + PG8_SA(b, h) + aoff + m * 2048 + k * 1024); } while (0)
; #define PG8_LDB(dst, b, h) do { _Pragma("unroll") for (int n = 0; n < 2; ++n) _Pragma("unroll") for (int k = 0; k < 2; ++k) dst[n][k] = *(const PG8_LAS bf16x8*)(lds + PG8_SB(b, h) + boff + n * 2048 + k * 1024); } while (0)
; #define PG8_MMA(ai, bj, At, Bt) do { __builtin_amdgcn_s_setprio(1); _Pragma("unroll") for (int m = 0; m < 4; ++m) _Pragma("unroll") for (int n = 0; n < 2; ++n) _Pragma("unroll") for (int k = 0; k < 2; ++k) \
;         acc[ai][bj][m][n] = __builtin_amdgcn_mfma_f32_16x16x32_bf16(Bt[n][k], At[m][k], acc[ai][bj][m][n], 0, 0, 0); __builtin_amdgcn_s_setprio(0); } while (0)
; #define PG8_WAIT_V(n) asm volatile("s_waitcnt vmcnt(" #n ")" ::: "memory")
; #define PG8_WAIT_L(n) asm volatile("s_waitcnt lgkmcnt(" #n ")" ::: "memory")
; #define PG8_BAR __builtin_amdgcn_s_barrier()
; #define PG8_SCHED __builtin_amdgcn_sched_barrier(0)
; template <class Epi, class Sched, bool ALIGN_EPI = false, bool SP2 = false>
; __device__ __forceinline__ void gemm_phase(PG8_LAS unsigned char* lds, const Gemm g, const Sched& S, const Epi& E) {
;     ...
;             PG8_WAIT_V(8); PG8_WAIT_L(0); PG8_BAR; PG8_MMA(1, 0, At, B0); PG8_MMA(1, 1, At, B1); PG8_BAR; PG8_SCHED;
;             PG8_LDB(B0, 1, 0); PG8_LDB(B1, 1, 1); PG8_SCHED; PG8_LDA(At, 1, 0); PG8_STAGE(PG8_SA(0, 1), a2 + hstep, voffA);
;             PG8_WAIT_V(8); PG8_WAIT_L(0); PG8_BAR; PG8_MMA(0, 0, At, B0); PG8_MMA(0, 1, At, B1); PG8_BAR; PG8_SCHED;
	s_setprio 1
	v_mfma_f32_16x16x32_bf16 v[60:63], v[144:147], v[184:187], 0
	v_mfma_f32_16x16x32_bf16 v[56:59], v[160:163], v[184:187], 0
	v_mfma_f32_16x16x32_bf16 v[44:47], v[144:147], v[194:197], 0
	v_mfma_f32_16x16x32_bf16 v[40:43], v[160:163], v[194:197], 0
	v_mfma_f32_16x16x32_bf16 v[28:31], v[144:147], v[202:205], 0
	v_mfma_f32_16x16x32_bf16 v[24:27], v[160:163], v[202:205], 0
	v_mfma_f32_16x16x32_bf16 v[12:15], v[144:147], v[210:213], 0
	v_mfma_f32_16x16x32_bf16 v[8:11], v[160:163], v[210:213], 0
	v_mfma_f32_16x16x32_bf16 v[60:63], v[156:159], v[190:193], v[60:63]
	v_mfma_f32_16x16x32_bf16 v[56:59], v[164:167], v[190:193], v[56:59]
	v_mfma_f32_16x16x32_bf16 v[44:47], v[156:159], v[198:201], v[44:47]
	v_mfma_f32_16x16x32_bf16 v[40:43], v[164:167], v[198:201], v[40:43]
	v_mfma_f32_16x16x32_bf16 v[28:31], v[156:159], v[206:209], v[28:31]
	v_mfma_f32_16x16x32_bf16 v[24:27], v[164:167], v[206:209], v[24:27]
	v_mfma_f32_16x16x32_bf16 v[12:15], v[156:159], v[214:217], v[12:15]
	v_mfma_f32_16x16x32_bf16 v[8:11], v[164:167], v[214:217], v[8:11]
	v_mfma_f32_16x16x32_bf16 v[52:55], v[168:171], v[184:187], 0
	v_mfma_f32_16x16x32_bf16 v[48:51], v[176:179], v[184:187], 0
	v_mfma_f32_16x16x32_bf16 v[36:39], v[168:171], v[194:197], 0
	v_mfma_f32_16x16x32_bf16 v[32:35], v[176:179], v[194:197], 0
	v_mfma_f32_16x16x32_bf16 v[20:23], v[168:171], v[202:205], 0
	v_mfma_f32_16x16x32_bf16 v[16:19], v[176:179], v[202:205], 0
	v_mfma_f32_16x16x32_bf16 v[4:7], v[168:171], v[210:213], 0
	v_mfma_f32_16x16x32_bf16 v[0:3], v[176:179], v[210:213], 0
	v_mfma_f32_16x16x32_bf16 v[52:55], v[172:175], v[190:193], v[52:55]
	v_mfma_f32_16x16x32_bf16 v[48:51], v[180:183], v[190:193], v[48:51]
	v_mfma_f32_16x16x32_bf16 v[36:39], v[172:175], v[198:201], v[36:39]
	v_mfma_f32_16x16x32_bf16 v[32:35], v[180:183], v[198:201], v[32:35]
	v_mfma_f32_16x16x32_bf16 v[20:23], v[172:175], v[206:209], v[20:23]
	v_mfma_f32_16x16x32_bf16 v[16:19], v[180:183], v[206:209], v[16:19]
	v_mfma_f32_16x16x32_bf16 v[4:7], v[172:175], v[214:217], v[4:7]
	v_mfma_f32_16x16x32_bf16 v[0:3], v[180:183], v[214:217], v[0:3]
	s_setprio 0
	s_barrier
	s_add_i32 s51, 0, 0x18000
	v_add_u32_e32 v155, s51, v149
	s_add_i32 s52, 0, 0x1c000
	ds_read_b128 v[144:147], v155
	ds_read_b128 v[156:159], v155 offset:1024
	ds_read_b128 v[160:163], v155 offset:2048
	ds_read_b128 v[164:167], v155 offset:3072
	v_add_u32_e32 v155, s52, v149
	ds_read_b128 v[168:171], v155
	ds_read_b128 v[172:175], v155 offset:1024
	ds_read_b128 v[176:179], v155 offset:2048
	ds_read_b128 v[180:183], v155 offset:3072
	s_add_u32 s30, s30, 0x40000
	s_addc_u32 s31, s31, 0
	s_mov_b32 m0, s37
	v_lshl_add_u64 v[226:227], s[30:31], 0, v[128:129]
	ds_read_b128 v[184:187], v153 offset:32768
	ds_read_b128 v[190:193], v153 offset:33792
	ds_read_b128 v[194:197], v153 offset:34816
	ds_read_b128 v[198:201], v153 offset:35840
	ds_read_b128 v[202:205], v153 offset:36864
	ds_read_b128 v[206:209], v153 offset:37888
	ds_read_b128 v[210:213], v153 offset:38912
	ds_read_b128 v[214:217], v153 offset:39936
	global_load_lds_dwordx4 v[226:227], off
	v_lshl_add_u64 v[226:227], s[30:31], 0, v[132:133]
	s_mov_b32 m0, s38
	s_nop 0
	global_load_lds_dwordx4 v[226:227], off
	s_waitcnt vmcnt(8)
	s_waitcnt lgkmcnt(0)
	s_barrier
	s_setprio 1
	v_mfma_f32_16x16x32_bf16 v[124:127], v[144:147], v[184:187], v[124:127]
	v_mfma_f32_16x16x32_bf16 v[120:123], v[160:163], v[184:187], v[120:123]
	v_mfma_f32_16x16x32_bf16 v[108:111], v[144:147], v[194:197], v[108:111]
	v_mfma_f32_16x16x32_bf16 v[104:107], v[160:163], v[194:197], v[104:107]
	v_mfma_f32_16x16x32_bf16 v[92:95], v[144:147], v[202:205], v[92:95]
	v_mfma_f32_16x16x32_bf16 v[88:91], v[160:163], v[202:205], v[88:91]
	v_mfma_f32_16x16x32_bf16 v[76:79], v[144:147], v[210:213], v[76:79]
	v_mfma_f32_16x16x32_bf16 v[72:75], v[160:163], v[210:213], v[72:75]
	v_mfma_f32_16x16x32_bf16 v[124:127], v[156:159], v[190:193], v[124:127]
	v_mfma_f32_16x16x32_bf16 v[120:123], v[164:167], v[190:193], v[120:123]
	v_mfma_f32_16x16x32_bf16 v[108:111], v[156:159], v[198:201], v[108:111]
	v_mfma_f32_16x16x32_bf16 v[104:107], v[164:167], v[198:201], v[104:107]
	v_mfma_f32_16x16x32_bf16 v[92:95], v[156:159], v[206:209], v[92:95]
	v_mfma_f32_16x16x32_bf16 v[88:91], v[164:167], v[206:209], v[88:91]
	v_mfma_f32_16x16x32_bf16 v[76:79], v[156:159], v[214:217], v[76:79]
	v_mfma_f32_16x16x32_bf16 v[72:75], v[164:167], v[214:217], v[72:75]
	v_mfma_f32_16x16x32_bf16 v[116:119], v[168:171], v[184:187], v[116:119]
	v_mfma_f32_16x16x32_bf16 v[112:115], v[176:179], v[184:187], v[112:115]
	v_mfma_f32_16x16x32_bf16 v[100:103], v[168:171], v[194:197], v[100:103]
	v_mfma_f32_16x16x32_bf16 v[96:99], v[176:179], v[194:197], v[96:99]
	v_mfma_f32_16x16x32_bf16 v[84:87], v[168:171], v[202:205], v[84:87]
	v_mfma_f32_16x16x32_bf16 v[80:83], v[176:179], v[202:205], v[80:83]
	v_mfma_f32_16x16x32_bf16 v[68:71], v[168:171], v[210:213], v[68:71]
	v_mfma_f32_16x16x32_bf16 v[64:67], v[176:179], v[210:213], v[64:67]
	v_mfma_f32_16x16x32_bf16 v[116:119], v[172:175], v[190:193], v[116:119]
	v_mfma_f32_16x16x32_bf16 v[112:115], v[180:183], v[190:193], v[112:115]
	v_mfma_f32_16x16x32_bf16 v[100:103], v[172:175], v[198:201], v[100:103]
	v_mfma_f32_16x16x32_bf16 v[96:99], v[180:183], v[198:201], v[96:99]
	v_mfma_f32_16x16x32_bf16 v[84:87], v[172:175], v[206:209], v[84:87]
	v_mfma_f32_16x16x32_bf16 v[80:83], v[180:183], v[206:209], v[80:83]
	v_mfma_f32_16x16x32_bf16 v[68:71], v[172:175], v[214:217], v[68:71]
	v_mfma_f32_16x16x32_bf16 v[64:67], v[180:183], v[214:217], v[64:67]
	s_setprio 0
	s_barrier
; #define PG8_STAGE(bufoff, gbase, voff) do { _Pragma("unroll") for (int _i = 0; _i < 2; ++_i) \
;         __builtin_amdgcn_global_load_lds((const unsigned*)((const char*)(gbase) + (voff)[_i]), (PG8_LAS unsigned*)(lds + (bufoff) + ldsw + _i * 8192), 16, 0, 0); } while (0)
; #define PG8_LDA(dst, b, h) do { _Pragma("unroll") for (int m = 0; m < 4; ++m) _Pragma("unroll") for (int k = 0; k < 2; ++k) dst[m][k] = *(const PG8_LAS bf16x8*)(lds + PG8_SA(b, h) + aoff + m * 2048 + k * 1024); } while (0)
; #define PG8_MMA(ai, bj, At, Bt) do { __builtin_amdgcn_s_setprio(1); _Pragma("unroll") for (int m = 0; m < 4; ++m) _Pragma("unroll") for (int n = 0; n < 2; ++n) _Pragma("unroll") for (int k = 0; k < 2; ++k) \
;         acc[ai][bj][m][n] = __builtin_amdgcn_mfma_f32_16x16x32_bf16(Bt[n][k], At[m][k], acc[ai][bj][m][n], 0, 0, 0); __builtin_amdgcn_s_setprio(0); } while (0)
; #define PG8_WAIT_V(n) asm volatile("s_waitcnt vmcnt(" #n ")" ::: "memory")
; #define PG8_WAIT_L(n) asm volatile("s_waitcnt lgkmcnt(" #n ")" ::: "memory")
; #define PG8_BAR __builtin_amdgcn_s_barrier()
; #define PG8_SCHED __builtin_amdgcn_sched_barrier(0)
; template <class Epi, class Sched, bool ALIGN_EPI = false, bool SP2 = false>
; __device__ __forceinline__ void gemm_phase(PG8_LAS unsigned char* lds, const Gemm g, const Sched& S, const Epi& E) {
;     ...
;             PG8_LDA(At, 1, 1); PG8_STAGE(PG8_SB(1, 0), b3, voffB); PG8_STAGE(PG8_SB(1, 1), b3 + hstep, voffB); PG8_STAGE(PG8_SA(1, 0), a3, voffA);
;             PG8_WAIT_V(8); PG8_WAIT_L(0); PG8_BAR; PG8_MMA(1, 0, At, B0); PG8_MMA(1, 1, At, B1); PG8_BAR; PG8_SCHED;
	s_add_i32 s30, s51, s35
	v_lshl_add_u64 v[218:219], v[218:219], 0, s[2:3]
	s_mov_b32 m0, s30
	ds_read_b128 v[184:187], v153 offset:49152
	ds_read_b128 v[190:193], v153 offset:50176
	ds_read_b128 v[194:197], v153 offset:51200
	ds_read_b128 v[198:201], v153 offset:52224
	ds_read_b128 v[202:205], v153 offset:53248
	ds_read_b128 v[206:209], v153 offset:54272
	ds_read_b128 v[210:213], v153 offset:55296
	ds_read_b128 v[214:217], v153 offset:56320
	global_load_lds_dwordx4 v[218:219], off
	s_add_i32 m0, s30, 0x2000
	s_add_u32 s28, s28, 0x40080
	v_lshl_add_u64 v[218:219], v[220:221], 0, s[2:3]
	s_addc_u32 s29, s29, 0
	s_add_i32 s30, s52, s35
	global_load_lds_dwordx4 v[218:219], off
	v_lshl_add_u64 v[218:219], s[28:29], 0, v[130:131]
	s_mov_b32 m0, s30
	s_nop 0
	global_load_lds_dwordx4 v[218:219], off
	v_lshl_add_u64 v[218:219], s[28:29], 0, v[134:135]
	s_add_i32 m0, s30, 0x2000
	s_nop 0
	global_load_lds_dwordx4 v[218:219], off
	v_lshl_add_u64 v[218:219], v[222:223], 0, s[2:3]
	s_mov_b32 m0, s40
	s_nop 0
	global_load_lds_dwordx4 v[218:219], off
	v_lshl_add_u64 v[218:219], v[224:225], 0, s[2:3]
	s_mov_b32 m0, s41
	s_nop 0
	global_load_lds_dwordx4 v[218:219], off
	s_waitcnt vmcnt(8)
	s_waitcnt lgkmcnt(0)
	s_barrier
	s_setprio 1
	v_mfma_f32_16x16x32_bf16 v[60:63], v[144:147], v[184:187], v[60:63]
	v_mfma_f32_16x16x32_bf16 v[56:59], v[160:163], v[184:187], v[56:59]
	v_mfma_f32_16x16x32_bf16 v[44:47], v[144:147], v[194:197], v[44:47]
	v_mfma_f32_16x16x32_bf16 v[40:43], v[160:163], v[194:197], v[40:43]
	v_mfma_f32_16x16x32_bf16 v[28:31], v[144:147], v[202:205], v[28:31]
	v_mfma_f32_16x16x32_bf16 v[24:27], v[160:163], v[202:205], v[24:27]
	v_mfma_f32_16x16x32_bf16 v[12:15], v[144:147], v[210:213], v[12:15]
	v_mfma_f32_16x16x32_bf16 v[8:11], v[160:163], v[210:213], v[8:11]
	v_mfma_f32_16x16x32_bf16 v[60:63], v[156:159], v[190:193], v[60:63]
	v_mfma_f32_16x16x32_bf16 v[56:59], v[164:167], v[190:193], v[56:59]
	v_mfma_f32_16x16x32_bf16 v[44:47], v[156:159], v[198:201], v[44:47]
	v_mfma_f32_16x16x32_bf16 v[40:43], v[164:167], v[198:201], v[40:43]
	v_mfma_f32_16x16x32_bf16 v[28:31], v[156:159], v[206:209], v[28:31]
	v_mfma_f32_16x16x32_bf16 v[24:27], v[164:167], v[206:209], v[24:27]
	v_mfma_f32_16x16x32_bf16 v[12:15], v[156:159], v[214:217], v[12:15]
	v_mfma_f32_16x16x32_bf16 v[8:11], v[164:167], v[214:217], v[8:11]
	v_mfma_f32_16x16x32_bf16 v[52:55], v[168:171], v[184:187], v[52:55]
	v_mfma_f32_16x16x32_bf16 v[48:51], v[176:179], v[184:187], v[48:51]
	v_mfma_f32_16x16x32_bf16 v[36:39], v[168:171], v[194:197], v[36:39]
	v_mfma_f32_16x16x32_bf16 v[32:35], v[176:179], v[194:197], v[32:35]
	v_mfma_f32_16x16x32_bf16 v[20:23], v[168:171], v[202:205], v[20:23]
	v_mfma_f32_16x16x32_bf16 v[16:19], v[176:179], v[202:205], v[16:19]
	v_mfma_f32_16x16x32_bf16 v[4:7], v[168:171], v[210:213], v[4:7]
	v_mfma_f32_16x16x32_bf16 v[0:3], v[176:179], v[210:213], v[0:3]
	v_mfma_f32_16x16x32_bf16 v[52:55], v[172:175], v[190:193], v[52:55]
	v_mfma_f32_16x16x32_bf16 v[48:51], v[180:183], v[190:193], v[48:51]
	v_mfma_f32_16x16x32_bf16 v[36:39], v[172:175], v[198:201], v[36:39]
	v_mfma_f32_16x16x32_bf16 v[32:35], v[180:183], v[198:201], v[32:35]
	v_mfma_f32_16x16x32_bf16 v[20:23], v[172:175], v[206:209], v[20:23]
	v_mfma_f32_16x16x32_bf16 v[16:19], v[180:183], v[206:209], v[16:19]
	v_mfma_f32_16x16x32_bf16 v[4:7], v[172:175], v[214:217], v[4:7]
	v_mfma_f32_16x16x32_bf16 v[0:3], v[180:183], v[214:217], v[0:3]
	s_setprio 0
	s_nop 0
	s_add_i32 s50, s50, 2
	s_add_u32 s26, s26, 0x100
	s_addc_u32 s27, s27, 0
	s_add_u32 s48, s48, 0x100
	s_addc_u32 s49, s49, 0

; #define PG8_STAGE(bufoff, gbase, voff) do { _Pragma("unroll") for (int _i = 0; _i < 2; ++_i) \
;         __builtin_amdgcn_global_load_lds((const unsigned*)((const char*)(gbase) + (voff)[_i]), (PG8_LAS unsigned*)(lds + (bufoff) + ldsw + _i * 8192), 16, 0, 0); } while (0)
; #define PG8_LDA(dst, b, h) do { _Pragma("unroll") for (int m = 0; m < 4; ++m) _Pragma("unroll") for (int k = 0; k < 2; ++k) dst[m][k] = *(const PG8_LAS bf16x8*)(lds + PG8_SA(b, h) + aoff + m * 2048 + k * 1024); } while (0)
; #define PG8_LDB(dst, b, h) do { _Pragma("unroll") for (int n = 0; n < 2; ++n) _Pragma("unroll") for (int k = 0; k < 2; ++k) dst[n][k] = *(const PG8_LAS bf16x8*)(lds + PG8_SB(b, h) + boff + n * 2048 + k * 1024); } while (0)
; #define PG8_MMA(ai, bj, At, Bt) do { __builtin_amdgcn_s_setprio(1); _Pragma("unroll") for (int m = 0; m < 4; ++m) _Pragma("unroll") for (int n = 0; n < 2; ++n) _Pragma("unroll") for (int k = 0; k < 2; ++k) \
;         acc[ai][bj][m][n] = __builtin_amdgcn_mfma_f32_16x16x32_bf16(Bt[n][k], At[m][k], acc[ai][bj][m][n], 0, 0, 0); __builtin_amdgcn_s_setprio(0); } while (0)
; #define PG8_WAIT_V(n) asm volatile("s_waitcnt vmcnt(" #n ")" ::: "memory")
; #define PG8_WAIT_L(n) asm volatile("s_waitcnt lgkmcnt(" #n ")" ::: "memory")
; #define PG8_BAR __builtin_amdgcn_s_barrier()
; #define PG8_SCHED __builtin_amdgcn_sched_barrier(0)
; template <class Epi, class Sched, bool ALIGN_EPI = false, bool SP2 = false>
; __device__ __forceinline__ void gemm_phase(PG8_LAS unsigned char* lds, const Gemm g, const Sched& S, const Epi& E) {
;     ...
;         for (int t = 0; t < nt; t += 2) {
;             const bool last = (t == nt - 2);
;             const char* a1 = cA + (size_t)(t + 1) * kstep;
;             const char* a2 = last ? nA : cA + (size_t)(t + 2) * kstep; const char* b2 = last ? nB : cB + (size_t)(t + 2) * kstep;
;             const char* a3 = a2 + kstep; const char* b3 = b2 + kstep;
;             if (last && has_next) S.a_ready(nxt);
;             if constexpr (SP2) {
;             PG8_LDB(B0, 0, 0); PG8_LDB(B1, 0, 1); PG8_SCHED; PG8_LDA(At, 0, 0); PG8_STAGE(PG8_SA(1, 1), a1 + hstep, voffA);
;             PG8_WAIT_V(8); PG8_WAIT_L(0); PG8_BAR; PG8_MMA(0, 0, At, B0); PG8_MMA(0, 1, At, B1); PG8_BAR; PG8_SCHED;
;             PG8_LDA(At, 0, 1); PG8_STAGE(PG8_SB(0, 0), b2, voffB); PG8_STAGE(PG8_SB(0, 1), b2 + hstep, voffB); PG8_STAGE(PG8_SA(0, 0), a2, voffA);
.LBB0_698:
	ds_read_b128 v[144:147], v151
	ds_read_b128 v[156:159], v151 offset:1024
	ds_read_b128 v[160:163], v151 offset:2048
	ds_read_b128 v[164:167], v151 offset:3072
	ds_read_b128 v[168:171], v152
	ds_read_b128 v[172:175], v152 offset:1024
	ds_read_b128 v[176:179], v152 offset:2048
	ds_read_b128 v[180:183], v152 offset:3072
	s_add_u32 s28, s26, 0xfffc0080
	s_addc_u32 s29, s27, -1
	s_cmp_eq_u32 s50, 12
	s_cselect_b32 s31, s17, s29
	s_cselect_b32 s30, s23, s28
	s_cselect_b32 s29, s15, s49
	s_cselect_b32 s28, s47, s48
	v_lshl_add_u64 v[218:219], s[26:27], 0, v[136:137]
	s_add_i32 m0, s25, 0xc000
	ds_read_b128 v[184:187], v153
	ds_read_b128 v[190:193], v153 offset:1024
	ds_read_b128 v[194:197], v153 offset:2048
	ds_read_b128 v[198:201], v153 offset:3072
	ds_read_b128 v[202:205], v153 offset:4096
	ds_read_b128 v[206:209], v153 offset:5120
	ds_read_b128 v[210:213], v153 offset:6144
	ds_read_b128 v[214:217], v153 offset:7168
	global_load_lds_dwordx4 v[218:219], off
	v_lshl_add_u64 v[218:219], s[26:27], 0, v[138:139]
	s_add_i32 m0, s25, 0xe000
	s_nop 0
	global_load_lds_dwordx4 v[218:219], off
	s_waitcnt vmcnt(8)
	s_waitcnt lgkmcnt(0)
	s_barrier
	s_setprio 1
	v_mfma_f32_16x16x32_bf16 v[124:127], v[144:147], v[184:187], v[124:127]
	v_mfma_f32_16x16x32_bf16 v[120:123], v[160:163], v[184:187], v[120:123]
	v_mfma_f32_16x16x32_bf16 v[108:111], v[144:147], v[194:197], v[108:111]
	v_mfma_f32_16x16x32_bf16 v[104:107], v[160:163], v[194:197], v[104:107]
	v_mfma_f32_16x16x32_bf16 v[92:95], v[144:147], v[202:205], v[92:95]
	v_mfma_f32_16x16x32_bf16 v[88:91], v[160:163], v[202:205], v[88:91]
	v_mfma_f32_16x16x32_bf16 v[76:79], v[144:147], v[210:213], v[76:79]
	v_mfma_f32_16x16x32_bf16 v[72:75], v[160:163], v[210:213], v[72:75]
	v_mfma_f32_16x16x32_bf16 v[124:127], v[156:159], v[190:193], v[124:127]
	v_mfma_f32_16x16x32_bf16 v[120:123], v[164:167], v[190:193], v[120:123]
	v_mfma_f32_16x16x32_bf16 v[108:111], v[156:159], v[198:201], v[108:111]
	v_mfma_f32_16x16x32_bf16 v[104:107], v[164:167], v[198:201], v[104:107]
	v_mfma_f32_16x16x32_bf16 v[92:95], v[156:159], v[206:209], v[92:95]
	v_mfma_f32_16x16x32_bf16 v[88:91], v[164:167], v[206:209], v[88:91]
	v_mfma_f32_16x16x32_bf16 v[76:79], v[156:159], v[214:217], v[76:79]
	v_mfma_f32_16x16x32_bf16 v[72:75], v[164:167], v[214:217], v[72:75]
	v_mfma_f32_16x16x32_bf16 v[116:119], v[168:171], v[184:187], v[116:119]
	v_mfma_f32_16x16x32_bf16 v[112:115], v[176:179], v[184:187], v[112:115]
	v_mfma_f32_16x16x32_bf16 v[100:103], v[168:171], v[194:197], v[100:103]
	v_mfma_f32_16x16x32_bf16 v[96:99], v[176:179], v[194:197], v[96:99]
	v_mfma_f32_16x16x32_bf16 v[84:87], v[168:171], v[202:205], v[84:87]
	v_mfma_f32_16x16x32_bf16 v[80:83], v[176:179], v[202:205], v[80:83]
	v_mfma_f32_16x16x32_bf16 v[68:71], v[168:171], v[210:213], v[68:71]
	v_mfma_f32_16x16x32_bf16 v[64:67], v[176:179], v[210:213], v[64:67]
	v_mfma_f32_16x16x32_bf16 v[116:119], v[172:175], v[190:193], v[116:119]
	v_mfma_f32_16x16x32_bf16 v[112:115], v[180:183], v[190:193], v[112:115]
	v_mfma_f32_16x16x32_bf16 v[100:103], v[172:175], v[198:201], v[100:103]
	v_mfma_f32_16x16x32_bf16 v[96:99], v[180:183], v[198:201], v[96:99]
	v_mfma_f32_16x16x32_bf16 v[84:87], v[172:175], v[206:209], v[84:87]
	v_mfma_f32_16x16x32_bf16 v[80:83], v[180:183], v[206:209], v[80:83]
	v_mfma_f32_16x16x32_bf16 v[68:71], v[172:175], v[214:217], v[68:71]
	v_mfma_f32_16x16x32_bf16 v[64:67], v[180:183], v[214:217], v[64:67]
	s_setprio 0
	s_barrier
	s_add_i32 s51, s45, s35
	v_lshl_add_u64 v[218:219], s[28:29], 0, v[130:131]
	s_mov_b32 m0, s51
	ds_read_b128 v[184:187], v153 offset:16384
	ds_read_b128 v[190:193], v153 offset:17408
	ds_read_b128 v[194:197], v153 offset:18432
	ds_read_b128 v[198:201], v153 offset:19456
	ds_read_b128 v[202:205], v153 offset:20480
	ds_read_b128 v[206:209], v153 offset:21504
	ds_read_b128 v[210:213], v153 offset:22528
	ds_read_b128 v[214:217], v153 offset:23552
	global_load_lds_dwordx4 v[218:219], off
	s_add_i32 m0, s51, 0x2000
	s_add_u32 s52, s28, 0x40000
	v_lshl_add_u64 v[220:221], s[28:29], 0, v[134:135]
	s_addc_u32 s53, s29, 0
	s_add_i32 s51, s46, s35
	global_load_lds_dwordx4 v[220:221], off
	v_lshl_add_u64 v[222:223], s[52:53], 0, v[130:131]
	s_mov_b32 m0, s51
	v_lshl_add_u64 v[224:225], s[30:31], 0, v[132:133]
	global_load_lds_dwordx4 v[222:223], off
	v_lshl_add_u64 v[222:223], s[52:53], 0, v[134:135]
	s_add_i32 m0, s51, 0x2000
	s_nop 0
	global_load_lds_dwordx4 v[222:223], off
	v_lshl_add_u64 v[222:223], s[30:31], 0, v[128:129]
	s_mov_b32 m0, s25
	s_nop 0
	global_load_lds_dwordx4 v[222:223], off
	s_mov_b32 m0, s36
	s_nop 0
	global_load_lds_dwordx4 v[224:225], off
	s_waitcnt vmcnt(8)
	s_waitcnt lgkmcnt(0)
	s_barrier
; #define PG8_STAGE(bufoff, gbase, voff) do { _Pragma("unroll") for (int _i = 0; _i < 2; ++_i) \
;         __builtin_amdgcn_global_load_lds((const unsigned*)((const char*)(gbase) + (voff)[_i]), (PG8_LAS unsigned*)(lds + (bufoff) + ldsw + _i * 8192), 16, 0, 0); } while (0)
; #define PG8_LDA(dst, b, h) do { _Pragma("unroll") for (int m = 0; m < 4; ++m) _Pragma("unroll") for (int k = 0; k < 2; ++k) dst[m][k] = *(const PG8_LAS bf16x8*)(lds + PG8_SA(b, h) + aoff + m * 2048 + k * 1024); } while (0)
; #define PG8_LDB(dst, b, h) do { _Pragma("unroll") for (int n = 0; n < 2; ++n) _Pragma("unroll") for (int k = 0; k < 2; ++k) dst[n][k] = *(const PG8_LAS bf16x8*)(lds + PG8_SB(b, h) + boff + n * 2048 + k * 1024); } while (0)
; #define PG8_MMA(ai, bj, At, Bt) do { __builtin_amdgcn_s_setprio(1); _Pragma("unroll") for (int m = 0; m < 4; ++m) _Pragma("unroll") for (int n = 0; n < 2; ++n) _Pragma("unroll") for (int k = 0; k < 2; ++k) \
;         acc[ai][bj][m][n] = __builtin_amdgcn_mfma_f32_16x16x32_bf16(Bt[n][k], At[m][k], acc[ai][bj][m][n], 0, 0, 0); __builtin_amdgcn_s_setprio(0); } while (0)
; #define PG8_WAIT_V(n) asm volatile("s_waitcnt vmcnt(" #n ")" ::: "memory")
; #define PG8_WAIT_L(n) asm volatile("s_waitcnt lgkmcnt(" #n ")" ::: "memory")
; #define PG8_BAR __builtin_amdgcn_s_barrier()
; #define PG8_SCHED __builtin_amdgcn_sched_barrier(0)
; template <class Epi, class Sched, bool ALIGN_EPI = false, bool SP2 = false>
; __device__ __forceinline__ void gemm_phase(PG8_LAS unsigned char* lds, const Gemm g, const Sched& S, const Epi& E) {
;     ...
;             PG8_WAIT_V(8); PG8_WAIT_L(0); PG8_BAR; PG8_MMA(1, 0, At, B0); PG8_MMA(1, 1, At, B1); PG8_BAR; PG8_SCHED;
;             PG8_LDB(B0, 1, 0); PG8_LDB(B1, 1, 1); PG8_SCHED; PG8_LDA(At, 1, 0); PG8_STAGE(PG8_SA(0, 1), a2 + hstep, voffA);
;             PG8_WAIT_V(8); PG8_WAIT_L(0); PG8_BAR; PG8_MMA(0, 0, At, B0); PG8_MMA(0, 1, At, B1); PG8_BAR; PG8_SCHED;
	s_setprio 1
	v_mfma_f32_16x16x32_bf16 v[60:63], v[144:147], v[184:187], v[60:63]
	v_mfma_f32_16x16x32_bf16 v[56:59], v[160:163], v[184:187], v[56:59]
	v_mfma_f32_16x16x32_bf16 v[44:47], v[144:147], v[194:197], v[44:47]
	v_mfma_f32_16x16x32_bf16 v[40:43], v[160:163], v[194:197], v[40:43]
	v_mfma_f32_16x16x32_bf16 v[28:31], v[144:147], v[202:205], v[28:31]
	v_mfma_f32_16x16x32_bf16 v[24:27], v[160:163], v[202:205], v[24:27]
	v_mfma_f32_16x16x32_bf16 v[12:15], v[144:147], v[210:213], v[12:15]
	v_mfma_f32_16x16x32_bf16 v[8:11], v[160:163], v[210:213], v[8:11]
	v_mfma_f32_16x16x32_bf16 v[60:63], v[156:159], v[190:193], v[60:63]
	v_mfma_f32_16x16x32_bf16 v[56:59], v[164:167], v[190:193], v[56:59]
	v_mfma_f32_16x16x32_bf16 v[44:47], v[156:159], v[198:201], v[44:47]
	v_mfma_f32_16x16x32_bf16 v[40:43], v[164:167], v[198:201], v[40:43]
	v_mfma_f32_16x16x32_bf16 v[28:31], v[156:159], v[206:209], v[28:31]
	v_mfma_f32_16x16x32_bf16 v[24:27], v[164:167], v[206:209], v[24:27]
	v_mfma_f32_16x16x32_bf16 v[12:15], v[156:159], v[214:217], v[12:15]
	v_mfma_f32_16x16x32_bf16 v[8:11], v[164:167], v[214:217], v[8:11]
	v_mfma_f32_16x16x32_bf16 v[52:55], v[168:171], v[184:187], v[52:55]
	v_mfma_f32_16x16x32_bf16 v[48:51], v[176:179], v[184:187], v[48:51]
	v_mfma_f32_16x16x32_bf16 v[36:39], v[168:171], v[194:197], v[36:39]
	v_mfma_f32_16x16x32_bf16 v[32:35], v[176:179], v[194:197], v[32:35]
	v_mfma_f32_16x16x32_bf16 v[20:23], v[168:171], v[202:205], v[20:23]
	v_mfma_f32_16x16x32_bf16 v[16:19], v[176:179], v[202:205], v[16:19]
	v_mfma_f32_16x16x32_bf16 v[4:7], v[168:171], v[210:213], v[4:7]
	v_mfma_f32_16x16x32_bf16 v[0:3], v[176:179], v[210:213], v[0:3]
	v_mfma_f32_16x16x32_bf16 v[52:55], v[172:175], v[190:193], v[52:55]
	v_mfma_f32_16x16x32_bf16 v[48:51], v[180:183], v[190:193], v[48:51]
	v_mfma_f32_16x16x32_bf16 v[36:39], v[172:175], v[198:201], v[36:39]
	v_mfma_f32_16x16x32_bf16 v[32:35], v[180:183], v[198:201], v[32:35]
	v_mfma_f32_16x16x32_bf16 v[20:23], v[172:175], v[206:209], v[20:23]
	v_mfma_f32_16x16x32_bf16 v[16:19], v[180:183], v[206:209], v[16:19]
	v_mfma_f32_16x16x32_bf16 v[4:7], v[172:175], v[214:217], v[4:7]
	v_mfma_f32_16x16x32_bf16 v[0:3], v[180:183], v[214:217], v[0:3]
	s_setprio 0
	s_barrier
	s_add_i32 s51, 0, 0x18000
	v_add_u32_e32 v155, s51, v149
	s_add_i32 s52, 0, 0x1c000
	ds_read_b128 v[144:147], v155
	ds_read_b128 v[156:159], v155 offset:1024
	ds_read_b128 v[160:163], v155 offset:2048
	ds_read_b128 v[164:167], v155 offset:3072
	v_add_u32_e32 v155, s52, v149
	ds_read_b128 v[168:171], v155
	ds_read_b128 v[172:175], v155 offset:1024
	ds_read_b128 v[176:179], v155 offset:2048
	ds_read_b128 v[180:183], v155 offset:3072
	s_add_u32 s30, s30, 0x40000
	s_addc_u32 s31, s31, 0
	s_mov_b32 m0, s37
	v_lshl_add_u64 v[226:227], s[30:31], 0, v[128:129]
	ds_read_b128 v[184:187], v153 offset:32768
	ds_read_b128 v[190:193], v153 offset:33792
	ds_read_b128 v[194:197], v153 offset:34816
	ds_read_b128 v[198:201], v153 offset:35840
	ds_read_b128 v[202:205], v153 offset:36864
	ds_read_b128 v[206:209], v153 offset:37888
	ds_read_b128 v[210:213], v153 offset:38912
	ds_read_b128 v[214:217], v153 offset:39936
	global_load_lds_dwordx4 v[226:227], off
	v_lshl_add_u64 v[226:227], s[30:31], 0, v[132:133]
	s_mov_b32 m0, s38
	s_nop 0
	global_load_lds_dwordx4 v[226:227], off
	s_waitcnt vmcnt(8)
	s_waitcnt lgkmcnt(0)
	s_barrier
	s_setprio 1
	v_mfma_f32_16x16x32_bf16 v[124:127], v[144:147], v[184:187], v[124:127]
	v_mfma_f32_16x16x32_bf16 v[120:123], v[160:163], v[184:187], v[120:123]
	v_mfma_f32_16x16x32_bf16 v[108:111], v[144:147], v[194:197], v[108:111]
	v_mfma_f32_16x16x32_bf16 v[104:107], v[160:163], v[194:197], v[104:107]
	v_mfma_f32_16x16x32_bf16 v[92:95], v[144:147], v[202:205], v[92:95]
	v_mfma_f32_16x16x32_bf16 v[88:91], v[160:163], v[202:205], v[88:91]
	v_mfma_f32_16x16x32_bf16 v[76:79], v[144:147], v[210:213], v[76:79]
	v_mfma_f32_16x16x32_bf16 v[72:75], v[160:163], v[210:213], v[72:75]
	v_mfma_f32_16x16x32_bf16 v[124:127], v[156:159], v[190:193], v[124:127]
	v_mfma_f32_16x16x32_bf16 v[120:123], v[164:167], v[190:193], v[120:123]
	v_mfma_f32_16x16x32_bf16 v[108:111], v[156:159], v[198:201], v[108:111]
	v_mfma_f32_16x16x32_bf16 v[104:107], v[164:167], v[198:201], v[104:107]
	v_mfma_f32_16x16x32_bf16 v[92:95], v[156:159], v[206:209], v[92:95]
	v_mfma_f32_16x16x32_bf16 v[88:91], v[164:167], v[206:209], v[88:91]
	v_mfma_f32_16x16x32_bf16 v[76:79], v[156:159], v[214:217], v[76:79]
	v_mfma_f32_16x16x32_bf16 v[72:75], v[164:167], v[214:217], v[72:75]
	v_mfma_f32_16x16x32_bf16 v[116:119], v[168:171], v[184:187], v[116:119]
	v_mfma_f32_16x16x32_bf16 v[112:115], v[176:179], v[184:187], v[112:115]
	v_mfma_f32_16x16x32_bf16 v[100:103], v[168:171], v[194:197], v[100:103]
	v_mfma_f32_16x16x32_bf16 v[96:99], v[176:179], v[194:197], v[96:99]
	v_mfma_f32_16x16x32_bf16 v[84:87], v[168:171], v[202:205], v[84:87]
	v_mfma_f32_16x16x32_bf16 v[80:83], v[176:179], v[202:205], v[80:83]
	v_mfma_f32_16x16x32_bf16 v[68:71], v[168:171], v[210:213], v[68:71]
	v_mfma_f32_16x16x32_bf16 v[64:67], v[176:179], v[210:213], v[64:67]
	v_mfma_f32_16x16x32_bf16 v[116:119], v[172:175], v[190:193], v[116:119]
	v_mfma_f32_16x16x32_bf16 v[112:115], v[180:183], v[190:193], v[112:115]
	v_mfma_f32_16x16x32_bf16 v[100:103], v[172:175], v[198:201], v[100:103]
	v_mfma_f32_16x16x32_bf16 v[96:99], v[180:183], v[198:201], v[96:99]
	v_mfma_f32_16x16x32_bf16 v[84:87], v[172:175], v[206:209], v[84:87]
	v_mfma_f32_16x16x32_bf16 v[80:83], v[180:183], v[206:209], v[80:83]
	v_mfma_f32_16x16x32_bf16 v[68:71], v[172:175], v[214:217], v[68:71]
	v_mfma_f32_16x16x32_bf16 v[64:67], v[180:183], v[214:217], v[64:67]
	s_setprio 0
	s_barrier
; #define PG8_STAGE(bufoff, gbase, voff) do { _Pragma("unroll") for (int _i = 0; _i < 2; ++_i) \
;         __builtin_amdgcn_global_load_lds((const unsigned*)((const char*)(gbase) + (voff)[_i]), (PG8_LAS unsigned*)(lds + (bufoff) + ldsw + _i * 8192), 16, 0, 0); } while (0)
; #define PG8_LDA(dst, b, h) do { _Pragma("unroll") for (int m = 0; m < 4; ++m) _Pragma("unroll") for (int k = 0; k < 2; ++k) dst[m][k] = *(const PG8_LAS bf16x8*)(lds + PG8_SA(b, h) + aoff + m * 2048 + k * 1024); } while (0)
; #define PG8_MMA(ai, bj, At, Bt) do { __builtin_amdgcn_s_setprio(1); _Pragma("unroll") for (int m = 0; m < 4; ++m) _Pragma("unroll") for (int n = 0; n < 2; ++n) _Pragma("unroll") for (int k = 0; k < 2; ++k) \
;         acc[ai][bj][m][n] = __builtin_amdgcn_mfma_f32_16x16x32_bf16(Bt[n][k], At[m][k], acc[ai][bj][m][n], 0, 0, 0); __builtin_amdgcn_s_setprio(0); } while (0)
; #define PG8_WAIT_V(n) asm volatile("s_waitcnt vmcnt(" #n ")" ::: "memory")
; #define PG8_WAIT_L(n) asm volatile("s_waitcnt lgkmcnt(" #n ")" ::: "memory")
; #define PG8_BAR __builtin_amdgcn_s_barrier()
; #define PG8_SCHED __builtin_amdgcn_sched_barrier(0)
; template <class Epi, class Sched, bool ALIGN_EPI = false, bool SP2 = false>
; __device__ __forceinline__ void gemm_phase(PG8_LAS unsigned char* lds, const Gemm g, const Sched& S, const Epi& E) {
;     ...
;         for (int t = 0; t < nt; t += 2) {
;             const bool last = (t == nt - 2);
;             const char* a1 = cA + (size_t)(t + 1) * kstep;
;             const char* a2 = last ? nA : cA + (size_t)(t + 2) * kstep; const char* b2 = last ? nB : cB + (size_t)(t + 2) * kstep;
;     ...
;             PG8_LDA(At, 1, 1); PG8_STAGE(PG8_SB(1, 0), b3, voffB); PG8_STAGE(PG8_SB(1, 1), b3 + hstep, voffB); PG8_STAGE(PG8_SA(1, 0), a3, voffA);
;             PG8_WAIT_V(8); PG8_WAIT_L(0); PG8_BAR; PG8_MMA(1, 0, At, B0); PG8_MMA(1, 1, At, B1); PG8_BAR; PG8_SCHED;
;     ...
;         if constexpr (ALIGN_EPI) { if (wr == 0) PG8_BAR; }
	s_add_i32 s30, s51, s35
	v_lshl_add_u64 v[218:219], v[218:219], 0, s[2:3]
	s_mov_b32 m0, s30
	ds_read_b128 v[184:187], v153 offset:49152
	ds_read_b128 v[190:193], v153 offset:50176
	ds_read_b128 v[194:197], v153 offset:51200
	ds_read_b128 v[198:201], v153 offset:52224
	ds_read_b128 v[202:205], v153 offset:53248
	ds_read_b128 v[206:209], v153 offset:54272
	ds_read_b128 v[210:213], v153 offset:55296
	ds_read_b128 v[214:217], v153 offset:56320
	global_load_lds_dwordx4 v[218:219], off
	s_add_i32 m0, s30, 0x2000
	s_add_u32 s28, s28, 0x40080
	v_lshl_add_u64 v[218:219], v[220:221], 0, s[2:3]
	s_addc_u32 s29, s29, 0
	s_add_i32 s30, s52, s35
	global_load_lds_dwordx4 v[218:219], off
	v_lshl_add_u64 v[218:219], s[28:29], 0, v[130:131]
	s_mov_b32 m0, s30
	s_nop 0
	global_load_lds_dwordx4 v[218:219], off
	v_lshl_add_u64 v[218:219], s[28:29], 0, v[134:135]
	s_add_i32 m0, s30, 0x2000
	s_nop 0
	global_load_lds_dwordx4 v[218:219], off
	v_lshl_add_u64 v[218:219], v[222:223], 0, s[2:3]
	s_mov_b32 m0, s40
	s_nop 0
	global_load_lds_dwordx4 v[218:219], off
	v_lshl_add_u64 v[218:219], v[224:225], 0, s[2:3]
	s_mov_b32 m0, s41
	s_nop 0
	global_load_lds_dwordx4 v[218:219], off
	s_waitcnt vmcnt(8)
	s_waitcnt lgkmcnt(0)
	s_barrier
	s_setprio 1
	v_mfma_f32_16x16x32_bf16 v[60:63], v[144:147], v[184:187], v[60:63]
	v_mfma_f32_16x16x32_bf16 v[56:59], v[160:163], v[184:187], v[56:59]
	v_mfma_f32_16x16x32_bf16 v[44:47], v[144:147], v[194:197], v[44:47]
	v_mfma_f32_16x16x32_bf16 v[40:43], v[160:163], v[194:197], v[40:43]
	v_mfma_f32_16x16x32_bf16 v[28:31], v[144:147], v[202:205], v[28:31]
	v_mfma_f32_16x16x32_bf16 v[24:27], v[160:163], v[202:205], v[24:27]
	v_mfma_f32_16x16x32_bf16 v[12:15], v[144:147], v[210:213], v[12:15]
	v_mfma_f32_16x16x32_bf16 v[8:11], v[160:163], v[210:213], v[8:11]
	v_mfma_f32_16x16x32_bf16 v[60:63], v[156:159], v[190:193], v[60:63]
	v_mfma_f32_16x16x32_bf16 v[56:59], v[164:167], v[190:193], v[56:59]
	v_mfma_f32_16x16x32_bf16 v[44:47], v[156:159], v[198:201], v[44:47]
	v_mfma_f32_16x16x32_bf16 v[40:43], v[164:167], v[198:201], v[40:43]
	v_mfma_f32_16x16x32_bf16 v[28:31], v[156:159], v[206:209], v[28:31]
	v_mfma_f32_16x16x32_bf16 v[24:27], v[164:167], v[206:209], v[24:27]
	v_mfma_f32_16x16x32_bf16 v[12:15], v[156:159], v[214:217], v[12:15]
	v_mfma_f32_16x16x32_bf16 v[8:11], v[164:167], v[214:217], v[8:11]
	v_mfma_f32_16x16x32_bf16 v[52:55], v[168:171], v[184:187], v[52:55]
	v_mfma_f32_16x16x32_bf16 v[48:51], v[176:179], v[184:187], v[48:51]
	v_mfma_f32_16x16x32_bf16 v[36:39], v[168:171], v[194:197], v[36:39]
	v_mfma_f32_16x16x32_bf16 v[32:35], v[176:179], v[194:197], v[32:35]
	v_mfma_f32_16x16x32_bf16 v[20:23], v[168:171], v[202:205], v[20:23]
	v_mfma_f32_16x16x32_bf16 v[16:19], v[176:179], v[202:205], v[16:19]
	v_mfma_f32_16x16x32_bf16 v[4:7], v[168:171], v[210:213], v[4:7]
	v_mfma_f32_16x16x32_bf16 v[0:3], v[176:179], v[210:213], v[0:3]
	v_mfma_f32_16x16x32_bf16 v[52:55], v[172:175], v[190:193], v[52:55]
	v_mfma_f32_16x16x32_bf16 v[48:51], v[180:183], v[190:193], v[48:51]
	v_mfma_f32_16x16x32_bf16 v[36:39], v[172:175], v[198:201], v[36:39]
	v_mfma_f32_16x16x32_bf16 v[32:35], v[180:183], v[198:201], v[32:35]
	v_mfma_f32_16x16x32_bf16 v[20:23], v[172:175], v[206:209], v[20:23]
	v_mfma_f32_16x16x32_bf16 v[16:19], v[180:183], v[206:209], v[16:19]
	v_mfma_f32_16x16x32_bf16 v[4:7], v[172:175], v[214:217], v[4:7]
	v_mfma_f32_16x16x32_bf16 v[0:3], v[180:183], v[214:217], v[0:3]
	s_setprio 0
	s_nop 0
	s_add_i32 s50, s50, 2
	s_add_u32 s26, s26, 0x100
	s_addc_u32 s27, s27, 0
	s_add_u32 s48, s48, 0x100
	s_addc_u32 s49, s49, 0
	s_cmp_gt_u32 s50, 13
	s_cbranch_scc0 .Lrot_698
	s_barrier
	s_and_b64 vcc, exec, s[12:13]
	s_cbranch_vccz .LBB0_701
	s_barrier

; #define PG8_STAGE(bufoff, gbase, voff) do { _Pragma("unroll") for (int _i = 0; _i < 2; ++_i) \
;         __builtin_amdgcn_global_load_lds((const unsigned*)((const char*)(gbase) + (voff)[_i]), (PG8_LAS unsigned*)(lds + (bufoff) + ldsw + _i * 8192), 16, 0, 0); } while (0)
; #define PG8_LDA(dst, b, h) do { _Pragma("unroll") for (int m = 0; m < 4; ++m) _Pragma("unroll") for (int k = 0; k < 2; ++k) dst[m][k] = *(const PG8_LAS bf16x8*)(lds + PG8_SA(b, h) + aoff + m * 2048 + k * 1024); } while (0)
; #define PG8_LDB(dst, b, h) do { _Pragma("unroll") for (int n = 0; n < 2; ++n) _Pragma("unroll") for (int k = 0; k < 2; ++k) dst[n][k] = *(const PG8_LAS bf16x8*)(lds + PG8_SB(b, h) + boff + n * 2048 + k * 1024); } while (0)
; #define PG8_MMA(ai, bj, At, Bt) do { __builtin_amdgcn_s_setprio(1); _Pragma("unroll") for (int m = 0; m < 4; ++m) _Pragma("unroll") for (int n = 0; n < 2; ++n) _Pragma("unroll") for (int k = 0; k < 2; ++k) \
;         acc[ai][bj][m][n] = __builtin_amdgcn_mfma_f32_16x16x32_bf16(Bt[n][k], At[m][k], acc[ai][bj][m][n], 0, 0, 0); __builtin_amdgcn_s_setprio(0); } while (0)
; #define PG8_BAR __builtin_amdgcn_s_barrier()
; template <class Epi, class Sched, bool ALIGN_EPI = false, bool SP2 = false>
; __device__ __forceinline__ void gemm_phase(PG8_LAS unsigned char* lds, const Gemm g, const Sched& S, const Epi& E) {
;     ...
;         const bool has_next = S.next(ui + 1, nxt);
;         const char* nA = has_next ? (const char*)g.A + (size_t)nxt.pm * tstep : cA; const char* nB = has_next ? (const char*)g.Bt + (size_t)nxt.pn * tstep : cB;
;         for (int t = 0; t < nt; t += 2) {
;             const bool last = (t == nt - 2);
;             const char* a1 = cA + (size_t)(t + 1) * kstep;
;             const char* a2 = last ? nA : cA + (size_t)(t + 2) * kstep; const char* b2 = last ? nB : cB + (size_t)(t + 2) * kstep;
;             const char* a3 = a2 + kstep; const char* b3 = b2 + kstep;
;             if (last && has_next) S.a_ready(nxt);
;             if constexpr (SP2) {
;             PG8_LDB(B0, 0, 0); PG8_LDB(B1, 0, 1); PG8_SCHED; PG8_LDA(At, 0, 0); PG8_STAGE(PG8_SA(1, 1), a1 + hstep, voffA);
;             PG8_WAIT_V(8); PG8_WAIT_L(0); PG8_BAR; PG8_MMA(0, 0, At, B0); PG8_MMA(0, 1, At, B1); PG8_BAR; PG8_SCHED;
;             PG8_LDA(At, 0, 1); PG8_STAGE(PG8_SB(0, 0), b2, voffB); PG8_STAGE(PG8_SB(0, 1), b2 + hstep, voffB); PG8_STAGE(PG8_SA(0, 0), a2, voffA);
.LBB0_781:
	s_ashr_i32 s17, s16, 31
	s_lshl_b64 s[18:19], s[16:17], 19
	s_add_u32 s18, s8, s18
	s_addc_u32 s19, s9, s19
	s_and_b64 s[20:21], s[4:5], exec
	s_cselect_b32 s17, s19, s23
	s_cselect_b32 s47, s18, s22
	s_ashr_i32 s15, s14, 31
	s_lshl_b64 s[20:21], s[14:15], 19
	s_add_u32 s20, s28, s20
	s_addc_u32 s21, s29, s21
	s_and_b64 s[26:27], s[4:5], exec
	s_cselect_b32 s15, s21, s25
	s_cselect_b32 s48, s20, s24
	s_add_u32 s22, s22, 0x40080
	s_addc_u32 s23, s23, 0
	s_add_u32 s49, s24, 0x100
	s_addc_u32 s50, s25, 0
	s_mov_b32 s51, -2
	ds_read_b128 v[144:147], v151
	ds_read_b128 v[156:159], v151 offset:1024
	ds_read_b128 v[160:163], v151 offset:2048
	ds_read_b128 v[164:167], v151 offset:3072
	ds_read_b128 v[168:171], v152
	ds_read_b128 v[172:175], v152 offset:1024
	ds_read_b128 v[176:179], v152 offset:2048
	ds_read_b128 v[180:183], v152 offset:3072
	s_add_u32 s24, s22, 0xfffc0080
	s_addc_u32 s25, s23, -1
	s_cmp_eq_u32 s51, 12
	s_cselect_b32 s27, s17, s25
	s_cselect_b32 s26, s47, s24
	s_cselect_b32 s25, s15, s50
	s_cselect_b32 s24, s48, s49
	v_lshl_add_u64 v[218:219], s[22:23], 0, v[136:137]
	s_add_i32 m0, s34, 0xc000
	ds_read_b128 v[184:187], v153
	ds_read_b128 v[190:193], v153 offset:1024
	ds_read_b128 v[194:197], v153 offset:2048
	ds_read_b128 v[198:201], v153 offset:3072
	ds_read_b128 v[202:205], v153 offset:4096
	ds_read_b128 v[206:209], v153 offset:5120
	ds_read_b128 v[210:213], v153 offset:6144
	ds_read_b128 v[214:217], v153 offset:7168
	global_load_lds_dwordx4 v[218:219], off
	v_lshl_add_u64 v[218:219], s[22:23], 0, v[138:139]
	s_add_i32 m0, s34, 0xe000
	s_nop 0
	global_load_lds_dwordx4 v[218:219], off
	s_waitcnt vmcnt(16)
	s_waitcnt lgkmcnt(0)
	s_barrier
	s_setprio 1
	v_mfma_f32_16x16x32_bf16 v[116:119], v[144:147], v[184:187], 0
	v_mfma_f32_16x16x32_bf16 v[112:115], v[160:163], v[184:187], 0
	v_mfma_f32_16x16x32_bf16 v[100:103], v[144:147], v[194:197], 0
	v_mfma_f32_16x16x32_bf16 v[96:99], v[160:163], v[194:197], 0
	v_mfma_f32_16x16x32_bf16 v[84:87], v[144:147], v[202:205], 0
	v_mfma_f32_16x16x32_bf16 v[80:83], v[160:163], v[202:205], 0
	v_mfma_f32_16x16x32_bf16 v[72:75], v[144:147], v[210:213], 0
	v_mfma_f32_16x16x32_bf16 v[64:67], v[160:163], v[210:213], 0
	v_mfma_f32_16x16x32_bf16 v[116:119], v[156:159], v[190:193], v[116:119]
	v_mfma_f32_16x16x32_bf16 v[112:115], v[164:167], v[190:193], v[112:115]
	v_mfma_f32_16x16x32_bf16 v[100:103], v[156:159], v[198:201], v[100:103]
	v_mfma_f32_16x16x32_bf16 v[96:99], v[164:167], v[198:201], v[96:99]
	v_mfma_f32_16x16x32_bf16 v[84:87], v[156:159], v[206:209], v[84:87]
	v_mfma_f32_16x16x32_bf16 v[80:83], v[164:167], v[206:209], v[80:83]
	v_mfma_f32_16x16x32_bf16 v[72:75], v[156:159], v[214:217], v[72:75]
	v_mfma_f32_16x16x32_bf16 v[64:67], v[164:167], v[214:217], v[64:67]
	v_mfma_f32_16x16x32_bf16 v[124:127], v[168:171], v[184:187], 0
	v_mfma_f32_16x16x32_bf16 v[120:123], v[176:179], v[184:187], 0
	v_mfma_f32_16x16x32_bf16 v[108:111], v[168:171], v[194:197], 0
	v_mfma_f32_16x16x32_bf16 v[104:107], v[176:179], v[194:197], 0
	v_mfma_f32_16x16x32_bf16 v[92:95], v[168:171], v[202:205], 0
	v_mfma_f32_16x16x32_bf16 v[88:91], v[176:179], v[202:205], 0
	v_mfma_f32_16x16x32_bf16 v[76:79], v[168:171], v[210:213], 0
	v_mfma_f32_16x16x32_bf16 v[68:71], v[176:179], v[210:213], 0
	v_mfma_f32_16x16x32_bf16 v[124:127], v[172:175], v[190:193], v[124:127]
	v_mfma_f32_16x16x32_bf16 v[120:123], v[180:183], v[190:193], v[120:123]
	v_mfma_f32_16x16x32_bf16 v[108:111], v[172:175], v[198:201], v[108:111]
	v_mfma_f32_16x16x32_bf16 v[104:107], v[180:183], v[198:201], v[104:107]
	v_mfma_f32_16x16x32_bf16 v[92:95], v[172:175], v[206:209], v[92:95]
	v_mfma_f32_16x16x32_bf16 v[88:91], v[180:183], v[206:209], v[88:91]
	v_mfma_f32_16x16x32_bf16 v[76:79], v[172:175], v[214:217], v[76:79]
	v_mfma_f32_16x16x32_bf16 v[68:71], v[180:183], v[214:217], v[68:71]
	s_setprio 0
	s_barrier
	s_add_i32 s52, s43, s30
	v_lshl_add_u64 v[218:219], s[24:25], 0, v[132:133]
	s_mov_b32 m0, s52
	ds_read_b128 v[184:187], v153 offset:16384
	ds_read_b128 v[190:193], v153 offset:17408
	ds_read_b128 v[194:197], v153 offset:18432
	ds_read_b128 v[198:201], v153 offset:19456
	ds_read_b128 v[202:205], v153 offset:20480
	ds_read_b128 v[206:209], v153 offset:21504
	ds_read_b128 v[210:213], v153 offset:22528
	ds_read_b128 v[214:217], v153 offset:23552
	global_load_lds_dwordx4 v[218:219], off
	s_add_i32 m0, s52, 0x2000
	s_add_u32 s52, s24, 0x40000
	v_lshl_add_u64 v[220:221], s[24:25], 0, v[128:129]
	s_addc_u32 s53, s25, 0
	s_add_i32 s54, s44, s30
	global_load_lds_dwordx4 v[220:221], off
	v_lshl_add_u64 v[222:223], s[52:53], 0, v[132:133]
	s_mov_b32 m0, s54
	v_lshl_add_u64 v[224:225], s[26:27], 0, v[130:131]
	global_load_lds_dwordx4 v[222:223], off
	v_lshl_add_u64 v[222:223], s[52:53], 0, v[128:129]
	s_add_i32 m0, s54, 0x2000
	s_nop 0
	global_load_lds_dwordx4 v[222:223], off
	v_lshl_add_u64 v[222:223], s[26:27], 0, v[134:135]
	s_mov_b32 m0, s34
	s_nop 0
	global_load_lds_dwordx4 v[222:223], off
	s_mov_b32 m0, s35
	s_nop 0
	global_load_lds_dwordx4 v[224:225], off
	s_waitcnt vmcnt(16)
	s_waitcnt lgkmcnt(0)
	s_barrier
; #define PG8_STAGE(bufoff, gbase, voff) do { _Pragma("unroll") for (int _i = 0; _i < 2; ++_i) \
;         __builtin_amdgcn_global_load_lds((const unsigned*)((const char*)(gbase) + (voff)[_i]), (PG8_LAS unsigned*)(lds + (bufoff) + ldsw + _i * 8192), 16, 0, 0); } while (0)
; #define PG8_LDA(dst, b, h) do { _Pragma("unroll") for (int m = 0; m < 4; ++m) _Pragma("unroll") for (int k = 0; k < 2; ++k) dst[m][k] = *(const PG8_LAS bf16x8*)(lds + PG8_SA(b, h) + aoff + m * 2048 + k * 1024); } while (0)
; #define PG8_LDB(dst, b, h) do { _Pragma("unroll") for (int n = 0; n < 2; ++n) _Pragma("unroll") for (int k = 0; k < 2; ++k) dst[n][k] = *(const PG8_LAS bf16x8*)(lds + PG8_SB(b, h) + boff + n * 2048 + k * 1024); } while (0)
; #define PG8_MMA(ai, bj, At, Bt) do { __builtin_amdgcn_s_setprio(1); _Pragma("unroll") for (int m = 0; m < 4; ++m) _Pragma("unroll") for (int n = 0; n < 2; ++n) _Pragma("unroll") for (int k = 0; k < 2; ++k) \
;         acc[ai][bj][m][n] = __builtin_amdgcn_mfma_f32_16x16x32_bf16(Bt[n][k], At[m][k], acc[ai][bj][m][n], 0, 0, 0); __builtin_amdgcn_s_setprio(0); } while (0)
; #define PG8_WAIT_V(n) asm volatile("s_waitcnt vmcnt(" #n ")" ::: "memory")
; #define PG8_WAIT_L(n) asm volatile("s_waitcnt lgkmcnt(" #n ")" ::: "memory")
; #define PG8_BAR __builtin_amdgcn_s_barrier()
; #define PG8_SCHED __builtin_amdgcn_sched_barrier(0)
; template <class Epi, class Sched, bool ALIGN_EPI = false, bool SP2 = false>
; __device__ __forceinline__ void gemm_phase(PG8_LAS unsigned char* lds, const Gemm g, const Sched& S, const Epi& E) {
;     ...
;             PG8_WAIT_V(8); PG8_WAIT_L(0); PG8_BAR; PG8_MMA(0, 0, At, B0); PG8_MMA(0, 1, At, B1); PG8_BAR; PG8_SCHED;
;             PG8_LDA(At, 0, 1); PG8_STAGE(PG8_SB(0, 0), b2, voffB); PG8_STAGE(PG8_SB(0, 1), b2 + hstep, voffB); PG8_STAGE(PG8_SA(0, 0), a2, voffA);
;             PG8_WAIT_V(8); PG8_WAIT_L(0); PG8_BAR; PG8_MMA(1, 0, At, B0); PG8_MMA(1, 1, At, B1); PG8_BAR; PG8_SCHED;
;             PG8_LDB(B0, 1, 0); PG8_LDB(B1, 1, 1); PG8_SCHED; PG8_LDA(At, 1, 0); PG8_STAGE(PG8_SA(0, 1), a2 + hstep, voffA);
;             PG8_WAIT_V(8); PG8_WAIT_L(0); PG8_BAR; PG8_MMA(0, 0, At, B0); PG8_MMA(0, 1, At, B1); PG8_BAR; PG8_SCHED;
	s_setprio 1
	v_mfma_f32_16x16x32_bf16 v[56:59], v[144:147], v[184:187], 0
	v_mfma_f32_16x16x32_bf16 v[48:51], v[160:163], v[184:187], 0
	v_mfma_f32_16x16x32_bf16 v[40:43], v[144:147], v[194:197], 0
	v_mfma_f32_16x16x32_bf16 v[32:35], v[160:163], v[194:197], 0
	v_mfma_f32_16x16x32_bf16 v[24:27], v[144:147], v[202:205], 0
	v_mfma_f32_16x16x32_bf16 v[16:19], v[160:163], v[202:205], 0
	v_mfma_f32_16x16x32_bf16 v[8:11], v[144:147], v[210:213], 0
	v_mfma_f32_16x16x32_bf16 v[0:3], v[160:163], v[210:213], 0
	v_mfma_f32_16x16x32_bf16 v[56:59], v[156:159], v[190:193], v[56:59]
	v_mfma_f32_16x16x32_bf16 v[48:51], v[164:167], v[190:193], v[48:51]
	v_mfma_f32_16x16x32_bf16 v[40:43], v[156:159], v[198:201], v[40:43]
	v_mfma_f32_16x16x32_bf16 v[32:35], v[164:167], v[198:201], v[32:35]
	v_mfma_f32_16x16x32_bf16 v[24:27], v[156:159], v[206:209], v[24:27]
	v_mfma_f32_16x16x32_bf16 v[16:19], v[164:167], v[206:209], v[16:19]
	v_mfma_f32_16x16x32_bf16 v[8:11], v[156:159], v[214:217], v[8:11]
	v_mfma_f32_16x16x32_bf16 v[0:3], v[164:167], v[214:217], v[0:3]
	v_mfma_f32_16x16x32_bf16 v[60:63], v[168:171], v[184:187], 0
	v_mfma_f32_16x16x32_bf16 v[52:55], v[176:179], v[184:187], 0
	v_mfma_f32_16x16x32_bf16 v[44:47], v[168:171], v[194:197], 0
	v_mfma_f32_16x16x32_bf16 v[36:39], v[176:179], v[194:197], 0
	v_mfma_f32_16x16x32_bf16 v[28:31], v[168:171], v[202:205], 0
	v_mfma_f32_16x16x32_bf16 v[20:23], v[176:179], v[202:205], 0
	v_mfma_f32_16x16x32_bf16 v[12:15], v[168:171], v[210:213], 0
	v_mfma_f32_16x16x32_bf16 v[4:7], v[176:179], v[210:213], 0
	v_mfma_f32_16x16x32_bf16 v[60:63], v[172:175], v[190:193], v[60:63]
	v_mfma_f32_16x16x32_bf16 v[52:55], v[180:183], v[190:193], v[52:55]
	v_mfma_f32_16x16x32_bf16 v[44:47], v[172:175], v[198:201], v[44:47]
	v_mfma_f32_16x16x32_bf16 v[36:39], v[180:183], v[198:201], v[36:39]
	v_mfma_f32_16x16x32_bf16 v[28:31], v[172:175], v[206:209], v[28:31]
	v_mfma_f32_16x16x32_bf16 v[20:23], v[180:183], v[206:209], v[20:23]
	v_mfma_f32_16x16x32_bf16 v[12:15], v[172:175], v[214:217], v[12:15]
	v_mfma_f32_16x16x32_bf16 v[4:7], v[180:183], v[214:217], v[4:7]
	s_setprio 0
	s_barrier
	s_add_i32 s52, 0, 0x18000
	v_add_u32_e32 v155, s52, v149
	s_add_i32 s53, 0, 0x1c000
	ds_read_b128 v[144:147], v155
	ds_read_b128 v[156:159], v155 offset:1024
	ds_read_b128 v[160:163], v155 offset:2048
	ds_read_b128 v[164:167], v155 offset:3072
	v_add_u32_e32 v155, s53, v149
	ds_read_b128 v[168:171], v155
	ds_read_b128 v[172:175], v155 offset:1024
	ds_read_b128 v[176:179], v155 offset:2048
	ds_read_b128 v[180:183], v155 offset:3072
	s_add_u32 s26, s26, 0x40000
	s_addc_u32 s27, s27, 0
	s_mov_b32 m0, s36
	v_lshl_add_u64 v[226:227], s[26:27], 0, v[134:135]
	ds_read_b128 v[184:187], v153 offset:32768
	ds_read_b128 v[190:193], v153 offset:33792
	ds_read_b128 v[194:197], v153 offset:34816
	ds_read_b128 v[198:201], v153 offset:35840
	ds_read_b128 v[202:205], v153 offset:36864
	ds_read_b128 v[206:209], v153 offset:37888
	ds_read_b128 v[210:213], v153 offset:38912
	ds_read_b128 v[214:217], v153 offset:39936
	global_load_lds_dwordx4 v[226:227], off
	v_lshl_add_u64 v[226:227], s[26:27], 0, v[130:131]
	s_mov_b32 m0, s37
	s_nop 0
	global_load_lds_dwordx4 v[226:227], off
	s_waitcnt vmcnt(8)
	s_waitcnt lgkmcnt(0)
	s_barrier
	s_setprio 1
	v_mfma_f32_16x16x32_bf16 v[116:119], v[144:147], v[184:187], v[116:119]
	v_mfma_f32_16x16x32_bf16 v[112:115], v[160:163], v[184:187], v[112:115]
	v_mfma_f32_16x16x32_bf16 v[100:103], v[144:147], v[194:197], v[100:103]
	v_mfma_f32_16x16x32_bf16 v[96:99], v[160:163], v[194:197], v[96:99]
	v_mfma_f32_16x16x32_bf16 v[84:87], v[144:147], v[202:205], v[84:87]
	v_mfma_f32_16x16x32_bf16 v[80:83], v[160:163], v[202:205], v[80:83]
	v_mfma_f32_16x16x32_bf16 v[72:75], v[144:147], v[210:213], v[72:75]
	v_mfma_f32_16x16x32_bf16 v[64:67], v[160:163], v[210:213], v[64:67]
	v_mfma_f32_16x16x32_bf16 v[116:119], v[156:159], v[190:193], v[116:119]
	v_mfma_f32_16x16x32_bf16 v[112:115], v[164:167], v[190:193], v[112:115]
	v_mfma_f32_16x16x32_bf16 v[100:103], v[156:159], v[198:201], v[100:103]
	v_mfma_f32_16x16x32_bf16 v[96:99], v[164:167], v[198:201], v[96:99]
	v_mfma_f32_16x16x32_bf16 v[84:87], v[156:159], v[206:209], v[84:87]
	v_mfma_f32_16x16x32_bf16 v[80:83], v[164:167], v[206:209], v[80:83]
	v_mfma_f32_16x16x32_bf16 v[72:75], v[156:159], v[214:217], v[72:75]
	v_mfma_f32_16x16x32_bf16 v[64:67], v[164:167], v[214:217], v[64:67]
	v_mfma_f32_16x16x32_bf16 v[124:127], v[168:171], v[184:187], v[124:127]
	v_mfma_f32_16x16x32_bf16 v[120:123], v[176:179], v[184:187], v[120:123]
	v_mfma_f32_16x16x32_bf16 v[108:111], v[168:171], v[194:197], v[108:111]
	v_mfma_f32_16x16x32_bf16 v[104:107], v[176:179], v[194:197], v[104:107]
	v_mfma_f32_16x16x32_bf16 v[92:95], v[168:171], v[202:205], v[92:95]
	v_mfma_f32_16x16x32_bf16 v[88:91], v[176:179], v[202:205], v[88:91]
	v_mfma_f32_16x16x32_bf16 v[76:79], v[168:171], v[210:213], v[76:79]
	v_mfma_f32_16x16x32_bf16 v[68:71], v[176:179], v[210:213], v[68:71]
	v_mfma_f32_16x16x32_bf16 v[124:127], v[172:175], v[190:193], v[124:127]
	v_mfma_f32_16x16x32_bf16 v[120:123], v[180:183], v[190:193], v[120:123]
	v_mfma_f32_16x16x32_bf16 v[108:111], v[172:175], v[198:201], v[108:111]
	v_mfma_f32_16x16x32_bf16 v[104:107], v[180:183], v[198:201], v[104:107]
	v_mfma_f32_16x16x32_bf16 v[92:95], v[172:175], v[206:209], v[92:95]
	v_mfma_f32_16x16x32_bf16 v[88:91], v[180:183], v[206:209], v[88:91]
	v_mfma_f32_16x16x32_bf16 v[76:79], v[172:175], v[214:217], v[76:79]
	v_mfma_f32_16x16x32_bf16 v[68:71], v[180:183], v[214:217], v[68:71]
	s_setprio 0
	s_barrier
; #define PG8_STAGE(bufoff, gbase, voff) do { _Pragma("unroll") for (int _i = 0; _i < 2; ++_i) \
;         __builtin_amdgcn_global_load_lds((const unsigned*)((const char*)(gbase) + (voff)[_i]), (PG8_LAS unsigned*)(lds + (bufoff) + ldsw + _i * 8192), 16, 0, 0); } while (0)
; #define PG8_LDA(dst, b, h) do { _Pragma("unroll") for (int m = 0; m < 4; ++m) _Pragma("unroll") for (int k = 0; k < 2; ++k) dst[m][k] = *(const PG8_LAS bf16x8*)(lds + PG8_SA(b, h) + aoff + m * 2048 + k * 1024); } while (0)
; #define PG8_MMA(ai, bj, At, Bt) do { __builtin_amdgcn_s_setprio(1); _Pragma("unroll") for (int m = 0; m < 4; ++m) _Pragma("unroll") for (int n = 0; n < 2; ++n) _Pragma("unroll") for (int k = 0; k < 2; ++k) \
;         acc[ai][bj][m][n] = __builtin_amdgcn_mfma_f32_16x16x32_bf16(Bt[n][k], At[m][k], acc[ai][bj][m][n], 0, 0, 0); __builtin_amdgcn_s_setprio(0); } while (0)
; #define PG8_WAIT_V(n) asm volatile("s_waitcnt vmcnt(" #n ")" ::: "memory")
; #define PG8_WAIT_L(n) asm volatile("s_waitcnt lgkmcnt(" #n ")" ::: "memory")
; #define PG8_BAR __builtin_amdgcn_s_barrier()
; #define PG8_SCHED __builtin_amdgcn_sched_barrier(0)
; template <class Epi, class Sched, bool ALIGN_EPI = false, bool SP2 = false>
; __device__ __forceinline__ void gemm_phase(PG8_LAS unsigned char* lds, const Gemm g, const Sched& S, const Epi& E) {
;     ...
;         for (int t = 0; t < nt; t += 2) {
;     ...
;             PG8_LDA(At, 1, 1); PG8_STAGE(PG8_SB(1, 0), b3, voffB); PG8_STAGE(PG8_SB(1, 1), b3 + hstep, voffB); PG8_STAGE(PG8_SA(1, 0), a3, voffA);
;             PG8_WAIT_V(8); PG8_WAIT_L(0); PG8_BAR; PG8_MMA(1, 0, At, B0); PG8_MMA(1, 1, At, B1); PG8_BAR; PG8_SCHED;
	s_add_i32 s26, s52, s30
	v_lshl_add_u64 v[218:219], v[218:219], 0, s[6:7]
	s_mov_b32 m0, s26
	ds_read_b128 v[184:187], v153 offset:49152
	ds_read_b128 v[190:193], v153 offset:50176
	ds_read_b128 v[194:197], v153 offset:51200
	ds_read_b128 v[198:201], v153 offset:52224
	ds_read_b128 v[202:205], v153 offset:53248
	ds_read_b128 v[206:209], v153 offset:54272
	ds_read_b128 v[210:213], v153 offset:55296
	ds_read_b128 v[214:217], v153 offset:56320
	global_load_lds_dwordx4 v[218:219], off
	s_add_i32 m0, s26, 0x2000
	s_add_u32 s24, s24, 0x40080
	v_lshl_add_u64 v[218:219], v[220:221], 0, s[6:7]
	s_addc_u32 s25, s25, 0
	s_add_i32 s26, s53, s30
	global_load_lds_dwordx4 v[218:219], off
	v_lshl_add_u64 v[218:219], s[24:25], 0, v[132:133]
	s_mov_b32 m0, s26
	s_nop 0
	global_load_lds_dwordx4 v[218:219], off
	v_lshl_add_u64 v[218:219], s[24:25], 0, v[128:129]
	s_add_i32 m0, s26, 0x2000
	s_nop 0
	global_load_lds_dwordx4 v[218:219], off
	v_lshl_add_u64 v[218:219], v[222:223], 0, s[6:7]
	s_mov_b32 m0, s39
	s_nop 0
	global_load_lds_dwordx4 v[218:219], off
	v_lshl_add_u64 v[218:219], v[224:225], 0, s[6:7]
	s_mov_b32 m0, s40
	s_nop 0
	global_load_lds_dwordx4 v[218:219], off
	s_waitcnt vmcnt(8)
	s_waitcnt lgkmcnt(0)
	s_barrier
	s_setprio 1
	v_mfma_f32_16x16x32_bf16 v[56:59], v[144:147], v[184:187], v[56:59]
	v_mfma_f32_16x16x32_bf16 v[48:51], v[160:163], v[184:187], v[48:51]
	v_mfma_f32_16x16x32_bf16 v[40:43], v[144:147], v[194:197], v[40:43]
	v_mfma_f32_16x16x32_bf16 v[32:35], v[160:163], v[194:197], v[32:35]
	v_mfma_f32_16x16x32_bf16 v[24:27], v[144:147], v[202:205], v[24:27]
	v_mfma_f32_16x16x32_bf16 v[16:19], v[160:163], v[202:205], v[16:19]
	v_mfma_f32_16x16x32_bf16 v[8:11], v[144:147], v[210:213], v[8:11]
	v_mfma_f32_16x16x32_bf16 v[0:3], v[160:163], v[210:213], v[0:3]
	v_mfma_f32_16x16x32_bf16 v[56:59], v[156:159], v[190:193], v[56:59]
	v_mfma_f32_16x16x32_bf16 v[48:51], v[164:167], v[190:193], v[48:51]
	v_mfma_f32_16x16x32_bf16 v[40:43], v[156:159], v[198:201], v[40:43]
	v_mfma_f32_16x16x32_bf16 v[32:35], v[164:167], v[198:201], v[32:35]
	v_mfma_f32_16x16x32_bf16 v[24:27], v[156:159], v[206:209], v[24:27]
	v_mfma_f32_16x16x32_bf16 v[16:19], v[164:167], v[206:209], v[16:19]
	v_mfma_f32_16x16x32_bf16 v[8:11], v[156:159], v[214:217], v[8:11]
	v_mfma_f32_16x16x32_bf16 v[0:3], v[164:167], v[214:217], v[0:3]
	v_mfma_f32_16x16x32_bf16 v[60:63], v[168:171], v[184:187], v[60:63]
	v_mfma_f32_16x16x32_bf16 v[52:55], v[176:179], v[184:187], v[52:55]
	v_mfma_f32_16x16x32_bf16 v[44:47], v[168:171], v[194:197], v[44:47]
	v_mfma_f32_16x16x32_bf16 v[36:39], v[176:179], v[194:197], v[36:39]
	v_mfma_f32_16x16x32_bf16 v[28:31], v[168:171], v[202:205], v[28:31]
	v_mfma_f32_16x16x32_bf16 v[20:23], v[176:179], v[202:205], v[20:23]
	v_mfma_f32_16x16x32_bf16 v[12:15], v[168:171], v[210:213], v[12:15]
	v_mfma_f32_16x16x32_bf16 v[4:7], v[176:179], v[210:213], v[4:7]
	v_mfma_f32_16x16x32_bf16 v[60:63], v[172:175], v[190:193], v[60:63]
	v_mfma_f32_16x16x32_bf16 v[52:55], v[180:183], v[190:193], v[52:55]
	v_mfma_f32_16x16x32_bf16 v[44:47], v[172:175], v[198:201], v[44:47]
	v_mfma_f32_16x16x32_bf16 v[36:39], v[180:183], v[198:201], v[36:39]
	v_mfma_f32_16x16x32_bf16 v[28:31], v[172:175], v[206:209], v[28:31]
	v_mfma_f32_16x16x32_bf16 v[20:23], v[180:183], v[206:209], v[20:23]
	v_mfma_f32_16x16x32_bf16 v[12:15], v[172:175], v[214:217], v[12:15]
	v_mfma_f32_16x16x32_bf16 v[4:7], v[180:183], v[214:217], v[4:7]
	s_setprio 0
	s_nop 0
	s_add_i32 s51, s51, 2
	s_add_u32 s22, s22, 0x100
	s_addc_u32 s23, s23, 0
	s_add_u32 s49, s49, 0x100
	s_addc_u32 s50, s50, 0

; #define PG8_STAGE(bufoff, gbase, voff) do { _Pragma("unroll") for (int _i = 0; _i < 2; ++_i) \
;         __builtin_amdgcn_global_load_lds((const unsigned*)((const char*)(gbase) + (voff)[_i]), (PG8_LAS unsigned*)(lds + (bufoff) + ldsw + _i * 8192), 16, 0, 0); } while (0)
; #define PG8_LDA(dst, b, h) do { _Pragma("unroll") for (int m = 0; m < 4; ++m) _Pragma("unroll") for (int k = 0; k < 2; ++k) dst[m][k] = *(const PG8_LAS bf16x8*)(lds + PG8_SA(b, h) + aoff + m * 2048 + k * 1024); } while (0)
; #define PG8_LDB(dst, b, h) do { _Pragma("unroll") for (int n = 0; n < 2; ++n) _Pragma("unroll") for (int k = 0; k < 2; ++k) dst[n][k] = *(const PG8_LAS bf16x8*)(lds + PG8_SB(b, h) + boff + n * 2048 + k * 1024); } while (0)
; #define PG8_MMA(ai, bj, At, Bt) do { __builtin_amdgcn_s_setprio(1); _Pragma("unroll") for (int m = 0; m < 4; ++m) _Pragma("unroll") for (int n = 0; n < 2; ++n) _Pragma("unroll") for (int k = 0; k < 2; ++k) \
;         acc[ai][bj][m][n] = __builtin_amdgcn_mfma_f32_16x16x32_bf16(Bt[n][k], At[m][k], acc[ai][bj][m][n], 0, 0, 0); __builtin_amdgcn_s_setprio(0); } while (0)
; #define PG8_WAIT_V(n) asm volatile("s_waitcnt vmcnt(" #n ")" ::: "memory")
; #define PG8_WAIT_L(n) asm volatile("s_waitcnt lgkmcnt(" #n ")" ::: "memory")
; #define PG8_BAR __builtin_amdgcn_s_barrier()
; #define PG8_SCHED __builtin_amdgcn_sched_barrier(0)
; template <class Epi, class Sched, bool ALIGN_EPI = false, bool SP2 = false>
; __device__ __forceinline__ void gemm_phase(PG8_LAS unsigned char* lds, const Gemm g, const Sched& S, const Epi& E) {
;     ...
;             PG8_LDB(B0, 0, 0); PG8_LDB(B1, 0, 1); PG8_SCHED; PG8_LDA(At, 0, 0); PG8_STAGE(PG8_SA(1, 1), a1 + hstep, voffA);
;             PG8_WAIT_V(8); PG8_WAIT_L(0); PG8_BAR; PG8_MMA(0, 0, At, B0); PG8_MMA(0, 1, At, B1); PG8_BAR; PG8_SCHED;
;             PG8_LDA(At, 0, 1); PG8_STAGE(PG8_SB(0, 0), b2, voffB); PG8_STAGE(PG8_SB(0, 1), b2 + hstep, voffB); PG8_STAGE(PG8_SA(0, 0), a2, voffA);
;             PG8_WAIT_V(8); PG8_WAIT_L(0); PG8_BAR; PG8_MMA(1, 0, At, B0); PG8_MMA(1, 1, At, B1); PG8_BAR; PG8_SCHED;
.LBB0_782:
	ds_read_b128 v[144:147], v151
	ds_read_b128 v[156:159], v151 offset:1024
	ds_read_b128 v[160:163], v151 offset:2048
	ds_read_b128 v[164:167], v151 offset:3072
	ds_read_b128 v[168:171], v152
	ds_read_b128 v[172:175], v152 offset:1024
	ds_read_b128 v[176:179], v152 offset:2048
	ds_read_b128 v[180:183], v152 offset:3072
	s_add_u32 s24, s22, 0xfffc0080
	s_addc_u32 s25, s23, -1
	s_cmp_eq_u32 s51, 12
	s_cselect_b32 s27, s17, s25
	s_cselect_b32 s26, s47, s24
	s_cselect_b32 s25, s15, s50
	s_cselect_b32 s24, s48, s49
	v_lshl_add_u64 v[218:219], s[22:23], 0, v[136:137]
	s_add_i32 m0, s34, 0xc000
	ds_read_b128 v[184:187], v153
	ds_read_b128 v[190:193], v153 offset:1024
	ds_read_b128 v[194:197], v153 offset:2048
	ds_read_b128 v[198:201], v153 offset:3072
	ds_read_b128 v[202:205], v153 offset:4096
	ds_read_b128 v[206:209], v153 offset:5120
	ds_read_b128 v[210:213], v153 offset:6144
	ds_read_b128 v[214:217], v153 offset:7168
	global_load_lds_dwordx4 v[218:219], off
	v_lshl_add_u64 v[218:219], s[22:23], 0, v[138:139]
	s_add_i32 m0, s34, 0xe000
	s_nop 0
	global_load_lds_dwordx4 v[218:219], off
	s_waitcnt vmcnt(8)
	s_waitcnt lgkmcnt(0)
	s_barrier
	s_setprio 1
	v_mfma_f32_16x16x32_bf16 v[116:119], v[144:147], v[184:187], v[116:119]
	v_mfma_f32_16x16x32_bf16 v[112:115], v[160:163], v[184:187], v[112:115]
	v_mfma_f32_16x16x32_bf16 v[100:103], v[144:147], v[194:197], v[100:103]
	v_mfma_f32_16x16x32_bf16 v[96:99], v[160:163], v[194:197], v[96:99]
	v_mfma_f32_16x16x32_bf16 v[84:87], v[144:147], v[202:205], v[84:87]
	v_mfma_f32_16x16x32_bf16 v[80:83], v[160:163], v[202:205], v[80:83]
	v_mfma_f32_16x16x32_bf16 v[72:75], v[144:147], v[210:213], v[72:75]
	v_mfma_f32_16x16x32_bf16 v[64:67], v[160:163], v[210:213], v[64:67]
	v_mfma_f32_16x16x32_bf16 v[116:119], v[156:159], v[190:193], v[116:119]
	v_mfma_f32_16x16x32_bf16 v[112:115], v[164:167], v[190:193], v[112:115]
	v_mfma_f32_16x16x32_bf16 v[100:103], v[156:159], v[198:201], v[100:103]
	v_mfma_f32_16x16x32_bf16 v[96:99], v[164:167], v[198:201], v[96:99]
	v_mfma_f32_16x16x32_bf16 v[84:87], v[156:159], v[206:209], v[84:87]
	v_mfma_f32_16x16x32_bf16 v[80:83], v[164:167], v[206:209], v[80:83]
	v_mfma_f32_16x16x32_bf16 v[72:75], v[156:159], v[214:217], v[72:75]
	v_mfma_f32_16x16x32_bf16 v[64:67], v[164:167], v[214:217], v[64:67]
	v_mfma_f32_16x16x32_bf16 v[124:127], v[168:171], v[184:187], v[124:127]
	v_mfma_f32_16x16x32_bf16 v[120:123], v[176:179], v[184:187], v[120:123]
	v_mfma_f32_16x16x32_bf16 v[108:111], v[168:171], v[194:197], v[108:111]
	v_mfma_f32_16x16x32_bf16 v[104:107], v[176:179], v[194:197], v[104:107]
	v_mfma_f32_16x16x32_bf16 v[92:95], v[168:171], v[202:205], v[92:95]
	v_mfma_f32_16x16x32_bf16 v[88:91], v[176:179], v[202:205], v[88:91]
	v_mfma_f32_16x16x32_bf16 v[76:79], v[168:171], v[210:213], v[76:79]
	v_mfma_f32_16x16x32_bf16 v[68:71], v[176:179], v[210:213], v[68:71]
	v_mfma_f32_16x16x32_bf16 v[124:127], v[172:175], v[190:193], v[124:127]
	v_mfma_f32_16x16x32_bf16 v[120:123], v[180:183], v[190:193], v[120:123]
	v_mfma_f32_16x16x32_bf16 v[108:111], v[172:175], v[198:201], v[108:111]
	v_mfma_f32_16x16x32_bf16 v[104:107], v[180:183], v[198:201], v[104:107]
	v_mfma_f32_16x16x32_bf16 v[92:95], v[172:175], v[206:209], v[92:95]
	v_mfma_f32_16x16x32_bf16 v[88:91], v[180:183], v[206:209], v[88:91]
	v_mfma_f32_16x16x32_bf16 v[76:79], v[172:175], v[214:217], v[76:79]
	v_mfma_f32_16x16x32_bf16 v[68:71], v[180:183], v[214:217], v[68:71]
	s_setprio 0
	s_barrier
	s_add_i32 s52, s43, s30
	v_lshl_add_u64 v[218:219], s[24:25], 0, v[132:133]
	s_mov_b32 m0, s52
	ds_read_b128 v[184:187], v153 offset:16384
	ds_read_b128 v[190:193], v153 offset:17408
	ds_read_b128 v[194:197], v153 offset:18432
	ds_read_b128 v[198:201], v153 offset:19456
	ds_read_b128 v[202:205], v153 offset:20480
	ds_read_b128 v[206:209], v153 offset:21504
	ds_read_b128 v[210:213], v153 offset:22528
	ds_read_b128 v[214:217], v153 offset:23552
	global_load_lds_dwordx4 v[218:219], off
	s_add_i32 m0, s52, 0x2000
	s_add_u32 s52, s24, 0x40000
	v_lshl_add_u64 v[220:221], s[24:25], 0, v[128:129]
	s_addc_u32 s53, s25, 0
	s_add_i32 s54, s44, s30
	global_load_lds_dwordx4 v[220:221], off
	v_lshl_add_u64 v[222:223], s[52:53], 0, v[132:133]
	s_mov_b32 m0, s54
	v_lshl_add_u64 v[224:225], s[26:27], 0, v[130:131]
	global_load_lds_dwordx4 v[222:223], off
	v_lshl_add_u64 v[222:223], s[52:53], 0, v[128:129]
	s_add_i32 m0, s54, 0x2000
	s_nop 0
	global_load_lds_dwordx4 v[222:223], off
	v_lshl_add_u64 v[222:223], s[26:27], 0, v[134:135]
	s_mov_b32 m0, s34
	s_nop 0
	global_load_lds_dwordx4 v[222:223], off
	s_mov_b32 m0, s35
	s_nop 0
	global_load_lds_dwordx4 v[224:225], off
	s_waitcnt vmcnt(8)
	s_waitcnt lgkmcnt(0)
	s_barrier
; #define PG8_STAGE(bufoff, gbase, voff) do { _Pragma("unroll") for (int _i = 0; _i < 2; ++_i) \
;         __builtin_amdgcn_global_load_lds((const unsigned*)((const char*)(gbase) + (voff)[_i]), (PG8_LAS unsigned*)(lds + (bufoff) + ldsw + _i * 8192), 16, 0, 0); } while (0)
; #define PG8_LDA(dst, b, h) do { _Pragma("unroll") for (int m = 0; m < 4; ++m) _Pragma("unroll") for (int k = 0; k < 2; ++k) dst[m][k] = *(const PG8_LAS bf16x8*)(lds + PG8_SA(b, h) + aoff + m * 2048 + k * 1024); } while (0)
; #define PG8_LDB(dst, b, h) do { _Pragma("unroll") for (int n = 0; n < 2; ++n) _Pragma("unroll") for (int k = 0; k < 2; ++k) dst[n][k] = *(const PG8_LAS bf16x8*)(lds + PG8_SB(b, h) + boff + n * 2048 + k * 1024); } while (0)
; #define PG8_MMA(ai, bj, At, Bt) do { __builtin_amdgcn_s_setprio(1); _Pragma("unroll") for (int m = 0; m < 4; ++m) _Pragma("unroll") for (int n = 0; n < 2; ++n) _Pragma("unroll") for (int k = 0; k < 2; ++k) \
;         acc[ai][bj][m][n] = __builtin_amdgcn_mfma_f32_16x16x32_bf16(Bt[n][k], At[m][k], acc[ai][bj][m][n], 0, 0, 0); __builtin_amdgcn_s_setprio(0); } while (0)
; #define PG8_WAIT_V(n) asm volatile("s_waitcnt vmcnt(" #n ")" ::: "memory")
; #define PG8_WAIT_L(n) asm volatile("s_waitcnt lgkmcnt(" #n ")" ::: "memory")
; #define PG8_BAR __builtin_amdgcn_s_barrier()
; #define PG8_SCHED __builtin_amdgcn_sched_barrier(0)
; template <class Epi, class Sched, bool ALIGN_EPI = false, bool SP2 = false>
; __device__ __forceinline__ void gemm_phase(PG8_LAS unsigned char* lds, const Gemm g, const Sched& S, const Epi& E) {
;     ...
;             PG8_WAIT_V(8); PG8_WAIT_L(0); PG8_BAR; PG8_MMA(1, 0, At, B0); PG8_MMA(1, 1, At, B1); PG8_BAR; PG8_SCHED;
;             PG8_LDB(B0, 1, 0); PG8_LDB(B1, 1, 1); PG8_SCHED; PG8_LDA(At, 1, 0); PG8_STAGE(PG8_SA(0, 1), a2 + hstep, voffA);
;             PG8_WAIT_V(8); PG8_WAIT_L(0); PG8_BAR; PG8_MMA(0, 0, At, B0); PG8_MMA(0, 1, At, B1); PG8_BAR; PG8_SCHED;
	s_setprio 1
	v_mfma_f32_16x16x32_bf16 v[56:59], v[144:147], v[184:187], v[56:59]
	v_mfma_f32_16x16x32_bf16 v[48:51], v[160:163], v[184:187], v[48:51]
	v_mfma_f32_16x16x32_bf16 v[40:43], v[144:147], v[194:197], v[40:43]
	v_mfma_f32_16x16x32_bf16 v[32:35], v[160:163], v[194:197], v[32:35]
	v_mfma_f32_16x16x32_bf16 v[24:27], v[144:147], v[202:205], v[24:27]
	v_mfma_f32_16x16x32_bf16 v[16:19], v[160:163], v[202:205], v[16:19]
	v_mfma_f32_16x16x32_bf16 v[8:11], v[144:147], v[210:213], v[8:11]
	v_mfma_f32_16x16x32_bf16 v[0:3], v[160:163], v[210:213], v[0:3]
	v_mfma_f32_16x16x32_bf16 v[56:59], v[156:159], v[190:193], v[56:59]
	v_mfma_f32_16x16x32_bf16 v[48:51], v[164:167], v[190:193], v[48:51]
	v_mfma_f32_16x16x32_bf16 v[40:43], v[156:159], v[198:201], v[40:43]
	v_mfma_f32_16x16x32_bf16 v[32:35], v[164:167], v[198:201], v[32:35]
	v_mfma_f32_16x16x32_bf16 v[24:27], v[156:159], v[206:209], v[24:27]
	v_mfma_f32_16x16x32_bf16 v[16:19], v[164:167], v[206:209], v[16:19]
	v_mfma_f32_16x16x32_bf16 v[8:11], v[156:159], v[214:217], v[8:11]
	v_mfma_f32_16x16x32_bf16 v[0:3], v[164:167], v[214:217], v[0:3]
	v_mfma_f32_16x16x32_bf16 v[60:63], v[168:171], v[184:187], v[60:63]
	v_mfma_f32_16x16x32_bf16 v[52:55], v[176:179], v[184:187], v[52:55]
	v_mfma_f32_16x16x32_bf16 v[44:47], v[168:171], v[194:197], v[44:47]
	v_mfma_f32_16x16x32_bf16 v[36:39], v[176:179], v[194:197], v[36:39]
	v_mfma_f32_16x16x32_bf16 v[28:31], v[168:171], v[202:205], v[28:31]
	v_mfma_f32_16x16x32_bf16 v[20:23], v[176:179], v[202:205], v[20:23]
	v_mfma_f32_16x16x32_bf16 v[12:15], v[168:171], v[210:213], v[12:15]
	v_mfma_f32_16x16x32_bf16 v[4:7], v[176:179], v[210:213], v[4:7]
	v_mfma_f32_16x16x32_bf16 v[60:63], v[172:175], v[190:193], v[60:63]
	v_mfma_f32_16x16x32_bf16 v[52:55], v[180:183], v[190:193], v[52:55]
	v_mfma_f32_16x16x32_bf16 v[44:47], v[172:175], v[198:201], v[44:47]
	v_mfma_f32_16x16x32_bf16 v[36:39], v[180:183], v[198:201], v[36:39]
	v_mfma_f32_16x16x32_bf16 v[28:31], v[172:175], v[206:209], v[28:31]
	v_mfma_f32_16x16x32_bf16 v[20:23], v[180:183], v[206:209], v[20:23]
	v_mfma_f32_16x16x32_bf16 v[12:15], v[172:175], v[214:217], v[12:15]
	v_mfma_f32_16x16x32_bf16 v[4:7], v[180:183], v[214:217], v[4:7]
	s_setprio 0
	s_barrier
	s_add_i32 s52, 0, 0x18000
	v_add_u32_e32 v155, s52, v149
	s_add_i32 s53, 0, 0x1c000
	ds_read_b128 v[144:147], v155
	ds_read_b128 v[156:159], v155 offset:1024
	ds_read_b128 v[160:163], v155 offset:2048
	ds_read_b128 v[164:167], v155 offset:3072
	v_add_u32_e32 v155, s53, v149
	ds_read_b128 v[168:171], v155
	ds_read_b128 v[172:175], v155 offset:1024
	ds_read_b128 v[176:179], v155 offset:2048
	ds_read_b128 v[180:183], v155 offset:3072
	s_add_u32 s26, s26, 0x40000
	s_addc_u32 s27, s27, 0
	s_mov_b32 m0, s36
	v_lshl_add_u64 v[226:227], s[26:27], 0, v[134:135]
	ds_read_b128 v[184:187], v153 offset:32768
	ds_read_b128 v[190:193], v153 offset:33792
	ds_read_b128 v[194:197], v153 offset:34816
	ds_read_b128 v[198:201], v153 offset:35840
	ds_read_b128 v[202:205], v153 offset:36864
	ds_read_b128 v[206:209], v153 offset:37888
	ds_read_b128 v[210:213], v153 offset:38912
	ds_read_b128 v[214:217], v153 offset:39936
	global_load_lds_dwordx4 v[226:227], off
	v_lshl_add_u64 v[226:227], s[26:27], 0, v[130:131]
	s_mov_b32 m0, s37
	s_nop 0
	global_load_lds_dwordx4 v[226:227], off
	s_waitcnt vmcnt(8)
	s_waitcnt lgkmcnt(0)
	s_barrier
	s_setprio 1
	v_mfma_f32_16x16x32_bf16 v[116:119], v[144:147], v[184:187], v[116:119]
	v_mfma_f32_16x16x32_bf16 v[112:115], v[160:163], v[184:187], v[112:115]
	v_mfma_f32_16x16x32_bf16 v[100:103], v[144:147], v[194:197], v[100:103]
	v_mfma_f32_16x16x32_bf16 v[96:99], v[160:163], v[194:197], v[96:99]
	v_mfma_f32_16x16x32_bf16 v[84:87], v[144:147], v[202:205], v[84:87]
	v_mfma_f32_16x16x32_bf16 v[80:83], v[160:163], v[202:205], v[80:83]
	v_mfma_f32_16x16x32_bf16 v[72:75], v[144:147], v[210:213], v[72:75]
	v_mfma_f32_16x16x32_bf16 v[64:67], v[160:163], v[210:213], v[64:67]
	v_mfma_f32_16x16x32_bf16 v[116:119], v[156:159], v[190:193], v[116:119]
	v_mfma_f32_16x16x32_bf16 v[112:115], v[164:167], v[190:193], v[112:115]
	v_mfma_f32_16x16x32_bf16 v[100:103], v[156:159], v[198:201], v[100:103]
	v_mfma_f32_16x16x32_bf16 v[96:99], v[164:167], v[198:201], v[96:99]
	v_mfma_f32_16x16x32_bf16 v[84:87], v[156:159], v[206:209], v[84:87]
	v_mfma_f32_16x16x32_bf16 v[80:83], v[164:167], v[206:209], v[80:83]
	v_mfma_f32_16x16x32_bf16 v[72:75], v[156:159], v[214:217], v[72:75]
	v_mfma_f32_16x16x32_bf16 v[64:67], v[164:167], v[214:217], v[64:67]
	v_mfma_f32_16x16x32_bf16 v[124:127], v[168:171], v[184:187], v[124:127]
	v_mfma_f32_16x16x32_bf16 v[120:123], v[176:179], v[184:187], v[120:123]
	v_mfma_f32_16x16x32_bf16 v[108:111], v[168:171], v[194:197], v[108:111]
	v_mfma_f32_16x16x32_bf16 v[104:107], v[176:179], v[194:197], v[104:107]
	v_mfma_f32_16x16x32_bf16 v[92:95], v[168:171], v[202:205], v[92:95]
	v_mfma_f32_16x16x32_bf16 v[88:91], v[176:179], v[202:205], v[88:91]
	v_mfma_f32_16x16x32_bf16 v[76:79], v[168:171], v[210:213], v[76:79]
	v_mfma_f32_16x16x32_bf16 v[68:71], v[176:179], v[210:213], v[68:71]
	v_mfma_f32_16x16x32_bf16 v[124:127], v[172:175], v[190:193], v[124:127]
	v_mfma_f32_16x16x32_bf16 v[120:123], v[180:183], v[190:193], v[120:123]
	v_mfma_f32_16x16x32_bf16 v[108:111], v[172:175], v[198:201], v[108:111]
	v_mfma_f32_16x16x32_bf16 v[104:107], v[180:183], v[198:201], v[104:107]
	v_mfma_f32_16x16x32_bf16 v[92:95], v[172:175], v[206:209], v[92:95]
	v_mfma_f32_16x16x32_bf16 v[88:91], v[180:183], v[206:209], v[88:91]
	v_mfma_f32_16x16x32_bf16 v[76:79], v[172:175], v[214:217], v[76:79]
	v_mfma_f32_16x16x32_bf16 v[68:71], v[180:183], v[214:217], v[68:71]
	s_setprio 0
	s_barrier
; #define PG8_STAGE(bufoff, gbase, voff) do { _Pragma("unroll") for (int _i = 0; _i < 2; ++_i) \
;         __builtin_amdgcn_global_load_lds((const unsigned*)((const char*)(gbase) + (voff)[_i]), (PG8_LAS unsigned*)(lds + (bufoff) + ldsw + _i * 8192), 16, 0, 0); } while (0)
; #define PG8_LDA(dst, b, h) do { _Pragma("unroll") for (int m = 0; m < 4; ++m) _Pragma("unroll") for (int k = 0; k < 2; ++k) dst[m][k] = *(const PG8_LAS bf16x8*)(lds + PG8_SA(b, h) + aoff + m * 2048 + k * 1024); } while (0)
; #define PG8_MMA(ai, bj, At, Bt) do { __builtin_amdgcn_s_setprio(1); _Pragma("unroll") for (int m = 0; m < 4; ++m) _Pragma("unroll") for (int n = 0; n < 2; ++n) _Pragma("unroll") for (int k = 0; k < 2; ++k) \
;         acc[ai][bj][m][n] = __builtin_amdgcn_mfma_f32_16x16x32_bf16(Bt[n][k], At[m][k], acc[ai][bj][m][n], 0, 0, 0); __builtin_amdgcn_s_setprio(0); } while (0)
; #define PG8_WAIT_V(n) asm volatile("s_waitcnt vmcnt(" #n ")" ::: "memory")
; #define PG8_WAIT_L(n) asm volatile("s_waitcnt lgkmcnt(" #n ")" ::: "memory")
; #define PG8_BAR __builtin_amdgcn_s_barrier()
; #define PG8_SCHED __builtin_amdgcn_sched_barrier(0)
; template <class Epi, class Sched, bool ALIGN_EPI = false, bool SP2 = false>
; __device__ __forceinline__ void gemm_phase(PG8_LAS unsigned char* lds, const Gemm g, const Sched& S, const Epi& E) {
;     ...
;             PG8_LDA(At, 1, 1); PG8_STAGE(PG8_SB(1, 0), b3, voffB); PG8_STAGE(PG8_SB(1, 1), b3 + hstep, voffB); PG8_STAGE(PG8_SA(1, 0), a3, voffA);
;             PG8_WAIT_V(8); PG8_WAIT_L(0); PG8_BAR; PG8_MMA(1, 0, At, B0); PG8_MMA(1, 1, At, B1); PG8_BAR; PG8_SCHED;
;     ...
;         if constexpr (ALIGN_EPI) { if (wr == 0) PG8_BAR; }
	s_add_i32 s26, s52, s30
	v_lshl_add_u64 v[218:219], v[218:219], 0, s[6:7]
	s_mov_b32 m0, s26
	ds_read_b128 v[184:187], v153 offset:49152
	ds_read_b128 v[190:193], v153 offset:50176
	ds_read_b128 v[194:197], v153 offset:51200
	ds_read_b128 v[198:201], v153 offset:52224
	ds_read_b128 v[202:205], v153 offset:53248
	ds_read_b128 v[206:209], v153 offset:54272
	ds_read_b128 v[210:213], v153 offset:55296
	ds_read_b128 v[214:217], v153 offset:56320
	global_load_lds_dwordx4 v[218:219], off
	s_add_i32 m0, s26, 0x2000
	s_add_u32 s24, s24, 0x40080
	v_lshl_add_u64 v[218:219], v[220:221], 0, s[6:7]
	s_addc_u32 s25, s25, 0
	s_add_i32 s26, s53, s30
	global_load_lds_dwordx4 v[218:219], off
	v_lshl_add_u64 v[218:219], s[24:25], 0, v[132:133]
	s_mov_b32 m0, s26
	s_nop 0
	global_load_lds_dwordx4 v[218:219], off
	v_lshl_add_u64 v[218:219], s[24:25], 0, v[128:129]
	s_add_i32 m0, s26, 0x2000
	s_nop 0
	global_load_lds_dwordx4 v[218:219], off
	v_lshl_add_u64 v[218:219], v[222:223], 0, s[6:7]
	s_mov_b32 m0, s39
	s_nop 0
	global_load_lds_dwordx4 v[218:219], off
	v_lshl_add_u64 v[218:219], v[224:225], 0, s[6:7]
	s_mov_b32 m0, s40
	s_nop 0
	global_load_lds_dwordx4 v[218:219], off
	s_waitcnt vmcnt(8)
	s_waitcnt lgkmcnt(0)
	s_barrier
	s_setprio 1
	v_mfma_f32_16x16x32_bf16 v[56:59], v[144:147], v[184:187], v[56:59]
	v_mfma_f32_16x16x32_bf16 v[48:51], v[160:163], v[184:187], v[48:51]
	v_mfma_f32_16x16x32_bf16 v[40:43], v[144:147], v[194:197], v[40:43]
	v_mfma_f32_16x16x32_bf16 v[32:35], v[160:163], v[194:197], v[32:35]
	v_mfma_f32_16x16x32_bf16 v[24:27], v[144:147], v[202:205], v[24:27]
	v_mfma_f32_16x16x32_bf16 v[16:19], v[160:163], v[202:205], v[16:19]
	v_mfma_f32_16x16x32_bf16 v[8:11], v[144:147], v[210:213], v[8:11]
	v_mfma_f32_16x16x32_bf16 v[0:3], v[160:163], v[210:213], v[0:3]
	v_mfma_f32_16x16x32_bf16 v[56:59], v[156:159], v[190:193], v[56:59]
	v_mfma_f32_16x16x32_bf16 v[48:51], v[164:167], v[190:193], v[48:51]
	v_mfma_f32_16x16x32_bf16 v[40:43], v[156:159], v[198:201], v[40:43]
	v_mfma_f32_16x16x32_bf16 v[32:35], v[164:167], v[198:201], v[32:35]
	v_mfma_f32_16x16x32_bf16 v[24:27], v[156:159], v[206:209], v[24:27]
	v_mfma_f32_16x16x32_bf16 v[16:19], v[164:167], v[206:209], v[16:19]
	v_mfma_f32_16x16x32_bf16 v[8:11], v[156:159], v[214:217], v[8:11]
	v_mfma_f32_16x16x32_bf16 v[0:3], v[164:167], v[214:217], v[0:3]
	v_mfma_f32_16x16x32_bf16 v[60:63], v[168:171], v[184:187], v[60:63]
	v_mfma_f32_16x16x32_bf16 v[52:55], v[176:179], v[184:187], v[52:55]
	v_mfma_f32_16x16x32_bf16 v[44:47], v[168:171], v[194:197], v[44:47]
	v_mfma_f32_16x16x32_bf16 v[36:39], v[176:179], v[194:197], v[36:39]
	v_mfma_f32_16x16x32_bf16 v[28:31], v[168:171], v[202:205], v[28:31]
	v_mfma_f32_16x16x32_bf16 v[20:23], v[176:179], v[202:205], v[20:23]
	v_mfma_f32_16x16x32_bf16 v[12:15], v[168:171], v[210:213], v[12:15]
	v_mfma_f32_16x16x32_bf16 v[4:7], v[176:179], v[210:213], v[4:7]
	v_mfma_f32_16x16x32_bf16 v[60:63], v[172:175], v[190:193], v[60:63]
	v_mfma_f32_16x16x32_bf16 v[52:55], v[180:183], v[190:193], v[52:55]
	v_mfma_f32_16x16x32_bf16 v[44:47], v[172:175], v[198:201], v[44:47]
	v_mfma_f32_16x16x32_bf16 v[36:39], v[180:183], v[198:201], v[36:39]
	v_mfma_f32_16x16x32_bf16 v[28:31], v[172:175], v[206:209], v[28:31]
	v_mfma_f32_16x16x32_bf16 v[20:23], v[180:183], v[206:209], v[20:23]
	v_mfma_f32_16x16x32_bf16 v[12:15], v[172:175], v[214:217], v[12:15]
	v_mfma_f32_16x16x32_bf16 v[4:7], v[180:183], v[214:217], v[4:7]
	s_setprio 0
	s_nop 0
	s_add_i32 s51, s51, 2
	s_add_u32 s22, s22, 0x100
	s_addc_u32 s23, s23, 0
	s_add_u32 s49, s49, 0x100
	s_addc_u32 s50, s50, 0
	s_cmp_gt_u32 s51, 13
	s_cbranch_scc0 .Lrot_782
	s_barrier
	s_and_b64 vcc, exec, s[12:13]
	s_cbranch_vccz .LBB0_785
	s_barrier

; #define PG8_STAGE(bufoff, gbase, voff) do { _Pragma("unroll") for (int _i = 0; _i < 2; ++_i) \
;         __builtin_amdgcn_global_load_lds((const unsigned*)((const char*)(gbase) + (voff)[_i]), (PG8_LAS unsigned*)(lds + (bufoff) + ldsw + _i * 8192), 16, 0, 0); } while (0)
; #define PG8_LDA(dst, b, h) do { _Pragma("unroll") for (int m = 0; m < 4; ++m) _Pragma("unroll") for (int k = 0; k < 2; ++k) dst[m][k] = *(const PG8_LAS bf16x8*)(lds + PG8_SA(b, h) + aoff + m * 2048 + k * 1024); } while (0)
; #define PG8_LDB(dst, b, h) do { _Pragma("unroll") for (int n = 0; n < 2; ++n) _Pragma("unroll") for (int k = 0; k < 2; ++k) dst[n][k] = *(const PG8_LAS bf16x8*)(lds + PG8_SB(b, h) + boff + n * 2048 + k * 1024); } while (0)
; #define PG8_MMA(ai, bj, At, Bt) do { __builtin_amdgcn_s_setprio(1); _Pragma("unroll") for (int m = 0; m < 4; ++m) _Pragma("unroll") for (int n = 0; n < 2; ++n) _Pragma("unroll") for (int k = 0; k < 2; ++k) \
;         acc[ai][bj][m][n] = __builtin_amdgcn_mfma_f32_16x16x32_bf16(Bt[n][k], At[m][k], acc[ai][bj][m][n], 0, 0, 0); __builtin_amdgcn_s_setprio(0); } while (0)
; #define PG8_WAIT_V(n) asm volatile("s_waitcnt vmcnt(" #n ")" ::: "memory")
; template <class Epi, class Sched, bool ALIGN_EPI = false, bool SP2 = false>
; __device__ __forceinline__ void gemm_phase(PG8_LAS unsigned char* lds, const Gemm g, const Sched& S, const Epi& E) {
;     ...
;         const char* nA = has_next ? (const char*)g.A + (size_t)nxt.pm * tstep : cA; const char* nB = has_next ? (const char*)g.Bt + (size_t)nxt.pn * tstep : cB;
;         for (int t = 0; t < nt; t += 2) {
;             const bool last = (t == nt - 2);
;             const char* a1 = cA + (size_t)(t + 1) * kstep;
;             const char* a2 = last ? nA : cA + (size_t)(t + 2) * kstep; const char* b2 = last ? nB : cB + (size_t)(t + 2) * kstep;
;             const char* a3 = a2 + kstep; const char* b3 = b2 + kstep;
;             if (last && has_next) S.a_ready(nxt);
;             if constexpr (SP2) {
;             PG8_LDB(B0, 0, 0); PG8_LDB(B1, 0, 1); PG8_SCHED; PG8_LDA(At, 0, 0); PG8_STAGE(PG8_SA(1, 1), a1 + hstep, voffA);
;             PG8_WAIT_V(8); PG8_WAIT_L(0); PG8_BAR; PG8_MMA(0, 0, At, B0); PG8_MMA(0, 1, At, B1); PG8_BAR; PG8_SCHED;
;             PG8_LDA(At, 0, 1); PG8_STAGE(PG8_SB(0, 0), b2, voffB); PG8_STAGE(PG8_SB(0, 1), b2 + hstep, voffB); PG8_STAGE(PG8_SA(0, 0), a2, voffA);
.LBB0_861:
	s_add_u32 s49, s24, 0x100
	s_addc_u32 s50, s25, 0
	s_mov_b32 s51, -2
	ds_read_b128 v[144:147], v153
	ds_read_b128 v[156:159], v153 offset:1024
	ds_read_b128 v[160:163], v153 offset:2048
	ds_read_b128 v[164:167], v153 offset:3072
	ds_read_b128 v[168:171], v154
	ds_read_b128 v[172:175], v154 offset:1024
	ds_read_b128 v[176:179], v154 offset:2048
	ds_read_b128 v[180:183], v154 offset:3072
	s_add_u32 s24, s22, 0x100
	s_addc_u32 s25, s23, 0
	s_cmp_eq_u32 s51, 40
	s_cselect_b32 s29, s5, s25
	s_cselect_b32 s28, s4, s24
	s_cselect_b32 s27, s21, s50
	s_cselect_b32 s26, s20, s49
	v_lshl_add_u64 v[148:149], s[22:23], 0, v[136:137]
	s_add_i32 m0, s35, 0xc000
	ds_read_b128 v[184:187], v155
	ds_read_b128 v[188:191], v155 offset:1024
	ds_read_b128 v[192:195], v155 offset:2048
	ds_read_b128 v[196:199], v155 offset:3072
	ds_read_b128 v[200:203], v155 offset:4096
	ds_read_b128 v[204:207], v155 offset:5120
	ds_read_b128 v[208:211], v155 offset:6144
	ds_read_b128 v[212:215], v155 offset:7168
	global_load_lds_dwordx4 v[148:149], off
	v_lshl_add_u64 v[148:149], s[22:23], 0, v[138:139]
	s_add_i32 m0, s35, 0xe000
	s_nop 0
	global_load_lds_dwordx4 v[148:149], off
	s_waitcnt vmcnt(8)
	s_waitcnt lgkmcnt(0)
	s_barrier
	s_setprio 1
	v_mfma_f32_16x16x32_bf16 v[124:127], v[144:147], v[184:187], 0
	v_mfma_f32_16x16x32_bf16 v[120:123], v[160:163], v[184:187], 0
	v_mfma_f32_16x16x32_bf16 v[108:111], v[144:147], v[192:195], 0
	v_mfma_f32_16x16x32_bf16 v[104:107], v[160:163], v[192:195], 0
	v_mfma_f32_16x16x32_bf16 v[92:95], v[144:147], v[200:203], 0
	v_mfma_f32_16x16x32_bf16 v[88:91], v[160:163], v[200:203], 0
	v_mfma_f32_16x16x32_bf16 v[76:79], v[144:147], v[208:211], 0
	v_mfma_f32_16x16x32_bf16 v[72:75], v[160:163], v[208:211], 0
	v_mfma_f32_16x16x32_bf16 v[124:127], v[156:159], v[188:191], v[124:127]
	v_mfma_f32_16x16x32_bf16 v[120:123], v[164:167], v[188:191], v[120:123]
	v_mfma_f32_16x16x32_bf16 v[108:111], v[156:159], v[196:199], v[108:111]
	v_mfma_f32_16x16x32_bf16 v[104:107], v[164:167], v[196:199], v[104:107]
	v_mfma_f32_16x16x32_bf16 v[92:95], v[156:159], v[204:207], v[92:95]
	v_mfma_f32_16x16x32_bf16 v[88:91], v[164:167], v[204:207], v[88:91]
	v_mfma_f32_16x16x32_bf16 v[76:79], v[156:159], v[212:215], v[76:79]
	v_mfma_f32_16x16x32_bf16 v[72:75], v[164:167], v[212:215], v[72:75]
	v_mfma_f32_16x16x32_bf16 v[116:119], v[168:171], v[184:187], 0
	v_mfma_f32_16x16x32_bf16 v[112:115], v[176:179], v[184:187], 0
	v_mfma_f32_16x16x32_bf16 v[100:103], v[168:171], v[192:195], 0
	v_mfma_f32_16x16x32_bf16 v[96:99], v[176:179], v[192:195], 0
	v_mfma_f32_16x16x32_bf16 v[84:87], v[168:171], v[200:203], 0
	v_mfma_f32_16x16x32_bf16 v[80:83], v[176:179], v[200:203], 0
	v_mfma_f32_16x16x32_bf16 v[68:71], v[168:171], v[208:211], 0
	v_mfma_f32_16x16x32_bf16 v[64:67], v[176:179], v[208:211], 0
	v_mfma_f32_16x16x32_bf16 v[116:119], v[172:175], v[188:191], v[116:119]
	v_mfma_f32_16x16x32_bf16 v[112:115], v[180:183], v[188:191], v[112:115]
	v_mfma_f32_16x16x32_bf16 v[100:103], v[172:175], v[196:199], v[100:103]
	v_mfma_f32_16x16x32_bf16 v[96:99], v[180:183], v[196:199], v[96:99]
	v_mfma_f32_16x16x32_bf16 v[84:87], v[172:175], v[204:207], v[84:87]
	v_mfma_f32_16x16x32_bf16 v[80:83], v[180:183], v[204:207], v[80:83]
	v_mfma_f32_16x16x32_bf16 v[68:71], v[172:175], v[212:215], v[68:71]
	v_mfma_f32_16x16x32_bf16 v[64:67], v[180:183], v[212:215], v[64:67]
	s_setprio 0
	s_barrier
	s_add_i32 s22, s43, s34
	v_lshl_add_u64 v[148:149], s[26:27], 0, v[130:131]
	s_mov_b32 m0, s22
	ds_read_b128 v[184:187], v155 offset:16384
	ds_read_b128 v[188:191], v155 offset:17408
	ds_read_b128 v[192:195], v155 offset:18432
	ds_read_b128 v[196:199], v155 offset:19456
	ds_read_b128 v[200:203], v155 offset:20480
	ds_read_b128 v[204:207], v155 offset:21504
	ds_read_b128 v[208:211], v155 offset:22528
	ds_read_b128 v[212:215], v155 offset:23552
	global_load_lds_dwordx4 v[148:149], off
	s_add_i32 m0, s22, 0x2000
	s_add_u32 s22, s26, 0xb0000
	v_lshl_add_u64 v[216:217], s[26:27], 0, v[134:135]
	s_addc_u32 s23, s27, 0
	s_add_i32 s52, s44, s34
	global_load_lds_dwordx4 v[216:217], off
	v_lshl_add_u64 v[218:219], s[22:23], 0, v[130:131]
	s_mov_b32 m0, s52
	v_lshl_add_u64 v[220:221], s[28:29], 0, v[132:133]
	global_load_lds_dwordx4 v[218:219], off
	v_lshl_add_u64 v[218:219], s[22:23], 0, v[134:135]
	s_add_i32 m0, s52, 0x2000
	s_nop 0
	global_load_lds_dwordx4 v[218:219], off
	v_lshl_add_u64 v[218:219], s[28:29], 0, v[128:129]
	s_mov_b32 m0, s35
	s_nop 0
	global_load_lds_dwordx4 v[218:219], off
	s_mov_b32 m0, s36
	s_nop 0
	global_load_lds_dwordx4 v[220:221], off
	s_waitcnt vmcnt(8)
	s_waitcnt lgkmcnt(0)
	s_barrier
; #define PG8_STAGE(bufoff, gbase, voff) do { _Pragma("unroll") for (int _i = 0; _i < 2; ++_i) \
;         __builtin_amdgcn_global_load_lds((const unsigned*)((const char*)(gbase) + (voff)[_i]), (PG8_LAS unsigned*)(lds + (bufoff) + ldsw + _i * 8192), 16, 0, 0); } while (0)
; #define PG8_LDA(dst, b, h) do { _Pragma("unroll") for (int m = 0; m < 4; ++m) _Pragma("unroll") for (int k = 0; k < 2; ++k) dst[m][k] = *(const PG8_LAS bf16x8*)(lds + PG8_SA(b, h) + aoff + m * 2048 + k * 1024); } while (0)
; #define PG8_LDB(dst, b, h) do { _Pragma("unroll") for (int n = 0; n < 2; ++n) _Pragma("unroll") for (int k = 0; k < 2; ++k) dst[n][k] = *(const PG8_LAS bf16x8*)(lds + PG8_SB(b, h) + boff + n * 2048 + k * 1024); } while (0)
; #define PG8_MMA(ai, bj, At, Bt) do { __builtin_amdgcn_s_setprio(1); _Pragma("unroll") for (int m = 0; m < 4; ++m) _Pragma("unroll") for (int n = 0; n < 2; ++n) _Pragma("unroll") for (int k = 0; k < 2; ++k) \
;         acc[ai][bj][m][n] = __builtin_amdgcn_mfma_f32_16x16x32_bf16(Bt[n][k], At[m][k], acc[ai][bj][m][n], 0, 0, 0); __builtin_amdgcn_s_setprio(0); } while (0)
; #define PG8_WAIT_V(n) asm volatile("s_waitcnt vmcnt(" #n ")" ::: "memory")
; #define PG8_WAIT_L(n) asm volatile("s_waitcnt lgkmcnt(" #n ")" ::: "memory")
; #define PG8_BAR __builtin_amdgcn_s_barrier()
; #define PG8_SCHED __builtin_amdgcn_sched_barrier(0)
; template <class Epi, class Sched, bool ALIGN_EPI = false, bool SP2 = false>
; __device__ __forceinline__ void gemm_phase(PG8_LAS unsigned char* lds, const Gemm g, const Sched& S, const Epi& E) {
;     ...
;             PG8_WAIT_V(8); PG8_WAIT_L(0); PG8_BAR; PG8_MMA(0, 0, At, B0); PG8_MMA(0, 1, At, B1); PG8_BAR; PG8_SCHED;
;             PG8_LDA(At, 0, 1); PG8_STAGE(PG8_SB(0, 0), b2, voffB); PG8_STAGE(PG8_SB(0, 1), b2 + hstep, voffB); PG8_STAGE(PG8_SA(0, 0), a2, voffA);
;             PG8_WAIT_V(8); PG8_WAIT_L(0); PG8_BAR; PG8_MMA(1, 0, At, B0); PG8_MMA(1, 1, At, B1); PG8_BAR; PG8_SCHED;
;             PG8_LDB(B0, 1, 0); PG8_LDB(B1, 1, 1); PG8_SCHED; PG8_LDA(At, 1, 0); PG8_STAGE(PG8_SA(0, 1), a2 + hstep, voffA);
;             PG8_WAIT_V(8); PG8_WAIT_L(0); PG8_BAR; PG8_MMA(0, 0, At, B0); PG8_MMA(0, 1, At, B1); PG8_BAR; PG8_SCHED;
	s_setprio 1
	v_mfma_f32_16x16x32_bf16 v[60:63], v[144:147], v[184:187], 0
	v_mfma_f32_16x16x32_bf16 v[56:59], v[160:163], v[184:187], 0
	v_mfma_f32_16x16x32_bf16 v[44:47], v[144:147], v[192:195], 0
	v_mfma_f32_16x16x32_bf16 v[40:43], v[160:163], v[192:195], 0
	v_mfma_f32_16x16x32_bf16 v[28:31], v[144:147], v[200:203], 0
	v_mfma_f32_16x16x32_bf16 v[24:27], v[160:163], v[200:203], 0
	v_mfma_f32_16x16x32_bf16 v[12:15], v[144:147], v[208:211], 0
	v_mfma_f32_16x16x32_bf16 v[8:11], v[160:163], v[208:211], 0
	v_mfma_f32_16x16x32_bf16 v[60:63], v[156:159], v[188:191], v[60:63]
	v_mfma_f32_16x16x32_bf16 v[56:59], v[164:167], v[188:191], v[56:59]
	v_mfma_f32_16x16x32_bf16 v[44:47], v[156:159], v[196:199], v[44:47]
	v_mfma_f32_16x16x32_bf16 v[40:43], v[164:167], v[196:199], v[40:43]
	v_mfma_f32_16x16x32_bf16 v[28:31], v[156:159], v[204:207], v[28:31]
	v_mfma_f32_16x16x32_bf16 v[24:27], v[164:167], v[204:207], v[24:27]
	v_mfma_f32_16x16x32_bf16 v[12:15], v[156:159], v[212:215], v[12:15]
	v_mfma_f32_16x16x32_bf16 v[8:11], v[164:167], v[212:215], v[8:11]
	v_mfma_f32_16x16x32_bf16 v[52:55], v[168:171], v[184:187], 0
	v_mfma_f32_16x16x32_bf16 v[48:51], v[176:179], v[184:187], 0
	v_mfma_f32_16x16x32_bf16 v[36:39], v[168:171], v[192:195], 0
	v_mfma_f32_16x16x32_bf16 v[32:35], v[176:179], v[192:195], 0
	v_mfma_f32_16x16x32_bf16 v[20:23], v[168:171], v[200:203], 0
	v_mfma_f32_16x16x32_bf16 v[16:19], v[176:179], v[200:203], 0
	v_mfma_f32_16x16x32_bf16 v[4:7], v[168:171], v[208:211], 0
	v_mfma_f32_16x16x32_bf16 v[0:3], v[176:179], v[208:211], 0
	v_mfma_f32_16x16x32_bf16 v[52:55], v[172:175], v[188:191], v[52:55]
	v_mfma_f32_16x16x32_bf16 v[48:51], v[180:183], v[188:191], v[48:51]
	v_mfma_f32_16x16x32_bf16 v[36:39], v[172:175], v[196:199], v[36:39]
	v_mfma_f32_16x16x32_bf16 v[32:35], v[180:183], v[196:199], v[32:35]
	v_mfma_f32_16x16x32_bf16 v[20:23], v[172:175], v[204:207], v[20:23]
	v_mfma_f32_16x16x32_bf16 v[16:19], v[180:183], v[204:207], v[16:19]
	v_mfma_f32_16x16x32_bf16 v[4:7], v[172:175], v[212:215], v[4:7]
	v_mfma_f32_16x16x32_bf16 v[0:3], v[180:183], v[212:215], v[0:3]
	s_setprio 0
	s_barrier
	s_add_i32 s52, 0, 0x18000
	s_add_i32 s53, 0, 0x1c000
	v_add_u32_e32 v164, s52, v151
	v_add_u32_e32 v180, s53, v151
	ds_read_b128 v[144:147], v164
	ds_read_b128 v[156:159], v164 offset:1024
	ds_read_b128 v[160:163], v164 offset:2048
	ds_read_b128 v[164:167], v164 offset:3072
	ds_read_b128 v[168:171], v180
	ds_read_b128 v[172:175], v180 offset:1024
	ds_read_b128 v[176:179], v180 offset:2048
	ds_read_b128 v[180:183], v180 offset:3072
	s_add_u32 s22, s28, 0xb0000
	s_addc_u32 s23, s29, 0
	s_mov_b32 m0, s37
	v_lshl_add_u64 v[222:223], s[22:23], 0, v[128:129]
	ds_read_b128 v[184:187], v155 offset:32768
	ds_read_b128 v[188:191], v155 offset:33792
	ds_read_b128 v[192:195], v155 offset:34816
	ds_read_b128 v[196:199], v155 offset:35840
	ds_read_b128 v[200:203], v155 offset:36864
	ds_read_b128 v[204:207], v155 offset:37888
	ds_read_b128 v[208:211], v155 offset:38912
	ds_read_b128 v[212:215], v155 offset:39936
	global_load_lds_dwordx4 v[222:223], off
	v_lshl_add_u64 v[222:223], s[22:23], 0, v[132:133]
	s_mov_b32 m0, s38
	s_nop 0
	global_load_lds_dwordx4 v[222:223], off
	s_waitcnt vmcnt(8)
	s_waitcnt lgkmcnt(0)
	s_barrier
	s_setprio 1
	v_mfma_f32_16x16x32_bf16 v[124:127], v[144:147], v[184:187], v[124:127]
	v_mfma_f32_16x16x32_bf16 v[120:123], v[160:163], v[184:187], v[120:123]
	v_mfma_f32_16x16x32_bf16 v[108:111], v[144:147], v[192:195], v[108:111]
	v_mfma_f32_16x16x32_bf16 v[104:107], v[160:163], v[192:195], v[104:107]
	v_mfma_f32_16x16x32_bf16 v[92:95], v[144:147], v[200:203], v[92:95]
	v_mfma_f32_16x16x32_bf16 v[88:91], v[160:163], v[200:203], v[88:91]
	v_mfma_f32_16x16x32_bf16 v[76:79], v[144:147], v[208:211], v[76:79]
	v_mfma_f32_16x16x32_bf16 v[72:75], v[160:163], v[208:211], v[72:75]
	v_mfma_f32_16x16x32_bf16 v[124:127], v[156:159], v[188:191], v[124:127]
	v_mfma_f32_16x16x32_bf16 v[120:123], v[164:167], v[188:191], v[120:123]
	v_mfma_f32_16x16x32_bf16 v[108:111], v[156:159], v[196:199], v[108:111]
	v_mfma_f32_16x16x32_bf16 v[104:107], v[164:167], v[196:199], v[104:107]
	v_mfma_f32_16x16x32_bf16 v[92:95], v[156:159], v[204:207], v[92:95]
	v_mfma_f32_16x16x32_bf16 v[88:91], v[164:167], v[204:207], v[88:91]
	v_mfma_f32_16x16x32_bf16 v[76:79], v[156:159], v[212:215], v[76:79]
	v_mfma_f32_16x16x32_bf16 v[72:75], v[164:167], v[212:215], v[72:75]
	v_mfma_f32_16x16x32_bf16 v[116:119], v[168:171], v[184:187], v[116:119]
	v_mfma_f32_16x16x32_bf16 v[112:115], v[176:179], v[184:187], v[112:115]
	v_mfma_f32_16x16x32_bf16 v[100:103], v[168:171], v[192:195], v[100:103]
	v_mfma_f32_16x16x32_bf16 v[96:99], v[176:179], v[192:195], v[96:99]
	v_mfma_f32_16x16x32_bf16 v[84:87], v[168:171], v[200:203], v[84:87]
	v_mfma_f32_16x16x32_bf16 v[80:83], v[176:179], v[200:203], v[80:83]
	v_mfma_f32_16x16x32_bf16 v[68:71], v[168:171], v[208:211], v[68:71]
	v_mfma_f32_16x16x32_bf16 v[64:67], v[176:179], v[208:211], v[64:67]
	v_mfma_f32_16x16x32_bf16 v[116:119], v[172:175], v[188:191], v[116:119]
	v_mfma_f32_16x16x32_bf16 v[112:115], v[180:183], v[188:191], v[112:115]
	v_mfma_f32_16x16x32_bf16 v[100:103], v[172:175], v[196:199], v[100:103]
	v_mfma_f32_16x16x32_bf16 v[96:99], v[180:183], v[196:199], v[96:99]
	v_mfma_f32_16x16x32_bf16 v[84:87], v[172:175], v[204:207], v[84:87]
	v_mfma_f32_16x16x32_bf16 v[80:83], v[180:183], v[204:207], v[80:83]
	v_mfma_f32_16x16x32_bf16 v[68:71], v[172:175], v[212:215], v[68:71]
	v_mfma_f32_16x16x32_bf16 v[64:67], v[180:183], v[212:215], v[64:67]
	s_setprio 0
	s_barrier
; #define PG8_STAGE(bufoff, gbase, voff) do { _Pragma("unroll") for (int _i = 0; _i < 2; ++_i) \
;         __builtin_amdgcn_global_load_lds((const unsigned*)((const char*)(gbase) + (voff)[_i]), (PG8_LAS unsigned*)(lds + (bufoff) + ldsw + _i * 8192), 16, 0, 0); } while (0)
; #define PG8_LDA(dst, b, h) do { _Pragma("unroll") for (int m = 0; m < 4; ++m) _Pragma("unroll") for (int k = 0; k < 2; ++k) dst[m][k] = *(const PG8_LAS bf16x8*)(lds + PG8_SA(b, h) + aoff + m * 2048 + k * 1024); } while (0)
; #define PG8_MMA(ai, bj, At, Bt) do { __builtin_amdgcn_s_setprio(1); _Pragma("unroll") for (int m = 0; m < 4; ++m) _Pragma("unroll") for (int n = 0; n < 2; ++n) _Pragma("unroll") for (int k = 0; k < 2; ++k) \
;         acc[ai][bj][m][n] = __builtin_amdgcn_mfma_f32_16x16x32_bf16(Bt[n][k], At[m][k], acc[ai][bj][m][n], 0, 0, 0); __builtin_amdgcn_s_setprio(0); } while (0)
; #define PG8_WAIT_V(n) asm volatile("s_waitcnt vmcnt(" #n ")" ::: "memory")
; #define PG8_WAIT_L(n) asm volatile("s_waitcnt lgkmcnt(" #n ")" ::: "memory")
; #define PG8_BAR __builtin_amdgcn_s_barrier()
; #define PG8_SCHED __builtin_amdgcn_sched_barrier(0)
; template <class Epi, class Sched, bool ALIGN_EPI = false, bool SP2 = false>
; __device__ __forceinline__ void gemm_phase(PG8_LAS unsigned char* lds, const Gemm g, const Sched& S, const Epi& E) {
;     ...
;             PG8_LDA(At, 1, 1); PG8_STAGE(PG8_SB(1, 0), b3, voffB); PG8_STAGE(PG8_SB(1, 1), b3 + hstep, voffB); PG8_STAGE(PG8_SA(1, 0), a3, voffA);
;             PG8_WAIT_V(8); PG8_WAIT_L(0); PG8_BAR; PG8_MMA(1, 0, At, B0); PG8_MMA(1, 1, At, B1); PG8_BAR; PG8_SCHED;
	s_add_i32 s22, s52, s34
	v_lshl_add_u64 v[148:149], v[148:149], 0, s[6:7]
	s_mov_b32 m0, s22
	ds_read_b128 v[184:187], v155 offset:49152
	ds_read_b128 v[188:191], v155 offset:50176
	ds_read_b128 v[192:195], v155 offset:51200
	ds_read_b128 v[196:199], v155 offset:52224
	ds_read_b128 v[200:203], v155 offset:53248
	ds_read_b128 v[204:207], v155 offset:54272
	ds_read_b128 v[208:211], v155 offset:55296
	ds_read_b128 v[212:215], v155 offset:56320
	global_load_lds_dwordx4 v[148:149], off
	s_add_i32 m0, s22, 0x2000
	s_add_u32 s22, s26, 0xb0080
	v_lshl_add_u64 v[148:149], v[216:217], 0, s[6:7]
	s_addc_u32 s23, s27, 0
	s_add_i32 s26, s53, s34
	global_load_lds_dwordx4 v[148:149], off
	v_lshl_add_u64 v[148:149], s[22:23], 0, v[130:131]
	s_mov_b32 m0, s26
	s_nop 0
	global_load_lds_dwordx4 v[148:149], off
	v_lshl_add_u64 v[148:149], s[22:23], 0, v[134:135]
	s_add_i32 m0, s26, 0x2000
	s_nop 0
	global_load_lds_dwordx4 v[148:149], off
	v_lshl_add_u64 v[148:149], v[218:219], 0, s[6:7]
	s_mov_b32 m0, s40
	s_nop 0
	global_load_lds_dwordx4 v[148:149], off
	v_lshl_add_u64 v[148:149], v[220:221], 0, s[6:7]
	s_mov_b32 m0, s41
	s_nop 0
	global_load_lds_dwordx4 v[148:149], off
	s_waitcnt vmcnt(8)
	s_waitcnt lgkmcnt(0)
	s_barrier
	s_setprio 1
	v_mfma_f32_16x16x32_bf16 v[60:63], v[144:147], v[184:187], v[60:63]
	v_mfma_f32_16x16x32_bf16 v[56:59], v[160:163], v[184:187], v[56:59]
	v_mfma_f32_16x16x32_bf16 v[44:47], v[144:147], v[192:195], v[44:47]
	v_mfma_f32_16x16x32_bf16 v[40:43], v[160:163], v[192:195], v[40:43]
	v_mfma_f32_16x16x32_bf16 v[28:31], v[144:147], v[200:203], v[28:31]
	v_mfma_f32_16x16x32_bf16 v[24:27], v[160:163], v[200:203], v[24:27]
	v_mfma_f32_16x16x32_bf16 v[12:15], v[144:147], v[208:211], v[12:15]
	v_mfma_f32_16x16x32_bf16 v[8:11], v[160:163], v[208:211], v[8:11]
	v_mfma_f32_16x16x32_bf16 v[60:63], v[156:159], v[188:191], v[60:63]
	v_mfma_f32_16x16x32_bf16 v[56:59], v[164:167], v[188:191], v[56:59]
	v_mfma_f32_16x16x32_bf16 v[44:47], v[156:159], v[196:199], v[44:47]
	v_mfma_f32_16x16x32_bf16 v[40:43], v[164:167], v[196:199], v[40:43]
	v_mfma_f32_16x16x32_bf16 v[28:31], v[156:159], v[204:207], v[28:31]
	v_mfma_f32_16x16x32_bf16 v[24:27], v[164:167], v[204:207], v[24:27]
	v_mfma_f32_16x16x32_bf16 v[12:15], v[156:159], v[212:215], v[12:15]
	v_mfma_f32_16x16x32_bf16 v[8:11], v[164:167], v[212:215], v[8:11]
	v_mfma_f32_16x16x32_bf16 v[52:55], v[168:171], v[184:187], v[52:55]
	v_mfma_f32_16x16x32_bf16 v[48:51], v[176:179], v[184:187], v[48:51]
	v_mfma_f32_16x16x32_bf16 v[36:39], v[168:171], v[192:195], v[36:39]
	v_mfma_f32_16x16x32_bf16 v[32:35], v[176:179], v[192:195], v[32:35]
	v_mfma_f32_16x16x32_bf16 v[20:23], v[168:171], v[200:203], v[20:23]
	v_mfma_f32_16x16x32_bf16 v[16:19], v[176:179], v[200:203], v[16:19]
	v_mfma_f32_16x16x32_bf16 v[4:7], v[168:171], v[208:211], v[4:7]
	v_mfma_f32_16x16x32_bf16 v[0:3], v[176:179], v[208:211], v[0:3]
	v_mfma_f32_16x16x32_bf16 v[52:55], v[172:175], v[188:191], v[52:55]
	v_mfma_f32_16x16x32_bf16 v[48:51], v[180:183], v[188:191], v[48:51]
	v_mfma_f32_16x16x32_bf16 v[36:39], v[172:175], v[196:199], v[36:39]
	v_mfma_f32_16x16x32_bf16 v[32:35], v[180:183], v[196:199], v[32:35]
	v_mfma_f32_16x16x32_bf16 v[20:23], v[172:175], v[204:207], v[20:23]
	v_mfma_f32_16x16x32_bf16 v[16:19], v[180:183], v[204:207], v[16:19]
	v_mfma_f32_16x16x32_bf16 v[4:7], v[172:175], v[212:215], v[4:7]
	v_mfma_f32_16x16x32_bf16 v[0:3], v[180:183], v[212:215], v[0:3]
	s_setprio 0
	s_nop 0
	s_add_i32 s51, s51, 2
	s_add_u32 s49, s49, 0x100
	s_addc_u32 s50, s50, 0
	s_mov_b64 s[22:23], s[24:25]

; #define PG8_STAGE(bufoff, gbase, voff) do { _Pragma("unroll") for (int _i = 0; _i < 2; ++_i) \
;         __builtin_amdgcn_global_load_lds((const unsigned*)((const char*)(gbase) + (voff)[_i]), (PG8_LAS unsigned*)(lds + (bufoff) + ldsw + _i * 8192), 16, 0, 0); } while (0)
; #define PG8_LDA(dst, b, h) do { _Pragma("unroll") for (int m = 0; m < 4; ++m) _Pragma("unroll") for (int k = 0; k < 2; ++k) dst[m][k] = *(const PG8_LAS bf16x8*)(lds + PG8_SA(b, h) + aoff + m * 2048 + k * 1024); } while (0)
; #define PG8_LDB(dst, b, h) do { _Pragma("unroll") for (int n = 0; n < 2; ++n) _Pragma("unroll") for (int k = 0; k < 2; ++k) dst[n][k] = *(const PG8_LAS bf16x8*)(lds + PG8_SB(b, h) + boff + n * 2048 + k * 1024); } while (0)
; #define PG8_MMA(ai, bj, At, Bt) do { __builtin_amdgcn_s_setprio(1); _Pragma("unroll") for (int m = 0; m < 4; ++m) _Pragma("unroll") for (int n = 0; n < 2; ++n) _Pragma("unroll") for (int k = 0; k < 2; ++k) \
;         acc[ai][bj][m][n] = __builtin_amdgcn_mfma_f32_16x16x32_bf16(Bt[n][k], At[m][k], acc[ai][bj][m][n], 0, 0, 0); __builtin_amdgcn_s_setprio(0); } while (0)
; #define PG8_WAIT_V(n) asm volatile("s_waitcnt vmcnt(" #n ")" ::: "memory")
; #define PG8_WAIT_L(n) asm volatile("s_waitcnt lgkmcnt(" #n ")" ::: "memory")
; #define PG8_BAR __builtin_amdgcn_s_barrier()
; #define PG8_SCHED __builtin_amdgcn_sched_barrier(0)
; template <class Epi, class Sched, bool ALIGN_EPI = false, bool SP2 = false>
; __device__ __forceinline__ void gemm_phase(PG8_LAS unsigned char* lds, const Gemm g, const Sched& S, const Epi& E) {
;     ...
;             PG8_LDB(B0, 0, 0); PG8_LDB(B1, 0, 1); PG8_SCHED; PG8_LDA(At, 0, 0); PG8_STAGE(PG8_SA(1, 1), a1 + hstep, voffA);
;             PG8_WAIT_V(8); PG8_WAIT_L(0); PG8_BAR; PG8_MMA(0, 0, At, B0); PG8_MMA(0, 1, At, B1); PG8_BAR; PG8_SCHED;
;             PG8_LDA(At, 0, 1); PG8_STAGE(PG8_SB(0, 0), b2, voffB); PG8_STAGE(PG8_SB(0, 1), b2 + hstep, voffB); PG8_STAGE(PG8_SA(0, 0), a2, voffA);
;             PG8_WAIT_V(8); PG8_WAIT_L(0); PG8_BAR; PG8_MMA(1, 0, At, B0); PG8_MMA(1, 1, At, B1); PG8_BAR; PG8_SCHED;
.LBB0_862:
	ds_read_b128 v[144:147], v153
	ds_read_b128 v[156:159], v153 offset:1024
	ds_read_b128 v[160:163], v153 offset:2048
	ds_read_b128 v[164:167], v153 offset:3072
	ds_read_b128 v[168:171], v154
	ds_read_b128 v[172:175], v154 offset:1024
	ds_read_b128 v[176:179], v154 offset:2048
	ds_read_b128 v[180:183], v154 offset:3072
	s_add_u32 s24, s22, 0x100
	s_addc_u32 s25, s23, 0
	s_cmp_eq_u32 s51, 40
	s_cselect_b32 s29, s5, s25
	s_cselect_b32 s28, s4, s24
	s_cselect_b32 s27, s21, s50
	s_cselect_b32 s26, s20, s49
	v_lshl_add_u64 v[148:149], s[22:23], 0, v[136:137]
	s_add_i32 m0, s35, 0xc000
	ds_read_b128 v[184:187], v155
	ds_read_b128 v[188:191], v155 offset:1024
	ds_read_b128 v[192:195], v155 offset:2048
	ds_read_b128 v[196:199], v155 offset:3072
	ds_read_b128 v[200:203], v155 offset:4096
	ds_read_b128 v[204:207], v155 offset:5120
	ds_read_b128 v[208:211], v155 offset:6144
	ds_read_b128 v[212:215], v155 offset:7168
	global_load_lds_dwordx4 v[148:149], off
	v_lshl_add_u64 v[148:149], s[22:23], 0, v[138:139]
	s_add_i32 m0, s35, 0xe000
	s_nop 0
	global_load_lds_dwordx4 v[148:149], off
	s_waitcnt vmcnt(8)
	s_waitcnt lgkmcnt(0)
	s_barrier
	s_setprio 1
	v_mfma_f32_16x16x32_bf16 v[124:127], v[144:147], v[184:187], v[124:127]
	v_mfma_f32_16x16x32_bf16 v[120:123], v[160:163], v[184:187], v[120:123]
	v_mfma_f32_16x16x32_bf16 v[108:111], v[144:147], v[192:195], v[108:111]
	v_mfma_f32_16x16x32_bf16 v[104:107], v[160:163], v[192:195], v[104:107]
	v_mfma_f32_16x16x32_bf16 v[92:95], v[144:147], v[200:203], v[92:95]
	v_mfma_f32_16x16x32_bf16 v[88:91], v[160:163], v[200:203], v[88:91]
	v_mfma_f32_16x16x32_bf16 v[76:79], v[144:147], v[208:211], v[76:79]
	v_mfma_f32_16x16x32_bf16 v[72:75], v[160:163], v[208:211], v[72:75]
	v_mfma_f32_16x16x32_bf16 v[124:127], v[156:159], v[188:191], v[124:127]
	v_mfma_f32_16x16x32_bf16 v[120:123], v[164:167], v[188:191], v[120:123]
	v_mfma_f32_16x16x32_bf16 v[108:111], v[156:159], v[196:199], v[108:111]
	v_mfma_f32_16x16x32_bf16 v[104:107], v[164:167], v[196:199], v[104:107]
	v_mfma_f32_16x16x32_bf16 v[92:95], v[156:159], v[204:207], v[92:95]
	v_mfma_f32_16x16x32_bf16 v[88:91], v[164:167], v[204:207], v[88:91]
	v_mfma_f32_16x16x32_bf16 v[76:79], v[156:159], v[212:215], v[76:79]
	v_mfma_f32_16x16x32_bf16 v[72:75], v[164:167], v[212:215], v[72:75]
	v_mfma_f32_16x16x32_bf16 v[116:119], v[168:171], v[184:187], v[116:119]
	v_mfma_f32_16x16x32_bf16 v[112:115], v[176:179], v[184:187], v[112:115]
	v_mfma_f32_16x16x32_bf16 v[100:103], v[168:171], v[192:195], v[100:103]
	v_mfma_f32_16x16x32_bf16 v[96:99], v[176:179], v[192:195], v[96:99]
	v_mfma_f32_16x16x32_bf16 v[84:87], v[168:171], v[200:203], v[84:87]
	v_mfma_f32_16x16x32_bf16 v[80:83], v[176:179], v[200:203], v[80:83]
	v_mfma_f32_16x16x32_bf16 v[68:71], v[168:171], v[208:211], v[68:71]
	v_mfma_f32_16x16x32_bf16 v[64:67], v[176:179], v[208:211], v[64:67]
	v_mfma_f32_16x16x32_bf16 v[116:119], v[172:175], v[188:191], v[116:119]
	v_mfma_f32_16x16x32_bf16 v[112:115], v[180:183], v[188:191], v[112:115]
	v_mfma_f32_16x16x32_bf16 v[100:103], v[172:175], v[196:199], v[100:103]
	v_mfma_f32_16x16x32_bf16 v[96:99], v[180:183], v[196:199], v[96:99]
	v_mfma_f32_16x16x32_bf16 v[84:87], v[172:175], v[204:207], v[84:87]
	v_mfma_f32_16x16x32_bf16 v[80:83], v[180:183], v[204:207], v[80:83]
	v_mfma_f32_16x16x32_bf16 v[68:71], v[172:175], v[212:215], v[68:71]
	v_mfma_f32_16x16x32_bf16 v[64:67], v[180:183], v[212:215], v[64:67]
	s_setprio 0
	s_barrier
	s_add_i32 s22, s43, s34
	v_lshl_add_u64 v[148:149], s[26:27], 0, v[130:131]
	s_mov_b32 m0, s22
	ds_read_b128 v[184:187], v155 offset:16384
	ds_read_b128 v[188:191], v155 offset:17408
	ds_read_b128 v[192:195], v155 offset:18432
	ds_read_b128 v[196:199], v155 offset:19456
	ds_read_b128 v[200:203], v155 offset:20480
	ds_read_b128 v[204:207], v155 offset:21504
	ds_read_b128 v[208:211], v155 offset:22528
	ds_read_b128 v[212:215], v155 offset:23552
	global_load_lds_dwordx4 v[148:149], off
	s_add_i32 m0, s22, 0x2000
	s_add_u32 s22, s26, 0xb0000
	v_lshl_add_u64 v[216:217], s[26:27], 0, v[134:135]
	s_addc_u32 s23, s27, 0
	s_add_i32 s52, s44, s34
	global_load_lds_dwordx4 v[216:217], off
	v_lshl_add_u64 v[218:219], s[22:23], 0, v[130:131]
	s_mov_b32 m0, s52
	v_lshl_add_u64 v[220:221], s[28:29], 0, v[132:133]
	global_load_lds_dwordx4 v[218:219], off
	v_lshl_add_u64 v[218:219], s[22:23], 0, v[134:135]
	s_add_i32 m0, s52, 0x2000
	s_nop 0
	global_load_lds_dwordx4 v[218:219], off
	v_lshl_add_u64 v[218:219], s[28:29], 0, v[128:129]
	s_mov_b32 m0, s35
	s_nop 0
	global_load_lds_dwordx4 v[218:219], off
	s_mov_b32 m0, s36
	s_nop 0
	global_load_lds_dwordx4 v[220:221], off
	s_waitcnt vmcnt(8)
	s_waitcnt lgkmcnt(0)
	s_barrier
; #define PG8_STAGE(bufoff, gbase, voff) do { _Pragma("unroll") for (int _i = 0; _i < 2; ++_i) \
;         __builtin_amdgcn_global_load_lds((const unsigned*)((const char*)(gbase) + (voff)[_i]), (PG8_LAS unsigned*)(lds + (bufoff) + ldsw + _i * 8192), 16, 0, 0); } while (0)
; #define PG8_LDA(dst, b, h) do { _Pragma("unroll") for (int m = 0; m < 4; ++m) _Pragma("unroll") for (int k = 0; k < 2; ++k) dst[m][k] = *(const PG8_LAS bf16x8*)(lds + PG8_SA(b, h) + aoff + m * 2048 + k * 1024); } while (0)
; #define PG8_LDB(dst, b, h) do { _Pragma("unroll") for (int n = 0; n < 2; ++n) _Pragma("unroll") for (int k = 0; k < 2; ++k) dst[n][k] = *(const PG8_LAS bf16x8*)(lds + PG8_SB(b, h) + boff + n * 2048 + k * 1024); } while (0)
; #define PG8_MMA(ai, bj, At, Bt) do { __builtin_amdgcn_s_setprio(1); _Pragma("unroll") for (int m = 0; m < 4; ++m) _Pragma("unroll") for (int n = 0; n < 2; ++n) _Pragma("unroll") for (int k = 0; k < 2; ++k) \
;         acc[ai][bj][m][n] = __builtin_amdgcn_mfma_f32_16x16x32_bf16(Bt[n][k], At[m][k], acc[ai][bj][m][n], 0, 0, 0); __builtin_amdgcn_s_setprio(0); } while (0)
; #define PG8_WAIT_V(n) asm volatile("s_waitcnt vmcnt(" #n ")" ::: "memory")
; #define PG8_WAIT_L(n) asm volatile("s_waitcnt lgkmcnt(" #n ")" ::: "memory")
; #define PG8_BAR __builtin_amdgcn_s_barrier()
; #define PG8_SCHED __builtin_amdgcn_sched_barrier(0)
; template <class Epi, class Sched, bool ALIGN_EPI = false, bool SP2 = false>
; __device__ __forceinline__ void gemm_phase(PG8_LAS unsigned char* lds, const Gemm g, const Sched& S, const Epi& E) {
;     ...
;             PG8_WAIT_V(8); PG8_WAIT_L(0); PG8_BAR; PG8_MMA(1, 0, At, B0); PG8_MMA(1, 1, At, B1); PG8_BAR; PG8_SCHED;
;             PG8_LDB(B0, 1, 0); PG8_LDB(B1, 1, 1); PG8_SCHED; PG8_LDA(At, 1, 0); PG8_STAGE(PG8_SA(0, 1), a2 + hstep, voffA);
;             PG8_WAIT_V(8); PG8_WAIT_L(0); PG8_BAR; PG8_MMA(0, 0, At, B0); PG8_MMA(0, 1, At, B1); PG8_BAR; PG8_SCHED;
	s_setprio 1
	v_mfma_f32_16x16x32_bf16 v[60:63], v[144:147], v[184:187], v[60:63]
	v_mfma_f32_16x16x32_bf16 v[56:59], v[160:163], v[184:187], v[56:59]
	v_mfma_f32_16x16x32_bf16 v[44:47], v[144:147], v[192:195], v[44:47]
	v_mfma_f32_16x16x32_bf16 v[40:43], v[160:163], v[192:195], v[40:43]
	v_mfma_f32_16x16x32_bf16 v[28:31], v[144:147], v[200:203], v[28:31]
	v_mfma_f32_16x16x32_bf16 v[24:27], v[160:163], v[200:203], v[24:27]
	v_mfma_f32_16x16x32_bf16 v[12:15], v[144:147], v[208:211], v[12:15]
	v_mfma_f32_16x16x32_bf16 v[8:11], v[160:163], v[208:211], v[8:11]
	v_mfma_f32_16x16x32_bf16 v[60:63], v[156:159], v[188:191], v[60:63]
	v_mfma_f32_16x16x32_bf16 v[56:59], v[164:167], v[188:191], v[56:59]
	v_mfma_f32_16x16x32_bf16 v[44:47], v[156:159], v[196:199], v[44:47]
	v_mfma_f32_16x16x32_bf16 v[40:43], v[164:167], v[196:199], v[40:43]
	v_mfma_f32_16x16x32_bf16 v[28:31], v[156:159], v[204:207], v[28:31]
	v_mfma_f32_16x16x32_bf16 v[24:27], v[164:167], v[204:207], v[24:27]
	v_mfma_f32_16x16x32_bf16 v[12:15], v[156:159], v[212:215], v[12:15]
	v_mfma_f32_16x16x32_bf16 v[8:11], v[164:167], v[212:215], v[8:11]
	v_mfma_f32_16x16x32_bf16 v[52:55], v[168:171], v[184:187], v[52:55]
	v_mfma_f32_16x16x32_bf16 v[48:51], v[176:179], v[184:187], v[48:51]
	v_mfma_f32_16x16x32_bf16 v[36:39], v[168:171], v[192:195], v[36:39]
	v_mfma_f32_16x16x32_bf16 v[32:35], v[176:179], v[192:195], v[32:35]
	v_mfma_f32_16x16x32_bf16 v[20:23], v[168:171], v[200:203], v[20:23]
	v_mfma_f32_16x16x32_bf16 v[16:19], v[176:179], v[200:203], v[16:19]
	v_mfma_f32_16x16x32_bf16 v[4:7], v[168:171], v[208:211], v[4:7]
	v_mfma_f32_16x16x32_bf16 v[0:3], v[176:179], v[208:211], v[0:3]
	v_mfma_f32_16x16x32_bf16 v[52:55], v[172:175], v[188:191], v[52:55]
	v_mfma_f32_16x16x32_bf16 v[48:51], v[180:183], v[188:191], v[48:51]
	v_mfma_f32_16x16x32_bf16 v[36:39], v[172:175], v[196:199], v[36:39]
	v_mfma_f32_16x16x32_bf16 v[32:35], v[180:183], v[196:199], v[32:35]
	v_mfma_f32_16x16x32_bf16 v[20:23], v[172:175], v[204:207], v[20:23]
	v_mfma_f32_16x16x32_bf16 v[16:19], v[180:183], v[204:207], v[16:19]
	v_mfma_f32_16x16x32_bf16 v[4:7], v[172:175], v[212:215], v[4:7]
	v_mfma_f32_16x16x32_bf16 v[0:3], v[180:183], v[212:215], v[0:3]
	s_setprio 0
	s_barrier
	s_add_i32 s52, 0, 0x18000
	s_add_i32 s53, 0, 0x1c000
	v_add_u32_e32 v164, s52, v151
	v_add_u32_e32 v180, s53, v151
	ds_read_b128 v[144:147], v164
	ds_read_b128 v[156:159], v164 offset:1024
	ds_read_b128 v[160:163], v164 offset:2048
	ds_read_b128 v[164:167], v164 offset:3072
	ds_read_b128 v[168:171], v180
	ds_read_b128 v[172:175], v180 offset:1024
	ds_read_b128 v[176:179], v180 offset:2048
	ds_read_b128 v[180:183], v180 offset:3072
	s_add_u32 s22, s28, 0xb0000
	s_addc_u32 s23, s29, 0
	s_mov_b32 m0, s37
	v_lshl_add_u64 v[222:223], s[22:23], 0, v[128:129]
	ds_read_b128 v[184:187], v155 offset:32768
	ds_read_b128 v[188:191], v155 offset:33792
	ds_read_b128 v[192:195], v155 offset:34816
	ds_read_b128 v[196:199], v155 offset:35840
	ds_read_b128 v[200:203], v155 offset:36864
	ds_read_b128 v[204:207], v155 offset:37888
	ds_read_b128 v[208:211], v155 offset:38912
	ds_read_b128 v[212:215], v155 offset:39936
	global_load_lds_dwordx4 v[222:223], off
	v_lshl_add_u64 v[222:223], s[22:23], 0, v[132:133]
	s_mov_b32 m0, s38
	s_nop 0
	global_load_lds_dwordx4 v[222:223], off
	s_waitcnt vmcnt(8)
	s_waitcnt lgkmcnt(0)
	s_barrier
	s_setprio 1
	v_mfma_f32_16x16x32_bf16 v[124:127], v[144:147], v[184:187], v[124:127]
	v_mfma_f32_16x16x32_bf16 v[120:123], v[160:163], v[184:187], v[120:123]
	v_mfma_f32_16x16x32_bf16 v[108:111], v[144:147], v[192:195], v[108:111]
	v_mfma_f32_16x16x32_bf16 v[104:107], v[160:163], v[192:195], v[104:107]
	v_mfma_f32_16x16x32_bf16 v[92:95], v[144:147], v[200:203], v[92:95]
	v_mfma_f32_16x16x32_bf16 v[88:91], v[160:163], v[200:203], v[88:91]
	v_mfma_f32_16x16x32_bf16 v[76:79], v[144:147], v[208:211], v[76:79]
	v_mfma_f32_16x16x32_bf16 v[72:75], v[160:163], v[208:211], v[72:75]
	v_mfma_f32_16x16x32_bf16 v[124:127], v[156:159], v[188:191], v[124:127]
	v_mfma_f32_16x16x32_bf16 v[120:123], v[164:167], v[188:191], v[120:123]
	v_mfma_f32_16x16x32_bf16 v[108:111], v[156:159], v[196:199], v[108:111]
	v_mfma_f32_16x16x32_bf16 v[104:107], v[164:167], v[196:199], v[104:107]
	v_mfma_f32_16x16x32_bf16 v[92:95], v[156:159], v[204:207], v[92:95]
	v_mfma_f32_16x16x32_bf16 v[88:91], v[164:167], v[204:207], v[88:91]
	v_mfma_f32_16x16x32_bf16 v[76:79], v[156:159], v[212:215], v[76:79]
	v_mfma_f32_16x16x32_bf16 v[72:75], v[164:167], v[212:215], v[72:75]
	v_mfma_f32_16x16x32_bf16 v[116:119], v[168:171], v[184:187], v[116:119]
	v_mfma_f32_16x16x32_bf16 v[112:115], v[176:179], v[184:187], v[112:115]
	v_mfma_f32_16x16x32_bf16 v[100:103], v[168:171], v[192:195], v[100:103]
	v_mfma_f32_16x16x32_bf16 v[96:99], v[176:179], v[192:195], v[96:99]
	v_mfma_f32_16x16x32_bf16 v[84:87], v[168:171], v[200:203], v[84:87]
	v_mfma_f32_16x16x32_bf16 v[80:83], v[176:179], v[200:203], v[80:83]
	v_mfma_f32_16x16x32_bf16 v[68:71], v[168:171], v[208:211], v[68:71]
	v_mfma_f32_16x16x32_bf16 v[64:67], v[176:179], v[208:211], v[64:67]
	v_mfma_f32_16x16x32_bf16 v[116:119], v[172:175], v[188:191], v[116:119]
	v_mfma_f32_16x16x32_bf16 v[112:115], v[180:183], v[188:191], v[112:115]
	v_mfma_f32_16x16x32_bf16 v[100:103], v[172:175], v[196:199], v[100:103]
	v_mfma_f32_16x16x32_bf16 v[96:99], v[180:183], v[196:199], v[96:99]
	v_mfma_f32_16x16x32_bf16 v[84:87], v[172:175], v[204:207], v[84:87]
	v_mfma_f32_16x16x32_bf16 v[80:83], v[180:183], v[204:207], v[80:83]
	v_mfma_f32_16x16x32_bf16 v[68:71], v[172:175], v[212:215], v[68:71]
	v_mfma_f32_16x16x32_bf16 v[64:67], v[180:183], v[212:215], v[64:67]
	s_setprio 0
	s_barrier
; #define PG8_STAGE(bufoff, gbase, voff) do { _Pragma("unroll") for (int _i = 0; _i < 2; ++_i) \
;         __builtin_amdgcn_global_load_lds((const unsigned*)((const char*)(gbase) + (voff)[_i]), (PG8_LAS unsigned*)(lds + (bufoff) + ldsw + _i * 8192), 16, 0, 0); } while (0)
; #define PG8_LDA(dst, b, h) do { _Pragma("unroll") for (int m = 0; m < 4; ++m) _Pragma("unroll") for (int k = 0; k < 2; ++k) dst[m][k] = *(const PG8_LAS bf16x8*)(lds + PG8_SA(b, h) + aoff + m * 2048 + k * 1024); } while (0)
; #define PG8_MMA(ai, bj, At, Bt) do { __builtin_amdgcn_s_setprio(1); _Pragma("unroll") for (int m = 0; m < 4; ++m) _Pragma("unroll") for (int n = 0; n < 2; ++n) _Pragma("unroll") for (int k = 0; k < 2; ++k) \
;         acc[ai][bj][m][n] = __builtin_amdgcn_mfma_f32_16x16x32_bf16(Bt[n][k], At[m][k], acc[ai][bj][m][n], 0, 0, 0); __builtin_amdgcn_s_setprio(0); } while (0)
; #define PG8_WAIT_V(n) asm volatile("s_waitcnt vmcnt(" #n ")" ::: "memory")
; #define PG8_WAIT_L(n) asm volatile("s_waitcnt lgkmcnt(" #n ")" ::: "memory")
; #define PG8_BAR __builtin_amdgcn_s_barrier()
; #define PG8_SCHED __builtin_amdgcn_sched_barrier(0)
; template <class Epi, class Sched, bool ALIGN_EPI = false, bool SP2 = false>
; __device__ __forceinline__ void gemm_phase(PG8_LAS unsigned char* lds, const Gemm g, const Sched& S, const Epi& E) {
;     ...
;             PG8_LDA(At, 1, 1); PG8_STAGE(PG8_SB(1, 0), b3, voffB); PG8_STAGE(PG8_SB(1, 1), b3 + hstep, voffB); PG8_STAGE(PG8_SA(1, 0), a3, voffA);
;             PG8_WAIT_V(8); PG8_WAIT_L(0); PG8_BAR; PG8_MMA(1, 0, At, B0); PG8_MMA(1, 1, At, B1); PG8_BAR; PG8_SCHED;
;     ...
;         if constexpr (ALIGN_EPI) { if (wr == 0) PG8_BAR; }
	s_add_i32 s22, s52, s34
	v_lshl_add_u64 v[148:149], v[148:149], 0, s[6:7]
	s_mov_b32 m0, s22
	ds_read_b128 v[184:187], v155 offset:49152
	ds_read_b128 v[188:191], v155 offset:50176
	ds_read_b128 v[192:195], v155 offset:51200
	ds_read_b128 v[196:199], v155 offset:52224
	ds_read_b128 v[200:203], v155 offset:53248
	ds_read_b128 v[204:207], v155 offset:54272
	ds_read_b128 v[208:211], v155 offset:55296
	ds_read_b128 v[212:215], v155 offset:56320
	global_load_lds_dwordx4 v[148:149], off
	s_add_i32 m0, s22, 0x2000
	s_add_u32 s22, s26, 0xb0080
	v_lshl_add_u64 v[148:149], v[216:217], 0, s[6:7]
	s_addc_u32 s23, s27, 0
	s_add_i32 s26, s53, s34
	global_load_lds_dwordx4 v[148:149], off
	v_lshl_add_u64 v[148:149], s[22:23], 0, v[130:131]
	s_mov_b32 m0, s26
	s_nop 0
	global_load_lds_dwordx4 v[148:149], off
	v_lshl_add_u64 v[148:149], s[22:23], 0, v[134:135]
	s_add_i32 m0, s26, 0x2000
	s_nop 0
	global_load_lds_dwordx4 v[148:149], off
	v_lshl_add_u64 v[148:149], v[218:219], 0, s[6:7]
	s_mov_b32 m0, s40
	s_nop 0
	global_load_lds_dwordx4 v[148:149], off
	v_lshl_add_u64 v[148:149], v[220:221], 0, s[6:7]
	s_mov_b32 m0, s41
	s_nop 0
	global_load_lds_dwordx4 v[148:149], off
	s_waitcnt vmcnt(8)
	s_waitcnt lgkmcnt(0)
	s_barrier
	s_setprio 1
	v_mfma_f32_16x16x32_bf16 v[60:63], v[144:147], v[184:187], v[60:63]
	v_mfma_f32_16x16x32_bf16 v[56:59], v[160:163], v[184:187], v[56:59]
	v_mfma_f32_16x16x32_bf16 v[44:47], v[144:147], v[192:195], v[44:47]
	v_mfma_f32_16x16x32_bf16 v[40:43], v[160:163], v[192:195], v[40:43]
	v_mfma_f32_16x16x32_bf16 v[28:31], v[144:147], v[200:203], v[28:31]
	v_mfma_f32_16x16x32_bf16 v[24:27], v[160:163], v[200:203], v[24:27]
	v_mfma_f32_16x16x32_bf16 v[12:15], v[144:147], v[208:211], v[12:15]
	v_mfma_f32_16x16x32_bf16 v[8:11], v[160:163], v[208:211], v[8:11]
	v_mfma_f32_16x16x32_bf16 v[60:63], v[156:159], v[188:191], v[60:63]
	v_mfma_f32_16x16x32_bf16 v[56:59], v[164:167], v[188:191], v[56:59]
	v_mfma_f32_16x16x32_bf16 v[44:47], v[156:159], v[196:199], v[44:47]
	v_mfma_f32_16x16x32_bf16 v[40:43], v[164:167], v[196:199], v[40:43]
	v_mfma_f32_16x16x32_bf16 v[28:31], v[156:159], v[204:207], v[28:31]
	v_mfma_f32_16x16x32_bf16 v[24:27], v[164:167], v[204:207], v[24:27]
	v_mfma_f32_16x16x32_bf16 v[12:15], v[156:159], v[212:215], v[12:15]
	v_mfma_f32_16x16x32_bf16 v[8:11], v[164:167], v[212:215], v[8:11]
	v_mfma_f32_16x16x32_bf16 v[52:55], v[168:171], v[184:187], v[52:55]
	v_mfma_f32_16x16x32_bf16 v[48:51], v[176:179], v[184:187], v[48:51]
	v_mfma_f32_16x16x32_bf16 v[36:39], v[168:171], v[192:195], v[36:39]
	v_mfma_f32_16x16x32_bf16 v[32:35], v[176:179], v[192:195], v[32:35]
	v_mfma_f32_16x16x32_bf16 v[20:23], v[168:171], v[200:203], v[20:23]
	v_mfma_f32_16x16x32_bf16 v[16:19], v[176:179], v[200:203], v[16:19]
	v_mfma_f32_16x16x32_bf16 v[4:7], v[168:171], v[208:211], v[4:7]
	v_mfma_f32_16x16x32_bf16 v[0:3], v[176:179], v[208:211], v[0:3]
	v_mfma_f32_16x16x32_bf16 v[52:55], v[172:175], v[188:191], v[52:55]
	v_mfma_f32_16x16x32_bf16 v[48:51], v[180:183], v[188:191], v[48:51]
	v_mfma_f32_16x16x32_bf16 v[36:39], v[172:175], v[196:199], v[36:39]
	v_mfma_f32_16x16x32_bf16 v[32:35], v[180:183], v[196:199], v[32:35]
	v_mfma_f32_16x16x32_bf16 v[20:23], v[172:175], v[204:207], v[20:23]
	v_mfma_f32_16x16x32_bf16 v[16:19], v[180:183], v[204:207], v[16:19]
	v_mfma_f32_16x16x32_bf16 v[4:7], v[172:175], v[212:215], v[4:7]
	v_mfma_f32_16x16x32_bf16 v[0:3], v[180:183], v[212:215], v[0:3]
	s_setprio 0
	s_nop 0
	s_add_i32 s51, s51, 2
	s_add_u32 s49, s49, 0x100
	s_addc_u32 s50, s50, 0
	s_cmp_gt_u32 s51, 41
	s_mov_b64 s[22:23], s[24:25]
	s_cbranch_scc0 .Lrot_862
	s_barrier
	s_and_b64 vcc, exec, s[10:11]
	s_cbranch_vccz .LBB0_865
	s_barrier
